# peel + epilogue cross-lane sums via v_permlane16/32_swap instead of ds_bpermute (192 sites)
# speedup vs baseline: 1.0145x; 1.0145x over previous
; __device__ __forceinline__ void rstd8(const float* ss, int row0, int fq, float (&rs)[8]) {
;     f32x4 a[8];
; #pragma unroll
;     for (int k = 0; k < 8; ++k) a[k] = *(const f32x4*)(ss + (size_t)(row0 + (k >> 2) * 128 + (k & 3) * 16) * 16 + 4 * fq);
; #pragma unroll
;     for (int k = 0; k < 8; ++k) { float s = (a[k][0] + a[k][1]) + (a[k][2] + a[k][3]); s += __shfl_xor(s, 16); s += __shfl_xor(s, 32); rs[k] = __builtin_amdgcn_rsqf(s * (1.f / 1024.f) + EPS); }
;     __device__ __forceinline__ void operator()(const pg8::f32x4 (&acc)[2][2][4][2], const Unit& u, int wr, int wc, int fr, int fq) const {
;         const int pn = u.pn; const int row0 = u.pm * BM + wr * 64 + fr; const int sp = pn / tps, pt = pn - sp * tps; bf16* const Ob = O + (size_t)sp * sstride;
;         float rsv[8]; rstd8(ss, row0, fq, rsv);
;         if (pn < rope_tiles) {
;             const float s_ = (pn >= sc_lo && pn < sc_hi) ? sc : 1.f;
.LBB0_200:
	s_lshl_b32 s19, s4, 8
	s_add_i32 s19, s19, s48
	v_or_b32_e32 v178, s19, v1
	v_or_b32_e32 v176, 16, v178
	v_ashrrev_i32_e32 v179, 31, v178
	v_ashrrev_i32_e32 v177, 31, v176
	v_lshlrev_b64 v[158:159], 6, v[178:179]
	v_lshlrev_b64 v[168:169], 6, v[176:177]
	v_lshl_add_u64 v[158:159], v[144:145], 0, v[158:159]
	v_lshl_add_u64 v[168:169], v[144:145], 0, v[168:169]
	v_or_b32_e32 v170, 32, v178
	global_load_dwordx4 v[190:193], v[158:159], off
	global_load_dwordx4 v[194:197], v[168:169], off
	v_ashrrev_i32_e32 v171, 31, v170
	v_or_b32_e32 v168, 48, v178
	v_lshlrev_b64 v[158:159], 6, v[170:171]
	v_ashrrev_i32_e32 v169, 31, v168
	v_lshl_add_u64 v[158:159], v[144:145], 0, v[158:159]
	v_lshlrev_b64 v[180:181], 6, v[168:169]
	v_lshl_add_u64 v[180:181], v[144:145], 0, v[180:181]
	global_load_dwordx4 v[198:201], v[158:159], off
	global_load_dwordx4 v[202:205], v[180:181], off
	v_add_u32_e32 v158, 0x80, v178
	v_ashrrev_i32_e32 v159, 31, v158
	v_lshlrev_b64 v[180:181], 6, v[158:159]
	v_lshl_add_u64 v[180:181], v[144:145], 0, v[180:181]
	global_load_dwordx4 v[206:209], v[180:181], off
	v_add_u32_e32 v188, 0x90, v178
	v_ashrrev_i32_e32 v189, 31, v188
	v_lshlrev_b64 v[180:181], 6, v[188:189]
	v_lshl_add_u64 v[180:181], v[144:145], 0, v[180:181]
	global_load_dwordx4 v[210:213], v[180:181], off
	v_add_u32_e32 v186, 0xa0, v178
	v_ashrrev_i32_e32 v187, 31, v186
	v_add_u32_e32 v184, 0xb0, v178
	v_lshlrev_b64 v[180:181], 6, v[186:187]
	v_lshl_add_u64 v[180:181], v[144:145], 0, v[180:181]
	v_ashrrev_i32_e32 v185, 31, v184
	global_load_dwordx4 v[214:217], v[180:181], off
	v_lshlrev_b64 v[180:181], 6, v[184:185]
	v_lshl_add_u64 v[180:181], v[144:145], 0, v[180:181]
	global_load_dwordx4 v[218:221], v[180:181], off
	v_and_b32_e32 v155, 64, v173
	v_xor_b32_e32 v138, 16, v173
	v_add_u32_e32 v155, 64, v155
	v_xor_b32_e32 v157, 32, v173
	v_cmp_lt_i32_e32 vcc, v138, v155
	s_ashr_i32 s1, s0, 31
	s_lshr_b32 s1, s1, 12
	v_cndmask_b32_e32 v138, v173, v138, vcc
	v_cmp_lt_i32_e32 vcc, v157, v155
	v_lshlrev_b32_e32 v138, 2, v138
	s_add_i32 s1, s0, s1
	v_cndmask_b32_e32 v155, v173, v157, vcc
	v_lshlrev_b32_e32 v155, 2, v155
	s_ashr_i32 s4, s1, 20
	s_ashr_i32 s5, s4, 31
	s_lshl_b64 s[26:27], s[4:5], 26
	s_add_u32 s1, s46, s26
	s_addc_u32 s2, s47, s27
	s_cmp_gt_i32 s0, 3
	s_mov_b64 s[26:27], -1
	s_waitcnt vmcnt(0)
	v_add_f32_e32 v157, v190, v191
	v_add_f32_e32 v160, v192, v193
	v_add_f32_e32 v157, v157, v160
	v_add_f32_e32 v160, v194, v195
	v_add_f32_e32 v162, v196, v197
	v_mov_b32_e32 v191, v157
	s_nop 1
	v_permlane16_swap_b32 v157, v191
	v_add_f32_e32 v160, v160, v162
	v_add_f32_e32 v164, v198, v199
	v_add_f32_e32 v166, v200, v201
	v_add_f32_e32 v172, v202, v203
	v_add_f32_e32 v174, v204, v205
	v_add_f32_e32 v162, v164, v166
	v_add_f32_e32 v164, v172, v174
	v_add_f32_e32 v180, v206, v207
	v_add_f32_e32 v181, v208, v209
	v_mov_b32_e32 v172, v160
	s_nop 1
	v_permlane16_swap_b32 v160, v172
	v_add_f32_e32 v166, v180, v181
	v_mov_b32_e32 v180, v164
	s_nop 1
	v_permlane16_swap_b32 v164, v180
	v_add_f32_e32 v182, v210, v211
	v_add_f32_e32 v190, v212, v213
	s_waitcnt lgkmcnt(2)
	v_add_f32_e32 v157, v157, v191
	v_add_f32_e32 v181, v182, v190
	v_mov_b32_e32 v174, v162
	s_nop 1
	v_permlane16_swap_b32 v162, v174
	v_mov_b32_e32 v190, v157
	s_nop 1
	v_permlane32_swap_b32 v157, v190
	s_waitcnt lgkmcnt(3)
	v_add_f32_e32 v160, v160, v172
	s_waitcnt lgkmcnt(2)
	v_add_f32_e32 v164, v164, v180
	v_mov_b32_e32 v172, v160
	s_nop 1
	v_permlane32_swap_b32 v160, v172
	v_mov_b32_e32 v182, v166
	s_nop 1
	v_permlane16_swap_b32 v166, v182
	v_mov_b32_e32 v180, v164
	s_nop 1
	v_permlane32_swap_b32 v164, v180
	s_waitcnt lgkmcnt(4)
	v_add_f32_e32 v162, v162, v174
	s_waitcnt lgkmcnt(3)
	v_add_f32_e32 v157, v157, v190
	v_mov_b32_e32 v174, v162
	s_nop 1
	v_permlane32_swap_b32 v162, v174
	v_fmamk_f32 v157, v157, 0x3a800000, v175
	s_waitcnt lgkmcnt(3)
	v_add_f32_e32 v160, v160, v172
	s_waitcnt lgkmcnt(2)
	v_add_f32_e32 v166, v166, v182
	s_waitcnt lgkmcnt(1)
	v_add_f32_e32 v164, v164, v180
	v_rsq_f32_e32 v180, v157
	v_fmamk_f32 v157, v160, 0x3a800000, v175
	v_mov_b32_e32 v191, v166
	s_nop 1
	v_permlane32_swap_b32 v166, v191
	v_rsq_f32_e32 v182, v157
	v_mov_b32_e32 v157, v181
	s_nop 1
	v_permlane16_swap_b32 v181, v157
	s_waitcnt lgkmcnt(2)
	v_add_f32_e32 v162, v162, v174
	v_fmamk_f32 v160, v162, 0x3a800000, v175
	v_fmamk_f32 v162, v164, 0x3a800000, v175
	v_rsq_f32_e32 v172, v160
	v_rsq_f32_e32 v174, v162
	s_waitcnt lgkmcnt(1)
	v_add_f32_e32 v160, v166, v191
	s_waitcnt lgkmcnt(0)
	v_add_f32_e32 v157, v181, v157
	v_add_f32_e32 v162, v214, v215
	v_add_f32_e32 v166, v216, v217
	v_add_f32_e32 v181, v218, v219
	v_add_f32_e32 v190, v220, v221
	v_fmamk_f32 v160, v160, 0x3a800000, v175
	v_add_f32_e32 v162, v162, v166
	v_add_f32_e32 v181, v181, v190
	v_rsq_f32_e32 v164, v160
	v_mov_b32_e32 v160, v157
	s_nop 1
	v_permlane32_swap_b32 v157, v160
	v_mov_b32_e32 v166, v162
	s_nop 1
	v_permlane16_swap_b32 v162, v166
	v_mov_b32_e32 v138, v181
	s_nop 1
	v_permlane16_swap_b32 v181, v138
	s_waitcnt lgkmcnt(2)
	v_add_f32_e32 v157, v157, v160
	s_waitcnt lgkmcnt(1)
	v_add_f32_e32 v160, v162, v166
	s_waitcnt lgkmcnt(0)
	v_add_f32_e32 v138, v181, v138
	v_mov_b32_e32 v162, v160
	s_nop 1
	v_permlane32_swap_b32 v160, v162
	v_mov_b32_e32 v155, v138
	s_nop 1
	v_permlane32_swap_b32 v138, v155
	v_fmamk_f32 v157, v157, 0x3a800000, v175
	v_rsq_f32_e32 v166, v157
	s_waitcnt lgkmcnt(1)
	v_add_f32_e32 v157, v160, v162
	s_waitcnt lgkmcnt(0)
	v_add_f32_e32 v138, v138, v155
	v_fmamk_f32 v157, v157, 0x3a800000, v175
	v_fmamk_f32 v138, v138, 0x3a800000, v175
	v_rsq_f32_e32 v160, v157
	v_rsq_f32_e32 v162, v138
	s_cbranch_scc1 .LBB0_203
	s_andn2_b64 vcc, exec, s[26:27]
	s_cbranch_vccz .LBB0_208

; __device__ __forceinline__ unsigned cvt_pk_bf16(float lo, float hi) { unsigned r; asm volatile("v_cvt_pk_bf16_f32 %0, %1, %2" : "=v"(r) : "v"(lo), "v"(hi)); return r; }
; __device__ __forceinline__ float bflo(unsigned w) { return __uint_as_float(w << 16); }
; __device__ __forceinline__ float bfhi(unsigned w) { return __uint_as_float(w & 0xffff0000u); }
;     __device__ __forceinline__ void ld(Ld& L, size_t o) const {
; #pragma unroll
;         for (int bj = 0; bj < 2; ++bj) { if (BASEF32) { L.a[bj][0] = *(const f32x4*)((const float*)base + o + bj * HALF); L.a[bj][1] = *(const f32x4*)((const float*)base + o + bj * HALF + 4); }
;             else { const v4u w = *(const v4u*)((const bf16*)base + o + bj * HALF); L.a[bj][0] = __builtin_bit_cast(f32x4, w); } }
;     }
;     __device__ __forceinline__ void operator()(const pg8::f32x4 (&acc)[2][2][4][2], const Unit& u, int wr, int wc, int fr, int fq) const {
;         const int row0 = u.pm * BM + wr * 64 + fr, col0 = u.pn * BM + wc * 32 + 8 * fq;
;         Ld nx; ld(nx, (size_t)row0 * DM_ + col0);
; #pragma unroll
;         for (int k = 0; k < 8; ++k) { const int ai = k >> 2, m = k & 3; const int row = row0 + ai * HALF + m * 16; float q = 0.f; const Ld cu = nx;
;             if (k < 7) ld(nx, (size_t)(row0 + ((k + 1) >> 2) * HALF + ((k + 1) & 3) * 16) * DM_ + col0);
; #pragma unroll
;             for (int bj = 0; bj < 2; ++bj) { const size_t o = (size_t)row * DM_ + col0 + bj * HALF; f32x4 b0, b1;
;                 if (BASEF32) { b0 = cu.a[bj][0]; b1 = cu.a[bj][1]; }
;                 else { const v4u w = __builtin_bit_cast(v4u, cu.a[bj][0]); b0 = (f32x4){bflo(w.x), bfhi(w.x), bflo(w.y), bfhi(w.y)}; b1 = (f32x4){bflo(w.z), bfhi(w.z), bflo(w.w), bfhi(w.w)}; }
;                 const f32x4 r0 = b0 + acc[ai][bj][m][0], r1 = b1 + acc[ai][bj][m][1];
;                 q += (r0[0] * r0[0] + r0[1] * r0[1]) + (r0[2] * r0[2] + r0[3] * r0[3]) + (r1[0] * r1[0] + r1[1] * r1[1]) + (r1[2] * r1[2] + r1[3] * r1[3]);
;                 v4u w; w.x = cvt_pk_bf16(r0[0], r0[1]); w.y = cvt_pk_bf16(r0[2], r0[3]); w.z = cvt_pk_bf16(r1[0], r1[1]); w.w = cvt_pk_bf16(r1[2], r1[3]); *(v4u*)(out + o) = w; }
;             q += __shfl_xor(q, 16); q += __shfl_xor(q, 32); if (fq == 0) ssq[(size_t)row * 16 + u.pn * 4 + wc] = q; }
.LBB0_608:
	v_lshl_add_u32 v164, s30, 8, v1
	v_lshl_or_b32 v162, s10, 8, v171
	v_ashrrev_i32_e32 v165, 31, v164
	v_ashrrev_i32_e32 v163, 31, v162
	v_lshlrev_b64 v[130:131], 12, v[164:165]
	v_lshl_add_u64 v[130:131], s[4:5], 0, v[130:131]
	v_lshlrev_b64 v[132:133], 2, v[162:163]
	v_lshl_add_u64 v[130:131], v[130:131], 0, v[132:133]
	global_load_dwordx4 v[178:181], v[130:131], off
	global_load_dwordx4 v[182:185], v[130:131], off offset:16
	global_load_dwordx4 v[186:189], v[130:131], off offset:512
	global_load_dwordx4 v[190:193], v[130:131], off offset:528
	v_or_b32_e32 v166, 16, v164
	v_ashrrev_i32_e32 v167, 31, v166
	v_lshlrev_b64 v[130:131], 12, v[166:167]
	v_lshl_add_u64 v[130:131], s[4:5], 0, v[130:131]
	v_lshl_add_u64 v[134:135], v[130:131], 0, v[132:133]
	global_load_dwordx4 v[138:141], v[134:135], off offset:16
	global_load_dwordx4 v[142:145], v[134:135], off
	global_load_dwordx4 v[130:133], v[134:135], off offset:528
	s_nop 0
	global_load_dwordx4 v[134:137], v[134:135], off offset:512
	v_and_b32_e32 v168, 64, v175
	v_xor_b32_e32 v176, 16, v175
	v_add_u32_e32 v194, 64, v168
	v_cmp_lt_i32_e32 vcc, v176, v194
	v_xor_b32_e32 v177, 32, v175
	v_lshlrev_b64 v[168:169], 11, v[164:165]
	v_cndmask_b32_e32 v176, v175, v176, vcc
	v_lshlrev_b32_e32 v176, 2, v176
	v_cmp_lt_i32_e32 vcc, v177, v194
	v_lshl_add_u64 v[168:169], s[14:15], 0, v[168:169]
	v_lshl_add_u64 v[168:169], v[162:163], 1, v[168:169]
	v_cndmask_b32_e32 v177, v175, v177, vcc
	v_lshlrev_b32_e32 v177, 2, v177
	s_lshl_b32 s30, s10, 2
	s_ashr_i32 s31, s30, 31
	s_waitcnt vmcnt(0)
	v_pk_add_f32 v[128:129], v[128:129], v[180:181]
	v_pk_add_f32 v[126:127], v[126:127], v[178:179]
	v_pk_add_f32 v[120:121], v[120:121], v[188:189]
	v_pk_add_f32 v[118:119], v[118:119], v[186:187]
	v_pk_add_f32 v[122:123], v[122:123], v[182:183]
	v_pk_add_f32 v[178:179], v[116:117], v[192:193]
	v_pk_add_f32 v[180:181], v[114:115], v[190:191]
	v_mul_f32_e32 v116, v127, v127
	v_mul_f32_e32 v117, v129, v129
	v_cvt_pk_bf16_f32 v114, v126, v127
	v_cvt_pk_bf16_f32 v115, v128, v129
	v_mul_f32_e32 v127, v119, v119
	v_mul_f32_e32 v129, v121, v121
	v_pk_add_f32 v[124:125], v[124:125], v[184:185]
	v_mul_f32_e32 v182, v123, v123
	v_mul_f32_e32 v184, v181, v181
	v_fmac_f32_e32 v116, v126, v126
	v_fmac_f32_e32 v117, v128, v128
	v_fmac_f32_e32 v127, v118, v118
	v_fmac_f32_e32 v129, v120, v120
	v_mul_f32_e32 v183, v125, v125
	v_mul_f32_e32 v185, v179, v179
	v_fmac_f32_e32 v182, v122, v122
	v_fmac_f32_e32 v184, v180, v180
	v_add_f32_e32 v116, v116, v117
	v_add_f32_e32 v117, v127, v129
	v_fmac_f32_e32 v183, v124, v124
	v_fmac_f32_e32 v185, v178, v178
	v_add_f32_e32 v116, v116, v182
	v_add_f32_e32 v117, v117, v184
	v_add_f32_e32 v116, v183, v116
	v_add_f32_e32 v117, v185, v117
	v_add_f32_e32 v126, v116, v117
	v_mov_b32_e32 v127, v126
	s_nop 1
	v_permlane16_swap_b32 v126, v127
	v_cvt_pk_bf16_f32 v116, v122, v123
	v_cvt_pk_bf16_f32 v117, v124, v125
	global_store_dwordx4 v[168:169], v[114:117], off
	s_waitcnt lgkmcnt(0)
	s_nop 0
	v_add_f32_e32 v114, v126, v127
	v_mov_b32_e32 v115, v114
	s_nop 1
	v_permlane32_swap_b32 v114, v115
	v_cvt_pk_bf16_f32 v116, v118, v119
	v_cvt_pk_bf16_f32 v117, v120, v121
	v_cvt_pk_bf16_f32 v118, v180, v181
	v_cvt_pk_bf16_f32 v119, v178, v179
	global_store_dwordx4 v[168:169], v[116:119], off offset:256
	s_and_saveexec_b64 s[34:35], s[6:7]
	s_cbranch_execz .LBB0_610
	v_lshlrev_b64 v[116:117], 6, v[164:165]
	v_lshl_add_u64 v[116:117], s[16:17], 0, v[116:117]
	v_lshl_add_u64 v[116:117], s[30:31], 2, v[116:117]
	s_lshl_b32 s10, s44, 2
	v_lshl_add_u64 v[116:117], v[116:117], 0, s[10:11]
	s_waitcnt lgkmcnt(0)
	v_add_f32_e32 v114, v114, v115
	global_store_dword v[116:117], v114, off
.LBB0_610:
	s_or_b64 exec, exec, s[34:35]
	v_or_b32_e32 v168, 32, v164
	v_ashrrev_i32_e32 v169, 31, v168
	s_waitcnt lgkmcnt(0)
	v_lshlrev_b64 v[114:115], 12, v[168:169]
	v_lshl_add_u64 v[114:115], s[4:5], 0, v[114:115]
	v_lshl_add_u64 v[118:119], v[162:163], 2, v[114:115]
	global_load_dwordx4 v[122:125], v[118:119], off offset:16
	global_load_dwordx4 v[126:129], v[118:119], off
	global_load_dwordx4 v[114:117], v[118:119], off offset:528
	s_nop 0
	global_load_dwordx4 v[118:121], v[118:119], off offset:512
	v_pk_add_f32 v[112:113], v[112:113], v[144:145]
	v_pk_add_f32 v[110:111], v[110:111], v[142:143]
	v_pk_add_f32 v[140:141], v[108:109], v[140:141]
	v_pk_add_f32 v[108:109], v[106:107], v[138:139]
	v_mul_f32_e32 v106, v111, v111
	v_mul_f32_e32 v107, v113, v113
	v_fmac_f32_e32 v106, v110, v110
	v_fmac_f32_e32 v107, v112, v112
	v_add_f32_e32 v106, v106, v107
	v_mul_f32_e32 v107, v109, v109
	v_fmac_f32_e32 v107, v108, v108
	v_add_f32_e32 v106, v106, v107
	v_mul_f32_e32 v107, v141, v141
	v_fmac_f32_e32 v107, v140, v140
	v_pk_add_f32 v[104:105], v[104:105], v[136:137]
	v_pk_add_f32 v[102:103], v[102:103], v[134:135]
	v_add_f32_e32 v138, v107, v106
	v_cvt_pk_bf16_f32 v106, v110, v111
	v_cvt_pk_bf16_f32 v107, v112, v113
	v_pk_add_f32 v[112:113], v[98:99], v[130:131]
	v_mul_f32_e32 v98, v103, v103
	v_mul_f32_e32 v99, v105, v105
	v_fmac_f32_e32 v98, v102, v102
	v_fmac_f32_e32 v99, v104, v104
	v_add_f32_e32 v98, v98, v99
	v_mul_f32_e32 v99, v113, v113
	v_pk_add_f32 v[110:111], v[100:101], v[132:133]
	v_fmac_f32_e32 v99, v112, v112
	v_add_f32_e32 v98, v98, v99
	v_mul_f32_e32 v99, v111, v111
	v_fmac_f32_e32 v99, v110, v110
	v_add_f32_e32 v98, v99, v98
	v_add_f32_e32 v101, v138, v98
	v_mov_b32_e32 v132, v101
	s_nop 1
	v_permlane16_swap_b32 v101, v132
	v_lshlrev_b64 v[178:179], 11, v[166:167]
	v_lshl_add_u64 v[98:99], s[14:15], 0, v[178:179]
	v_lshl_add_u64 v[130:131], v[162:163], 1, v[98:99]
	v_cvt_pk_bf16_f32 v108, v108, v109
	s_waitcnt lgkmcnt(0)
	v_add_f32_e32 v98, v101, v132
	v_mov_b32_e32 v99, v98
	s_nop 1
	v_permlane32_swap_b32 v98, v99
	v_cvt_pk_bf16_f32 v109, v140, v141
	global_store_dwordx4 v[130:131], v[106:109], off
	v_cvt_pk_bf16_f32 v100, v102, v103
	v_cvt_pk_bf16_f32 v101, v104, v105
	v_cvt_pk_bf16_f32 v102, v112, v113
	v_cvt_pk_bf16_f32 v103, v110, v111
	global_store_dwordx4 v[130:131], v[100:103], off offset:256
	s_and_saveexec_b64 s[34:35], s[6:7]
	s_cbranch_execz .LBB0_612
	v_lshlrev_b64 v[100:101], 6, v[166:167]
	v_lshl_add_u64 v[100:101], s[16:17], 0, v[100:101]
	v_lshl_add_u64 v[100:101], s[30:31], 2, v[100:101]
	s_lshl_b32 s10, s44, 2
	v_lshl_add_u64 v[100:101], v[100:101], 0, s[10:11]
	s_waitcnt lgkmcnt(0)
	v_add_f32_e32 v98, v98, v99
	global_store_dword v[100:101], v98, off
; __device__ __forceinline__ unsigned cvt_pk_bf16(float lo, float hi) { unsigned r; asm volatile("v_cvt_pk_bf16_f32 %0, %1, %2" : "=v"(r) : "v"(lo), "v"(hi)); return r; }
; __device__ __forceinline__ float bflo(unsigned w) { return __uint_as_float(w << 16); }
; __device__ __forceinline__ float bfhi(unsigned w) { return __uint_as_float(w & 0xffff0000u); }
;     __device__ __forceinline__ void ld(Ld& L, size_t o) const {
; #pragma unroll
;         for (int bj = 0; bj < 2; ++bj) { if (BASEF32) { L.a[bj][0] = *(const f32x4*)((const float*)base + o + bj * HALF); L.a[bj][1] = *(const f32x4*)((const float*)base + o + bj * HALF + 4); }
;             else { const v4u w = *(const v4u*)((const bf16*)base + o + bj * HALF); L.a[bj][0] = __builtin_bit_cast(f32x4, w); } }
;     }
;     __device__ __forceinline__ void operator()(const pg8::f32x4 (&acc)[2][2][4][2], const Unit& u, int wr, int wc, int fr, int fq) const {
;         const int row0 = u.pm * BM + wr * 64 + fr, col0 = u.pn * BM + wc * 32 + 8 * fq;
;         Ld nx; ld(nx, (size_t)row0 * DM_ + col0);
; #pragma unroll
;         for (int k = 0; k < 8; ++k) { const int ai = k >> 2, m = k & 3; const int row = row0 + ai * HALF + m * 16; float q = 0.f; const Ld cu = nx;
;             if (k < 7) ld(nx, (size_t)(row0 + ((k + 1) >> 2) * HALF + ((k + 1) & 3) * 16) * DM_ + col0);
; #pragma unroll
;             for (int bj = 0; bj < 2; ++bj) { const size_t o = (size_t)row * DM_ + col0 + bj * HALF; f32x4 b0, b1;
;                 if (BASEF32) { b0 = cu.a[bj][0]; b1 = cu.a[bj][1]; }
;                 else { const v4u w = __builtin_bit_cast(v4u, cu.a[bj][0]); b0 = (f32x4){bflo(w.x), bfhi(w.x), bflo(w.y), bfhi(w.y)}; b1 = (f32x4){bflo(w.z), bfhi(w.z), bflo(w.w), bfhi(w.w)}; }
;                 const f32x4 r0 = b0 + acc[ai][bj][m][0], r1 = b1 + acc[ai][bj][m][1];
;                 q += (r0[0] * r0[0] + r0[1] * r0[1]) + (r0[2] * r0[2] + r0[3] * r0[3]) + (r1[0] * r1[0] + r1[1] * r1[1]) + (r1[2] * r1[2] + r1[3] * r1[3]);
;                 v4u w; w.x = cvt_pk_bf16(r0[0], r0[1]); w.y = cvt_pk_bf16(r0[2], r0[3]); w.z = cvt_pk_bf16(r1[0], r1[1]); w.w = cvt_pk_bf16(r1[2], r1[3]); *(v4u*)(out + o) = w; }
;             q += __shfl_xor(q, 16); q += __shfl_xor(q, 32); if (fq == 0) ssq[(size_t)row * 16 + u.pn * 4 + wc] = q; }
.LBB0_612:
	s_or_b64 exec, exec, s[34:35]
	v_or_b32_e32 v130, 48, v164
	v_ashrrev_i32_e32 v131, 31, v130
	s_waitcnt lgkmcnt(0)
	v_lshlrev_b64 v[98:99], 12, v[130:131]
	v_lshl_add_u64 v[98:99], s[4:5], 0, v[98:99]
	v_lshl_add_u64 v[102:103], v[162:163], 2, v[98:99]
	global_load_dwordx4 v[106:109], v[102:103], off offset:16
	global_load_dwordx4 v[110:113], v[102:103], off
	global_load_dwordx4 v[98:101], v[102:103], off offset:528
	s_nop 0
	global_load_dwordx4 v[102:105], v[102:103], off offset:512
	s_waitcnt vmcnt(8)
	v_pk_add_f32 v[96:97], v[96:97], v[128:129]
	v_pk_add_f32 v[94:95], v[94:95], v[126:127]
	v_pk_add_f32 v[124:125], v[92:93], v[124:125]
	v_pk_add_f32 v[92:93], v[90:91], v[122:123]
	v_mul_f32_e32 v90, v95, v95
	v_mul_f32_e32 v91, v97, v97
	v_fmac_f32_e32 v90, v94, v94
	v_fmac_f32_e32 v91, v96, v96
	v_add_f32_e32 v90, v90, v91
	v_mul_f32_e32 v91, v93, v93
	v_fmac_f32_e32 v91, v92, v92
	v_add_f32_e32 v90, v90, v91
	v_mul_f32_e32 v91, v125, v125
	v_fmac_f32_e32 v91, v124, v124
	s_waitcnt vmcnt(6)
	v_pk_add_f32 v[88:89], v[88:89], v[120:121]
	v_pk_add_f32 v[86:87], v[86:87], v[118:119]
	v_add_f32_e32 v122, v91, v90
	v_cvt_pk_bf16_f32 v90, v94, v95
	v_cvt_pk_bf16_f32 v91, v96, v97
	v_pk_add_f32 v[96:97], v[82:83], v[114:115]
	v_mul_f32_e32 v82, v87, v87
	v_mul_f32_e32 v83, v89, v89
	v_fmac_f32_e32 v82, v86, v86
	v_fmac_f32_e32 v83, v88, v88
	v_add_f32_e32 v82, v82, v83
	v_mul_f32_e32 v83, v97, v97
	v_pk_add_f32 v[94:95], v[84:85], v[116:117]
	v_fmac_f32_e32 v83, v96, v96
	v_add_f32_e32 v82, v82, v83
	v_mul_f32_e32 v83, v95, v95
	v_fmac_f32_e32 v83, v94, v94
	v_add_f32_e32 v82, v83, v82
	v_add_f32_e32 v85, v122, v82
	v_mov_b32_e32 v116, v85
	s_nop 1
	v_permlane16_swap_b32 v85, v116
	v_lshlrev_b64 v[132:133], 11, v[168:169]
	v_lshl_add_u64 v[82:83], s[14:15], 0, v[132:133]
	v_lshl_add_u64 v[114:115], v[162:163], 1, v[82:83]
	v_cvt_pk_bf16_f32 v92, v92, v93
	s_waitcnt lgkmcnt(0)
	v_add_f32_e32 v82, v85, v116
	v_mov_b32_e32 v83, v82
	s_nop 1
	v_permlane32_swap_b32 v82, v83
	v_cvt_pk_bf16_f32 v93, v124, v125
	global_store_dwordx4 v[114:115], v[90:93], off
	v_cvt_pk_bf16_f32 v84, v86, v87
	v_cvt_pk_bf16_f32 v85, v88, v89
	v_cvt_pk_bf16_f32 v86, v96, v97
	v_cvt_pk_bf16_f32 v87, v94, v95
	global_store_dwordx4 v[114:115], v[84:87], off offset:256
	s_and_saveexec_b64 s[34:35], s[6:7]
	s_cbranch_execz .LBB0_614
	v_lshlrev_b64 v[84:85], 6, v[168:169]
	v_lshl_add_u64 v[84:85], s[16:17], 0, v[84:85]
	v_lshl_add_u64 v[84:85], s[30:31], 2, v[84:85]
	s_lshl_b32 s10, s44, 2
	v_lshl_add_u64 v[84:85], v[84:85], 0, s[10:11]
	s_waitcnt lgkmcnt(0)
	v_add_f32_e32 v82, v82, v83
	global_store_dword v[84:85], v82, off
.LBB0_614:
	s_or_b64 exec, exec, s[34:35]
	v_add_u32_e32 v114, 0x80, v164
	v_ashrrev_i32_e32 v115, 31, v114
	s_waitcnt lgkmcnt(0)
	v_lshlrev_b64 v[82:83], 12, v[114:115]
	v_lshl_add_u64 v[82:83], s[4:5], 0, v[82:83]
	v_lshl_add_u64 v[86:87], v[162:163], 2, v[82:83]
	global_load_dwordx4 v[90:93], v[86:87], off offset:16
	global_load_dwordx4 v[94:97], v[86:87], off
	global_load_dwordx4 v[82:85], v[86:87], off offset:528
	s_nop 0
	global_load_dwordx4 v[86:89], v[86:87], off offset:512
	s_waitcnt vmcnt(8)
	v_pk_add_f32 v[80:81], v[80:81], v[112:113]
	v_pk_add_f32 v[78:79], v[78:79], v[110:111]
	v_pk_add_f32 v[108:109], v[76:77], v[108:109]
	v_pk_add_f32 v[76:77], v[74:75], v[106:107]
	v_mul_f32_e32 v74, v79, v79
	v_mul_f32_e32 v75, v81, v81
	v_fmac_f32_e32 v74, v78, v78
	v_fmac_f32_e32 v75, v80, v80
	v_add_f32_e32 v74, v74, v75
	v_mul_f32_e32 v75, v77, v77
	v_fmac_f32_e32 v75, v76, v76
	v_add_f32_e32 v74, v74, v75
	v_mul_f32_e32 v75, v109, v109
	v_fmac_f32_e32 v75, v108, v108
	s_waitcnt vmcnt(6)
	v_pk_add_f32 v[72:73], v[72:73], v[104:105]
	v_pk_add_f32 v[70:71], v[70:71], v[102:103]
	v_add_f32_e32 v106, v75, v74
	v_cvt_pk_bf16_f32 v74, v78, v79
	v_cvt_pk_bf16_f32 v75, v80, v81
	v_pk_add_f32 v[80:81], v[66:67], v[98:99]
	v_mul_f32_e32 v66, v71, v71
	v_mul_f32_e32 v67, v73, v73
	v_fmac_f32_e32 v66, v70, v70
	v_fmac_f32_e32 v67, v72, v72
	v_add_f32_e32 v66, v66, v67
	v_mul_f32_e32 v67, v81, v81
	v_pk_add_f32 v[78:79], v[68:69], v[100:101]
	v_fmac_f32_e32 v67, v80, v80
	v_add_f32_e32 v66, v66, v67
	v_mul_f32_e32 v67, v79, v79
	v_fmac_f32_e32 v67, v78, v78
	v_add_f32_e32 v66, v67, v66
	v_add_f32_e32 v69, v106, v66
	v_mov_b32_e32 v100, v69
	s_nop 1
	v_permlane16_swap_b32 v69, v100
	v_lshlrev_b64 v[116:117], 11, v[130:131]
	v_lshl_add_u64 v[66:67], s[14:15], 0, v[116:117]
	v_lshl_add_u64 v[98:99], v[162:163], 1, v[66:67]
	v_cvt_pk_bf16_f32 v76, v76, v77
	s_waitcnt lgkmcnt(0)
	v_add_f32_e32 v66, v69, v100
	v_mov_b32_e32 v67, v66
	s_nop 1
	v_permlane32_swap_b32 v66, v67
	v_cvt_pk_bf16_f32 v77, v108, v109
	global_store_dwordx4 v[98:99], v[74:77], off
	v_cvt_pk_bf16_f32 v68, v70, v71
	v_cvt_pk_bf16_f32 v69, v72, v73
	v_cvt_pk_bf16_f32 v70, v80, v81
	v_cvt_pk_bf16_f32 v71, v78, v79
	global_store_dwordx4 v[98:99], v[68:71], off offset:256
	s_and_saveexec_b64 s[34:35], s[6:7]
	s_cbranch_execz .LBB0_616
	v_lshlrev_b64 v[68:69], 6, v[130:131]
	v_lshl_add_u64 v[68:69], s[16:17], 0, v[68:69]
	v_lshl_add_u64 v[68:69], s[30:31], 2, v[68:69]
	s_lshl_b32 s10, s44, 2
	v_lshl_add_u64 v[68:69], v[68:69], 0, s[10:11]
	s_waitcnt lgkmcnt(0)
	v_add_f32_e32 v66, v66, v67
	global_store_dword v[68:69], v66, off
; __device__ __forceinline__ unsigned cvt_pk_bf16(float lo, float hi) { unsigned r; asm volatile("v_cvt_pk_bf16_f32 %0, %1, %2" : "=v"(r) : "v"(lo), "v"(hi)); return r; }
; __device__ __forceinline__ float bflo(unsigned w) { return __uint_as_float(w << 16); }
; __device__ __forceinline__ float bfhi(unsigned w) { return __uint_as_float(w & 0xffff0000u); }
;     __device__ __forceinline__ void ld(Ld& L, size_t o) const {
; #pragma unroll
;         for (int bj = 0; bj < 2; ++bj) { if (BASEF32) { L.a[bj][0] = *(const f32x4*)((const float*)base + o + bj * HALF); L.a[bj][1] = *(const f32x4*)((const float*)base + o + bj * HALF + 4); }
;             else { const v4u w = *(const v4u*)((const bf16*)base + o + bj * HALF); L.a[bj][0] = __builtin_bit_cast(f32x4, w); } }
;     }
;     __device__ __forceinline__ void operator()(const pg8::f32x4 (&acc)[2][2][4][2], const Unit& u, int wr, int wc, int fr, int fq) const {
;         const int row0 = u.pm * BM + wr * 64 + fr, col0 = u.pn * BM + wc * 32 + 8 * fq;
;         Ld nx; ld(nx, (size_t)row0 * DM_ + col0);
; #pragma unroll
;         for (int k = 0; k < 8; ++k) { const int ai = k >> 2, m = k & 3; const int row = row0 + ai * HALF + m * 16; float q = 0.f; const Ld cu = nx;
;             if (k < 7) ld(nx, (size_t)(row0 + ((k + 1) >> 2) * HALF + ((k + 1) & 3) * 16) * DM_ + col0);
; #pragma unroll
;             for (int bj = 0; bj < 2; ++bj) { const size_t o = (size_t)row * DM_ + col0 + bj * HALF; f32x4 b0, b1;
;                 if (BASEF32) { b0 = cu.a[bj][0]; b1 = cu.a[bj][1]; }
;                 else { const v4u w = __builtin_bit_cast(v4u, cu.a[bj][0]); b0 = (f32x4){bflo(w.x), bfhi(w.x), bflo(w.y), bfhi(w.y)}; b1 = (f32x4){bflo(w.z), bfhi(w.z), bflo(w.w), bfhi(w.w)}; }
;                 const f32x4 r0 = b0 + acc[ai][bj][m][0], r1 = b1 + acc[ai][bj][m][1];
;                 q += (r0[0] * r0[0] + r0[1] * r0[1]) + (r0[2] * r0[2] + r0[3] * r0[3]) + (r1[0] * r1[0] + r1[1] * r1[1]) + (r1[2] * r1[2] + r1[3] * r1[3]);
;                 v4u w; w.x = cvt_pk_bf16(r0[0], r0[1]); w.y = cvt_pk_bf16(r0[2], r0[3]); w.z = cvt_pk_bf16(r1[0], r1[1]); w.w = cvt_pk_bf16(r1[2], r1[3]); *(v4u*)(out + o) = w; }
;             q += __shfl_xor(q, 16); q += __shfl_xor(q, 32); if (fq == 0) ssq[(size_t)row * 16 + u.pn * 4 + wc] = q; }
.LBB0_616:
	s_or_b64 exec, exec, s[34:35]
	v_or_b32_e32 v98, 16, v114
	v_ashrrev_i32_e32 v99, 31, v98
	s_waitcnt lgkmcnt(0)
	v_lshlrev_b64 v[66:67], 12, v[98:99]
	v_lshl_add_u64 v[66:67], s[4:5], 0, v[66:67]
	v_lshl_add_u64 v[70:71], v[162:163], 2, v[66:67]
	global_load_dwordx4 v[74:77], v[70:71], off offset:16
	global_load_dwordx4 v[78:81], v[70:71], off
	global_load_dwordx4 v[66:69], v[70:71], off offset:528
	s_nop 0
	global_load_dwordx4 v[70:73], v[70:71], off offset:512
	s_waitcnt vmcnt(8)
	v_pk_add_f32 v[64:65], v[64:65], v[96:97]
	v_pk_add_f32 v[62:63], v[62:63], v[94:95]
	v_pk_add_f32 v[92:93], v[60:61], v[92:93]
	v_pk_add_f32 v[60:61], v[58:59], v[90:91]
	v_mul_f32_e32 v58, v63, v63
	v_mul_f32_e32 v59, v65, v65
	v_fmac_f32_e32 v58, v62, v62
	v_fmac_f32_e32 v59, v64, v64
	v_add_f32_e32 v58, v58, v59
	v_mul_f32_e32 v59, v61, v61
	v_fmac_f32_e32 v59, v60, v60
	v_add_f32_e32 v58, v58, v59
	v_mul_f32_e32 v59, v93, v93
	v_fmac_f32_e32 v59, v92, v92
	s_waitcnt vmcnt(6)
	v_pk_add_f32 v[56:57], v[56:57], v[88:89]
	v_pk_add_f32 v[54:55], v[54:55], v[86:87]
	v_add_f32_e32 v90, v59, v58
	v_cvt_pk_bf16_f32 v58, v62, v63
	v_cvt_pk_bf16_f32 v59, v64, v65
	v_pk_add_f32 v[64:65], v[50:51], v[82:83]
	v_mul_f32_e32 v50, v55, v55
	v_mul_f32_e32 v51, v57, v57
	v_fmac_f32_e32 v50, v54, v54
	v_fmac_f32_e32 v51, v56, v56
	v_add_f32_e32 v50, v50, v51
	v_mul_f32_e32 v51, v65, v65
	v_pk_add_f32 v[62:63], v[52:53], v[84:85]
	v_fmac_f32_e32 v51, v64, v64
	v_add_f32_e32 v50, v50, v51
	v_mul_f32_e32 v51, v63, v63
	v_fmac_f32_e32 v51, v62, v62
	v_add_f32_e32 v50, v51, v50
	v_add_f32_e32 v53, v90, v50
	v_mov_b32_e32 v84, v53
	s_nop 1
	v_permlane16_swap_b32 v53, v84
	v_lshlrev_b64 v[100:101], 11, v[114:115]
	v_lshl_add_u64 v[50:51], s[14:15], 0, v[100:101]
	v_lshl_add_u64 v[82:83], v[162:163], 1, v[50:51]
	v_cvt_pk_bf16_f32 v60, v60, v61
	s_waitcnt lgkmcnt(0)
	v_add_f32_e32 v50, v53, v84
	v_mov_b32_e32 v51, v50
	s_nop 1
	v_permlane32_swap_b32 v50, v51
	v_cvt_pk_bf16_f32 v61, v92, v93
	global_store_dwordx4 v[82:83], v[58:61], off
	v_cvt_pk_bf16_f32 v52, v54, v55
	v_cvt_pk_bf16_f32 v53, v56, v57
	v_cvt_pk_bf16_f32 v54, v64, v65
	v_cvt_pk_bf16_f32 v55, v62, v63
	global_store_dwordx4 v[82:83], v[52:55], off offset:256
	s_and_saveexec_b64 s[34:35], s[6:7]
	s_cbranch_execz .LBB0_618
	v_lshlrev_b64 v[52:53], 6, v[114:115]
	v_lshl_add_u64 v[52:53], s[16:17], 0, v[52:53]
	v_lshl_add_u64 v[52:53], s[30:31], 2, v[52:53]
	s_lshl_b32 s10, s44, 2
	v_lshl_add_u64 v[52:53], v[52:53], 0, s[10:11]
	s_waitcnt lgkmcnt(0)
	v_add_f32_e32 v50, v50, v51
	global_store_dword v[52:53], v50, off
.LBB0_618:
	s_or_b64 exec, exec, s[34:35]
	v_or_b32_e32 v82, 32, v114
	v_ashrrev_i32_e32 v83, 31, v82
	s_waitcnt lgkmcnt(0)
	v_lshlrev_b64 v[50:51], 12, v[82:83]
	v_lshl_add_u64 v[50:51], s[4:5], 0, v[50:51]
	v_lshl_add_u64 v[54:55], v[162:163], 2, v[50:51]
	global_load_dwordx4 v[58:61], v[54:55], off offset:16
	global_load_dwordx4 v[62:65], v[54:55], off
	global_load_dwordx4 v[50:53], v[54:55], off offset:528
	s_nop 0
	global_load_dwordx4 v[54:57], v[54:55], off offset:512
	s_waitcnt vmcnt(8)
	v_pk_add_f32 v[48:49], v[48:49], v[80:81]
	v_pk_add_f32 v[46:47], v[46:47], v[78:79]
	v_pk_add_f32 v[76:77], v[44:45], v[76:77]
	v_pk_add_f32 v[44:45], v[42:43], v[74:75]
	v_mul_f32_e32 v42, v47, v47
	v_mul_f32_e32 v43, v49, v49
	v_fmac_f32_e32 v42, v46, v46
	v_fmac_f32_e32 v43, v48, v48
	v_add_f32_e32 v42, v42, v43
	v_mul_f32_e32 v43, v45, v45
	v_fmac_f32_e32 v43, v44, v44
	v_add_f32_e32 v42, v42, v43
	v_mul_f32_e32 v43, v77, v77
	v_fmac_f32_e32 v43, v76, v76
	s_waitcnt vmcnt(6)
	v_pk_add_f32 v[40:41], v[40:41], v[72:73]
	v_pk_add_f32 v[38:39], v[38:39], v[70:71]
	v_add_f32_e32 v74, v43, v42
	v_cvt_pk_bf16_f32 v42, v46, v47
	v_cvt_pk_bf16_f32 v43, v48, v49
	v_pk_add_f32 v[48:49], v[34:35], v[66:67]
	v_mul_f32_e32 v34, v39, v39
	v_mul_f32_e32 v35, v41, v41
	v_fmac_f32_e32 v34, v38, v38
	v_fmac_f32_e32 v35, v40, v40
	v_add_f32_e32 v34, v34, v35
	v_mul_f32_e32 v35, v49, v49
	v_pk_add_f32 v[46:47], v[36:37], v[68:69]
	v_fmac_f32_e32 v35, v48, v48
	v_add_f32_e32 v34, v34, v35
	v_mul_f32_e32 v35, v47, v47
	v_fmac_f32_e32 v35, v46, v46
	v_add_f32_e32 v34, v35, v34
	v_add_f32_e32 v37, v74, v34
	v_mov_b32_e32 v68, v37
	s_nop 1
	v_permlane16_swap_b32 v37, v68
	v_lshlrev_b64 v[84:85], 11, v[98:99]
	v_lshl_add_u64 v[34:35], s[14:15], 0, v[84:85]
	v_lshl_add_u64 v[66:67], v[162:163], 1, v[34:35]
	v_cvt_pk_bf16_f32 v44, v44, v45
	s_waitcnt lgkmcnt(0)
	v_add_f32_e32 v34, v37, v68
	v_mov_b32_e32 v35, v34
	s_nop 1
	v_permlane32_swap_b32 v34, v35
	v_cvt_pk_bf16_f32 v45, v76, v77
	global_store_dwordx4 v[66:67], v[42:45], off
	v_cvt_pk_bf16_f32 v36, v38, v39
	v_cvt_pk_bf16_f32 v37, v40, v41
	v_cvt_pk_bf16_f32 v38, v48, v49
	v_cvt_pk_bf16_f32 v39, v46, v47
	global_store_dwordx4 v[66:67], v[36:39], off offset:256
	s_and_saveexec_b64 s[34:35], s[6:7]
	s_cbranch_execz .LBB0_620
	v_lshlrev_b64 v[36:37], 6, v[98:99]
	v_lshl_add_u64 v[36:37], s[16:17], 0, v[36:37]
	v_lshl_add_u64 v[36:37], s[30:31], 2, v[36:37]
	s_lshl_b32 s10, s44, 2
	v_lshl_add_u64 v[36:37], v[36:37], 0, s[10:11]
	s_waitcnt lgkmcnt(0)
	v_add_f32_e32 v34, v34, v35
	global_store_dword v[36:37], v34, off
; __device__ __forceinline__ unsigned cvt_pk_bf16(float lo, float hi) { unsigned r; asm volatile("v_cvt_pk_bf16_f32 %0, %1, %2" : "=v"(r) : "v"(lo), "v"(hi)); return r; }
; __device__ __forceinline__ float bflo(unsigned w) { return __uint_as_float(w << 16); }
; __device__ __forceinline__ float bfhi(unsigned w) { return __uint_as_float(w & 0xffff0000u); }
;     __device__ __forceinline__ void ld(Ld& L, size_t o) const {
; #pragma unroll
;         for (int bj = 0; bj < 2; ++bj) { if (BASEF32) { L.a[bj][0] = *(const f32x4*)((const float*)base + o + bj * HALF); L.a[bj][1] = *(const f32x4*)((const float*)base + o + bj * HALF + 4); }
;             else { const v4u w = *(const v4u*)((const bf16*)base + o + bj * HALF); L.a[bj][0] = __builtin_bit_cast(f32x4, w); } }
;     }
;     __device__ __forceinline__ void operator()(const pg8::f32x4 (&acc)[2][2][4][2], const Unit& u, int wr, int wc, int fr, int fq) const {
;         const int row0 = u.pm * BM + wr * 64 + fr, col0 = u.pn * BM + wc * 32 + 8 * fq;
;         Ld nx; ld(nx, (size_t)row0 * DM_ + col0);
; #pragma unroll
;         for (int k = 0; k < 8; ++k) { const int ai = k >> 2, m = k & 3; const int row = row0 + ai * HALF + m * 16; float q = 0.f; const Ld cu = nx;
;             if (k < 7) ld(nx, (size_t)(row0 + ((k + 1) >> 2) * HALF + ((k + 1) & 3) * 16) * DM_ + col0);
; #pragma unroll
;             for (int bj = 0; bj < 2; ++bj) { const size_t o = (size_t)row * DM_ + col0 + bj * HALF; f32x4 b0, b1;
;                 if (BASEF32) { b0 = cu.a[bj][0]; b1 = cu.a[bj][1]; }
;                 else { const v4u w = __builtin_bit_cast(v4u, cu.a[bj][0]); b0 = (f32x4){bflo(w.x), bfhi(w.x), bflo(w.y), bfhi(w.y)}; b1 = (f32x4){bflo(w.z), bfhi(w.z), bflo(w.w), bfhi(w.w)}; }
;                 const f32x4 r0 = b0 + acc[ai][bj][m][0], r1 = b1 + acc[ai][bj][m][1];
;                 q += (r0[0] * r0[0] + r0[1] * r0[1]) + (r0[2] * r0[2] + r0[3] * r0[3]) + (r1[0] * r1[0] + r1[1] * r1[1]) + (r1[2] * r1[2] + r1[3] * r1[3]);
;                 v4u w; w.x = cvt_pk_bf16(r0[0], r0[1]); w.y = cvt_pk_bf16(r0[2], r0[3]); w.z = cvt_pk_bf16(r1[0], r1[1]); w.w = cvt_pk_bf16(r1[2], r1[3]); *(v4u*)(out + o) = w; }
;             q += __shfl_xor(q, 16); q += __shfl_xor(q, 32); if (fq == 0) ssq[(size_t)row * 16 + u.pn * 4 + wc] = q; }
.LBB0_620:
	s_or_b64 exec, exec, s[34:35]
	v_or_b32_e32 v66, 48, v114
	v_ashrrev_i32_e32 v67, 31, v66
	s_waitcnt lgkmcnt(0)
	v_lshlrev_b64 v[34:35], 12, v[66:67]
	v_lshl_add_u64 v[34:35], s[4:5], 0, v[34:35]
	v_lshl_add_u64 v[38:39], v[162:163], 2, v[34:35]
	global_load_dwordx4 v[42:45], v[38:39], off offset:16
	global_load_dwordx4 v[46:49], v[38:39], off
	global_load_dwordx4 v[34:37], v[38:39], off offset:528
	s_nop 0
	global_load_dwordx4 v[38:41], v[38:39], off offset:512
	s_waitcnt vmcnt(8)
	v_pk_add_f32 v[32:33], v[32:33], v[64:65]
	v_pk_add_f32 v[30:31], v[30:31], v[62:63]
	v_pk_add_f32 v[60:61], v[28:29], v[60:61]
	v_pk_add_f32 v[28:29], v[26:27], v[58:59]
	v_mul_f32_e32 v26, v31, v31
	v_mul_f32_e32 v27, v33, v33
	v_fmac_f32_e32 v26, v30, v30
	v_fmac_f32_e32 v27, v32, v32
	v_add_f32_e32 v26, v26, v27
	v_mul_f32_e32 v27, v29, v29
	v_fmac_f32_e32 v27, v28, v28
	v_add_f32_e32 v26, v26, v27
	v_mul_f32_e32 v27, v61, v61
	v_fmac_f32_e32 v27, v60, v60
	s_waitcnt vmcnt(6)
	v_pk_add_f32 v[24:25], v[24:25], v[56:57]
	v_pk_add_f32 v[22:23], v[22:23], v[54:55]
	v_add_f32_e32 v58, v27, v26
	v_cvt_pk_bf16_f32 v26, v30, v31
	v_cvt_pk_bf16_f32 v27, v32, v33
	v_pk_add_f32 v[32:33], v[18:19], v[50:51]
	v_mul_f32_e32 v18, v23, v23
	v_mul_f32_e32 v19, v25, v25
	v_fmac_f32_e32 v18, v22, v22
	v_fmac_f32_e32 v19, v24, v24
	v_add_f32_e32 v18, v18, v19
	v_mul_f32_e32 v19, v33, v33
	v_pk_add_f32 v[30:31], v[20:21], v[52:53]
	v_fmac_f32_e32 v19, v32, v32
	v_add_f32_e32 v18, v18, v19
	v_mul_f32_e32 v19, v31, v31
	v_fmac_f32_e32 v19, v30, v30
	v_add_f32_e32 v18, v19, v18
	v_add_f32_e32 v21, v58, v18
	v_mov_b32_e32 v52, v21
	s_nop 1
	v_permlane16_swap_b32 v21, v52
	v_lshlrev_b64 v[68:69], 11, v[82:83]
	v_lshl_add_u64 v[18:19], s[14:15], 0, v[68:69]
	v_lshl_add_u64 v[50:51], v[162:163], 1, v[18:19]
	v_cvt_pk_bf16_f32 v28, v28, v29
	s_waitcnt lgkmcnt(0)
	v_add_f32_e32 v18, v21, v52
	v_mov_b32_e32 v19, v18
	s_nop 1
	v_permlane32_swap_b32 v18, v19
	v_cvt_pk_bf16_f32 v29, v60, v61
	global_store_dwordx4 v[50:51], v[26:29], off
	v_cvt_pk_bf16_f32 v20, v22, v23
	v_cvt_pk_bf16_f32 v21, v24, v25
	v_cvt_pk_bf16_f32 v22, v32, v33
	v_cvt_pk_bf16_f32 v23, v30, v31
	global_store_dwordx4 v[50:51], v[20:23], off offset:256
	s_and_saveexec_b64 s[34:35], s[6:7]
	s_cbranch_execz .LBB0_622
	v_lshlrev_b64 v[20:21], 6, v[82:83]
	v_lshl_add_u64 v[20:21], s[16:17], 0, v[20:21]
	v_lshl_add_u64 v[20:21], s[30:31], 2, v[20:21]
	s_lshl_b32 s10, s44, 2
	v_lshl_add_u64 v[20:21], v[20:21], 0, s[10:11]
	s_waitcnt lgkmcnt(0)
	v_add_f32_e32 v18, v18, v19
	global_store_dword v[20:21], v18, off
.LBB0_622:
	s_or_b64 exec, exec, s[34:35]
	s_waitcnt vmcnt(4)
	v_pk_add_f32 v[16:17], v[16:17], v[48:49]
	v_pk_add_f32 v[14:15], v[14:15], v[46:47]
	v_pk_add_f32 v[20:21], v[12:13], v[44:45]
	v_pk_add_f32 v[12:13], v[10:11], v[42:43]
	v_mul_f32_e32 v10, v15, v15
	v_mul_f32_e32 v11, v17, v17
	v_fmac_f32_e32 v10, v14, v14
	v_fmac_f32_e32 v11, v16, v16
	v_add_f32_e32 v10, v10, v11
	v_mul_f32_e32 v11, v13, v13
	v_fmac_f32_e32 v11, v12, v12
	v_add_f32_e32 v10, v10, v11
	v_mul_f32_e32 v11, v21, v21
	v_fmac_f32_e32 v11, v20, v20
	s_waitcnt vmcnt(2)
	v_pk_add_f32 v[8:9], v[8:9], v[40:41]
	v_pk_add_f32 v[6:7], v[6:7], v[38:39]
	v_add_f32_e32 v22, v11, v10
	v_cvt_pk_bf16_f32 v10, v14, v15
	v_cvt_pk_bf16_f32 v11, v16, v17
	v_pk_add_f32 v[16:17], v[2:3], v[34:35]
	v_mul_f32_e32 v2, v7, v7
	v_mul_f32_e32 v3, v9, v9
	v_fmac_f32_e32 v2, v6, v6
	v_fmac_f32_e32 v3, v8, v8
	v_add_f32_e32 v2, v2, v3
	v_mul_f32_e32 v3, v17, v17
	v_pk_add_f32 v[14:15], v[4:5], v[36:37]
	v_fmac_f32_e32 v3, v16, v16
	v_add_f32_e32 v2, v2, v3
	v_mul_f32_e32 v3, v15, v15
	v_fmac_f32_e32 v3, v14, v14
	v_add_f32_e32 v2, v3, v2
	v_add_f32_e32 v5, v22, v2
	v_cvt_pk_bf16_f32 v12, v12, v13
	v_cvt_pk_bf16_f32 v13, v20, v21
	v_mov_b32_e32 v20, v5
	s_nop 1
	v_permlane16_swap_b32 v5, v20
	s_waitcnt lgkmcnt(1)
	v_lshlrev_b64 v[18:19], 11, v[66:67]
	v_lshl_add_u64 v[2:3], s[14:15], 0, v[18:19]
	v_lshl_add_u64 v[18:19], v[162:163], 1, v[2:3]
	global_store_dwordx4 v[18:19], v[10:13], off
	s_waitcnt lgkmcnt(0)
	v_add_f32_e32 v2, v5, v20
	v_mov_b32_e32 v3, v2
	s_nop 1
	v_permlane32_swap_b32 v2, v3
	v_cvt_pk_bf16_f32 v4, v6, v7
	v_cvt_pk_bf16_f32 v5, v8, v9
	v_cvt_pk_bf16_f32 v6, v16, v17
	v_cvt_pk_bf16_f32 v7, v14, v15
	global_store_dwordx4 v[18:19], v[4:7], off offset:256
	s_and_saveexec_b64 s[34:35], s[6:7]
	s_cbranch_execz .LBB0_624
	v_lshlrev_b64 v[4:5], 6, v[66:67]
	v_lshl_add_u64 v[4:5], s[16:17], 0, v[4:5]
	v_lshl_add_u64 v[4:5], s[30:31], 2, v[4:5]
	s_lshl_b32 s10, s44, 2
	v_lshl_add_u64 v[4:5], v[4:5], 0, s[10:11]
	s_waitcnt lgkmcnt(0)
	v_add_f32_e32 v2, v2, v3
	global_store_dword v[4:5], v2, off

; __device__ __forceinline__ void rstd8(const float* ss, int row0, int fq, float (&rs)[8]) {
;     f32x4 a[8];
; #pragma unroll
;     for (int k = 0; k < 8; ++k) a[k] = *(const f32x4*)(ss + (size_t)(row0 + (k >> 2) * 128 + (k & 3) * 16) * 16 + 4 * fq);
; #pragma unroll
;     for (int k = 0; k < 8; ++k) { float s = (a[k][0] + a[k][1]) + (a[k][2] + a[k][3]); s += __shfl_xor(s, 16); s += __shfl_xor(s, 32); rs[k] = __builtin_amdgcn_rsqf(s * (1.f / 1024.f) + EPS); }
;     __device__ __forceinline__ void operator()(const pg8::f32x4 (&acc)[2][2][4][2], const Unit& u, int wr, int wc, int fr, int fq) const {
;         const int row0 = u.pm * BM + wr * 64 + fr, col0 = u.pn * HALF + wc * 32 + 8 * fq;
;         float rsv[8]; rstd8(ss, row0, fq, rsv);
; #pragma unroll
;         for (int ai = 0; ai < 2; ++ai)
; #pragma unroll
;             for (int m = 0; m < 4; ++m) { float r[8]; const float rs = rsv[ai * 4 + m]; const float c1 = -1.4426950408889634f * rs, rs2 = rs * rs;
; #pragma unroll
;                 for (int n = 0; n < 2; ++n)
; #pragma unroll
;                     for (int e = 0; e < 4; e += 2) { const f32x2 ag = {acc[ai][0][m][n][e], acc[ai][0][m][n][e + 1]}, au = {acc[ai][1][m][n][e], acc[ai][1][m][n][e + 1]};
;                         const f32x2 t = ag * c1; f32x2 d; d.x = __builtin_amdgcn_exp2f(t.x); d.y = __builtin_amdgcn_exp2f(t.y); d = d + 1.0f;
;                         f32x2 q; q.x = __builtin_amdgcn_rcpf(d.x); q.y = __builtin_amdgcn_rcpf(d.y); const f32x2 o = (ag * au) * rs2 * q; r[4 * n + e] = o.x; r[4 * n + e + 1] = o.y; }
.LBB0_694:
	v_lshl_add_u32 v162, s22, 8, v1
	v_ashrrev_i32_e32 v163, 31, v162
	v_or_b32_e32 v160, 16, v162
	v_lshlrev_b64 v[148:149], 6, v[162:163]
	v_ashrrev_i32_e32 v161, 31, v160
	v_or_b32_e32 v158, 32, v162
	v_lshl_add_u64 v[148:149], v[138:139], 0, v[148:149]
	v_lshlrev_b64 v[150:151], 6, v[160:161]
	v_ashrrev_i32_e32 v159, 31, v158
	v_or_b32_e32 v156, 48, v162
	v_lshl_add_u64 v[150:151], v[138:139], 0, v[150:151]
	global_load_dwordx4 v[174:177], v[148:149], off
	global_load_dwordx4 v[178:181], v[150:151], off
	v_lshlrev_b64 v[148:149], 6, v[158:159]
	v_ashrrev_i32_e32 v157, 31, v156
	v_lshl_add_u64 v[148:149], v[138:139], 0, v[148:149]
	v_lshlrev_b64 v[150:151], 6, v[156:157]
	v_lshl_add_u64 v[150:151], v[138:139], 0, v[150:151]
	global_load_dwordx4 v[182:185], v[148:149], off
	global_load_dwordx4 v[186:189], v[150:151], off
	v_add_u32_e32 v154, 0x80, v162
	v_ashrrev_i32_e32 v155, 31, v154
	v_lshlrev_b64 v[148:149], 6, v[154:155]
	v_lshl_add_u64 v[148:149], v[138:139], 0, v[148:149]
	global_load_dwordx4 v[190:193], v[148:149], off
	v_add_u32_e32 v152, 0x90, v162
	v_ashrrev_i32_e32 v153, 31, v152
	v_lshlrev_b64 v[148:149], 6, v[152:153]
	v_add_u32_e32 v150, 0xa0, v162
	v_lshl_add_u64 v[148:149], v[138:139], 0, v[148:149]
	v_ashrrev_i32_e32 v151, 31, v150
	global_load_dwordx4 v[194:197], v[148:149], off
	v_lshlrev_b64 v[148:149], 6, v[150:151]
	v_lshl_add_u64 v[148:149], v[138:139], 0, v[148:149]
	global_load_dwordx4 v[198:201], v[148:149], off
	v_add_u32_e32 v148, 0xb0, v162
	v_ashrrev_i32_e32 v149, 31, v148
	v_lshlrev_b64 v[202:203], 6, v[148:149]
	v_lshl_add_u64 v[202:203], v[138:139], 0, v[202:203]
	global_load_dwordx4 v[202:205], v[202:203], off
	v_and_b32_e32 v151, 64, v171
	v_xor_b32_e32 v149, 16, v171
	v_add_u32_e32 v151, 64, v151
	v_xor_b32_e32 v153, 32, v171
	v_cmp_lt_i32_e32 vcc, v149, v151
	v_pk_mul_f32 v[124:125], v[128:129], v[124:125]
	v_pk_mul_f32 v[122:123], v[126:127], v[122:123]
	v_cndmask_b32_e32 v149, v171, v149, vcc
	v_cmp_lt_i32_e32 vcc, v153, v151
	v_lshlrev_b32_e32 v149, 2, v149
	v_pk_mul_f32 v[114:115], v[118:119], v[114:115]
	v_cndmask_b32_e32 v151, v171, v153, vcc
	v_lshlrev_b32_e32 v151, 2, v151
	v_pk_mul_f32 v[116:117], v[120:121], v[116:117]
	v_lshl_or_b32 v164, s45, 7, v167
	v_pk_mul_f32 v[108:109], v[112:113], v[108:109]
	v_pk_mul_f32 v[106:107], v[110:111], v[106:107]
	v_pk_mul_f32 v[98:99], v[102:103], v[98:99]
	v_pk_mul_f32 v[100:101], v[104:105], v[100:101]
	v_pk_mul_f32 v[92:93], v[96:97], v[92:93]
	v_pk_mul_f32 v[90:91], v[94:95], v[90:91]
	v_pk_mul_f32 v[82:83], v[86:87], v[82:83]
	v_pk_mul_f32 v[84:85], v[88:89], v[84:85]
	v_pk_mul_f32 v[76:77], v[80:81], v[76:77]
	v_pk_mul_f32 v[74:75], v[78:79], v[74:75]
	v_pk_mul_f32 v[66:67], v[70:71], v[66:67]
	v_pk_mul_f32 v[68:69], v[72:73], v[68:69]
	v_pk_mul_f32 v[60:61], v[64:65], v[60:61]
	v_pk_mul_f32 v[58:59], v[62:63], v[58:59]
	v_pk_mul_f32 v[50:51], v[54:55], v[50:51]
	v_pk_mul_f32 v[52:53], v[56:57], v[52:53]
	v_pk_mul_f32 v[44:45], v[48:49], v[44:45]
	v_pk_mul_f32 v[42:43], v[46:47], v[42:43]
	v_pk_mul_f32 v[34:35], v[38:39], v[34:35]
	v_pk_mul_f32 v[36:37], v[40:41], v[36:37]
	v_pk_mul_f32 v[28:29], v[32:33], v[28:29]
	v_pk_mul_f32 v[26:27], v[30:31], v[26:27]
	v_pk_mul_f32 v[18:19], v[22:23], v[18:19]
	v_pk_mul_f32 v[20:21], v[24:25], v[20:21]
	v_pk_mul_f32 v[12:13], v[16:17], v[12:13]
	v_pk_mul_f32 v[10:11], v[14:15], v[10:11]
	v_pk_mul_f32 v[2:3], v[6:7], v[2:3]
	v_pk_mul_f32 v[4:5], v[8:9], v[4:5]
	s_andn2_b64 vcc, exec, s[6:7]
	s_mov_b64 s[6:7], -1
	s_waitcnt vmcnt(0)
	v_mov_b32_e32 v206, v175
	v_mov_b32_e32 v207, v176
	v_mov_b32_e32 v175, v177
	v_pk_add_f32 v[174:175], v[206:207], v[174:175]
	v_mov_b32_e32 v176, v179
	v_mov_b32_e32 v177, v180
	v_mov_b32_e32 v179, v181
	v_mov_b32_e32 v180, v183
	v_mov_b32_e32 v181, v184
	v_mov_b32_e32 v183, v185
	v_mov_b32_e32 v184, v187
	v_mov_b32_e32 v185, v188
	v_mov_b32_e32 v187, v189
	v_add_f32_e32 v153, v174, v175
	v_pk_add_f32 v[174:175], v[176:177], v[178:179]
	v_pk_add_f32 v[176:177], v[180:181], v[182:183]
	v_pk_add_f32 v[178:179], v[184:185], v[186:187]
	v_add_f32_e32 v157, v174, v175
	v_add_f32_e32 v159, v176, v177
	v_add_f32_e32 v161, v178, v179
	v_mov_b32_e32 v155, v153
	s_nop 1
	v_permlane16_swap_b32 v153, v155
	v_mov_b32_e32 v165, v157
	s_nop 1
	v_permlane16_swap_b32 v157, v165
	v_mov_b32_e32 v173, v159
	s_nop 1
	v_permlane16_swap_b32 v159, v173
	v_mov_b32_e32 v174, v161
	s_nop 1
	v_permlane16_swap_b32 v161, v174
	v_mov_b32_e32 v188, v191
	v_mov_b32_e32 v189, v192
	v_mov_b32_e32 v191, v193
	v_pk_add_f32 v[180:181], v[188:189], v[190:191]
	s_waitcnt lgkmcnt(3)
	v_add_f32_e32 v153, v153, v155
	v_add_f32_e32 v163, v180, v181
	s_waitcnt lgkmcnt(2)
	v_add_f32_e32 v157, v157, v165
	s_waitcnt lgkmcnt(1)
	v_add_f32_e32 v159, v159, v173
	s_waitcnt lgkmcnt(0)
	v_add_f32_e32 v161, v161, v174
	v_mov_b32_e32 v175, v163
	s_nop 1
	v_permlane16_swap_b32 v163, v175
	v_mov_b32_e32 v155, v153
	s_nop 1
	v_permlane32_swap_b32 v153, v155
	v_mov_b32_e32 v165, v157
	s_nop 1
	v_permlane32_swap_b32 v157, v165
	v_mov_b32_e32 v173, v159
	s_nop 1
	v_permlane32_swap_b32 v159, v173
	v_mov_b32_e32 v174, v161
	s_nop 1
	v_permlane32_swap_b32 v161, v174
	s_waitcnt lgkmcnt(4)
	v_add_f32_e32 v163, v163, v175
	s_waitcnt lgkmcnt(3)
	v_add_f32_e32 v153, v153, v155
	s_waitcnt lgkmcnt(2)
	v_add_f32_e32 v155, v157, v165
	s_waitcnt lgkmcnt(1)
	v_add_f32_e32 v157, v159, v173
	s_waitcnt lgkmcnt(0)
; __device__ __forceinline__ unsigned cvt_pk_bf16(float lo, float hi) { unsigned r; asm volatile("v_cvt_pk_bf16_f32 %0, %1, %2" : "=v"(r) : "v"(lo), "v"(hi)); return r; }
; __device__ __forceinline__ void rstd8(const float* ss, int row0, int fq, float (&rs)[8]) {
;     f32x4 a[8];
; #pragma unroll
;     for (int k = 0; k < 8; ++k) a[k] = *(const f32x4*)(ss + (size_t)(row0 + (k >> 2) * 128 + (k & 3) * 16) * 16 + 4 * fq);
; #pragma unroll
;     for (int k = 0; k < 8; ++k) { float s = (a[k][0] + a[k][1]) + (a[k][2] + a[k][3]); s += __shfl_xor(s, 16); s += __shfl_xor(s, 32); rs[k] = __builtin_amdgcn_rsqf(s * (1.f / 1024.f) + EPS); }
;     __device__ __forceinline__ void operator()(const pg8::f32x4 (&acc)[2][2][4][2], const Unit& u, int wr, int wc, int fr, int fq) const {
;     ...
;             for (int m = 0; m < 4; ++m) { float r[8]; const float rs = rsv[ai * 4 + m]; const float c1 = -1.4426950408889634f * rs, rs2 = rs * rs;
; #pragma unroll
;                 for (int n = 0; n < 2; ++n)
; #pragma unroll
;                     for (int e = 0; e < 4; e += 2) { const f32x2 ag = {acc[ai][0][m][n][e], acc[ai][0][m][n][e + 1]}, au = {acc[ai][1][m][n][e], acc[ai][1][m][n][e + 1]};
;                         const f32x2 t = ag * c1; f32x2 d; d.x = __builtin_amdgcn_exp2f(t.x); d.y = __builtin_amdgcn_exp2f(t.y); d = d + 1.0f;
;                         f32x2 q; q.x = __builtin_amdgcn_rcpf(d.x); q.y = __builtin_amdgcn_rcpf(d.y); const f32x2 o = (ag * au) * rs2 * q; r[4 * n + e] = o.x; r[4 * n + e + 1] = o.y; }
;                 v4u w; w.x = cvt_pk_bf16(r[0], r[1]); w.y = cvt_pk_bf16(r[2], r[3]); w.z = cvt_pk_bf16(r[4], r[5]); w.w = cvt_pk_bf16(r[6], r[7]);
;                 __builtin_nontemporal_store(w, (v4u*)(O + (size_t)(row0 + ai * HALF + m * 16) * FF + col0)); }
	v_add_f32_e32 v159, v161, v174
	v_mov_b32_e32 v174, v195
	v_mov_b32_e32 v175, v196
	v_mov_b32_e32 v195, v197
	v_pk_add_f32 v[174:175], v[174:175], v[194:195]
	v_mov_b32_e32 v176, v163
	s_nop 1
	v_permlane32_swap_b32 v163, v176
	v_add_f32_e32 v161, v174, v175
	v_mov_b32_e32 v174, v199
	v_mov_b32_e32 v175, v200
	v_mov_b32_e32 v199, v201
	v_pk_add_f32 v[174:175], v[174:175], v[198:199]
	v_mov_b32_e32 v165, v161
	s_nop 1
	v_permlane16_swap_b32 v161, v165
	v_add_f32_e32 v173, v174, v175
	v_mov_b32_e32 v174, v203
	v_mov_b32_e32 v175, v204
	v_mov_b32_e32 v203, v205
	v_pk_add_f32 v[174:175], v[174:175], v[202:203]
	s_waitcnt lgkmcnt(1)
	v_add_f32_e32 v163, v163, v176
	v_add_f32_e32 v174, v174, v175
	v_mov_b32_e32 v176, v173
	s_nop 1
	v_permlane16_swap_b32 v173, v176
	v_mov_b32_e32 v149, v174
	s_nop 1
	v_permlane16_swap_b32 v174, v149
	v_fmamk_f32 v153, v153, 0x3a800000, v172
	v_rsq_f32_e32 v153, v153
	s_waitcnt lgkmcnt(2)
	v_add_f32_e32 v161, v161, v165
	v_mov_b32_e32 v165, v161
	s_nop 1
	v_permlane32_swap_b32 v161, v165
	s_waitcnt lgkmcnt(1)
	v_add_f32_e32 v149, v174, v149
	v_mov_b32_e32 v174, v149
	s_nop 1
	v_permlane32_swap_b32 v149, v174
	v_mul_f32_e32 v178, v153, v153
	v_pk_mul_f32 v[124:125], v[124:125], v[178:179] op_sel_hi:[1,0]
	s_waitcnt lgkmcnt(1)
	v_add_f32_e32 v161, v161, v165
	v_add_f32_e32 v165, v173, v176
	s_waitcnt lgkmcnt(0)
	v_add_f32_e32 v149, v149, v174
	v_mul_f32_e32 v174, 0xbfb8aa3b, v153
	v_pk_mul_f32 v[180:181], v[128:129], v[174:175] op_sel_hi:[1,0]
	v_pk_mul_f32 v[176:177], v[126:127], v[174:175] op_sel_hi:[1,0]
	v_exp_f32_e32 v180, v180
	v_exp_f32_e32 v181, v181
	v_pk_mul_f32 v[128:129], v[118:119], v[174:175] op_sel_hi:[1,0]
	v_exp_f32_e32 v176, v176
	v_exp_f32_e32 v128, v128
	v_pk_add_f32 v[126:127], v[180:181], 1.0 op_sel_hi:[1,0]
	v_exp_f32_e32 v129, v129
	v_rcp_f32_e32 v126, v126
	v_rcp_f32_e32 v127, v127
	v_exp_f32_e32 v177, v177
	v_mov_b32_e32 v173, v165
	s_nop 1
	v_permlane32_swap_b32 v165, v173
	v_fmamk_f32 v155, v155, 0x3a800000, v172
	v_pk_mul_f32 v[124:125], v[124:125], v[126:127]
	v_pk_add_f32 v[126:127], v[128:129], 1.0 op_sel_hi:[1,0]
	v_pk_mul_f32 v[128:129], v[120:121], v[174:175] op_sel_hi:[1,0]
	v_pk_add_f32 v[176:177], v[176:177], 1.0 op_sel_hi:[1,0]
	v_exp_f32_e32 v128, v128
	v_exp_f32_e32 v129, v129
	v_rcp_f32_e32 v126, v126
	v_rcp_f32_e32 v127, v127
	v_rcp_f32_e32 v176, v176
	v_pk_add_f32 v[118:119], v[128:129], 1.0 op_sel_hi:[1,0]
	v_rcp_f32_e32 v177, v177
	v_rcp_f32_e32 v118, v118
	v_rcp_f32_e32 v119, v119
	v_rsq_f32_e32 v155, v155
	v_pk_mul_f32 v[114:115], v[114:115], v[178:179] op_sel_hi:[1,0]
	v_pk_mul_f32 v[122:123], v[122:123], v[178:179] op_sel_hi:[1,0]
	v_pk_mul_f32 v[114:115], v[114:115], v[126:127]
	v_pk_mul_f32 v[116:117], v[116:117], v[178:179] op_sel_hi:[1,0]
	s_waitcnt lgkmcnt(0)
	v_add_f32_e32 v151, v165, v173
	v_ashrrev_i32_e32 v165, 31, v164
	v_pk_mul_f32 v[122:123], v[122:123], v[176:177]
	v_pk_mul_f32 v[116:117], v[116:117], v[118:119]
	v_cvt_pk_bf16_f32 v118, v122, v123
	v_cvt_pk_bf16_f32 v119, v124, v125
	v_cvt_pk_bf16_f32 v120, v114, v115
	v_mov_b64_e32 v[114:115], s[8:9]
	v_cvt_pk_bf16_f32 v121, v116, v117
	v_mad_i64_i32 v[122:123], s[24:25], v162, s44, v[114:115]
	v_lshlrev_b64 v[116:117], 1, v[164:165]
	v_mul_f32_e32 v124, 0xbfb8aa3b, v155
	v_lshl_add_u64 v[122:123], v[122:123], 0, v[116:117]
	global_store_dwordx4 v[122:123], v[118:121], off nt
	v_pk_mul_f32 v[122:123], v[112:113], v[124:125] op_sel_hi:[1,0]
	v_pk_mul_f32 v[126:127], v[110:111], v[124:125] op_sel_hi:[1,0]
	v_exp_f32_e32 v122, v122
	v_exp_f32_e32 v123, v123
	v_pk_mul_f32 v[112:113], v[102:103], v[124:125] op_sel_hi:[1,0]
	v_mul_f32_e32 v118, v155, v155
	v_exp_f32_e32 v112, v112
	v_pk_add_f32 v[110:111], v[122:123], 1.0 op_sel_hi:[1,0]
	v_exp_f32_e32 v113, v113
	v_rcp_f32_e32 v110, v110
	v_rcp_f32_e32 v111, v111
	v_pk_mul_f32 v[108:109], v[108:109], v[118:119] op_sel_hi:[1,0]
	v_exp_f32_e32 v126, v126
	v_exp_f32_e32 v127, v127
	v_pk_mul_f32 v[108:109], v[108:109], v[110:111]
	v_pk_add_f32 v[110:111], v[112:113], 1.0 op_sel_hi:[1,0]
	v_pk_mul_f32 v[112:113], v[104:105], v[124:125] op_sel_hi:[1,0]
	v_rcp_f32_e32 v110, v110
	v_exp_f32_e32 v112, v112
	v_exp_f32_e32 v113, v113
	v_rcp_f32_e32 v111, v111
	v_pk_add_f32 v[120:121], v[126:127], 1.0 op_sel_hi:[1,0]
	v_fmamk_f32 v157, v157, 0x3a800000, v172
	v_pk_add_f32 v[102:103], v[112:113], 1.0 op_sel_hi:[1,0]
	v_rcp_f32_e32 v120, v120
	v_rcp_f32_e32 v102, v102
	v_rcp_f32_e32 v103, v103
	v_rcp_f32_e32 v121, v121
	v_rsq_f32_e32 v157, v157
	v_pk_mul_f32 v[98:99], v[98:99], v[118:119] op_sel_hi:[1,0]
	v_pk_mul_f32 v[106:107], v[106:107], v[118:119] op_sel_hi:[1,0]
	v_pk_mul_f32 v[104:105], v[98:99], v[110:111]
	v_pk_mul_f32 v[98:99], v[100:101], v[118:119] op_sel_hi:[1,0]
	v_pk_mul_f32 v[106:107], v[106:107], v[120:121]
	v_pk_mul_f32 v[102:103], v[98:99], v[102:103]
	v_cvt_pk_bf16_f32 v98, v106, v107
	v_cvt_pk_bf16_f32 v99, v108, v109
	v_cvt_pk_bf16_f32 v100, v104, v105
	v_mul_f32_e32 v104, 0xbfb8aa3b, v157
	v_cvt_pk_bf16_f32 v101, v102, v103
	v_mad_i64_i32 v[102:103], s[24:25], v160, s44, v[114:115]
	v_lshl_add_u64 v[102:103], v[102:103], 0, v[116:117]
	global_store_dwordx4 v[102:103], v[98:101], off nt
	v_pk_mul_f32 v[102:103], v[96:97], v[104:105] op_sel_hi:[1,0]
	v_pk_mul_f32 v[106:107], v[94:95], v[104:105] op_sel_hi:[1,0]
	v_exp_f32_e32 v102, v102
	v_exp_f32_e32 v103, v103
	v_pk_mul_f32 v[96:97], v[86:87], v[104:105] op_sel_hi:[1,0]
	v_mul_f32_e32 v98, v157, v157
	v_exp_f32_e32 v96, v96
	v_pk_add_f32 v[94:95], v[102:103], 1.0 op_sel_hi:[1,0]
	v_exp_f32_e32 v97, v97
	v_rcp_f32_e32 v94, v94
	v_rcp_f32_e32 v95, v95
	v_pk_mul_f32 v[92:93], v[92:93], v[98:99] op_sel_hi:[1,0]
; __device__ __forceinline__ unsigned cvt_pk_bf16(float lo, float hi) { unsigned r; asm volatile("v_cvt_pk_bf16_f32 %0, %1, %2" : "=v"(r) : "v"(lo), "v"(hi)); return r; }
;     __device__ __forceinline__ void operator()(const pg8::f32x4 (&acc)[2][2][4][2], const Unit& u, int wr, int wc, int fr, int fq) const {
;     ...
;             for (int m = 0; m < 4; ++m) { float r[8]; const float rs = rsv[ai * 4 + m]; const float c1 = -1.4426950408889634f * rs, rs2 = rs * rs;
; #pragma unroll
;                 for (int n = 0; n < 2; ++n)
; #pragma unroll
;                     for (int e = 0; e < 4; e += 2) { const f32x2 ag = {acc[ai][0][m][n][e], acc[ai][0][m][n][e + 1]}, au = {acc[ai][1][m][n][e], acc[ai][1][m][n][e + 1]};
;                         const f32x2 t = ag * c1; f32x2 d; d.x = __builtin_amdgcn_exp2f(t.x); d.y = __builtin_amdgcn_exp2f(t.y); d = d + 1.0f;
;                         f32x2 q; q.x = __builtin_amdgcn_rcpf(d.x); q.y = __builtin_amdgcn_rcpf(d.y); const f32x2 o = (ag * au) * rs2 * q; r[4 * n + e] = o.x; r[4 * n + e + 1] = o.y; }
;                 v4u w; w.x = cvt_pk_bf16(r[0], r[1]); w.y = cvt_pk_bf16(r[2], r[3]); w.z = cvt_pk_bf16(r[4], r[5]); w.w = cvt_pk_bf16(r[6], r[7]);
;                 __builtin_nontemporal_store(w, (v4u*)(O + (size_t)(row0 + ai * HALF + m * 16) * FF + col0)); }
	v_exp_f32_e32 v106, v106
	v_exp_f32_e32 v107, v107
	v_pk_mul_f32 v[92:93], v[92:93], v[94:95]
	v_pk_add_f32 v[94:95], v[96:97], 1.0 op_sel_hi:[1,0]
	v_pk_mul_f32 v[96:97], v[88:89], v[104:105] op_sel_hi:[1,0]
	v_rcp_f32_e32 v94, v94
	v_exp_f32_e32 v96, v96
	v_exp_f32_e32 v97, v97
	v_rcp_f32_e32 v95, v95
	v_pk_add_f32 v[100:101], v[106:107], 1.0 op_sel_hi:[1,0]
	v_fmamk_f32 v159, v159, 0x3a800000, v172
	v_pk_add_f32 v[86:87], v[96:97], 1.0 op_sel_hi:[1,0]
	v_rcp_f32_e32 v100, v100
	v_rcp_f32_e32 v86, v86
	v_rcp_f32_e32 v87, v87
	v_rcp_f32_e32 v101, v101
	v_rsq_f32_e32 v159, v159
	v_pk_mul_f32 v[82:83], v[82:83], v[98:99] op_sel_hi:[1,0]
	v_pk_mul_f32 v[90:91], v[90:91], v[98:99] op_sel_hi:[1,0]
	v_pk_mul_f32 v[88:89], v[82:83], v[94:95]
	v_pk_mul_f32 v[82:83], v[84:85], v[98:99] op_sel_hi:[1,0]
	v_pk_mul_f32 v[90:91], v[90:91], v[100:101]
	v_pk_mul_f32 v[86:87], v[82:83], v[86:87]
	v_cvt_pk_bf16_f32 v82, v90, v91
	v_cvt_pk_bf16_f32 v83, v92, v93
	v_cvt_pk_bf16_f32 v84, v88, v89
	v_mul_f32_e32 v88, 0xbfb8aa3b, v159
	v_cvt_pk_bf16_f32 v85, v86, v87
	v_mad_i64_i32 v[86:87], s[24:25], v158, s44, v[114:115]
	v_lshl_add_u64 v[86:87], v[86:87], 0, v[116:117]
	global_store_dwordx4 v[86:87], v[82:85], off nt
	v_pk_mul_f32 v[86:87], v[80:81], v[88:89] op_sel_hi:[1,0]
	v_pk_mul_f32 v[90:91], v[78:79], v[88:89] op_sel_hi:[1,0]
	v_exp_f32_e32 v86, v86
	v_exp_f32_e32 v87, v87
	v_pk_mul_f32 v[80:81], v[70:71], v[88:89] op_sel_hi:[1,0]
	v_mul_f32_e32 v82, v159, v159
	v_exp_f32_e32 v80, v80
	v_pk_add_f32 v[78:79], v[86:87], 1.0 op_sel_hi:[1,0]
	v_exp_f32_e32 v81, v81
	v_rcp_f32_e32 v78, v78
	v_rcp_f32_e32 v79, v79
	v_pk_mul_f32 v[76:77], v[76:77], v[82:83] op_sel_hi:[1,0]
	v_exp_f32_e32 v90, v90
	v_exp_f32_e32 v91, v91
	v_pk_mul_f32 v[76:77], v[76:77], v[78:79]
	v_pk_add_f32 v[78:79], v[80:81], 1.0 op_sel_hi:[1,0]
	v_pk_mul_f32 v[80:81], v[72:73], v[88:89] op_sel_hi:[1,0]
	v_rcp_f32_e32 v78, v78
	v_exp_f32_e32 v80, v80
	v_exp_f32_e32 v81, v81
	v_rcp_f32_e32 v79, v79
	v_pk_add_f32 v[84:85], v[90:91], 1.0 op_sel_hi:[1,0]
	v_fmamk_f32 v163, v163, 0x3a800000, v172
	v_pk_add_f32 v[70:71], v[80:81], 1.0 op_sel_hi:[1,0]
	v_rcp_f32_e32 v84, v84
	v_rcp_f32_e32 v70, v70
	v_rcp_f32_e32 v71, v71
	v_rcp_f32_e32 v85, v85
	v_rsq_f32_e32 v163, v163
	v_pk_mul_f32 v[66:67], v[66:67], v[82:83] op_sel_hi:[1,0]
	v_pk_mul_f32 v[74:75], v[74:75], v[82:83] op_sel_hi:[1,0]
	v_pk_mul_f32 v[72:73], v[66:67], v[78:79]
	v_pk_mul_f32 v[66:67], v[68:69], v[82:83] op_sel_hi:[1,0]
	v_pk_mul_f32 v[74:75], v[74:75], v[84:85]
	v_pk_mul_f32 v[70:71], v[66:67], v[70:71]
	v_cvt_pk_bf16_f32 v66, v74, v75
	v_cvt_pk_bf16_f32 v67, v76, v77
	v_cvt_pk_bf16_f32 v68, v72, v73
	v_mul_f32_e32 v72, 0xbfb8aa3b, v163
	v_cvt_pk_bf16_f32 v69, v70, v71
	v_mad_i64_i32 v[70:71], s[24:25], v156, s44, v[114:115]
	v_lshl_add_u64 v[70:71], v[70:71], 0, v[116:117]
	global_store_dwordx4 v[70:71], v[66:69], off nt
	v_pk_mul_f32 v[70:71], v[64:65], v[72:73] op_sel_hi:[1,0]
	v_pk_mul_f32 v[74:75], v[62:63], v[72:73] op_sel_hi:[1,0]
	v_exp_f32_e32 v70, v70
	v_exp_f32_e32 v71, v71
	v_pk_mul_f32 v[64:65], v[54:55], v[72:73] op_sel_hi:[1,0]
	v_mul_f32_e32 v66, v163, v163
	v_exp_f32_e32 v64, v64
	v_pk_add_f32 v[62:63], v[70:71], 1.0 op_sel_hi:[1,0]
	v_exp_f32_e32 v65, v65
	v_rcp_f32_e32 v62, v62
	v_rcp_f32_e32 v63, v63
	v_pk_mul_f32 v[60:61], v[60:61], v[66:67] op_sel_hi:[1,0]
	v_exp_f32_e32 v74, v74
	v_exp_f32_e32 v75, v75
	v_pk_mul_f32 v[60:61], v[60:61], v[62:63]
	v_pk_add_f32 v[62:63], v[64:65], 1.0 op_sel_hi:[1,0]
	v_pk_mul_f32 v[64:65], v[56:57], v[72:73] op_sel_hi:[1,0]
	v_rcp_f32_e32 v62, v62
	v_exp_f32_e32 v64, v64
	v_exp_f32_e32 v65, v65
	v_rcp_f32_e32 v63, v63
	v_pk_add_f32 v[68:69], v[74:75], 1.0 op_sel_hi:[1,0]
	v_fmamk_f32 v161, v161, 0x3a800000, v172
	v_pk_add_f32 v[54:55], v[64:65], 1.0 op_sel_hi:[1,0]
	v_rcp_f32_e32 v68, v68
	v_rcp_f32_e32 v54, v54
	v_rcp_f32_e32 v55, v55
	v_rcp_f32_e32 v69, v69
	v_rsq_f32_e32 v161, v161
	v_pk_mul_f32 v[50:51], v[50:51], v[66:67] op_sel_hi:[1,0]
	v_pk_mul_f32 v[58:59], v[58:59], v[66:67] op_sel_hi:[1,0]
	v_pk_mul_f32 v[56:57], v[50:51], v[62:63]
	v_pk_mul_f32 v[50:51], v[52:53], v[66:67] op_sel_hi:[1,0]
	v_pk_mul_f32 v[58:59], v[58:59], v[68:69]
	v_pk_mul_f32 v[54:55], v[50:51], v[54:55]
	v_cvt_pk_bf16_f32 v50, v58, v59
	v_cvt_pk_bf16_f32 v51, v60, v61
	v_cvt_pk_bf16_f32 v52, v56, v57
	v_mul_f32_e32 v56, 0xbfb8aa3b, v161
	v_cvt_pk_bf16_f32 v53, v54, v55
	v_mad_i64_i32 v[54:55], s[24:25], v154, s44, v[114:115]
	v_lshl_add_u64 v[54:55], v[54:55], 0, v[116:117]
	global_store_dwordx4 v[54:55], v[50:53], off nt
	v_pk_mul_f32 v[54:55], v[48:49], v[56:57] op_sel_hi:[1,0]
	v_pk_mul_f32 v[58:59], v[46:47], v[56:57] op_sel_hi:[1,0]
	v_exp_f32_e32 v54, v54
	v_exp_f32_e32 v55, v55
	v_pk_mul_f32 v[48:49], v[38:39], v[56:57] op_sel_hi:[1,0]
; __device__ __forceinline__ unsigned cvt_pk_bf16(float lo, float hi) { unsigned r; asm volatile("v_cvt_pk_bf16_f32 %0, %1, %2" : "=v"(r) : "v"(lo), "v"(hi)); return r; }
; #define PG8_BAR __builtin_amdgcn_s_barrier()
; template <class Epi, class Sched, bool ALIGN_EPI = false, bool SP2 = false>
; __device__ __forceinline__ void gemm_phase(PG8_LAS unsigned char* lds, const Gemm g, const Sched& S, const Epi& E) {
;     ...
;         if constexpr (ALIGN_EPI) { if (wr == 0) PG8_BAR; }
;         if constexpr (!Epi::AFTER_DRAIN) { E(acc, cur, wr, wc, fr, fq); S.done(cur); }
;         if (!has_next) break;
; #pragma unroll
;         for (int a = 0; a < 2; ++a)
; #pragma unroll
;             for (int b = 0; b < 2; ++b)
; #pragma unroll
;                 for (int m = 0; m < 4; ++m)
; #pragma unroll
;                     for (int n = 0; n < 2; ++n) acc[a][b][m][n] = (f32x4){0.f, 0.f, 0.f, 0.f};
;         cur = nxt; cA = nA; cB = nB; ++ui;
;         if constexpr (ALIGN_EPI) { if (wr == 1) PG8_BAR; }
;     __device__ __forceinline__ void operator()(const pg8::f32x4 (&acc)[2][2][4][2], const Unit& u, int wr, int wc, int fr, int fq) const {
;     ...
;             for (int m = 0; m < 4; ++m) { float r[8]; const float rs = rsv[ai * 4 + m]; const float c1 = -1.4426950408889634f * rs, rs2 = rs * rs;
; #pragma unroll
;                 for (int n = 0; n < 2; ++n)
; #pragma unroll
;                     for (int e = 0; e < 4; e += 2) { const f32x2 ag = {acc[ai][0][m][n][e], acc[ai][0][m][n][e + 1]}, au = {acc[ai][1][m][n][e], acc[ai][1][m][n][e + 1]};
;                         const f32x2 t = ag * c1; f32x2 d; d.x = __builtin_amdgcn_exp2f(t.x); d.y = __builtin_amdgcn_exp2f(t.y); d = d + 1.0f;
;                         f32x2 q; q.x = __builtin_amdgcn_rcpf(d.x); q.y = __builtin_amdgcn_rcpf(d.y); const f32x2 o = (ag * au) * rs2 * q; r[4 * n + e] = o.x; r[4 * n + e + 1] = o.y; }
;                 v4u w; w.x = cvt_pk_bf16(r[0], r[1]); w.y = cvt_pk_bf16(r[2], r[3]); w.z = cvt_pk_bf16(r[4], r[5]); w.w = cvt_pk_bf16(r[6], r[7]);
;                 __builtin_nontemporal_store(w, (v4u*)(O + (size_t)(row0 + ai * HALF + m * 16) * FF + col0)); }
	v_mul_f32_e32 v50, v161, v161
	v_exp_f32_e32 v48, v48
	v_pk_add_f32 v[46:47], v[54:55], 1.0 op_sel_hi:[1,0]
	v_exp_f32_e32 v49, v49
	v_rcp_f32_e32 v46, v46
	v_rcp_f32_e32 v47, v47
	v_pk_mul_f32 v[44:45], v[44:45], v[50:51] op_sel_hi:[1,0]
	v_exp_f32_e32 v58, v58
	v_exp_f32_e32 v59, v59
	v_pk_mul_f32 v[44:45], v[44:45], v[46:47]
	v_pk_add_f32 v[46:47], v[48:49], 1.0 op_sel_hi:[1,0]
	v_pk_mul_f32 v[48:49], v[40:41], v[56:57] op_sel_hi:[1,0]
	v_rcp_f32_e32 v46, v46
	v_exp_f32_e32 v48, v48
	v_exp_f32_e32 v49, v49
	v_rcp_f32_e32 v47, v47
	v_pk_add_f32 v[52:53], v[58:59], 1.0 op_sel_hi:[1,0]
	v_fmamk_f32 v151, v151, 0x3a800000, v172
	v_pk_add_f32 v[38:39], v[48:49], 1.0 op_sel_hi:[1,0]
	v_rcp_f32_e32 v52, v52
	v_rcp_f32_e32 v38, v38
	v_rcp_f32_e32 v39, v39
	v_rcp_f32_e32 v53, v53
	v_rsq_f32_e32 v151, v151
	v_pk_mul_f32 v[34:35], v[34:35], v[50:51] op_sel_hi:[1,0]
	v_pk_mul_f32 v[42:43], v[42:43], v[50:51] op_sel_hi:[1,0]
	v_pk_mul_f32 v[40:41], v[34:35], v[46:47]
	v_pk_mul_f32 v[34:35], v[36:37], v[50:51] op_sel_hi:[1,0]
	v_pk_mul_f32 v[42:43], v[42:43], v[52:53]
	v_pk_mul_f32 v[38:39], v[34:35], v[38:39]
	v_cvt_pk_bf16_f32 v34, v42, v43
	v_cvt_pk_bf16_f32 v35, v44, v45
	v_cvt_pk_bf16_f32 v36, v40, v41
	v_mul_f32_e32 v40, 0xbfb8aa3b, v151
	v_cvt_pk_bf16_f32 v37, v38, v39
	v_mad_i64_i32 v[38:39], s[24:25], v152, s44, v[114:115]
	v_lshl_add_u64 v[38:39], v[38:39], 0, v[116:117]
	global_store_dwordx4 v[38:39], v[34:37], off nt
	v_pk_mul_f32 v[38:39], v[32:33], v[40:41] op_sel_hi:[1,0]
	v_pk_mul_f32 v[42:43], v[30:31], v[40:41] op_sel_hi:[1,0]
	v_exp_f32_e32 v38, v38
	v_exp_f32_e32 v39, v39
	v_pk_mul_f32 v[32:33], v[22:23], v[40:41] op_sel_hi:[1,0]
	v_mul_f32_e32 v34, v151, v151
	v_exp_f32_e32 v32, v32
	v_pk_add_f32 v[30:31], v[38:39], 1.0 op_sel_hi:[1,0]
	v_exp_f32_e32 v33, v33
	v_rcp_f32_e32 v30, v30
	v_rcp_f32_e32 v31, v31
	v_pk_mul_f32 v[28:29], v[28:29], v[34:35] op_sel_hi:[1,0]
	v_exp_f32_e32 v42, v42
	v_exp_f32_e32 v43, v43
	v_pk_mul_f32 v[28:29], v[28:29], v[30:31]
	v_pk_add_f32 v[30:31], v[32:33], 1.0 op_sel_hi:[1,0]
	v_pk_mul_f32 v[32:33], v[24:25], v[40:41] op_sel_hi:[1,0]
	v_rcp_f32_e32 v30, v30
	v_exp_f32_e32 v32, v32
	v_exp_f32_e32 v33, v33
	v_rcp_f32_e32 v31, v31
	v_pk_add_f32 v[36:37], v[42:43], 1.0 op_sel_hi:[1,0]
	v_fmamk_f32 v149, v149, 0x3a800000, v172
	v_pk_add_f32 v[22:23], v[32:33], 1.0 op_sel_hi:[1,0]
	v_rcp_f32_e32 v36, v36
	v_rcp_f32_e32 v22, v22
	v_rcp_f32_e32 v23, v23
	v_rcp_f32_e32 v37, v37
	v_rsq_f32_e32 v149, v149
	v_pk_mul_f32 v[18:19], v[18:19], v[34:35] op_sel_hi:[1,0]
	v_pk_mul_f32 v[26:27], v[26:27], v[34:35] op_sel_hi:[1,0]
	v_pk_mul_f32 v[24:25], v[18:19], v[30:31]
	v_pk_mul_f32 v[18:19], v[20:21], v[34:35] op_sel_hi:[1,0]
	v_pk_mul_f32 v[26:27], v[26:27], v[36:37]
	v_pk_mul_f32 v[22:23], v[18:19], v[22:23]
	v_cvt_pk_bf16_f32 v18, v26, v27
	v_cvt_pk_bf16_f32 v19, v28, v29
	v_cvt_pk_bf16_f32 v20, v24, v25
	v_mul_f32_e32 v24, 0xbfb8aa3b, v149
	v_cvt_pk_bf16_f32 v21, v22, v23
	v_mad_i64_i32 v[22:23], s[24:25], v150, s44, v[114:115]
	v_lshl_add_u64 v[22:23], v[22:23], 0, v[116:117]
	global_store_dwordx4 v[22:23], v[18:21], off nt
	v_pk_mul_f32 v[22:23], v[16:17], v[24:25] op_sel_hi:[1,0]
	v_pk_mul_f32 v[26:27], v[14:15], v[24:25] op_sel_hi:[1,0]
	v_exp_f32_e32 v22, v22
	v_exp_f32_e32 v23, v23
	v_pk_mul_f32 v[16:17], v[6:7], v[24:25] op_sel_hi:[1,0]
	v_mul_f32_e32 v18, v149, v149
	v_exp_f32_e32 v16, v16
	v_pk_add_f32 v[14:15], v[22:23], 1.0 op_sel_hi:[1,0]
	v_exp_f32_e32 v17, v17
	v_rcp_f32_e32 v14, v14
	v_rcp_f32_e32 v15, v15
	v_pk_mul_f32 v[12:13], v[12:13], v[18:19] op_sel_hi:[1,0]
	v_exp_f32_e32 v26, v26
	v_exp_f32_e32 v27, v27
	v_pk_mul_f32 v[12:13], v[12:13], v[14:15]
	v_pk_add_f32 v[14:15], v[16:17], 1.0 op_sel_hi:[1,0]
	v_pk_mul_f32 v[16:17], v[8:9], v[24:25] op_sel_hi:[1,0]
	v_rcp_f32_e32 v14, v14
	v_exp_f32_e32 v16, v16
	v_exp_f32_e32 v17, v17
	v_rcp_f32_e32 v15, v15
	v_pk_add_f32 v[20:21], v[26:27], 1.0 op_sel_hi:[1,0]
	v_pk_mul_f32 v[2:3], v[2:3], v[18:19] op_sel_hi:[1,0]
	v_pk_add_f32 v[6:7], v[16:17], 1.0 op_sel_hi:[1,0]
	v_rcp_f32_e32 v20, v20
	v_rcp_f32_e32 v6, v6
	v_rcp_f32_e32 v7, v7
	v_rcp_f32_e32 v21, v21
	v_pk_mul_f32 v[8:9], v[2:3], v[14:15]
	v_pk_mul_f32 v[2:3], v[4:5], v[18:19] op_sel_hi:[1,0]
	v_pk_mul_f32 v[10:11], v[10:11], v[18:19] op_sel_hi:[1,0]
	v_pk_mul_f32 v[6:7], v[2:3], v[6:7]
	v_pk_mul_f32 v[10:11], v[10:11], v[20:21]
	s_nop 0
	v_cvt_pk_bf16_f32 v2, v10, v11
	v_cvt_pk_bf16_f32 v3, v12, v13
	v_cvt_pk_bf16_f32 v4, v8, v9
	v_cvt_pk_bf16_f32 v5, v6, v7
	v_mad_i64_i32 v[6:7], s[24:25], v148, s44, v[114:115]
	v_lshl_add_u64 v[6:7], v[6:7], 0, v[116:117]
	global_store_dwordx4 v[6:7], v[2:5], off nt
	s_cbranch_vccnz .LBB0_687
	s_andn2_b64 vcc, exec, s[4:5]
	s_cbranch_vccnz .LBB0_686
	s_barrier
	s_branch .LBB0_686

; __device__ __forceinline__ unsigned cvt_pk_bf16(float lo, float hi) { unsigned r; asm volatile("v_cvt_pk_bf16_f32 %0, %1, %2" : "=v"(r) : "v"(lo), "v"(hi)); return r; }
; __device__ __forceinline__ float bflo(unsigned w) { return __uint_as_float(w << 16); }
; __device__ __forceinline__ float bfhi(unsigned w) { return __uint_as_float(w & 0xffff0000u); }
;     __device__ __forceinline__ void ld(Ld& L, size_t o) const {
; #pragma unroll
;         for (int bj = 0; bj < 2; ++bj) { if (BASEF32) { L.a[bj][0] = *(const f32x4*)((const float*)base + o + bj * HALF); L.a[bj][1] = *(const f32x4*)((const float*)base + o + bj * HALF + 4); }
;             else { const v4u w = *(const v4u*)((const bf16*)base + o + bj * HALF); L.a[bj][0] = __builtin_bit_cast(f32x4, w); } }
;     }
;     __device__ __forceinline__ void operator()(const pg8::f32x4 (&acc)[2][2][4][2], const Unit& u, int wr, int wc, int fr, int fq) const {
;         const int row0 = u.pm * BM + wr * 64 + fr, col0 = u.pn * BM + wc * 32 + 8 * fq;
;         Ld nx; ld(nx, (size_t)row0 * DM_ + col0);
; #pragma unroll
;         for (int k = 0; k < 8; ++k) { const int ai = k >> 2, m = k & 3; const int row = row0 + ai * HALF + m * 16; float q = 0.f; const Ld cu = nx;
;             if (k < 7) ld(nx, (size_t)(row0 + ((k + 1) >> 2) * HALF + ((k + 1) & 3) * 16) * DM_ + col0);
; #pragma unroll
;             for (int bj = 0; bj < 2; ++bj) { const size_t o = (size_t)row * DM_ + col0 + bj * HALF; f32x4 b0, b1;
;                 if (BASEF32) { b0 = cu.a[bj][0]; b1 = cu.a[bj][1]; }
;                 else { const v4u w = __builtin_bit_cast(v4u, cu.a[bj][0]); b0 = (f32x4){bflo(w.x), bfhi(w.x), bflo(w.y), bfhi(w.y)}; b1 = (f32x4){bflo(w.z), bfhi(w.z), bflo(w.w), bfhi(w.w)}; }
;                 const f32x4 r0 = b0 + acc[ai][bj][m][0], r1 = b1 + acc[ai][bj][m][1];
;                 q += (r0[0] * r0[0] + r0[1] * r0[1]) + (r0[2] * r0[2] + r0[3] * r0[3]) + (r1[0] * r1[0] + r1[1] * r1[1]) + (r1[2] * r1[2] + r1[3] * r1[3]);
;                 v4u w; w.x = cvt_pk_bf16(r0[0], r0[1]); w.y = cvt_pk_bf16(r0[2], r0[3]); w.z = cvt_pk_bf16(r1[0], r1[1]); w.w = cvt_pk_bf16(r1[2], r1[3]); *(v4u*)(out + o) = w; }
;             q += __shfl_xor(q, 16); q += __shfl_xor(q, 32); if (fq == 0) ssq[(size_t)row * 16 + u.pn * 4 + wc] = q; }
.LBB0_779:
	v_lshl_add_u32 v156, s52, 8, v1
	v_lshl_or_b32 v154, s51, 8, v163
	v_ashrrev_i32_e32 v157, 31, v156
	v_ashrrev_i32_e32 v155, 31, v154
	v_lshlrev_b64 v[130:131], 11, v[156:157]
	v_lshl_add_u64 v[130:131], s[16:17], 0, v[130:131]
	v_lshlrev_b64 v[132:133], 1, v[154:155]
	v_lshl_add_u64 v[178:179], v[130:131], 0, v[132:133]
	global_load_dwordx4 v[170:173], v[178:179], off
	global_load_dwordx4 v[174:177], v[178:179], off offset:256
	v_or_b32_e32 v158, 16, v156
	v_ashrrev_i32_e32 v159, 31, v158
	v_lshlrev_b64 v[130:131], 11, v[158:159]
	v_lshl_add_u64 v[130:131], s[16:17], 0, v[130:131]
	v_lshl_add_u64 v[160:161], v[130:131], 0, v[132:133]
	global_load_dwordx4 v[134:137], v[160:161], off
	global_load_dwordx4 v[130:133], v[160:161], off offset:256
	v_and_b32_e32 v169, 64, v167
	v_xor_b32_e32 v168, 16, v167
	v_add_u32_e32 v169, 64, v169
	v_xor_b32_e32 v180, 32, v167
	v_cmp_lt_i32_e32 vcc, v168, v169
	s_lshl_b32 s26, s51, 2
	s_ashr_i32 s27, s26, 31
	v_cndmask_b32_e32 v168, v167, v168, vcc
	v_cmp_lt_i32_e32 vcc, v180, v169
	v_lshlrev_b32_e32 v168, 2, v168
	s_waitcnt vmcnt(0)
	v_and_b32_e32 v181, 0xffff0000, v170
	v_cndmask_b32_e32 v169, v167, v180, vcc
	v_lshlrev_b32_e32 v180, 16, v170
	v_lshlrev_b32_e32 v170, 16, v171
	v_and_b32_e32 v171, 0xffff0000, v171
	v_lshlrev_b32_e32 v184, 16, v174
	v_and_b32_e32 v185, 0xffff0000, v174
	v_lshlrev_b32_e32 v174, 16, v175
	v_and_b32_e32 v175, 0xffff0000, v175
	v_lshlrev_b32_e32 v182, 16, v172
	v_and_b32_e32 v183, 0xffff0000, v172
	v_lshlrev_b32_e32 v172, 16, v173
	v_and_b32_e32 v173, 0xffff0000, v173
	v_lshlrev_b32_e32 v186, 16, v176
	v_and_b32_e32 v187, 0xffff0000, v176
	v_lshlrev_b32_e32 v176, 16, v177
	v_and_b32_e32 v177, 0xffff0000, v177
	v_pk_add_f32 v[128:129], v[128:129], v[170:171]
	v_pk_add_f32 v[126:127], v[126:127], v[180:181]
	v_pk_add_f32 v[120:121], v[120:121], v[174:175]
	v_pk_add_f32 v[118:119], v[118:119], v[184:185]
	v_pk_add_f32 v[124:125], v[124:125], v[172:173]
	v_pk_add_f32 v[122:123], v[122:123], v[182:183]
	v_pk_add_f32 v[170:171], v[116:117], v[176:177]
	v_pk_add_f32 v[172:173], v[114:115], v[186:187]
	v_mul_f32_e32 v116, v127, v127
	v_mul_f32_e32 v117, v129, v129
	v_cvt_pk_bf16_f32 v114, v126, v127
	v_cvt_pk_bf16_f32 v115, v128, v129
	v_mul_f32_e32 v127, v119, v119
	v_mul_f32_e32 v129, v121, v121
	v_mul_f32_e32 v174, v123, v123
	v_mul_f32_e32 v176, v173, v173
	v_fmac_f32_e32 v116, v126, v126
	v_fmac_f32_e32 v117, v128, v128
	v_fmac_f32_e32 v127, v118, v118
	v_fmac_f32_e32 v129, v120, v120
	v_mul_f32_e32 v175, v125, v125
	v_mul_f32_e32 v177, v171, v171
	v_fmac_f32_e32 v174, v122, v122
	v_fmac_f32_e32 v176, v172, v172
	v_add_f32_e32 v116, v116, v117
	v_add_f32_e32 v117, v127, v129
	v_fmac_f32_e32 v175, v124, v124
	v_fmac_f32_e32 v177, v170, v170
	v_add_f32_e32 v116, v174, v116
	v_add_f32_e32 v117, v176, v117
	v_add_f32_e32 v116, v175, v116
	v_add_f32_e32 v117, v177, v117
	v_add_f32_e32 v126, v116, v117
	v_mov_b32_e32 v127, v126
	s_nop 1
	v_permlane16_swap_b32 v126, v127
	v_cvt_pk_bf16_f32 v116, v122, v123
	v_cvt_pk_bf16_f32 v117, v124, v125
	global_store_dwordx4 v[178:179], v[114:117], off
	s_waitcnt lgkmcnt(0)
	s_nop 0
	v_add_f32_e32 v114, v126, v127
	v_lshlrev_b32_e32 v126, 2, v169
	v_mov_b32_e32 v115, v114
	s_nop 1
	v_permlane32_swap_b32 v114, v115
	v_cvt_pk_bf16_f32 v116, v118, v119
	v_cvt_pk_bf16_f32 v117, v120, v121
	v_cvt_pk_bf16_f32 v118, v172, v173
	v_cvt_pk_bf16_f32 v119, v170, v171
	global_store_dwordx4 v[178:179], v[116:119], off offset:256
	s_and_saveexec_b64 s[28:29], s[8:9]
	s_cbranch_execz .LBB0_781
	v_lshlrev_b64 v[116:117], 6, v[156:157]
	v_lshl_add_u64 v[116:117], s[18:19], 0, v[116:117]
	v_lshl_add_u64 v[116:117], s[26:27], 2, v[116:117]
	s_lshl_b32 s4, s40, 2
	v_lshl_add_u64 v[116:117], v[116:117], 0, s[4:5]
	s_waitcnt lgkmcnt(0)
	v_add_f32_e32 v114, v114, v115
	global_store_dword v[116:117], v114, off
.LBB0_781:
	s_or_b64 exec, exec, s[28:29]
	v_or_b32_e32 v122, 32, v156
	v_ashrrev_i32_e32 v123, 31, v122
	s_waitcnt lgkmcnt(0)
	v_lshlrev_b64 v[114:115], 11, v[122:123]
	v_lshl_add_u64 v[114:115], s[16:17], 0, v[114:115]
	v_lshl_add_u64 v[124:125], v[154:155], 1, v[114:115]
	global_load_dwordx4 v[118:121], v[124:125], off
	global_load_dwordx4 v[114:117], v[124:125], off offset:256
	v_lshlrev_b32_e32 v128, 16, v134
	v_and_b32_e32 v129, 0xffff0000, v134
	v_lshlrev_b32_e32 v134, 16, v135
	v_and_b32_e32 v135, 0xffff0000, v135
	v_lshlrev_b32_e32 v170, 16, v136
	v_and_b32_e32 v171, 0xffff0000, v136
	v_lshlrev_b32_e32 v136, 16, v137
	v_and_b32_e32 v137, 0xffff0000, v137
	v_pk_add_f32 v[112:113], v[112:113], v[134:135]
	v_pk_add_f32 v[110:111], v[110:111], v[128:129]
	v_pk_add_f32 v[128:129], v[108:109], v[136:137]
	v_pk_add_f32 v[108:109], v[106:107], v[170:171]
	v_mul_f32_e32 v106, v111, v111
	v_mul_f32_e32 v107, v113, v113
	v_fmac_f32_e32 v106, v110, v110
	v_fmac_f32_e32 v107, v112, v112
	v_add_f32_e32 v106, v106, v107
	v_mul_f32_e32 v107, v109, v109
	v_fmac_f32_e32 v107, v108, v108
	v_add_f32_e32 v106, v107, v106
	v_mul_f32_e32 v107, v129, v129
	v_fmac_f32_e32 v107, v128, v128
	v_add_f32_e32 v127, v107, v106
	v_cvt_pk_bf16_f32 v106, v110, v111
	v_cvt_pk_bf16_f32 v107, v112, v113
	v_lshlrev_b32_e32 v110, 16, v130
	v_and_b32_e32 v111, 0xffff0000, v130
	v_lshlrev_b32_e32 v112, 16, v131
	v_and_b32_e32 v113, 0xffff0000, v131
	v_lshlrev_b32_e32 v130, 16, v132
	v_and_b32_e32 v131, 0xffff0000, v132
	v_pk_add_f32 v[104:105], v[104:105], v[112:113]
	v_pk_add_f32 v[102:103], v[102:103], v[110:111]
	v_pk_add_f32 v[112:113], v[98:99], v[130:131]
	v_mul_f32_e32 v98, v103, v103
	v_mul_f32_e32 v99, v105, v105
	v_fmac_f32_e32 v98, v102, v102
	v_fmac_f32_e32 v99, v104, v104
	v_lshlrev_b32_e32 v132, 16, v133
	v_and_b32_e32 v133, 0xffff0000, v133
	v_add_f32_e32 v98, v98, v99
	v_mul_f32_e32 v99, v113, v113
	v_pk_add_f32 v[110:111], v[100:101], v[132:133]
	v_fmac_f32_e32 v99, v112, v112
	v_add_f32_e32 v98, v99, v98
	v_mul_f32_e32 v99, v111, v111
	v_fmac_f32_e32 v99, v110, v110
	v_add_f32_e32 v98, v99, v98
	v_add_f32_e32 v98, v127, v98
	v_mov_b32_e32 v99, v98
	s_nop 1
	v_permlane16_swap_b32 v98, v99
	v_cvt_pk_bf16_f32 v108, v108, v109
	v_cvt_pk_bf16_f32 v109, v128, v129
	global_store_dwordx4 v[160:161], v[106:109], off
	v_cvt_pk_bf16_f32 v100, v102, v103
	s_waitcnt lgkmcnt(0)
	v_add_f32_e32 v98, v98, v99
	v_mov_b32_e32 v99, v98
	s_nop 1
	v_permlane32_swap_b32 v98, v99
	v_cvt_pk_bf16_f32 v101, v104, v105
	v_cvt_pk_bf16_f32 v102, v112, v113
	v_cvt_pk_bf16_f32 v103, v110, v111
	global_store_dwordx4 v[160:161], v[100:103], off offset:256
	s_and_saveexec_b64 s[28:29], s[8:9]
	s_cbranch_execz .LBB0_783
	v_lshlrev_b64 v[100:101], 6, v[158:159]
	v_lshl_add_u64 v[100:101], s[18:19], 0, v[100:101]
	v_lshl_add_u64 v[100:101], s[26:27], 2, v[100:101]
	s_lshl_b32 s4, s40, 2
	v_lshl_add_u64 v[100:101], v[100:101], 0, s[4:5]
	s_waitcnt lgkmcnt(0)
	v_add_f32_e32 v98, v98, v99
	global_store_dword v[100:101], v98, off
; __device__ __forceinline__ unsigned cvt_pk_bf16(float lo, float hi) { unsigned r; asm volatile("v_cvt_pk_bf16_f32 %0, %1, %2" : "=v"(r) : "v"(lo), "v"(hi)); return r; }
; __device__ __forceinline__ float bflo(unsigned w) { return __uint_as_float(w << 16); }
; __device__ __forceinline__ float bfhi(unsigned w) { return __uint_as_float(w & 0xffff0000u); }
;     __device__ __forceinline__ void ld(Ld& L, size_t o) const {
; #pragma unroll
;         for (int bj = 0; bj < 2; ++bj) { if (BASEF32) { L.a[bj][0] = *(const f32x4*)((const float*)base + o + bj * HALF); L.a[bj][1] = *(const f32x4*)((const float*)base + o + bj * HALF + 4); }
;             else { const v4u w = *(const v4u*)((const bf16*)base + o + bj * HALF); L.a[bj][0] = __builtin_bit_cast(f32x4, w); } }
;     }
;     __device__ __forceinline__ void operator()(const pg8::f32x4 (&acc)[2][2][4][2], const Unit& u, int wr, int wc, int fr, int fq) const {
;         const int row0 = u.pm * BM + wr * 64 + fr, col0 = u.pn * BM + wc * 32 + 8 * fq;
;         Ld nx; ld(nx, (size_t)row0 * DM_ + col0);
; #pragma unroll
;         for (int k = 0; k < 8; ++k) { const int ai = k >> 2, m = k & 3; const int row = row0 + ai * HALF + m * 16; float q = 0.f; const Ld cu = nx;
;             if (k < 7) ld(nx, (size_t)(row0 + ((k + 1) >> 2) * HALF + ((k + 1) & 3) * 16) * DM_ + col0);
; #pragma unroll
;             for (int bj = 0; bj < 2; ++bj) { const size_t o = (size_t)row * DM_ + col0 + bj * HALF; f32x4 b0, b1;
;                 if (BASEF32) { b0 = cu.a[bj][0]; b1 = cu.a[bj][1]; }
;                 else { const v4u w = __builtin_bit_cast(v4u, cu.a[bj][0]); b0 = (f32x4){bflo(w.x), bfhi(w.x), bflo(w.y), bfhi(w.y)}; b1 = (f32x4){bflo(w.z), bfhi(w.z), bflo(w.w), bfhi(w.w)}; }
;                 const f32x4 r0 = b0 + acc[ai][bj][m][0], r1 = b1 + acc[ai][bj][m][1];
;                 q += (r0[0] * r0[0] + r0[1] * r0[1]) + (r0[2] * r0[2] + r0[3] * r0[3]) + (r1[0] * r1[0] + r1[1] * r1[1]) + (r1[2] * r1[2] + r1[3] * r1[3]);
;                 v4u w; w.x = cvt_pk_bf16(r0[0], r0[1]); w.y = cvt_pk_bf16(r0[2], r0[3]); w.z = cvt_pk_bf16(r1[0], r1[1]); w.w = cvt_pk_bf16(r1[2], r1[3]); *(v4u*)(out + o) = w; }
;             q += __shfl_xor(q, 16); q += __shfl_xor(q, 32); if (fq == 0) ssq[(size_t)row * 16 + u.pn * 4 + wc] = q; }
.LBB0_783:
	s_or_b64 exec, exec, s[28:29]
	v_or_b32_e32 v106, 48, v156
	v_ashrrev_i32_e32 v107, 31, v106
	s_waitcnt lgkmcnt(0)
	v_lshlrev_b64 v[98:99], 11, v[106:107]
	v_lshl_add_u64 v[98:99], s[16:17], 0, v[98:99]
	v_lshl_add_u64 v[108:109], v[154:155], 1, v[98:99]
	global_load_dwordx4 v[102:105], v[108:109], off
	global_load_dwordx4 v[98:101], v[108:109], off offset:256
	s_waitcnt vmcnt(5)
	v_lshlrev_b32_e32 v110, 16, v118
	v_and_b32_e32 v111, 0xffff0000, v118
	v_lshlrev_b32_e32 v112, 16, v119
	v_and_b32_e32 v113, 0xffff0000, v119
	v_lshlrev_b32_e32 v118, 16, v120
	v_and_b32_e32 v119, 0xffff0000, v120
	v_lshlrev_b32_e32 v120, 16, v121
	v_and_b32_e32 v121, 0xffff0000, v121
	v_pk_add_f32 v[96:97], v[96:97], v[112:113]
	v_pk_add_f32 v[94:95], v[94:95], v[110:111]
	v_pk_add_f32 v[110:111], v[92:93], v[120:121]
	v_pk_add_f32 v[92:93], v[90:91], v[118:119]
	v_mul_f32_e32 v90, v95, v95
	v_mul_f32_e32 v91, v97, v97
	v_fmac_f32_e32 v90, v94, v94
	v_fmac_f32_e32 v91, v96, v96
	v_add_f32_e32 v90, v90, v91
	v_mul_f32_e32 v91, v93, v93
	v_fmac_f32_e32 v91, v92, v92
	v_add_f32_e32 v90, v91, v90
	v_mul_f32_e32 v91, v111, v111
	v_fmac_f32_e32 v91, v110, v110
	v_add_f32_e32 v118, v91, v90
	v_cvt_pk_bf16_f32 v90, v94, v95
	v_cvt_pk_bf16_f32 v91, v96, v97
	s_waitcnt vmcnt(4)
	v_lshlrev_b32_e32 v94, 16, v114
	v_and_b32_e32 v95, 0xffff0000, v114
	v_lshlrev_b32_e32 v96, 16, v115
	v_and_b32_e32 v97, 0xffff0000, v115
	v_lshlrev_b32_e32 v112, 16, v116
	v_and_b32_e32 v113, 0xffff0000, v116
	v_pk_add_f32 v[88:89], v[88:89], v[96:97]
	v_pk_add_f32 v[86:87], v[86:87], v[94:95]
	v_pk_add_f32 v[96:97], v[82:83], v[112:113]
	v_mul_f32_e32 v82, v87, v87
	v_mul_f32_e32 v83, v89, v89
	v_fmac_f32_e32 v82, v86, v86
	v_fmac_f32_e32 v83, v88, v88
	v_lshlrev_b32_e32 v114, 16, v117
	v_and_b32_e32 v115, 0xffff0000, v117
	v_add_f32_e32 v82, v82, v83
	v_mul_f32_e32 v83, v97, v97
	v_pk_add_f32 v[94:95], v[84:85], v[114:115]
	v_fmac_f32_e32 v83, v96, v96
	v_add_f32_e32 v82, v83, v82
	v_mul_f32_e32 v83, v95, v95
	v_fmac_f32_e32 v83, v94, v94
	v_add_f32_e32 v82, v83, v82
	v_add_f32_e32 v82, v118, v82
	v_mov_b32_e32 v83, v82
	s_nop 1
	v_permlane16_swap_b32 v82, v83
	v_cvt_pk_bf16_f32 v92, v92, v93
	v_cvt_pk_bf16_f32 v93, v110, v111
	global_store_dwordx4 v[124:125], v[90:93], off
	v_cvt_pk_bf16_f32 v84, v86, v87
	s_waitcnt lgkmcnt(0)
	v_add_f32_e32 v82, v82, v83
	v_mov_b32_e32 v83, v82
	s_nop 1
	v_permlane32_swap_b32 v82, v83
	v_cvt_pk_bf16_f32 v85, v88, v89
	v_cvt_pk_bf16_f32 v86, v96, v97
	v_cvt_pk_bf16_f32 v87, v94, v95
	global_store_dwordx4 v[124:125], v[84:87], off offset:256
	s_and_saveexec_b64 s[28:29], s[8:9]
	s_cbranch_execz .LBB0_785
	v_lshlrev_b64 v[84:85], 6, v[122:123]
	v_lshl_add_u64 v[84:85], s[18:19], 0, v[84:85]
	v_lshl_add_u64 v[84:85], s[26:27], 2, v[84:85]
	s_lshl_b32 s4, s40, 2
	v_lshl_add_u64 v[84:85], v[84:85], 0, s[4:5]
	s_waitcnt lgkmcnt(0)
	v_add_f32_e32 v82, v82, v83
	global_store_dword v[84:85], v82, off
.LBB0_785:
	s_or_b64 exec, exec, s[28:29]
	v_add_u32_e32 v90, 0x80, v156
	v_ashrrev_i32_e32 v91, 31, v90
	s_waitcnt lgkmcnt(0)
	v_lshlrev_b64 v[82:83], 11, v[90:91]
	v_lshl_add_u64 v[82:83], s[16:17], 0, v[82:83]
	v_lshl_add_u64 v[92:93], v[154:155], 1, v[82:83]
	global_load_dwordx4 v[86:89], v[92:93], off
	global_load_dwordx4 v[82:85], v[92:93], off offset:256
	s_waitcnt vmcnt(5)
	v_lshlrev_b32_e32 v94, 16, v102
	v_and_b32_e32 v95, 0xffff0000, v102
	v_lshlrev_b32_e32 v96, 16, v103
	v_and_b32_e32 v97, 0xffff0000, v103
	v_lshlrev_b32_e32 v102, 16, v104
	v_and_b32_e32 v103, 0xffff0000, v104
	v_lshlrev_b32_e32 v104, 16, v105
	v_and_b32_e32 v105, 0xffff0000, v105
	v_pk_add_f32 v[80:81], v[80:81], v[96:97]
	v_pk_add_f32 v[78:79], v[78:79], v[94:95]
	v_pk_add_f32 v[94:95], v[76:77], v[104:105]
	v_pk_add_f32 v[76:77], v[74:75], v[102:103]
	v_mul_f32_e32 v74, v79, v79
	v_mul_f32_e32 v75, v81, v81
	v_fmac_f32_e32 v74, v78, v78
	v_fmac_f32_e32 v75, v80, v80
	v_add_f32_e32 v74, v74, v75
	v_mul_f32_e32 v75, v77, v77
	v_fmac_f32_e32 v75, v76, v76
	v_add_f32_e32 v74, v75, v74
	v_mul_f32_e32 v75, v95, v95
	v_fmac_f32_e32 v75, v94, v94
	v_add_f32_e32 v102, v75, v74
	v_cvt_pk_bf16_f32 v74, v78, v79
	v_cvt_pk_bf16_f32 v75, v80, v81
	s_waitcnt vmcnt(4)
	v_lshlrev_b32_e32 v78, 16, v98
	v_and_b32_e32 v79, 0xffff0000, v98
	v_lshlrev_b32_e32 v80, 16, v99
	v_and_b32_e32 v81, 0xffff0000, v99
	v_lshlrev_b32_e32 v96, 16, v100
	v_and_b32_e32 v97, 0xffff0000, v100
	v_pk_add_f32 v[72:73], v[72:73], v[80:81]
	v_pk_add_f32 v[70:71], v[70:71], v[78:79]
	v_pk_add_f32 v[80:81], v[66:67], v[96:97]
	v_mul_f32_e32 v66, v71, v71
	v_mul_f32_e32 v67, v73, v73
	v_fmac_f32_e32 v66, v70, v70
	v_fmac_f32_e32 v67, v72, v72
	v_lshlrev_b32_e32 v98, 16, v101
	v_and_b32_e32 v99, 0xffff0000, v101
	v_add_f32_e32 v66, v66, v67
	v_mul_f32_e32 v67, v81, v81
	v_pk_add_f32 v[78:79], v[68:69], v[98:99]
	v_fmac_f32_e32 v67, v80, v80
	v_add_f32_e32 v66, v67, v66
	v_mul_f32_e32 v67, v79, v79
	v_fmac_f32_e32 v67, v78, v78
	v_add_f32_e32 v66, v67, v66
	v_add_f32_e32 v66, v102, v66
	v_mov_b32_e32 v67, v66
	s_nop 1
	v_permlane16_swap_b32 v66, v67
	v_cvt_pk_bf16_f32 v76, v76, v77
	v_cvt_pk_bf16_f32 v77, v94, v95
	global_store_dwordx4 v[108:109], v[74:77], off
	v_cvt_pk_bf16_f32 v68, v70, v71
	s_waitcnt lgkmcnt(0)
	v_add_f32_e32 v66, v66, v67
	v_mov_b32_e32 v67, v66
	s_nop 1
	v_permlane32_swap_b32 v66, v67
	v_cvt_pk_bf16_f32 v69, v72, v73
	v_cvt_pk_bf16_f32 v70, v80, v81
	v_cvt_pk_bf16_f32 v71, v78, v79
	global_store_dwordx4 v[108:109], v[68:71], off offset:256
	s_and_saveexec_b64 s[28:29], s[8:9]
	s_cbranch_execz .LBB0_787
	v_lshlrev_b64 v[68:69], 6, v[106:107]
	v_lshl_add_u64 v[68:69], s[18:19], 0, v[68:69]
	v_lshl_add_u64 v[68:69], s[26:27], 2, v[68:69]
	s_lshl_b32 s4, s40, 2
	v_lshl_add_u64 v[68:69], v[68:69], 0, s[4:5]
	s_waitcnt lgkmcnt(0)
	v_add_f32_e32 v66, v66, v67
	global_store_dword v[68:69], v66, off
; __device__ __forceinline__ unsigned cvt_pk_bf16(float lo, float hi) { unsigned r; asm volatile("v_cvt_pk_bf16_f32 %0, %1, %2" : "=v"(r) : "v"(lo), "v"(hi)); return r; }
; __device__ __forceinline__ float bflo(unsigned w) { return __uint_as_float(w << 16); }
; __device__ __forceinline__ float bfhi(unsigned w) { return __uint_as_float(w & 0xffff0000u); }
;     __device__ __forceinline__ void ld(Ld& L, size_t o) const {
; #pragma unroll
;         for (int bj = 0; bj < 2; ++bj) { if (BASEF32) { L.a[bj][0] = *(const f32x4*)((const float*)base + o + bj * HALF); L.a[bj][1] = *(const f32x4*)((const float*)base + o + bj * HALF + 4); }
;             else { const v4u w = *(const v4u*)((const bf16*)base + o + bj * HALF); L.a[bj][0] = __builtin_bit_cast(f32x4, w); } }
;     }
;     __device__ __forceinline__ void operator()(const pg8::f32x4 (&acc)[2][2][4][2], const Unit& u, int wr, int wc, int fr, int fq) const {
;         const int row0 = u.pm * BM + wr * 64 + fr, col0 = u.pn * BM + wc * 32 + 8 * fq;
;         Ld nx; ld(nx, (size_t)row0 * DM_ + col0);
; #pragma unroll
;         for (int k = 0; k < 8; ++k) { const int ai = k >> 2, m = k & 3; const int row = row0 + ai * HALF + m * 16; float q = 0.f; const Ld cu = nx;
;             if (k < 7) ld(nx, (size_t)(row0 + ((k + 1) >> 2) * HALF + ((k + 1) & 3) * 16) * DM_ + col0);
; #pragma unroll
;             for (int bj = 0; bj < 2; ++bj) { const size_t o = (size_t)row * DM_ + col0 + bj * HALF; f32x4 b0, b1;
;                 if (BASEF32) { b0 = cu.a[bj][0]; b1 = cu.a[bj][1]; }
;                 else { const v4u w = __builtin_bit_cast(v4u, cu.a[bj][0]); b0 = (f32x4){bflo(w.x), bfhi(w.x), bflo(w.y), bfhi(w.y)}; b1 = (f32x4){bflo(w.z), bfhi(w.z), bflo(w.w), bfhi(w.w)}; }
;                 const f32x4 r0 = b0 + acc[ai][bj][m][0], r1 = b1 + acc[ai][bj][m][1];
;                 q += (r0[0] * r0[0] + r0[1] * r0[1]) + (r0[2] * r0[2] + r0[3] * r0[3]) + (r1[0] * r1[0] + r1[1] * r1[1]) + (r1[2] * r1[2] + r1[3] * r1[3]);
;                 v4u w; w.x = cvt_pk_bf16(r0[0], r0[1]); w.y = cvt_pk_bf16(r0[2], r0[3]); w.z = cvt_pk_bf16(r1[0], r1[1]); w.w = cvt_pk_bf16(r1[2], r1[3]); *(v4u*)(out + o) = w; }
;             q += __shfl_xor(q, 16); q += __shfl_xor(q, 32); if (fq == 0) ssq[(size_t)row * 16 + u.pn * 4 + wc] = q; }
.LBB0_787:
	s_or_b64 exec, exec, s[28:29]
	v_or_b32_e32 v74, 16, v90
	v_ashrrev_i32_e32 v75, 31, v74
	s_waitcnt lgkmcnt(0)
	v_lshlrev_b64 v[66:67], 11, v[74:75]
	v_lshl_add_u64 v[66:67], s[16:17], 0, v[66:67]
	v_lshl_add_u64 v[76:77], v[154:155], 1, v[66:67]
	global_load_dwordx4 v[70:73], v[76:77], off
	global_load_dwordx4 v[66:69], v[76:77], off offset:256
	s_waitcnt vmcnt(5)
	v_lshlrev_b32_e32 v78, 16, v86
	v_and_b32_e32 v79, 0xffff0000, v86
	v_lshlrev_b32_e32 v80, 16, v87
	v_and_b32_e32 v81, 0xffff0000, v87
	v_lshlrev_b32_e32 v86, 16, v88
	v_and_b32_e32 v87, 0xffff0000, v88
	v_lshlrev_b32_e32 v88, 16, v89
	v_and_b32_e32 v89, 0xffff0000, v89
	v_pk_add_f32 v[64:65], v[64:65], v[80:81]
	v_pk_add_f32 v[62:63], v[62:63], v[78:79]
	v_pk_add_f32 v[78:79], v[60:61], v[88:89]
	v_pk_add_f32 v[60:61], v[58:59], v[86:87]
	v_mul_f32_e32 v58, v63, v63
	v_mul_f32_e32 v59, v65, v65
	v_fmac_f32_e32 v58, v62, v62
	v_fmac_f32_e32 v59, v64, v64
	v_add_f32_e32 v58, v58, v59
	v_mul_f32_e32 v59, v61, v61
	v_fmac_f32_e32 v59, v60, v60
	v_add_f32_e32 v58, v59, v58
	v_mul_f32_e32 v59, v79, v79
	v_fmac_f32_e32 v59, v78, v78
	v_add_f32_e32 v86, v59, v58
	v_cvt_pk_bf16_f32 v58, v62, v63
	v_cvt_pk_bf16_f32 v59, v64, v65
	s_waitcnt vmcnt(4)
	v_lshlrev_b32_e32 v62, 16, v82
	v_and_b32_e32 v63, 0xffff0000, v82
	v_lshlrev_b32_e32 v64, 16, v83
	v_and_b32_e32 v65, 0xffff0000, v83
	v_lshlrev_b32_e32 v80, 16, v84
	v_and_b32_e32 v81, 0xffff0000, v84
	v_pk_add_f32 v[56:57], v[56:57], v[64:65]
	v_pk_add_f32 v[54:55], v[54:55], v[62:63]
	v_pk_add_f32 v[64:65], v[50:51], v[80:81]
	v_mul_f32_e32 v50, v55, v55
	v_mul_f32_e32 v51, v57, v57
	v_fmac_f32_e32 v50, v54, v54
	v_fmac_f32_e32 v51, v56, v56
	v_lshlrev_b32_e32 v82, 16, v85
	v_and_b32_e32 v83, 0xffff0000, v85
	v_add_f32_e32 v50, v50, v51
	v_mul_f32_e32 v51, v65, v65
	v_pk_add_f32 v[62:63], v[52:53], v[82:83]
	v_fmac_f32_e32 v51, v64, v64
	v_add_f32_e32 v50, v51, v50
	v_mul_f32_e32 v51, v63, v63
	v_fmac_f32_e32 v51, v62, v62
	v_add_f32_e32 v50, v51, v50
	v_add_f32_e32 v50, v86, v50
	v_mov_b32_e32 v51, v50
	s_nop 1
	v_permlane16_swap_b32 v50, v51
	v_cvt_pk_bf16_f32 v60, v60, v61
	v_cvt_pk_bf16_f32 v61, v78, v79
	global_store_dwordx4 v[92:93], v[58:61], off
	v_cvt_pk_bf16_f32 v52, v54, v55
	s_waitcnt lgkmcnt(0)
	v_add_f32_e32 v50, v50, v51
	v_mov_b32_e32 v51, v50
	s_nop 1
	v_permlane32_swap_b32 v50, v51
	v_cvt_pk_bf16_f32 v53, v56, v57
	v_cvt_pk_bf16_f32 v54, v64, v65
	v_cvt_pk_bf16_f32 v55, v62, v63
	global_store_dwordx4 v[92:93], v[52:55], off offset:256
	s_and_saveexec_b64 s[28:29], s[8:9]
	s_cbranch_execz .LBB0_789
	v_lshlrev_b64 v[52:53], 6, v[90:91]
	v_lshl_add_u64 v[52:53], s[18:19], 0, v[52:53]
	v_lshl_add_u64 v[52:53], s[26:27], 2, v[52:53]
	s_lshl_b32 s4, s40, 2
	v_lshl_add_u64 v[52:53], v[52:53], 0, s[4:5]
	s_waitcnt lgkmcnt(0)
	v_add_f32_e32 v50, v50, v51
	global_store_dword v[52:53], v50, off
.LBB0_789:
	s_or_b64 exec, exec, s[28:29]
	v_or_b32_e32 v58, 32, v90
	v_ashrrev_i32_e32 v59, 31, v58
	s_waitcnt lgkmcnt(0)
	v_lshlrev_b64 v[50:51], 11, v[58:59]
	v_lshl_add_u64 v[50:51], s[16:17], 0, v[50:51]
	v_lshl_add_u64 v[60:61], v[154:155], 1, v[50:51]
	global_load_dwordx4 v[54:57], v[60:61], off
	global_load_dwordx4 v[50:53], v[60:61], off offset:256
	s_waitcnt vmcnt(5)
	v_lshlrev_b32_e32 v62, 16, v70
	v_and_b32_e32 v63, 0xffff0000, v70
	v_lshlrev_b32_e32 v64, 16, v71
	v_and_b32_e32 v65, 0xffff0000, v71
	v_lshlrev_b32_e32 v70, 16, v72
	v_and_b32_e32 v71, 0xffff0000, v72
	v_lshlrev_b32_e32 v72, 16, v73
	v_and_b32_e32 v73, 0xffff0000, v73
	v_pk_add_f32 v[48:49], v[48:49], v[64:65]
	v_pk_add_f32 v[46:47], v[46:47], v[62:63]
	v_pk_add_f32 v[62:63], v[44:45], v[72:73]
	v_pk_add_f32 v[44:45], v[42:43], v[70:71]
	v_mul_f32_e32 v42, v47, v47
	v_mul_f32_e32 v43, v49, v49
	v_fmac_f32_e32 v42, v46, v46
	v_fmac_f32_e32 v43, v48, v48
	v_add_f32_e32 v42, v42, v43
	v_mul_f32_e32 v43, v45, v45
	v_fmac_f32_e32 v43, v44, v44
	v_add_f32_e32 v42, v43, v42
	v_mul_f32_e32 v43, v63, v63
	v_fmac_f32_e32 v43, v62, v62
	v_add_f32_e32 v70, v43, v42
	v_cvt_pk_bf16_f32 v42, v46, v47
	v_cvt_pk_bf16_f32 v43, v48, v49
	s_waitcnt vmcnt(4)
	v_lshlrev_b32_e32 v46, 16, v66
	v_and_b32_e32 v47, 0xffff0000, v66
	v_lshlrev_b32_e32 v48, 16, v67
	v_and_b32_e32 v49, 0xffff0000, v67
	v_lshlrev_b32_e32 v64, 16, v68
	v_and_b32_e32 v65, 0xffff0000, v68
	v_pk_add_f32 v[40:41], v[40:41], v[48:49]
	v_pk_add_f32 v[38:39], v[38:39], v[46:47]
	v_pk_add_f32 v[48:49], v[34:35], v[64:65]
	v_mul_f32_e32 v34, v39, v39
	v_mul_f32_e32 v35, v41, v41
	v_fmac_f32_e32 v34, v38, v38
	v_fmac_f32_e32 v35, v40, v40
	v_lshlrev_b32_e32 v66, 16, v69
	v_and_b32_e32 v67, 0xffff0000, v69
	v_add_f32_e32 v34, v34, v35
	v_mul_f32_e32 v35, v49, v49
	v_pk_add_f32 v[46:47], v[36:37], v[66:67]
	v_fmac_f32_e32 v35, v48, v48
	v_add_f32_e32 v34, v35, v34
	v_mul_f32_e32 v35, v47, v47
	v_fmac_f32_e32 v35, v46, v46
	v_add_f32_e32 v34, v35, v34
	v_add_f32_e32 v34, v70, v34
	v_mov_b32_e32 v35, v34
	s_nop 1
	v_permlane16_swap_b32 v34, v35
	v_cvt_pk_bf16_f32 v44, v44, v45
	v_cvt_pk_bf16_f32 v45, v62, v63
	global_store_dwordx4 v[76:77], v[42:45], off
	v_cvt_pk_bf16_f32 v36, v38, v39
	s_waitcnt lgkmcnt(0)
	v_add_f32_e32 v34, v34, v35
	v_mov_b32_e32 v35, v34
	s_nop 1
	v_permlane32_swap_b32 v34, v35
	v_cvt_pk_bf16_f32 v37, v40, v41
	v_cvt_pk_bf16_f32 v38, v48, v49
	v_cvt_pk_bf16_f32 v39, v46, v47
	global_store_dwordx4 v[76:77], v[36:39], off offset:256
	s_and_saveexec_b64 s[28:29], s[8:9]
	s_cbranch_execz .LBB0_791
	v_lshlrev_b64 v[36:37], 6, v[74:75]
	v_lshl_add_u64 v[36:37], s[18:19], 0, v[36:37]
	v_lshl_add_u64 v[36:37], s[26:27], 2, v[36:37]
	s_lshl_b32 s4, s40, 2
	v_lshl_add_u64 v[36:37], v[36:37], 0, s[4:5]
	s_waitcnt lgkmcnt(0)
	v_add_f32_e32 v34, v34, v35
	global_store_dword v[36:37], v34, off
; __device__ __forceinline__ unsigned cvt_pk_bf16(float lo, float hi) { unsigned r; asm volatile("v_cvt_pk_bf16_f32 %0, %1, %2" : "=v"(r) : "v"(lo), "v"(hi)); return r; }
; __device__ __forceinline__ float bflo(unsigned w) { return __uint_as_float(w << 16); }
; __device__ __forceinline__ float bfhi(unsigned w) { return __uint_as_float(w & 0xffff0000u); }
;     __device__ __forceinline__ void ld(Ld& L, size_t o) const {
; #pragma unroll
;         for (int bj = 0; bj < 2; ++bj) { if (BASEF32) { L.a[bj][0] = *(const f32x4*)((const float*)base + o + bj * HALF); L.a[bj][1] = *(const f32x4*)((const float*)base + o + bj * HALF + 4); }
;             else { const v4u w = *(const v4u*)((const bf16*)base + o + bj * HALF); L.a[bj][0] = __builtin_bit_cast(f32x4, w); } }
;     }
;     __device__ __forceinline__ void operator()(const pg8::f32x4 (&acc)[2][2][4][2], const Unit& u, int wr, int wc, int fr, int fq) const {
;         const int row0 = u.pm * BM + wr * 64 + fr, col0 = u.pn * BM + wc * 32 + 8 * fq;
;         Ld nx; ld(nx, (size_t)row0 * DM_ + col0);
; #pragma unroll
;         for (int k = 0; k < 8; ++k) { const int ai = k >> 2, m = k & 3; const int row = row0 + ai * HALF + m * 16; float q = 0.f; const Ld cu = nx;
;             if (k < 7) ld(nx, (size_t)(row0 + ((k + 1) >> 2) * HALF + ((k + 1) & 3) * 16) * DM_ + col0);
; #pragma unroll
;             for (int bj = 0; bj < 2; ++bj) { const size_t o = (size_t)row * DM_ + col0 + bj * HALF; f32x4 b0, b1;
;                 if (BASEF32) { b0 = cu.a[bj][0]; b1 = cu.a[bj][1]; }
;                 else { const v4u w = __builtin_bit_cast(v4u, cu.a[bj][0]); b0 = (f32x4){bflo(w.x), bfhi(w.x), bflo(w.y), bfhi(w.y)}; b1 = (f32x4){bflo(w.z), bfhi(w.z), bflo(w.w), bfhi(w.w)}; }
;                 const f32x4 r0 = b0 + acc[ai][bj][m][0], r1 = b1 + acc[ai][bj][m][1];
;                 q += (r0[0] * r0[0] + r0[1] * r0[1]) + (r0[2] * r0[2] + r0[3] * r0[3]) + (r1[0] * r1[0] + r1[1] * r1[1]) + (r1[2] * r1[2] + r1[3] * r1[3]);
;                 v4u w; w.x = cvt_pk_bf16(r0[0], r0[1]); w.y = cvt_pk_bf16(r0[2], r0[3]); w.z = cvt_pk_bf16(r1[0], r1[1]); w.w = cvt_pk_bf16(r1[2], r1[3]); *(v4u*)(out + o) = w; }
;             q += __shfl_xor(q, 16); q += __shfl_xor(q, 32); if (fq == 0) ssq[(size_t)row * 16 + u.pn * 4 + wc] = q; }
.LBB0_791:
	s_or_b64 exec, exec, s[28:29]
	v_or_b32_e32 v42, 48, v90
	v_ashrrev_i32_e32 v43, 31, v42
	s_waitcnt lgkmcnt(0)
	v_lshlrev_b64 v[34:35], 11, v[42:43]
	v_lshl_add_u64 v[34:35], s[16:17], 0, v[34:35]
	v_lshl_add_u64 v[44:45], v[154:155], 1, v[34:35]
	global_load_dwordx4 v[38:41], v[44:45], off
	global_load_dwordx4 v[34:37], v[44:45], off offset:256
	s_waitcnt vmcnt(5)
	v_lshlrev_b32_e32 v46, 16, v54
	v_and_b32_e32 v47, 0xffff0000, v54
	v_lshlrev_b32_e32 v48, 16, v55
	v_and_b32_e32 v49, 0xffff0000, v55
	v_lshlrev_b32_e32 v54, 16, v56
	v_and_b32_e32 v55, 0xffff0000, v56
	v_lshlrev_b32_e32 v56, 16, v57
	v_and_b32_e32 v57, 0xffff0000, v57
	v_pk_add_f32 v[32:33], v[32:33], v[48:49]
	v_pk_add_f32 v[30:31], v[30:31], v[46:47]
	v_pk_add_f32 v[46:47], v[28:29], v[56:57]
	v_pk_add_f32 v[28:29], v[26:27], v[54:55]
	v_mul_f32_e32 v26, v31, v31
	v_mul_f32_e32 v27, v33, v33
	v_fmac_f32_e32 v26, v30, v30
	v_fmac_f32_e32 v27, v32, v32
	v_add_f32_e32 v26, v26, v27
	v_mul_f32_e32 v27, v29, v29
	v_fmac_f32_e32 v27, v28, v28
	v_add_f32_e32 v26, v27, v26
	v_mul_f32_e32 v27, v47, v47
	v_fmac_f32_e32 v27, v46, v46
	v_add_f32_e32 v54, v27, v26
	v_cvt_pk_bf16_f32 v26, v30, v31
	v_cvt_pk_bf16_f32 v27, v32, v33
	s_waitcnt vmcnt(4)
	v_lshlrev_b32_e32 v30, 16, v50
	v_and_b32_e32 v31, 0xffff0000, v50
	v_lshlrev_b32_e32 v32, 16, v51
	v_and_b32_e32 v33, 0xffff0000, v51
	v_lshlrev_b32_e32 v48, 16, v52
	v_and_b32_e32 v49, 0xffff0000, v52
	v_pk_add_f32 v[24:25], v[24:25], v[32:33]
	v_pk_add_f32 v[22:23], v[22:23], v[30:31]
	v_pk_add_f32 v[32:33], v[18:19], v[48:49]
	v_mul_f32_e32 v18, v23, v23
	v_mul_f32_e32 v19, v25, v25
	v_fmac_f32_e32 v18, v22, v22
	v_fmac_f32_e32 v19, v24, v24
	v_lshlrev_b32_e32 v50, 16, v53
	v_and_b32_e32 v51, 0xffff0000, v53
	v_add_f32_e32 v18, v18, v19
	v_mul_f32_e32 v19, v33, v33
	v_pk_add_f32 v[30:31], v[20:21], v[50:51]
	v_fmac_f32_e32 v19, v32, v32
	v_add_f32_e32 v18, v19, v18
	v_mul_f32_e32 v19, v31, v31
	v_fmac_f32_e32 v19, v30, v30
	v_add_f32_e32 v18, v19, v18
	v_add_f32_e32 v18, v54, v18
	v_mov_b32_e32 v19, v18
	s_nop 1
	v_permlane16_swap_b32 v18, v19
	v_cvt_pk_bf16_f32 v28, v28, v29
	v_cvt_pk_bf16_f32 v29, v46, v47
	global_store_dwordx4 v[60:61], v[26:29], off
	v_cvt_pk_bf16_f32 v20, v22, v23
	s_waitcnt lgkmcnt(0)
	v_add_f32_e32 v18, v18, v19
	v_mov_b32_e32 v19, v18
	s_nop 1
	v_permlane32_swap_b32 v18, v19
	v_cvt_pk_bf16_f32 v21, v24, v25
	v_cvt_pk_bf16_f32 v22, v32, v33
	v_cvt_pk_bf16_f32 v23, v30, v31
	global_store_dwordx4 v[60:61], v[20:23], off offset:256
	s_and_saveexec_b64 s[28:29], s[8:9]
	s_cbranch_execz .LBB0_793
	v_lshlrev_b64 v[20:21], 6, v[58:59]
	v_lshl_add_u64 v[20:21], s[18:19], 0, v[20:21]
	v_lshl_add_u64 v[20:21], s[26:27], 2, v[20:21]
	s_lshl_b32 s4, s40, 2
	v_lshl_add_u64 v[20:21], v[20:21], 0, s[4:5]
	s_waitcnt lgkmcnt(0)
	v_add_f32_e32 v18, v18, v19
	global_store_dword v[20:21], v18, off
.LBB0_793:
	s_or_b64 exec, exec, s[28:29]
	s_waitcnt vmcnt(3)
	v_lshlrev_b32_e32 v18, 16, v38
	s_waitcnt lgkmcnt(0)
	v_and_b32_e32 v19, 0xffff0000, v38
	v_lshlrev_b32_e32 v20, 16, v39
	v_and_b32_e32 v21, 0xffff0000, v39
	v_lshlrev_b32_e32 v22, 16, v40
	v_and_b32_e32 v23, 0xffff0000, v40
	v_lshlrev_b32_e32 v24, 16, v41
	v_and_b32_e32 v25, 0xffff0000, v41
	v_pk_add_f32 v[16:17], v[16:17], v[20:21]
	v_pk_add_f32 v[14:15], v[14:15], v[18:19]
	v_pk_add_f32 v[18:19], v[12:13], v[24:25]
	v_pk_add_f32 v[12:13], v[10:11], v[22:23]
	v_mul_f32_e32 v10, v15, v15
	v_mul_f32_e32 v11, v17, v17
	v_fmac_f32_e32 v10, v14, v14
	v_fmac_f32_e32 v11, v16, v16
	v_add_f32_e32 v10, v10, v11
	v_mul_f32_e32 v11, v13, v13
	v_fmac_f32_e32 v11, v12, v12
	v_add_f32_e32 v10, v11, v10
	v_mul_f32_e32 v11, v19, v19
	v_fmac_f32_e32 v11, v18, v18
	v_add_f32_e32 v24, v11, v10
	v_cvt_pk_bf16_f32 v10, v14, v15
	v_cvt_pk_bf16_f32 v11, v16, v17
	s_waitcnt vmcnt(2)
	v_lshlrev_b32_e32 v14, 16, v34
	v_and_b32_e32 v15, 0xffff0000, v34
	v_lshlrev_b32_e32 v16, 16, v35
	v_and_b32_e32 v17, 0xffff0000, v35
	v_lshlrev_b32_e32 v20, 16, v36
	v_and_b32_e32 v21, 0xffff0000, v36
	v_pk_add_f32 v[8:9], v[8:9], v[16:17]
	v_pk_add_f32 v[6:7], v[6:7], v[14:15]
	v_pk_add_f32 v[16:17], v[2:3], v[20:21]
	v_mul_f32_e32 v2, v7, v7
	v_mul_f32_e32 v3, v9, v9
	v_fmac_f32_e32 v2, v6, v6
	v_fmac_f32_e32 v3, v8, v8
	v_lshlrev_b32_e32 v22, 16, v37
	v_and_b32_e32 v23, 0xffff0000, v37
	v_add_f32_e32 v2, v2, v3
	v_mul_f32_e32 v3, v17, v17
	v_pk_add_f32 v[14:15], v[4:5], v[22:23]
	v_fmac_f32_e32 v3, v16, v16
	v_add_f32_e32 v2, v3, v2
	v_mul_f32_e32 v3, v15, v15
	v_fmac_f32_e32 v3, v14, v14
	v_add_f32_e32 v2, v3, v2
	v_add_f32_e32 v2, v24, v2
	v_mov_b32_e32 v3, v2
	s_nop 1
	v_permlane16_swap_b32 v2, v3
	v_cvt_pk_bf16_f32 v12, v12, v13
	v_cvt_pk_bf16_f32 v13, v18, v19
	global_store_dwordx4 v[44:45], v[10:13], off
	v_cvt_pk_bf16_f32 v4, v6, v7
	s_waitcnt lgkmcnt(0)
	v_add_f32_e32 v2, v2, v3
	v_mov_b32_e32 v3, v2
	s_nop 1
	v_permlane32_swap_b32 v2, v3
	v_cvt_pk_bf16_f32 v5, v8, v9
	v_cvt_pk_bf16_f32 v6, v16, v17
	v_cvt_pk_bf16_f32 v7, v14, v15
	global_store_dwordx4 v[44:45], v[4:7], off offset:256
	s_and_saveexec_b64 s[28:29], s[8:9]
	s_cbranch_execz .LBB0_795
	v_lshlrev_b64 v[4:5], 6, v[42:43]
	v_lshl_add_u64 v[4:5], s[18:19], 0, v[4:5]
	v_lshl_add_u64 v[4:5], s[26:27], 2, v[4:5]
	s_lshl_b32 s4, s40, 2
	v_lshl_add_u64 v[4:5], v[4:5], 0, s[4:5]
	s_waitcnt lgkmcnt(0)
	v_add_f32_e32 v2, v2, v3
	global_store_dword v[4:5], v2, off

; __device__ __forceinline__ void rstd8(const float* ss, int row0, int fq, float (&rs)[8]) {
;     f32x4 a[8];
; #pragma unroll
;     for (int k = 0; k < 8; ++k) a[k] = *(const f32x4*)(ss + (size_t)(row0 + (k >> 2) * 128 + (k & 3) * 16) * 16 + 4 * fq);
; #pragma unroll
;     for (int k = 0; k < 8; ++k) { float s = (a[k][0] + a[k][1]) + (a[k][2] + a[k][3]); s += __shfl_xor(s, 16); s += __shfl_xor(s, 32); rs[k] = __builtin_amdgcn_rsqf(s * (1.f / 1024.f) + EPS); }
;     __device__ __forceinline__ void operator()(const pg8::f32x4 (&acc)[2][2][4][2], const Unit& u, int wr, int wc, int fr, int fq) const {
;         const int row0 = u.pm * BM + wr * 64 + fr, col0 = u.pn * BM + wc * 32 + 8 * fq;
;         float rsv[8]; rstd8(ss, row0, fq, rsv);
;         v4u nb[2], np[2];
; #pragma unroll
;         for (int bj = 0; bj < 2; ++bj) { const size_t o = (size_t)row0 * DM_ + col0 + bj * HALF; nb[bj] = *(const v4u*)(base + o); np[bj] = *(const v4u*)(pp + o); }
.LBB0_906:
	v_lshl_add_u32 v226, s12, 8, v1
	v_or_b32_e32 v180, 16, v226
	v_ashrrev_i32_e32 v227, 31, v226
	v_ashrrev_i32_e32 v181, 31, v180
	v_or_b32_e32 v176, 32, v226
	v_or_b32_e32 v172, 48, v226
	v_add_u32_e32 v166, 0x80, v226
	v_lshlrev_b64 v[182:183], 6, v[226:227]
	v_lshlrev_b64 v[178:179], 6, v[180:181]
	v_ashrrev_i32_e32 v177, 31, v176
	v_ashrrev_i32_e32 v173, 31, v172
	v_ashrrev_i32_e32 v167, 31, v166
	v_lshl_add_u64 v[164:165], v[154:155], 0, v[182:183]
	v_lshl_add_u64 v[134:135], v[154:155], 0, v[178:179]
	v_lshlrev_b64 v[174:175], 6, v[176:177]
	v_lshlrev_b64 v[170:171], 6, v[172:173]
	v_lshlrev_b64 v[168:169], 6, v[166:167]
	global_load_dwordx4 v[130:133], v[164:165], off
	s_nop 0
	global_load_dwordx4 v[134:137], v[134:135], off
	v_lshl_add_u64 v[138:139], v[154:155], 0, v[174:175]
	v_lshl_add_u64 v[142:143], v[154:155], 0, v[170:171]
	v_lshl_add_u64 v[192:193], v[154:155], 0, v[168:169]
	global_load_dwordx4 v[138:141], v[138:139], off
	s_nop 0
	global_load_dwordx4 v[142:145], v[142:143], off
	v_add_co_u32_e32 v164, vcc, s48, v164
	global_load_dwordx4 v[194:197], v[192:193], off
	s_nop 0
	v_addc_co_u32_e32 v165, vcc, 0, v165, vcc
	global_load_dwordx4 v[198:201], v[164:165], off offset:1024
	global_load_dwordx4 v[202:205], v[164:165], off offset:2048
	global_load_dwordx4 v[206:209], v[164:165], off offset:3072
	v_and_b32_e32 v165, 64, v189
	v_xor_b32_e32 v191, 16, v189
	v_add_u32_e32 v193, 64, v165
	v_xor_b32_e32 v192, 32, v189
	v_cmp_lt_i32_e32 vcc, v191, v193
	v_lshl_or_b32 v164, s4, 8, v185
	v_ashrrev_i32_e32 v165, 31, v164
	v_cndmask_b32_e32 v191, v189, v191, vcc
	v_cmp_lt_i32_e32 vcc, v192, v193
	v_lshlrev_b64 v[210:211], 10, v[226:227]
	v_lshl_add_u64 v[210:211], v[210:211], 0, v[164:165]
	v_cndmask_b32_e32 v193, v189, v192, vcc
	v_lshlrev_b32_e32 v192, 2, v191
	v_lshlrev_b32_e32 v191, 2, v193
	v_lshlrev_b64 v[222:223], 1, v[210:211]
	v_lshl_add_u64 v[210:211], s[10:11], 0, v[222:223]
	v_lshl_add_u64 v[214:215], s[16:17], 0, v[222:223]
	global_load_dwordx4 v[210:213], v[210:211], off
	s_nop 0
	global_load_dwordx4 v[214:217], v[214:215], off
	v_or_b32_e32 v222, 0x100, v222
	v_lshlrev_b64 v[226:227], 11, v[226:227]
	s_lshl_b32 s4, s4, 2
	s_ashr_i32 s5, s4, 31
	s_waitcnt vmcnt(0)
	v_mov_b32_e32 v218, v131
	v_mov_b32_e32 v219, v132
	v_mov_b32_e32 v131, v133
	v_pk_add_f32 v[130:131], v[218:219], v[130:131]
	v_add_f32_e32 v132, v134, v135
	v_add_f32_e32 v133, v136, v137
	v_add_f32_e32 v134, v138, v139
	v_add_f32_e32 v135, v140, v141
	v_add_f32_e32 v138, v194, v195
	v_add_f32_e32 v139, v196, v197
	v_add_f32_e32 v130, v130, v131
	v_add_f32_e32 v131, v132, v133
	v_add_f32_e32 v132, v134, v135
	v_add_f32_e32 v134, v138, v139
	v_mov_b32_e32 v138, v130
	s_nop 1
	v_permlane16_swap_b32 v130, v138
	v_mov_b32_e32 v139, v131
	s_nop 1
	v_permlane16_swap_b32 v131, v139
	v_add_f32_e32 v136, v142, v143
	v_add_f32_e32 v137, v144, v145
	v_add_f32_e32 v142, v202, v203
	s_waitcnt lgkmcnt(1)
	v_add_f32_e32 v130, v130, v138
	v_add_f32_e32 v143, v204, v205
	s_waitcnt lgkmcnt(0)
	v_add_f32_e32 v205, v131, v139
	v_mov_b32_e32 v131, v130
	s_nop 1
	v_permlane32_swap_b32 v130, v131
	v_add_f32_e32 v144, v206, v207
	v_add_f32_e32 v145, v208, v209
	v_add_f32_e32 v133, v136, v137
	v_add_f32_e32 v136, v142, v143
	v_add_f32_e32 v137, v144, v145
	v_mov_b32_e32 v144, v136
	s_nop 1
	v_permlane16_swap_b32 v136, v144
	s_waitcnt lgkmcnt(1)
	v_add_f32_e32 v130, v130, v131
	v_fmamk_f32 v130, v130, 0x3a800000, v190
	v_add_f32_e32 v140, v198, v199
	v_add_f32_e32 v141, v200, v201
	s_waitcnt lgkmcnt(0)
	v_add_f32_e32 v195, v136, v144
	v_rsq_f32_e32 v136, v130
	v_lshl_add_u64 v[130:131], s[10:11], 0, v[222:223]
	global_load_dwordx4 v[218:221], v[130:131], off
	v_lshl_add_u64 v[130:131], s[16:17], 0, v[222:223]
	global_load_dwordx4 v[222:225], v[130:131], off
	v_add_f32_e32 v135, v140, v141
	v_mov_b32_e32 v140, v132
	s_nop 1
	v_permlane16_swap_b32 v132, v140
	v_mov_b32_e32 v141, v133
	s_nop 1
	v_permlane16_swap_b32 v133, v141
	v_mov_b32_e32 v142, v134
	s_nop 1
	v_permlane16_swap_b32 v134, v142
	v_mov_b32_e32 v143, v135
	s_nop 1
	v_permlane16_swap_b32 v135, v143
	v_mov_b32_e32 v145, v137
	s_nop 1
	v_permlane16_swap_b32 v137, v145
	v_lshlrev_b64 v[130:131], 10, v[180:181]
	v_lshl_add_u64 v[130:131], v[130:131], 0, v[164:165]
	v_lshlrev_b64 v[130:131], 1, v[130:131]
	s_waitcnt lgkmcnt(4)
	v_add_f32_e32 v203, v132, v140
	s_waitcnt lgkmcnt(3)
	v_add_f32_e32 v201, v133, v141
	s_waitcnt lgkmcnt(2)
	v_add_f32_e32 v199, v134, v142
	s_waitcnt lgkmcnt(1)
	v_add_f32_e32 v197, v135, v143
	v_lshl_add_u64 v[132:133], s[10:11], 0, v[130:131]
	v_lshl_add_u64 v[134:135], s[16:17], 0, v[130:131]
	v_or_b32_e32 v130, 0x100, v130
	s_waitcnt lgkmcnt(0)
; __device__ __forceinline__ unsigned cvt_pk_bf16(float lo, float hi) { unsigned r; asm volatile("v_cvt_pk_bf16_f32 %0, %1, %2" : "=v"(r) : "v"(lo), "v"(hi)); return r; }
; #define PLE2(kk, A, e0, BW, PW) { const f32x2 t = (f32x2){A[e0], A[e0 + 1]} * c1; f32x2 d; d.x = __builtin_amdgcn_exp2f(t.x); d.y = __builtin_amdgcn_exp2f(t.y); d = d + 1.0f; \
;                     f32x2 q2; q2.x = __builtin_amdgcn_rcpf(d.x); q2.y = __builtin_amdgcn_rcpf(d.y); const f32x2 o2 = (f32x2){bflo(BW), bfhi(BW)} + (f32x2){bflo(PW), bfhi(PW)} * q2; r[kk] = o2.x; r[kk + 1] = o2.y; }
; __device__ __forceinline__ void rstd8(const float* ss, int row0, int fq, float (&rs)[8]) {
;     f32x4 a[8];
; #pragma unroll
;     for (int k = 0; k < 8; ++k) a[k] = *(const f32x4*)(ss + (size_t)(row0 + (k >> 2) * 128 + (k & 3) * 16) * 16 + 4 * fq);
; #pragma unroll
;     for (int k = 0; k < 8; ++k) { float s = (a[k][0] + a[k][1]) + (a[k][2] + a[k][3]); s += __shfl_xor(s, 16); s += __shfl_xor(s, 32); rs[k] = __builtin_amdgcn_rsqf(s * (1.f / 1024.f) + EPS); }
;     __device__ __forceinline__ void operator()(const pg8::f32x4 (&acc)[2][2][4][2], const Unit& u, int wr, int wc, int fr, int fq) const {
;     ...
;             for (int bj = 0; bj < 2; ++bj) { const size_t o = (size_t)row * DM_ + col0 + bj * HALF; const v4u bw = cb[bj], pw = cp[bj];
;                 const float c1 = -1.4426950408889634f * rs; float r[8];
;     ...
;                 { const f32x4 a0 = acc[ai][bj][m][0], a1 = acc[ai][bj][m][1];
;                   PLE2(0, a0, 0, bw.x, pw.x) PLE2(2, a0, 2, bw.y, pw.y) PLE2(4, a1, 0, bw.z, pw.z) PLE2(6, a1, 2, bw.w, pw.w) }
;     ...
; #pragma unroll
;                 for (int e = 0; e < 8; ++e) q += r[e] * r[e];
;                 v4u w; w.x = cvt_pk_bf16(r[0], r[1]); w.y = cvt_pk_bf16(r[2], r[3]); w.z = cvt_pk_bf16(r[4], r[5]); w.w = cvt_pk_bf16(r[6], r[7]); *(v4u*)(out + o) = w; }
;             q += __shfl_xor(q, 16); q += __shfl_xor(q, 32); if (fq == 0) ssq[(size_t)row * 16 + u.pn * 4 + wc] = q; }
	v_add_f32_e32 v193, v137, v145
	global_load_dwordx4 v[142:145], v[132:133], off
	global_load_dwordx4 v[138:141], v[134:135], off
	v_lshl_add_u64 v[132:133], s[10:11], 0, v[130:131]
	v_lshl_add_u64 v[130:131], s[16:17], 0, v[130:131]
	v_mul_f32_e32 v208, 0xbfb8aa3b, v136
	global_load_dwordx4 v[134:137], v[132:133], off
	s_nop 0
	global_load_dwordx4 v[130:133], v[130:131], off
	v_pk_mul_f32 v[128:129], v[128:129], v[208:209] op_sel_hi:[1,0]
	v_pk_mul_f32 v[122:123], v[122:123], v[208:209] op_sel_hi:[1,0]
	v_exp_f32_e32 v128, v128
	v_exp_f32_e32 v129, v129
	v_exp_f32_e32 v122, v122
	v_exp_f32_e32 v123, v123
	v_pk_mul_f32 v[126:127], v[126:127], v[208:209] op_sel_hi:[1,0]
	v_pk_add_f32 v[128:129], v[128:129], 1.0 op_sel_hi:[1,0]
	v_exp_f32_e32 v126, v126
	v_exp_f32_e32 v127, v127
	v_rcp_f32_e32 v128, v128
	v_rcp_f32_e32 v129, v129
	v_pk_add_f32 v[122:123], v[122:123], 1.0 op_sel_hi:[1,0]
	v_pk_mul_f32 v[124:125], v[124:125], v[208:209] op_sel_hi:[1,0]
	v_rcp_f32_e32 v122, v122
	v_rcp_f32_e32 v123, v123
	v_exp_f32_e32 v124, v124
	v_exp_f32_e32 v125, v125
	v_pk_mul_f32 v[118:119], v[118:119], v[208:209] op_sel_hi:[1,0]
	v_pk_mul_f32 v[120:121], v[120:121], v[208:209] op_sel_hi:[1,0]
	v_exp_f32_e32 v118, v118
	v_exp_f32_e32 v119, v119
	v_lshlrev_b32_e32 v228, 16, v210
	v_and_b32_e32 v229, 0xffff0000, v210
	v_lshlrev_b32_e32 v230, 16, v214
	v_and_b32_e32 v231, 0xffff0000, v214
	v_lshlrev_b32_e32 v210, 16, v211
	v_and_b32_e32 v211, 0xffff0000, v211
	v_lshlrev_b32_e32 v214, 16, v215
	v_and_b32_e32 v215, 0xffff0000, v215
	v_exp_f32_e32 v120, v120
	v_exp_f32_e32 v121, v121
	v_pk_mul_f32 v[114:115], v[114:115], v[208:209] op_sel_hi:[1,0]
	v_pk_add_f32 v[126:127], v[126:127], 1.0 op_sel_hi:[1,0]
	v_pk_fma_f32 v[128:129], v[128:129], v[214:215], v[210:211]
	v_lshlrev_b32_e32 v210, 16, v212
	v_and_b32_e32 v211, 0xffff0000, v212
	v_lshlrev_b32_e32 v214, 16, v216
	v_and_b32_e32 v215, 0xffff0000, v216
	v_exp_f32_e32 v114, v114
	v_exp_f32_e32 v115, v115
	v_rcp_f32_e32 v126, v126
	v_rcp_f32_e32 v127, v127
	v_pk_fma_f32 v[210:211], v[122:123], v[214:215], v[210:211]
	v_pk_add_f32 v[122:123], v[124:125], 1.0 op_sel_hi:[1,0]
	v_pk_add_f32 v[118:119], v[118:119], 1.0 op_sel_hi:[1,0]
	v_rcp_f32_e32 v122, v122
	v_rcp_f32_e32 v123, v123
	v_rcp_f32_e32 v118, v118
	v_rcp_f32_e32 v119, v119
	v_pk_add_f32 v[120:121], v[120:121], 1.0 op_sel_hi:[1,0]
	v_pk_add_f32 v[114:115], v[114:115], 1.0 op_sel_hi:[1,0]
	v_rcp_f32_e32 v120, v120
	v_rcp_f32_e32 v121, v121
	v_pk_mul_f32 v[116:117], v[116:117], v[208:209] op_sel_hi:[1,0]
	v_pk_fma_f32 v[126:127], v[126:127], v[230:231], v[228:229]
	v_lshlrev_b32_e32 v124, 16, v213
	v_and_b32_e32 v125, 0xffff0000, v213
	v_lshlrev_b32_e32 v212, 16, v217
	v_and_b32_e32 v213, 0xffff0000, v217
	v_rcp_f32_e32 v114, v114
	v_rcp_f32_e32 v115, v115
	v_exp_f32_e32 v116, v116
	v_exp_f32_e32 v117, v117
	v_pk_fma_f32 v[212:213], v[122:123], v[212:213], v[124:125]
	v_pk_mul_f32 v[214:215], v[126:127], v[126:127]
	v_pk_mul_f32 v[216:217], v[128:129], v[128:129]
	v_cvt_pk_bf16_f32 v122, v126, v127
	v_cvt_pk_bf16_f32 v123, v128, v129
	s_waitcnt vmcnt(5)
	v_lshlrev_b32_e32 v126, 16, v218
	v_and_b32_e32 v127, 0xffff0000, v218
	s_waitcnt vmcnt(4)
	v_lshlrev_b32_e32 v128, 16, v222
	v_and_b32_e32 v129, 0xffff0000, v222
	v_pk_fma_f32 v[118:119], v[118:119], v[128:129], v[126:127]
	v_lshlrev_b32_e32 v126, 16, v219
	v_and_b32_e32 v127, 0xffff0000, v219
	v_lshlrev_b32_e32 v128, 16, v223
	v_and_b32_e32 v129, 0xffff0000, v223
	v_pk_fma_f32 v[120:121], v[120:121], v[128:129], v[126:127]
	v_lshlrev_b32_e32 v126, 16, v220
	v_and_b32_e32 v127, 0xffff0000, v220
	v_lshlrev_b32_e32 v128, 16, v224
	v_and_b32_e32 v129, 0xffff0000, v224
	v_add_f32_e32 v207, v214, v215
	v_pk_fma_f32 v[126:127], v[114:115], v[128:129], v[126:127]
	v_pk_add_f32 v[114:115], v[116:117], 1.0 op_sel_hi:[1,0]
	v_add_f32_e32 v207, v216, v207
	v_pk_mul_f32 v[228:229], v[210:211], v[210:211]
	v_rcp_f32_e32 v114, v114
	v_rcp_f32_e32 v115, v115
	v_add_f32_e32 v207, v217, v207
	v_add_f32_e32 v207, v228, v207
	v_pk_mul_f32 v[230:231], v[212:213], v[212:213]
	v_add_f32_e32 v207, v229, v207
	v_lshlrev_b32_e32 v116, 16, v221
	v_and_b32_e32 v117, 0xffff0000, v221
	v_lshlrev_b32_e32 v128, 16, v225
	v_and_b32_e32 v129, 0xffff0000, v225
	v_add_f32_e32 v207, v230, v207
	v_pk_fma_f32 v[128:129], v[114:115], v[128:129], v[116:117]
	v_pk_mul_f32 v[114:115], v[118:119], v[118:119]
	v_add_f32_e32 v207, v231, v207
	v_add_f32_e32 v114, v114, v207
	v_pk_mul_f32 v[116:117], v[120:121], v[120:121]
	v_add_f32_e32 v114, v115, v114
	v_add_f32_e32 v114, v116, v114
	v_pk_mul_f32 v[208:209], v[126:127], v[126:127]
	v_add_f32_e32 v114, v117, v114
	v_add_f32_e32 v114, v208, v114
	v_cvt_pk_bf16_f32 v124, v210, v211
	v_pk_mul_f32 v[210:211], v[128:129], v[128:129]
	v_add_f32_e32 v114, v209, v114
	v_add_f32_e32 v114, v210, v114
	v_add_f32_e32 v117, v211, v114
	v_mov_b32_e32 v207, v117
	s_nop 1
	v_permlane16_swap_b32 v117, v207
	v_lshl_add_u64 v[114:115], s[18:19], 0, v[226:227]
	v_lshl_add_u64 v[208:209], v[164:165], 1, v[114:115]
	v_mov_b32_e32 v206, v205
	s_nop 1
	v_permlane32_swap_b32 v205, v206
	v_mov_b32_e32 v204, v203
	s_nop 1
	v_permlane32_swap_b32 v203, v204
	s_waitcnt lgkmcnt(2)
	v_add_f32_e32 v114, v117, v207
	v_mov_b32_e32 v202, v201
	s_nop 1
	v_permlane32_swap_b32 v201, v202
	v_mov_b32_e32 v200, v199
	s_nop 1
	v_permlane32_swap_b32 v199, v200
	v_mov_b32_e32 v198, v197
	s_nop 1
	v_permlane32_swap_b32 v197, v198
	v_mov_b32_e32 v196, v195
	s_nop 1
	v_permlane32_swap_b32 v195, v196
	v_mov_b32_e32 v194, v193
	s_nop 1
	v_permlane32_swap_b32 v193, v194
	v_mov_b32_e32 v115, v114
	s_nop 1
	v_permlane32_swap_b32 v114, v115
	v_cvt_pk_bf16_f32 v125, v212, v213
	global_store_dwordx4 v[208:209], v[122:125], off
	v_cvt_pk_bf16_f32 v116, v118, v119
	v_cvt_pk_bf16_f32 v117, v120, v121
	v_cvt_pk_bf16_f32 v118, v126, v127
	v_cvt_pk_bf16_f32 v119, v128, v129
	global_store_dwordx4 v[208:209], v[116:119], off offset:256
	s_and_saveexec_b64 s[36:37], s[6:7]
	s_cbranch_execz .LBB0_908
	v_lshl_add_u64 v[116:117], s[20:21], 0, v[182:183]
	v_lshl_add_u64 v[116:117], s[4:5], 2, v[116:117]
	s_lshl_b32 s12, s49, 2
	v_lshl_add_u64 v[116:117], v[116:117], 0, s[12:13]
	s_waitcnt lgkmcnt(0)
	v_add_f32_e32 v114, v114, v115
	global_store_dword v[116:117], v114, off
; __device__ __forceinline__ unsigned cvt_pk_bf16(float lo, float hi) { unsigned r; asm volatile("v_cvt_pk_bf16_f32 %0, %1, %2" : "=v"(r) : "v"(lo), "v"(hi)); return r; }
; #define PLE2(kk, A, e0, BW, PW) { const f32x2 t = (f32x2){A[e0], A[e0 + 1]} * c1; f32x2 d; d.x = __builtin_amdgcn_exp2f(t.x); d.y = __builtin_amdgcn_exp2f(t.y); d = d + 1.0f; \
;                     f32x2 q2; q2.x = __builtin_amdgcn_rcpf(d.x); q2.y = __builtin_amdgcn_rcpf(d.y); const f32x2 o2 = (f32x2){bflo(BW), bfhi(BW)} + (f32x2){bflo(PW), bfhi(PW)} * q2; r[kk] = o2.x; r[kk + 1] = o2.y; }
; __device__ __forceinline__ void rstd8(const float* ss, int row0, int fq, float (&rs)[8]) {
;     f32x4 a[8];
; #pragma unroll
;     for (int k = 0; k < 8; ++k) a[k] = *(const f32x4*)(ss + (size_t)(row0 + (k >> 2) * 128 + (k & 3) * 16) * 16 + 4 * fq);
; #pragma unroll
;     for (int k = 0; k < 8; ++k) { float s = (a[k][0] + a[k][1]) + (a[k][2] + a[k][3]); s += __shfl_xor(s, 16); s += __shfl_xor(s, 32); rs[k] = __builtin_amdgcn_rsqf(s * (1.f / 1024.f) + EPS); }
;     __device__ __forceinline__ void operator()(const pg8::f32x4 (&acc)[2][2][4][2], const Unit& u, int wr, int wc, int fr, int fq) const {
;     ...
;             for (int bj = 0; bj < 2; ++bj) { const size_t o = (size_t)row * DM_ + col0 + bj * HALF; const v4u bw = cb[bj], pw = cp[bj];
;                 const float c1 = -1.4426950408889634f * rs; float r[8];
;     ...
;                 { const f32x4 a0 = acc[ai][bj][m][0], a1 = acc[ai][bj][m][1];
;                   PLE2(0, a0, 0, bw.x, pw.x) PLE2(2, a0, 2, bw.y, pw.y) PLE2(4, a1, 0, bw.z, pw.z) PLE2(6, a1, 2, bw.w, pw.w) }
;     ...
; #pragma unroll
;                 for (int e = 0; e < 8; ++e) q += r[e] * r[e];
;                 v4u w; w.x = cvt_pk_bf16(r[0], r[1]); w.y = cvt_pk_bf16(r[2], r[3]); w.z = cvt_pk_bf16(r[4], r[5]); w.w = cvt_pk_bf16(r[6], r[7]); *(v4u*)(out + o) = w; }
;             q += __shfl_xor(q, 16); q += __shfl_xor(q, 32); if (fq == 0) ssq[(size_t)row * 16 + u.pn * 4 + wc] = q; }
.LBB0_908:
	s_or_b64 exec, exec, s[36:37]
	s_waitcnt lgkmcnt(7)
	v_add_f32_e32 v114, v205, v206
	v_fmamk_f32 v114, v114, 0x3a800000, v190
	v_rsq_f32_e32 v120, v114
	s_waitcnt lgkmcnt(0)
	v_lshlrev_b64 v[114:115], 10, v[176:177]
	v_lshl_add_u64 v[114:115], v[114:115], 0, v[164:165]
	v_lshlrev_b64 v[114:115], 1, v[114:115]
	v_lshl_add_u64 v[116:117], s[10:11], 0, v[114:115]
	v_lshl_add_u64 v[118:119], s[16:17], 0, v[114:115]
	v_or_b32_e32 v114, 0x100, v114
	global_load_dwordx4 v[126:129], v[116:117], off
	global_load_dwordx4 v[122:125], v[118:119], off
	v_lshl_add_u64 v[116:117], s[10:11], 0, v[114:115]
	v_lshl_add_u64 v[114:115], s[16:17], 0, v[114:115]
	v_mul_f32_e32 v182, 0xbfb8aa3b, v120
	global_load_dwordx4 v[118:121], v[116:117], off
	s_nop 0
	global_load_dwordx4 v[114:117], v[114:115], off
	v_pk_mul_f32 v[112:113], v[112:113], v[182:183] op_sel_hi:[1,0]
	v_pk_mul_f32 v[106:107], v[106:107], v[182:183] op_sel_hi:[1,0]
	v_exp_f32_e32 v112, v112
	v_exp_f32_e32 v113, v113
	v_exp_f32_e32 v106, v106
	v_exp_f32_e32 v107, v107
	v_pk_mul_f32 v[110:111], v[110:111], v[182:183] op_sel_hi:[1,0]
	v_pk_add_f32 v[112:113], v[112:113], 1.0 op_sel_hi:[1,0]
	v_exp_f32_e32 v110, v110
	v_exp_f32_e32 v111, v111
	v_rcp_f32_e32 v112, v112
	v_rcp_f32_e32 v113, v113
	v_pk_add_f32 v[106:107], v[106:107], 1.0 op_sel_hi:[1,0]
	v_pk_mul_f32 v[108:109], v[108:109], v[182:183] op_sel_hi:[1,0]
	v_rcp_f32_e32 v106, v106
	v_rcp_f32_e32 v107, v107
	v_exp_f32_e32 v108, v108
	v_exp_f32_e32 v109, v109
	v_pk_mul_f32 v[102:103], v[102:103], v[182:183] op_sel_hi:[1,0]
	v_pk_mul_f32 v[104:105], v[104:105], v[182:183] op_sel_hi:[1,0]
	v_exp_f32_e32 v102, v102
	v_exp_f32_e32 v103, v103
	s_waitcnt vmcnt(9)
	v_lshlrev_b32_e32 v206, 16, v142
	v_and_b32_e32 v207, 0xffff0000, v142
	s_waitcnt vmcnt(8)
	v_lshlrev_b32_e32 v208, 16, v138
	v_and_b32_e32 v209, 0xffff0000, v138
	v_lshlrev_b32_e32 v142, 16, v143
	v_and_b32_e32 v143, 0xffff0000, v143
	v_lshlrev_b32_e32 v138, 16, v139
	v_and_b32_e32 v139, 0xffff0000, v139
	v_exp_f32_e32 v104, v104
	v_exp_f32_e32 v105, v105
	v_pk_mul_f32 v[98:99], v[98:99], v[182:183] op_sel_hi:[1,0]
	v_pk_add_f32 v[110:111], v[110:111], 1.0 op_sel_hi:[1,0]
	v_pk_fma_f32 v[112:113], v[112:113], v[138:139], v[142:143]
	v_lshlrev_b32_e32 v138, 16, v144
	v_and_b32_e32 v139, 0xffff0000, v144
	v_lshlrev_b32_e32 v142, 16, v140
	v_and_b32_e32 v143, 0xffff0000, v140
	v_exp_f32_e32 v98, v98
	v_exp_f32_e32 v99, v99
	v_rcp_f32_e32 v110, v110
	v_rcp_f32_e32 v111, v111
	v_pk_fma_f32 v[138:139], v[106:107], v[142:143], v[138:139]
	v_pk_add_f32 v[106:107], v[108:109], 1.0 op_sel_hi:[1,0]
	v_pk_add_f32 v[102:103], v[102:103], 1.0 op_sel_hi:[1,0]
	v_rcp_f32_e32 v106, v106
	v_rcp_f32_e32 v107, v107
	v_rcp_f32_e32 v102, v102
	v_rcp_f32_e32 v103, v103
	v_pk_add_f32 v[104:105], v[104:105], 1.0 op_sel_hi:[1,0]
	v_pk_add_f32 v[98:99], v[98:99], 1.0 op_sel_hi:[1,0]
	v_rcp_f32_e32 v104, v104
	v_rcp_f32_e32 v105, v105
	v_pk_mul_f32 v[100:101], v[100:101], v[182:183] op_sel_hi:[1,0]
	v_pk_fma_f32 v[110:111], v[110:111], v[208:209], v[206:207]
	v_lshlrev_b32_e32 v108, 16, v145
	v_and_b32_e32 v109, 0xffff0000, v145
	v_lshlrev_b32_e32 v140, 16, v141
	v_and_b32_e32 v141, 0xffff0000, v141
	v_rcp_f32_e32 v98, v98
	v_rcp_f32_e32 v99, v99
	v_exp_f32_e32 v100, v100
	v_exp_f32_e32 v101, v101
	v_pk_fma_f32 v[140:141], v[106:107], v[140:141], v[108:109]
	v_pk_mul_f32 v[142:143], v[110:111], v[110:111]
	v_pk_mul_f32 v[144:145], v[112:113], v[112:113]
	v_cvt_pk_bf16_f32 v106, v110, v111
	v_cvt_pk_bf16_f32 v107, v112, v113
	s_waitcnt vmcnt(7)
	v_lshlrev_b32_e32 v110, 16, v134
	v_and_b32_e32 v111, 0xffff0000, v134
	s_waitcnt vmcnt(6)
	v_lshlrev_b32_e32 v112, 16, v130
	v_and_b32_e32 v113, 0xffff0000, v130
	v_pk_fma_f32 v[102:103], v[102:103], v[112:113], v[110:111]
	v_lshlrev_b32_e32 v110, 16, v135
	v_and_b32_e32 v111, 0xffff0000, v135
	v_lshlrev_b32_e32 v112, 16, v131
	v_and_b32_e32 v113, 0xffff0000, v131
	v_pk_fma_f32 v[104:105], v[104:105], v[112:113], v[110:111]
	v_lshlrev_b32_e32 v110, 16, v136
	v_and_b32_e32 v111, 0xffff0000, v136
	v_lshlrev_b32_e32 v112, 16, v132
	v_and_b32_e32 v113, 0xffff0000, v132
	v_add_f32_e32 v134, v142, v143
	v_pk_fma_f32 v[110:111], v[98:99], v[112:113], v[110:111]
	v_pk_add_f32 v[98:99], v[100:101], 1.0 op_sel_hi:[1,0]
	v_add_f32_e32 v134, v144, v134
	v_pk_mul_f32 v[206:207], v[138:139], v[138:139]
	v_rcp_f32_e32 v98, v98
	v_rcp_f32_e32 v99, v99
	v_add_f32_e32 v134, v145, v134
	v_add_f32_e32 v134, v206, v134
	v_pk_mul_f32 v[208:209], v[140:141], v[140:141]
	v_add_f32_e32 v134, v207, v134
	v_lshlrev_b32_e32 v100, 16, v137
	v_and_b32_e32 v101, 0xffff0000, v137
	v_lshlrev_b32_e32 v112, 16, v133
	v_and_b32_e32 v113, 0xffff0000, v133
	v_add_f32_e32 v134, v208, v134
	v_pk_fma_f32 v[112:113], v[98:99], v[112:113], v[100:101]
	v_pk_mul_f32 v[98:99], v[102:103], v[102:103]
	v_add_f32_e32 v134, v209, v134
	v_add_f32_e32 v98, v98, v134
	v_pk_mul_f32 v[100:101], v[104:105], v[104:105]
	v_add_f32_e32 v98, v99, v98
	v_add_f32_e32 v98, v100, v98
	v_pk_mul_f32 v[130:131], v[110:111], v[110:111]
	v_add_f32_e32 v98, v101, v98
	v_add_f32_e32 v98, v130, v98
	v_pk_mul_f32 v[132:133], v[112:113], v[112:113]
	v_add_f32_e32 v98, v131, v98
	v_add_f32_e32 v98, v132, v98
	v_add_f32_e32 v101, v133, v98
	v_mov_b32_e32 v132, v101
	s_nop 1
	v_permlane16_swap_b32 v101, v132
	v_lshlrev_b64 v[180:181], 11, v[180:181]
	v_lshl_add_u64 v[98:99], s[18:19], 0, v[180:181]
	v_lshl_add_u64 v[130:131], v[164:165], 1, v[98:99]
	v_cvt_pk_bf16_f32 v108, v138, v139
	s_waitcnt lgkmcnt(0)
	v_add_f32_e32 v98, v101, v132
	v_mov_b32_e32 v99, v98
	s_nop 1
	v_permlane32_swap_b32 v98, v99
	v_cvt_pk_bf16_f32 v109, v140, v141
	global_store_dwordx4 v[130:131], v[106:109], off
	v_cvt_pk_bf16_f32 v100, v102, v103
	v_cvt_pk_bf16_f32 v101, v104, v105
	v_cvt_pk_bf16_f32 v102, v110, v111
	v_cvt_pk_bf16_f32 v103, v112, v113
	global_store_dwordx4 v[130:131], v[100:103], off offset:256
	s_and_saveexec_b64 s[36:37], s[6:7]
	s_cbranch_execz .LBB0_910
	v_lshl_add_u64 v[100:101], s[20:21], 0, v[178:179]
	v_lshl_add_u64 v[100:101], s[4:5], 2, v[100:101]
	s_lshl_b32 s12, s49, 2
	v_lshl_add_u64 v[100:101], v[100:101], 0, s[12:13]
	s_waitcnt lgkmcnt(0)
	v_add_f32_e32 v98, v98, v99
	global_store_dword v[100:101], v98, off
; __device__ __forceinline__ unsigned cvt_pk_bf16(float lo, float hi) { unsigned r; asm volatile("v_cvt_pk_bf16_f32 %0, %1, %2" : "=v"(r) : "v"(lo), "v"(hi)); return r; }
; #define PLE2(kk, A, e0, BW, PW) { const f32x2 t = (f32x2){A[e0], A[e0 + 1]} * c1; f32x2 d; d.x = __builtin_amdgcn_exp2f(t.x); d.y = __builtin_amdgcn_exp2f(t.y); d = d + 1.0f; \
;                     f32x2 q2; q2.x = __builtin_amdgcn_rcpf(d.x); q2.y = __builtin_amdgcn_rcpf(d.y); const f32x2 o2 = (f32x2){bflo(BW), bfhi(BW)} + (f32x2){bflo(PW), bfhi(PW)} * q2; r[kk] = o2.x; r[kk + 1] = o2.y; }
; __device__ __forceinline__ void rstd8(const float* ss, int row0, int fq, float (&rs)[8]) {
;     f32x4 a[8];
; #pragma unroll
;     for (int k = 0; k < 8; ++k) a[k] = *(const f32x4*)(ss + (size_t)(row0 + (k >> 2) * 128 + (k & 3) * 16) * 16 + 4 * fq);
; #pragma unroll
;     for (int k = 0; k < 8; ++k) { float s = (a[k][0] + a[k][1]) + (a[k][2] + a[k][3]); s += __shfl_xor(s, 16); s += __shfl_xor(s, 32); rs[k] = __builtin_amdgcn_rsqf(s * (1.f / 1024.f) + EPS); }
;     __device__ __forceinline__ void operator()(const pg8::f32x4 (&acc)[2][2][4][2], const Unit& u, int wr, int wc, int fr, int fq) const {
;     ...
;             for (int bj = 0; bj < 2; ++bj) { const size_t o = (size_t)row * DM_ + col0 + bj * HALF; const v4u bw = cb[bj], pw = cp[bj];
;                 const float c1 = -1.4426950408889634f * rs; float r[8];
;     ...
;                 { const f32x4 a0 = acc[ai][bj][m][0], a1 = acc[ai][bj][m][1];
;                   PLE2(0, a0, 0, bw.x, pw.x) PLE2(2, a0, 2, bw.y, pw.y) PLE2(4, a1, 0, bw.z, pw.z) PLE2(6, a1, 2, bw.w, pw.w) }
;     ...
; #pragma unroll
;                 for (int e = 0; e < 8; ++e) q += r[e] * r[e];
;                 v4u w; w.x = cvt_pk_bf16(r[0], r[1]); w.y = cvt_pk_bf16(r[2], r[3]); w.z = cvt_pk_bf16(r[4], r[5]); w.w = cvt_pk_bf16(r[6], r[7]); *(v4u*)(out + o) = w; }
;             q += __shfl_xor(q, 16); q += __shfl_xor(q, 32); if (fq == 0) ssq[(size_t)row * 16 + u.pn * 4 + wc] = q; }
.LBB0_910:
	s_or_b64 exec, exec, s[36:37]
	v_add_f32_e32 v98, v203, v204
	v_fmamk_f32 v98, v98, 0x3a800000, v190
	v_rsq_f32_e32 v104, v98
	s_waitcnt lgkmcnt(0)
	v_lshlrev_b64 v[98:99], 10, v[172:173]
	v_lshl_add_u64 v[98:99], v[98:99], 0, v[164:165]
	v_lshlrev_b64 v[98:99], 1, v[98:99]
	v_lshl_add_u64 v[100:101], s[10:11], 0, v[98:99]
	v_lshl_add_u64 v[102:103], s[16:17], 0, v[98:99]
	v_or_b32_e32 v98, 0x100, v98
	global_load_dwordx4 v[110:113], v[100:101], off
	global_load_dwordx4 v[106:109], v[102:103], off
	v_lshl_add_u64 v[100:101], s[10:11], 0, v[98:99]
	v_lshl_add_u64 v[98:99], s[16:17], 0, v[98:99]
	v_mul_f32_e32 v130, 0xbfb8aa3b, v104
	global_load_dwordx4 v[102:105], v[100:101], off
	s_nop 0
	global_load_dwordx4 v[98:101], v[98:99], off
	v_pk_mul_f32 v[96:97], v[96:97], v[130:131] op_sel_hi:[1,0]
	v_pk_mul_f32 v[90:91], v[90:91], v[130:131] op_sel_hi:[1,0]
	v_exp_f32_e32 v96, v96
	v_exp_f32_e32 v97, v97
	v_exp_f32_e32 v90, v90
	v_exp_f32_e32 v91, v91
	v_pk_mul_f32 v[94:95], v[94:95], v[130:131] op_sel_hi:[1,0]
	v_pk_add_f32 v[96:97], v[96:97], 1.0 op_sel_hi:[1,0]
	v_exp_f32_e32 v94, v94
	v_exp_f32_e32 v95, v95
	v_rcp_f32_e32 v96, v96
	v_rcp_f32_e32 v97, v97
	v_pk_add_f32 v[90:91], v[90:91], 1.0 op_sel_hi:[1,0]
	v_pk_mul_f32 v[92:93], v[92:93], v[130:131] op_sel_hi:[1,0]
	v_rcp_f32_e32 v90, v90
	v_rcp_f32_e32 v91, v91
	v_exp_f32_e32 v92, v92
	v_exp_f32_e32 v93, v93
	v_pk_mul_f32 v[86:87], v[86:87], v[130:131] op_sel_hi:[1,0]
	v_pk_mul_f32 v[88:89], v[88:89], v[130:131] op_sel_hi:[1,0]
	v_exp_f32_e32 v86, v86
	v_exp_f32_e32 v87, v87
	s_waitcnt vmcnt(9)
	v_lshlrev_b32_e32 v134, 16, v126
	v_and_b32_e32 v135, 0xffff0000, v126
	s_waitcnt vmcnt(8)
	v_lshlrev_b32_e32 v136, 16, v122
	v_and_b32_e32 v137, 0xffff0000, v122
	v_lshlrev_b32_e32 v126, 16, v127
	v_and_b32_e32 v127, 0xffff0000, v127
	v_lshlrev_b32_e32 v122, 16, v123
	v_and_b32_e32 v123, 0xffff0000, v123
	v_exp_f32_e32 v88, v88
	v_exp_f32_e32 v89, v89
	v_pk_mul_f32 v[82:83], v[82:83], v[130:131] op_sel_hi:[1,0]
	v_pk_add_f32 v[94:95], v[94:95], 1.0 op_sel_hi:[1,0]
	v_pk_fma_f32 v[96:97], v[96:97], v[122:123], v[126:127]
	v_lshlrev_b32_e32 v122, 16, v128
	v_and_b32_e32 v123, 0xffff0000, v128
	v_lshlrev_b32_e32 v126, 16, v124
	v_and_b32_e32 v127, 0xffff0000, v124
	v_exp_f32_e32 v82, v82
	v_exp_f32_e32 v83, v83
	v_rcp_f32_e32 v94, v94
	v_rcp_f32_e32 v95, v95
	v_pk_fma_f32 v[122:123], v[90:91], v[126:127], v[122:123]
	v_pk_add_f32 v[90:91], v[92:93], 1.0 op_sel_hi:[1,0]
	v_pk_add_f32 v[86:87], v[86:87], 1.0 op_sel_hi:[1,0]
	v_rcp_f32_e32 v90, v90
	v_rcp_f32_e32 v91, v91
	v_rcp_f32_e32 v86, v86
	v_rcp_f32_e32 v87, v87
	v_pk_add_f32 v[88:89], v[88:89], 1.0 op_sel_hi:[1,0]
	v_pk_add_f32 v[82:83], v[82:83], 1.0 op_sel_hi:[1,0]
	v_rcp_f32_e32 v88, v88
	v_rcp_f32_e32 v89, v89
	v_pk_mul_f32 v[84:85], v[84:85], v[130:131] op_sel_hi:[1,0]
	v_pk_fma_f32 v[94:95], v[94:95], v[136:137], v[134:135]
	v_lshlrev_b32_e32 v92, 16, v129
	v_and_b32_e32 v93, 0xffff0000, v129
	v_lshlrev_b32_e32 v124, 16, v125
	v_and_b32_e32 v125, 0xffff0000, v125
	v_rcp_f32_e32 v82, v82
	v_rcp_f32_e32 v83, v83
	v_exp_f32_e32 v84, v84
	v_exp_f32_e32 v85, v85
	v_pk_fma_f32 v[124:125], v[90:91], v[124:125], v[92:93]
	v_pk_mul_f32 v[126:127], v[94:95], v[94:95]
	v_pk_mul_f32 v[128:129], v[96:97], v[96:97]
	v_cvt_pk_bf16_f32 v90, v94, v95
	v_cvt_pk_bf16_f32 v91, v96, v97
	s_waitcnt vmcnt(7)
	v_lshlrev_b32_e32 v94, 16, v118
	v_and_b32_e32 v95, 0xffff0000, v118
	s_waitcnt vmcnt(6)
	v_lshlrev_b32_e32 v96, 16, v114
	v_and_b32_e32 v97, 0xffff0000, v114
	v_pk_fma_f32 v[86:87], v[86:87], v[96:97], v[94:95]
	v_lshlrev_b32_e32 v94, 16, v119
	v_and_b32_e32 v95, 0xffff0000, v119
	v_lshlrev_b32_e32 v96, 16, v115
	v_and_b32_e32 v97, 0xffff0000, v115
	v_pk_fma_f32 v[88:89], v[88:89], v[96:97], v[94:95]
	v_lshlrev_b32_e32 v94, 16, v120
	v_and_b32_e32 v95, 0xffff0000, v120
	v_lshlrev_b32_e32 v96, 16, v116
	v_and_b32_e32 v97, 0xffff0000, v116
	v_add_f32_e32 v118, v126, v127
	v_pk_fma_f32 v[94:95], v[82:83], v[96:97], v[94:95]
	v_pk_add_f32 v[82:83], v[84:85], 1.0 op_sel_hi:[1,0]
	v_add_f32_e32 v118, v128, v118
	v_pk_mul_f32 v[134:135], v[122:123], v[122:123]
	v_rcp_f32_e32 v82, v82
	v_rcp_f32_e32 v83, v83
	v_add_f32_e32 v118, v129, v118
	v_add_f32_e32 v118, v134, v118
	v_pk_mul_f32 v[136:137], v[124:125], v[124:125]
	v_add_f32_e32 v118, v135, v118
	v_lshlrev_b32_e32 v84, 16, v121
	v_and_b32_e32 v85, 0xffff0000, v121
	v_lshlrev_b32_e32 v96, 16, v117
	v_and_b32_e32 v97, 0xffff0000, v117
	v_add_f32_e32 v118, v136, v118
	v_pk_fma_f32 v[96:97], v[82:83], v[96:97], v[84:85]
	v_pk_mul_f32 v[82:83], v[86:87], v[86:87]
	v_add_f32_e32 v118, v137, v118
	v_add_f32_e32 v82, v82, v118
	v_pk_mul_f32 v[84:85], v[88:89], v[88:89]
	v_add_f32_e32 v82, v83, v82
	v_add_f32_e32 v82, v84, v82
	v_pk_mul_f32 v[114:115], v[94:95], v[94:95]
	v_add_f32_e32 v82, v85, v82
	v_add_f32_e32 v82, v114, v82
	v_pk_mul_f32 v[116:117], v[96:97], v[96:97]
	v_add_f32_e32 v82, v115, v82
	v_add_f32_e32 v82, v116, v82
	v_add_f32_e32 v85, v117, v82
	v_mov_b32_e32 v116, v85
	s_nop 1
	v_permlane16_swap_b32 v85, v116
	v_lshlrev_b64 v[132:133], 11, v[176:177]
	v_lshl_add_u64 v[82:83], s[18:19], 0, v[132:133]
	v_lshl_add_u64 v[114:115], v[164:165], 1, v[82:83]
	v_cvt_pk_bf16_f32 v92, v122, v123
	s_waitcnt lgkmcnt(0)
	v_add_f32_e32 v82, v85, v116
	v_mov_b32_e32 v83, v82
	s_nop 1
	v_permlane32_swap_b32 v82, v83
	v_cvt_pk_bf16_f32 v93, v124, v125
	global_store_dwordx4 v[114:115], v[90:93], off
	v_cvt_pk_bf16_f32 v84, v86, v87
	v_cvt_pk_bf16_f32 v85, v88, v89
	v_cvt_pk_bf16_f32 v86, v94, v95
	v_cvt_pk_bf16_f32 v87, v96, v97
	global_store_dwordx4 v[114:115], v[84:87], off offset:256
	s_and_saveexec_b64 s[36:37], s[6:7]
	s_cbranch_execz .LBB0_912
	v_lshl_add_u64 v[84:85], s[20:21], 0, v[174:175]
	v_lshl_add_u64 v[84:85], s[4:5], 2, v[84:85]
	s_lshl_b32 s12, s49, 2
	v_lshl_add_u64 v[84:85], v[84:85], 0, s[12:13]
	s_waitcnt lgkmcnt(0)
	v_add_f32_e32 v82, v82, v83
	global_store_dword v[84:85], v82, off
; __device__ __forceinline__ unsigned cvt_pk_bf16(float lo, float hi) { unsigned r; asm volatile("v_cvt_pk_bf16_f32 %0, %1, %2" : "=v"(r) : "v"(lo), "v"(hi)); return r; }
; #define PLE2(kk, A, e0, BW, PW) { const f32x2 t = (f32x2){A[e0], A[e0 + 1]} * c1; f32x2 d; d.x = __builtin_amdgcn_exp2f(t.x); d.y = __builtin_amdgcn_exp2f(t.y); d = d + 1.0f; \
;                     f32x2 q2; q2.x = __builtin_amdgcn_rcpf(d.x); q2.y = __builtin_amdgcn_rcpf(d.y); const f32x2 o2 = (f32x2){bflo(BW), bfhi(BW)} + (f32x2){bflo(PW), bfhi(PW)} * q2; r[kk] = o2.x; r[kk + 1] = o2.y; }
; __device__ __forceinline__ void rstd8(const float* ss, int row0, int fq, float (&rs)[8]) {
;     f32x4 a[8];
; #pragma unroll
;     for (int k = 0; k < 8; ++k) a[k] = *(const f32x4*)(ss + (size_t)(row0 + (k >> 2) * 128 + (k & 3) * 16) * 16 + 4 * fq);
; #pragma unroll
;     for (int k = 0; k < 8; ++k) { float s = (a[k][0] + a[k][1]) + (a[k][2] + a[k][3]); s += __shfl_xor(s, 16); s += __shfl_xor(s, 32); rs[k] = __builtin_amdgcn_rsqf(s * (1.f / 1024.f) + EPS); }
;     __device__ __forceinline__ void operator()(const pg8::f32x4 (&acc)[2][2][4][2], const Unit& u, int wr, int wc, int fr, int fq) const {
;     ...
;             for (int bj = 0; bj < 2; ++bj) { const size_t o = (size_t)row * DM_ + col0 + bj * HALF; const v4u bw = cb[bj], pw = cp[bj];
;                 const float c1 = -1.4426950408889634f * rs; float r[8];
;     ...
;                 { const f32x4 a0 = acc[ai][bj][m][0], a1 = acc[ai][bj][m][1];
;                   PLE2(0, a0, 0, bw.x, pw.x) PLE2(2, a0, 2, bw.y, pw.y) PLE2(4, a1, 0, bw.z, pw.z) PLE2(6, a1, 2, bw.w, pw.w) }
;     ...
; #pragma unroll
;                 for (int e = 0; e < 8; ++e) q += r[e] * r[e];
;                 v4u w; w.x = cvt_pk_bf16(r[0], r[1]); w.y = cvt_pk_bf16(r[2], r[3]); w.z = cvt_pk_bf16(r[4], r[5]); w.w = cvt_pk_bf16(r[6], r[7]); *(v4u*)(out + o) = w; }
;             q += __shfl_xor(q, 16); q += __shfl_xor(q, 32); if (fq == 0) ssq[(size_t)row * 16 + u.pn * 4 + wc] = q; }
.LBB0_912:
	s_or_b64 exec, exec, s[36:37]
	v_add_f32_e32 v82, v201, v202
	v_fmamk_f32 v82, v82, 0x3a800000, v190
	v_rsq_f32_e32 v88, v82
	s_waitcnt lgkmcnt(0)
	v_lshlrev_b64 v[82:83], 10, v[166:167]
	v_lshl_add_u64 v[82:83], v[82:83], 0, v[164:165]
	v_lshlrev_b64 v[82:83], 1, v[82:83]
	v_lshl_add_u64 v[84:85], s[10:11], 0, v[82:83]
	v_lshl_add_u64 v[86:87], s[16:17], 0, v[82:83]
	v_or_b32_e32 v82, 0x100, v82
	global_load_dwordx4 v[94:97], v[84:85], off
	global_load_dwordx4 v[90:93], v[86:87], off
	v_lshl_add_u64 v[84:85], s[10:11], 0, v[82:83]
	v_lshl_add_u64 v[82:83], s[16:17], 0, v[82:83]
	v_mul_f32_e32 v114, 0xbfb8aa3b, v88
	global_load_dwordx4 v[86:89], v[84:85], off
	s_nop 0
	global_load_dwordx4 v[82:85], v[82:83], off
	v_pk_mul_f32 v[80:81], v[80:81], v[114:115] op_sel_hi:[1,0]
	v_pk_mul_f32 v[74:75], v[74:75], v[114:115] op_sel_hi:[1,0]
	v_exp_f32_e32 v80, v80
	v_exp_f32_e32 v81, v81
	v_exp_f32_e32 v74, v74
	v_exp_f32_e32 v75, v75
	v_pk_mul_f32 v[78:79], v[78:79], v[114:115] op_sel_hi:[1,0]
	v_pk_add_f32 v[80:81], v[80:81], 1.0 op_sel_hi:[1,0]
	v_exp_f32_e32 v78, v78
	v_exp_f32_e32 v79, v79
	v_rcp_f32_e32 v80, v80
	v_rcp_f32_e32 v81, v81
	v_pk_add_f32 v[74:75], v[74:75], 1.0 op_sel_hi:[1,0]
	v_pk_mul_f32 v[76:77], v[76:77], v[114:115] op_sel_hi:[1,0]
	v_rcp_f32_e32 v74, v74
	v_rcp_f32_e32 v75, v75
	v_exp_f32_e32 v76, v76
	v_exp_f32_e32 v77, v77
	v_pk_mul_f32 v[70:71], v[70:71], v[114:115] op_sel_hi:[1,0]
	v_pk_mul_f32 v[72:73], v[72:73], v[114:115] op_sel_hi:[1,0]
	v_exp_f32_e32 v70, v70
	v_exp_f32_e32 v71, v71
	s_waitcnt vmcnt(9)
	v_lshlrev_b32_e32 v118, 16, v110
	v_and_b32_e32 v119, 0xffff0000, v110
	s_waitcnt vmcnt(8)
	v_lshlrev_b32_e32 v120, 16, v106
	v_and_b32_e32 v121, 0xffff0000, v106
	v_lshlrev_b32_e32 v110, 16, v111
	v_and_b32_e32 v111, 0xffff0000, v111
	v_lshlrev_b32_e32 v106, 16, v107
	v_and_b32_e32 v107, 0xffff0000, v107
	v_exp_f32_e32 v72, v72
	v_exp_f32_e32 v73, v73
	v_pk_mul_f32 v[66:67], v[66:67], v[114:115] op_sel_hi:[1,0]
	v_pk_add_f32 v[78:79], v[78:79], 1.0 op_sel_hi:[1,0]
	v_pk_fma_f32 v[80:81], v[80:81], v[106:107], v[110:111]
	v_lshlrev_b32_e32 v106, 16, v112
	v_and_b32_e32 v107, 0xffff0000, v112
	v_lshlrev_b32_e32 v110, 16, v108
	v_and_b32_e32 v111, 0xffff0000, v108
	v_exp_f32_e32 v66, v66
	v_exp_f32_e32 v67, v67
	v_rcp_f32_e32 v78, v78
	v_rcp_f32_e32 v79, v79
	v_pk_fma_f32 v[106:107], v[74:75], v[110:111], v[106:107]
	v_pk_add_f32 v[74:75], v[76:77], 1.0 op_sel_hi:[1,0]
	v_pk_add_f32 v[70:71], v[70:71], 1.0 op_sel_hi:[1,0]
	v_rcp_f32_e32 v74, v74
	v_rcp_f32_e32 v75, v75
	v_rcp_f32_e32 v70, v70
	v_rcp_f32_e32 v71, v71
	v_pk_add_f32 v[72:73], v[72:73], 1.0 op_sel_hi:[1,0]
	v_pk_add_f32 v[66:67], v[66:67], 1.0 op_sel_hi:[1,0]
	v_rcp_f32_e32 v72, v72
	v_rcp_f32_e32 v73, v73
	v_pk_mul_f32 v[68:69], v[68:69], v[114:115] op_sel_hi:[1,0]
	v_pk_fma_f32 v[78:79], v[78:79], v[120:121], v[118:119]
	v_lshlrev_b32_e32 v76, 16, v113
	v_and_b32_e32 v77, 0xffff0000, v113
	v_lshlrev_b32_e32 v108, 16, v109
	v_and_b32_e32 v109, 0xffff0000, v109
	v_rcp_f32_e32 v66, v66
	v_rcp_f32_e32 v67, v67
	v_exp_f32_e32 v68, v68
	v_exp_f32_e32 v69, v69
	v_pk_fma_f32 v[108:109], v[74:75], v[108:109], v[76:77]
	v_pk_mul_f32 v[110:111], v[78:79], v[78:79]
	v_pk_mul_f32 v[112:113], v[80:81], v[80:81]
	v_cvt_pk_bf16_f32 v74, v78, v79
	v_cvt_pk_bf16_f32 v75, v80, v81
	s_waitcnt vmcnt(7)
	v_lshlrev_b32_e32 v78, 16, v102
	v_and_b32_e32 v79, 0xffff0000, v102
	s_waitcnt vmcnt(6)
	v_lshlrev_b32_e32 v80, 16, v98
	v_and_b32_e32 v81, 0xffff0000, v98
	v_pk_fma_f32 v[70:71], v[70:71], v[80:81], v[78:79]
	v_lshlrev_b32_e32 v78, 16, v103
	v_and_b32_e32 v79, 0xffff0000, v103
	v_lshlrev_b32_e32 v80, 16, v99
	v_and_b32_e32 v81, 0xffff0000, v99
	v_pk_fma_f32 v[72:73], v[72:73], v[80:81], v[78:79]
	v_lshlrev_b32_e32 v78, 16, v104
	v_and_b32_e32 v79, 0xffff0000, v104
	v_lshlrev_b32_e32 v80, 16, v100
	v_and_b32_e32 v81, 0xffff0000, v100
	v_add_f32_e32 v102, v110, v111
	v_pk_fma_f32 v[78:79], v[66:67], v[80:81], v[78:79]
	v_pk_add_f32 v[66:67], v[68:69], 1.0 op_sel_hi:[1,0]
	v_add_f32_e32 v102, v112, v102
	v_pk_mul_f32 v[118:119], v[106:107], v[106:107]
	v_rcp_f32_e32 v66, v66
	v_rcp_f32_e32 v67, v67
	v_add_f32_e32 v102, v113, v102
	v_add_f32_e32 v102, v118, v102
	v_pk_mul_f32 v[120:121], v[108:109], v[108:109]
	v_add_f32_e32 v102, v119, v102
	v_lshlrev_b32_e32 v68, 16, v105
	v_and_b32_e32 v69, 0xffff0000, v105
	v_lshlrev_b32_e32 v80, 16, v101
	v_and_b32_e32 v81, 0xffff0000, v101
	v_add_f32_e32 v102, v120, v102
	v_pk_fma_f32 v[80:81], v[66:67], v[80:81], v[68:69]
	v_pk_mul_f32 v[66:67], v[70:71], v[70:71]
	v_add_f32_e32 v102, v121, v102
	v_add_f32_e32 v66, v66, v102
	v_pk_mul_f32 v[68:69], v[72:73], v[72:73]
	v_add_f32_e32 v66, v67, v66
	v_add_f32_e32 v66, v68, v66
	v_pk_mul_f32 v[98:99], v[78:79], v[78:79]
	v_add_f32_e32 v66, v69, v66
	v_add_f32_e32 v66, v98, v66
	v_pk_mul_f32 v[100:101], v[80:81], v[80:81]
	v_add_f32_e32 v66, v99, v66
	v_add_f32_e32 v66, v100, v66
	v_add_f32_e32 v69, v101, v66
	v_mov_b32_e32 v100, v69
	s_nop 1
	v_permlane16_swap_b32 v69, v100
	v_lshlrev_b64 v[116:117], 11, v[172:173]
	v_lshl_add_u64 v[66:67], s[18:19], 0, v[116:117]
	v_lshl_add_u64 v[98:99], v[164:165], 1, v[66:67]
	v_cvt_pk_bf16_f32 v76, v106, v107
	s_waitcnt lgkmcnt(0)
	v_add_f32_e32 v66, v69, v100
	v_mov_b32_e32 v67, v66
	s_nop 1
	v_permlane32_swap_b32 v66, v67
	v_cvt_pk_bf16_f32 v77, v108, v109
	global_store_dwordx4 v[98:99], v[74:77], off
	v_cvt_pk_bf16_f32 v68, v70, v71
	v_cvt_pk_bf16_f32 v69, v72, v73
	v_cvt_pk_bf16_f32 v70, v78, v79
	v_cvt_pk_bf16_f32 v71, v80, v81
	global_store_dwordx4 v[98:99], v[68:71], off offset:256
	s_and_saveexec_b64 s[36:37], s[6:7]
	s_cbranch_execz .LBB0_914
	v_lshl_add_u64 v[68:69], s[20:21], 0, v[170:171]
	v_lshl_add_u64 v[68:69], s[4:5], 2, v[68:69]
	s_lshl_b32 s12, s49, 2
	v_lshl_add_u64 v[68:69], v[68:69], 0, s[12:13]
	s_waitcnt lgkmcnt(0)
	v_add_f32_e32 v66, v66, v67
	global_store_dword v[68:69], v66, off
; __device__ __forceinline__ unsigned cvt_pk_bf16(float lo, float hi) { unsigned r; asm volatile("v_cvt_pk_bf16_f32 %0, %1, %2" : "=v"(r) : "v"(lo), "v"(hi)); return r; }
; #define PLE2(kk, A, e0, BW, PW) { const f32x2 t = (f32x2){A[e0], A[e0 + 1]} * c1; f32x2 d; d.x = __builtin_amdgcn_exp2f(t.x); d.y = __builtin_amdgcn_exp2f(t.y); d = d + 1.0f; \
;                     f32x2 q2; q2.x = __builtin_amdgcn_rcpf(d.x); q2.y = __builtin_amdgcn_rcpf(d.y); const f32x2 o2 = (f32x2){bflo(BW), bfhi(BW)} + (f32x2){bflo(PW), bfhi(PW)} * q2; r[kk] = o2.x; r[kk + 1] = o2.y; }
; __device__ __forceinline__ void rstd8(const float* ss, int row0, int fq, float (&rs)[8]) {
;     f32x4 a[8];
; #pragma unroll
;     for (int k = 0; k < 8; ++k) a[k] = *(const f32x4*)(ss + (size_t)(row0 + (k >> 2) * 128 + (k & 3) * 16) * 16 + 4 * fq);
; #pragma unroll
;     for (int k = 0; k < 8; ++k) { float s = (a[k][0] + a[k][1]) + (a[k][2] + a[k][3]); s += __shfl_xor(s, 16); s += __shfl_xor(s, 32); rs[k] = __builtin_amdgcn_rsqf(s * (1.f / 1024.f) + EPS); }
;     __device__ __forceinline__ void operator()(const pg8::f32x4 (&acc)[2][2][4][2], const Unit& u, int wr, int wc, int fr, int fq) const {
;     ...
;             for (int bj = 0; bj < 2; ++bj) { const size_t o = (size_t)row * DM_ + col0 + bj * HALF; const v4u bw = cb[bj], pw = cp[bj];
;                 const float c1 = -1.4426950408889634f * rs; float r[8];
;     ...
;                 { const f32x4 a0 = acc[ai][bj][m][0], a1 = acc[ai][bj][m][1];
;                   PLE2(0, a0, 0, bw.x, pw.x) PLE2(2, a0, 2, bw.y, pw.y) PLE2(4, a1, 0, bw.z, pw.z) PLE2(6, a1, 2, bw.w, pw.w) }
;     ...
; #pragma unroll
;                 for (int e = 0; e < 8; ++e) q += r[e] * r[e];
;                 v4u w; w.x = cvt_pk_bf16(r[0], r[1]); w.y = cvt_pk_bf16(r[2], r[3]); w.z = cvt_pk_bf16(r[4], r[5]); w.w = cvt_pk_bf16(r[6], r[7]); *(v4u*)(out + o) = w; }
;             q += __shfl_xor(q, 16); q += __shfl_xor(q, 32); if (fq == 0) ssq[(size_t)row * 16 + u.pn * 4 + wc] = q; }
.LBB0_914:
	s_or_b64 exec, exec, s[36:37]
	v_add_f32_e32 v66, v199, v200
	v_or_b32_e32 v98, 16, v166
	v_fmamk_f32 v66, v66, 0x3a800000, v190
	v_ashrrev_i32_e32 v99, 31, v98
	v_rsq_f32_e32 v72, v66
	s_waitcnt lgkmcnt(0)
	v_lshlrev_b64 v[66:67], 10, v[98:99]
	v_lshl_add_u64 v[66:67], v[66:67], 0, v[164:165]
	v_lshlrev_b64 v[66:67], 1, v[66:67]
	v_lshl_add_u64 v[68:69], s[10:11], 0, v[66:67]
	v_lshl_add_u64 v[70:71], s[16:17], 0, v[66:67]
	v_or_b32_e32 v66, 0x100, v66
	global_load_dwordx4 v[78:81], v[68:69], off
	global_load_dwordx4 v[74:77], v[70:71], off
	v_lshl_add_u64 v[68:69], s[10:11], 0, v[66:67]
	v_lshl_add_u64 v[66:67], s[16:17], 0, v[66:67]
	v_mul_f32_e32 v100, 0xbfb8aa3b, v72
	global_load_dwordx4 v[70:73], v[68:69], off
	s_nop 0
	global_load_dwordx4 v[66:69], v[66:67], off
	v_pk_mul_f32 v[64:65], v[64:65], v[100:101] op_sel_hi:[1,0]
	v_pk_mul_f32 v[58:59], v[58:59], v[100:101] op_sel_hi:[1,0]
	v_exp_f32_e32 v64, v64
	v_exp_f32_e32 v65, v65
	v_exp_f32_e32 v58, v58
	v_exp_f32_e32 v59, v59
	v_pk_mul_f32 v[62:63], v[62:63], v[100:101] op_sel_hi:[1,0]
	v_pk_add_f32 v[64:65], v[64:65], 1.0 op_sel_hi:[1,0]
	v_exp_f32_e32 v62, v62
	v_exp_f32_e32 v63, v63
	v_rcp_f32_e32 v64, v64
	v_rcp_f32_e32 v65, v65
	v_pk_add_f32 v[58:59], v[58:59], 1.0 op_sel_hi:[1,0]
	v_pk_mul_f32 v[60:61], v[60:61], v[100:101] op_sel_hi:[1,0]
	v_rcp_f32_e32 v58, v58
	v_rcp_f32_e32 v59, v59
	v_exp_f32_e32 v60, v60
	v_exp_f32_e32 v61, v61
	v_pk_mul_f32 v[54:55], v[54:55], v[100:101] op_sel_hi:[1,0]
	v_pk_mul_f32 v[56:57], v[56:57], v[100:101] op_sel_hi:[1,0]
	v_exp_f32_e32 v54, v54
	v_exp_f32_e32 v55, v55
	s_waitcnt vmcnt(9)
	v_lshlrev_b32_e32 v104, 16, v94
	v_and_b32_e32 v105, 0xffff0000, v94
	s_waitcnt vmcnt(8)
	v_lshlrev_b32_e32 v106, 16, v90
	v_and_b32_e32 v107, 0xffff0000, v90
	v_lshlrev_b32_e32 v94, 16, v95
	v_and_b32_e32 v95, 0xffff0000, v95
	v_lshlrev_b32_e32 v90, 16, v91
	v_and_b32_e32 v91, 0xffff0000, v91
	v_exp_f32_e32 v56, v56
	v_exp_f32_e32 v57, v57
	v_pk_mul_f32 v[50:51], v[50:51], v[100:101] op_sel_hi:[1,0]
	v_pk_add_f32 v[62:63], v[62:63], 1.0 op_sel_hi:[1,0]
	v_pk_fma_f32 v[64:65], v[64:65], v[90:91], v[94:95]
	v_lshlrev_b32_e32 v90, 16, v96
	v_and_b32_e32 v91, 0xffff0000, v96
	v_lshlrev_b32_e32 v94, 16, v92
	v_and_b32_e32 v95, 0xffff0000, v92
	v_exp_f32_e32 v50, v50
	v_exp_f32_e32 v51, v51
	v_rcp_f32_e32 v62, v62
	v_rcp_f32_e32 v63, v63
	v_pk_fma_f32 v[90:91], v[58:59], v[94:95], v[90:91]
	v_pk_add_f32 v[58:59], v[60:61], 1.0 op_sel_hi:[1,0]
	v_pk_add_f32 v[54:55], v[54:55], 1.0 op_sel_hi:[1,0]
	v_rcp_f32_e32 v58, v58
	v_rcp_f32_e32 v59, v59
	v_rcp_f32_e32 v54, v54
	v_rcp_f32_e32 v55, v55
	v_pk_add_f32 v[56:57], v[56:57], 1.0 op_sel_hi:[1,0]
	v_pk_add_f32 v[50:51], v[50:51], 1.0 op_sel_hi:[1,0]
	v_rcp_f32_e32 v56, v56
	v_rcp_f32_e32 v57, v57
	v_pk_mul_f32 v[52:53], v[52:53], v[100:101] op_sel_hi:[1,0]
	v_pk_fma_f32 v[62:63], v[62:63], v[106:107], v[104:105]
	v_lshlrev_b32_e32 v60, 16, v97
	v_and_b32_e32 v61, 0xffff0000, v97
	v_lshlrev_b32_e32 v92, 16, v93
	v_and_b32_e32 v93, 0xffff0000, v93
	v_rcp_f32_e32 v50, v50
	v_rcp_f32_e32 v51, v51
	v_exp_f32_e32 v52, v52
	v_exp_f32_e32 v53, v53
	v_pk_fma_f32 v[92:93], v[58:59], v[92:93], v[60:61]
	v_pk_mul_f32 v[94:95], v[62:63], v[62:63]
	v_pk_mul_f32 v[96:97], v[64:65], v[64:65]
	v_cvt_pk_bf16_f32 v58, v62, v63
	v_cvt_pk_bf16_f32 v59, v64, v65
	s_waitcnt vmcnt(7)
	v_lshlrev_b32_e32 v62, 16, v86
	v_and_b32_e32 v63, 0xffff0000, v86
	s_waitcnt vmcnt(6)
	v_lshlrev_b32_e32 v64, 16, v82
	v_and_b32_e32 v65, 0xffff0000, v82
	v_pk_fma_f32 v[54:55], v[54:55], v[64:65], v[62:63]
	v_lshlrev_b32_e32 v62, 16, v87
	v_and_b32_e32 v63, 0xffff0000, v87
	v_lshlrev_b32_e32 v64, 16, v83
	v_and_b32_e32 v65, 0xffff0000, v83
	v_pk_fma_f32 v[56:57], v[56:57], v[64:65], v[62:63]
	v_lshlrev_b32_e32 v62, 16, v88
	v_and_b32_e32 v63, 0xffff0000, v88
	v_lshlrev_b32_e32 v64, 16, v84
	v_and_b32_e32 v65, 0xffff0000, v84
	v_add_f32_e32 v86, v94, v95
	v_pk_fma_f32 v[62:63], v[50:51], v[64:65], v[62:63]
	v_pk_add_f32 v[50:51], v[52:53], 1.0 op_sel_hi:[1,0]
	v_add_f32_e32 v86, v96, v86
	v_pk_mul_f32 v[104:105], v[90:91], v[90:91]
	v_rcp_f32_e32 v50, v50
	v_rcp_f32_e32 v51, v51
	v_add_f32_e32 v86, v97, v86
	v_add_f32_e32 v86, v104, v86
	v_pk_mul_f32 v[106:107], v[92:93], v[92:93]
	v_add_f32_e32 v86, v105, v86
	v_lshlrev_b32_e32 v52, 16, v89
	v_and_b32_e32 v53, 0xffff0000, v89
	v_lshlrev_b32_e32 v64, 16, v85
	v_and_b32_e32 v65, 0xffff0000, v85
	v_add_f32_e32 v86, v106, v86
	v_pk_fma_f32 v[64:65], v[50:51], v[64:65], v[52:53]
	v_pk_mul_f32 v[50:51], v[54:55], v[54:55]
	v_add_f32_e32 v86, v107, v86
	v_add_f32_e32 v50, v50, v86
	v_pk_mul_f32 v[52:53], v[56:57], v[56:57]
	v_add_f32_e32 v50, v51, v50
	v_add_f32_e32 v50, v52, v50
	v_pk_mul_f32 v[82:83], v[62:63], v[62:63]
	v_add_f32_e32 v50, v53, v50
	v_add_f32_e32 v50, v82, v50
	v_pk_mul_f32 v[84:85], v[64:65], v[64:65]
	v_add_f32_e32 v50, v83, v50
	v_add_f32_e32 v50, v84, v50
	v_add_f32_e32 v53, v85, v50
	v_mov_b32_e32 v84, v53
	s_nop 1
	v_permlane16_swap_b32 v53, v84
	v_lshlrev_b64 v[102:103], 11, v[166:167]
	v_lshl_add_u64 v[50:51], s[18:19], 0, v[102:103]
	v_lshl_add_u64 v[82:83], v[164:165], 1, v[50:51]
	v_cvt_pk_bf16_f32 v60, v90, v91
	s_waitcnt lgkmcnt(0)
	v_add_f32_e32 v50, v53, v84
	v_mov_b32_e32 v51, v50
	s_nop 1
	v_permlane32_swap_b32 v50, v51
	v_cvt_pk_bf16_f32 v61, v92, v93
	global_store_dwordx4 v[82:83], v[58:61], off
	v_cvt_pk_bf16_f32 v52, v54, v55
	v_cvt_pk_bf16_f32 v53, v56, v57
	v_cvt_pk_bf16_f32 v54, v62, v63
	v_cvt_pk_bf16_f32 v55, v64, v65
	global_store_dwordx4 v[82:83], v[52:55], off offset:256
	s_and_saveexec_b64 s[36:37], s[6:7]
	s_cbranch_execz .LBB0_916
	v_lshl_add_u64 v[52:53], s[20:21], 0, v[168:169]
	v_lshl_add_u64 v[52:53], s[4:5], 2, v[52:53]
	s_lshl_b32 s12, s49, 2
	v_lshl_add_u64 v[52:53], v[52:53], 0, s[12:13]
	s_waitcnt lgkmcnt(0)
	v_add_f32_e32 v50, v50, v51
	global_store_dword v[52:53], v50, off
; __device__ __forceinline__ unsigned cvt_pk_bf16(float lo, float hi) { unsigned r; asm volatile("v_cvt_pk_bf16_f32 %0, %1, %2" : "=v"(r) : "v"(lo), "v"(hi)); return r; }
; #define PLE2(kk, A, e0, BW, PW) { const f32x2 t = (f32x2){A[e0], A[e0 + 1]} * c1; f32x2 d; d.x = __builtin_amdgcn_exp2f(t.x); d.y = __builtin_amdgcn_exp2f(t.y); d = d + 1.0f; \
;                     f32x2 q2; q2.x = __builtin_amdgcn_rcpf(d.x); q2.y = __builtin_amdgcn_rcpf(d.y); const f32x2 o2 = (f32x2){bflo(BW), bfhi(BW)} + (f32x2){bflo(PW), bfhi(PW)} * q2; r[kk] = o2.x; r[kk + 1] = o2.y; }
; __device__ __forceinline__ void rstd8(const float* ss, int row0, int fq, float (&rs)[8]) {
;     f32x4 a[8];
; #pragma unroll
;     for (int k = 0; k < 8; ++k) a[k] = *(const f32x4*)(ss + (size_t)(row0 + (k >> 2) * 128 + (k & 3) * 16) * 16 + 4 * fq);
; #pragma unroll
;     for (int k = 0; k < 8; ++k) { float s = (a[k][0] + a[k][1]) + (a[k][2] + a[k][3]); s += __shfl_xor(s, 16); s += __shfl_xor(s, 32); rs[k] = __builtin_amdgcn_rsqf(s * (1.f / 1024.f) + EPS); }
;     __device__ __forceinline__ void operator()(const pg8::f32x4 (&acc)[2][2][4][2], const Unit& u, int wr, int wc, int fr, int fq) const {
;     ...
;             for (int bj = 0; bj < 2; ++bj) { const size_t o = (size_t)row * DM_ + col0 + bj * HALF; const v4u bw = cb[bj], pw = cp[bj];
;                 const float c1 = -1.4426950408889634f * rs; float r[8];
;     ...
;                 { const f32x4 a0 = acc[ai][bj][m][0], a1 = acc[ai][bj][m][1];
;                   PLE2(0, a0, 0, bw.x, pw.x) PLE2(2, a0, 2, bw.y, pw.y) PLE2(4, a1, 0, bw.z, pw.z) PLE2(6, a1, 2, bw.w, pw.w) }
;     ...
; #pragma unroll
;                 for (int e = 0; e < 8; ++e) q += r[e] * r[e];
;                 v4u w; w.x = cvt_pk_bf16(r[0], r[1]); w.y = cvt_pk_bf16(r[2], r[3]); w.z = cvt_pk_bf16(r[4], r[5]); w.w = cvt_pk_bf16(r[6], r[7]); *(v4u*)(out + o) = w; }
;             q += __shfl_xor(q, 16); q += __shfl_xor(q, 32); if (fq == 0) ssq[(size_t)row * 16 + u.pn * 4 + wc] = q; }
.LBB0_916:
	s_or_b64 exec, exec, s[36:37]
	v_add_f32_e32 v50, v197, v198
	v_or_b32_e32 v82, 32, v166
	v_fmamk_f32 v50, v50, 0x3a800000, v190
	v_ashrrev_i32_e32 v83, 31, v82
	v_rsq_f32_e32 v56, v50
	s_waitcnt lgkmcnt(0)
	v_lshlrev_b64 v[50:51], 10, v[82:83]
	v_lshl_add_u64 v[50:51], v[50:51], 0, v[164:165]
	v_lshlrev_b64 v[50:51], 1, v[50:51]
	v_lshl_add_u64 v[52:53], s[10:11], 0, v[50:51]
	v_lshl_add_u64 v[54:55], s[16:17], 0, v[50:51]
	v_or_b32_e32 v50, 0x100, v50
	global_load_dwordx4 v[62:65], v[52:53], off
	global_load_dwordx4 v[58:61], v[54:55], off
	v_lshl_add_u64 v[52:53], s[10:11], 0, v[50:51]
	v_lshl_add_u64 v[50:51], s[16:17], 0, v[50:51]
	v_mul_f32_e32 v84, 0xbfb8aa3b, v56
	global_load_dwordx4 v[54:57], v[52:53], off
	s_nop 0
	global_load_dwordx4 v[50:53], v[50:51], off
	v_pk_mul_f32 v[48:49], v[48:49], v[84:85] op_sel_hi:[1,0]
	v_pk_mul_f32 v[42:43], v[42:43], v[84:85] op_sel_hi:[1,0]
	v_exp_f32_e32 v48, v48
	v_exp_f32_e32 v49, v49
	v_exp_f32_e32 v42, v42
	v_exp_f32_e32 v43, v43
	v_pk_mul_f32 v[46:47], v[46:47], v[84:85] op_sel_hi:[1,0]
	v_pk_add_f32 v[48:49], v[48:49], 1.0 op_sel_hi:[1,0]
	v_exp_f32_e32 v46, v46
	v_exp_f32_e32 v47, v47
	v_rcp_f32_e32 v48, v48
	v_rcp_f32_e32 v49, v49
	v_pk_add_f32 v[42:43], v[42:43], 1.0 op_sel_hi:[1,0]
	v_pk_mul_f32 v[44:45], v[44:45], v[84:85] op_sel_hi:[1,0]
	v_rcp_f32_e32 v42, v42
	v_rcp_f32_e32 v43, v43
	v_exp_f32_e32 v44, v44
	v_exp_f32_e32 v45, v45
	v_pk_mul_f32 v[38:39], v[38:39], v[84:85] op_sel_hi:[1,0]
	v_pk_mul_f32 v[40:41], v[40:41], v[84:85] op_sel_hi:[1,0]
	v_exp_f32_e32 v38, v38
	v_exp_f32_e32 v39, v39
	s_waitcnt vmcnt(9)
	v_lshlrev_b32_e32 v88, 16, v78
	v_and_b32_e32 v89, 0xffff0000, v78
	s_waitcnt vmcnt(8)
	v_lshlrev_b32_e32 v90, 16, v74
	v_and_b32_e32 v91, 0xffff0000, v74
	v_lshlrev_b32_e32 v78, 16, v79
	v_and_b32_e32 v79, 0xffff0000, v79
	v_lshlrev_b32_e32 v74, 16, v75
	v_and_b32_e32 v75, 0xffff0000, v75
	v_exp_f32_e32 v40, v40
	v_exp_f32_e32 v41, v41
	v_pk_mul_f32 v[34:35], v[34:35], v[84:85] op_sel_hi:[1,0]
	v_pk_add_f32 v[46:47], v[46:47], 1.0 op_sel_hi:[1,0]
	v_pk_fma_f32 v[48:49], v[48:49], v[74:75], v[78:79]
	v_lshlrev_b32_e32 v74, 16, v80
	v_and_b32_e32 v75, 0xffff0000, v80
	v_lshlrev_b32_e32 v78, 16, v76
	v_and_b32_e32 v79, 0xffff0000, v76
	v_exp_f32_e32 v34, v34
	v_exp_f32_e32 v35, v35
	v_rcp_f32_e32 v46, v46
	v_rcp_f32_e32 v47, v47
	v_pk_fma_f32 v[74:75], v[42:43], v[78:79], v[74:75]
	v_pk_add_f32 v[42:43], v[44:45], 1.0 op_sel_hi:[1,0]
	v_pk_add_f32 v[38:39], v[38:39], 1.0 op_sel_hi:[1,0]
	v_rcp_f32_e32 v42, v42
	v_rcp_f32_e32 v43, v43
	v_rcp_f32_e32 v38, v38
	v_rcp_f32_e32 v39, v39
	v_pk_add_f32 v[40:41], v[40:41], 1.0 op_sel_hi:[1,0]
	v_pk_add_f32 v[34:35], v[34:35], 1.0 op_sel_hi:[1,0]
	v_rcp_f32_e32 v40, v40
	v_rcp_f32_e32 v41, v41
	v_pk_mul_f32 v[36:37], v[36:37], v[84:85] op_sel_hi:[1,0]
	v_pk_fma_f32 v[46:47], v[46:47], v[90:91], v[88:89]
	v_lshlrev_b32_e32 v44, 16, v81
	v_and_b32_e32 v45, 0xffff0000, v81
	v_lshlrev_b32_e32 v76, 16, v77
	v_and_b32_e32 v77, 0xffff0000, v77
	v_rcp_f32_e32 v34, v34
	v_rcp_f32_e32 v35, v35
	v_exp_f32_e32 v36, v36
	v_exp_f32_e32 v37, v37
	v_pk_fma_f32 v[76:77], v[42:43], v[76:77], v[44:45]
	v_pk_mul_f32 v[78:79], v[46:47], v[46:47]
	v_pk_mul_f32 v[80:81], v[48:49], v[48:49]
	v_cvt_pk_bf16_f32 v42, v46, v47
	v_cvt_pk_bf16_f32 v43, v48, v49
	s_waitcnt vmcnt(7)
	v_lshlrev_b32_e32 v46, 16, v70
	v_and_b32_e32 v47, 0xffff0000, v70
	s_waitcnt vmcnt(6)
	v_lshlrev_b32_e32 v48, 16, v66
	v_and_b32_e32 v49, 0xffff0000, v66
	v_pk_fma_f32 v[38:39], v[38:39], v[48:49], v[46:47]
	v_lshlrev_b32_e32 v46, 16, v71
	v_and_b32_e32 v47, 0xffff0000, v71
	v_lshlrev_b32_e32 v48, 16, v67
	v_and_b32_e32 v49, 0xffff0000, v67
	v_pk_fma_f32 v[40:41], v[40:41], v[48:49], v[46:47]
	v_lshlrev_b32_e32 v46, 16, v72
	v_and_b32_e32 v47, 0xffff0000, v72
	v_lshlrev_b32_e32 v48, 16, v68
	v_and_b32_e32 v49, 0xffff0000, v68
	v_add_f32_e32 v70, v78, v79
	v_pk_fma_f32 v[46:47], v[34:35], v[48:49], v[46:47]
	v_pk_add_f32 v[34:35], v[36:37], 1.0 op_sel_hi:[1,0]
	v_add_f32_e32 v70, v80, v70
	v_pk_mul_f32 v[88:89], v[74:75], v[74:75]
	v_rcp_f32_e32 v34, v34
	v_rcp_f32_e32 v35, v35
	v_add_f32_e32 v70, v81, v70
	v_add_f32_e32 v70, v88, v70
	v_pk_mul_f32 v[90:91], v[76:77], v[76:77]
	v_add_f32_e32 v70, v89, v70
	v_lshlrev_b32_e32 v36, 16, v73
	v_and_b32_e32 v37, 0xffff0000, v73
	v_lshlrev_b32_e32 v48, 16, v69
	v_and_b32_e32 v49, 0xffff0000, v69
	v_add_f32_e32 v70, v90, v70
	v_pk_fma_f32 v[48:49], v[34:35], v[48:49], v[36:37]
	v_pk_mul_f32 v[34:35], v[38:39], v[38:39]
	v_add_f32_e32 v70, v91, v70
	v_add_f32_e32 v34, v34, v70
	v_pk_mul_f32 v[36:37], v[40:41], v[40:41]
	v_add_f32_e32 v34, v35, v34
	v_add_f32_e32 v34, v36, v34
	v_pk_mul_f32 v[66:67], v[46:47], v[46:47]
	v_add_f32_e32 v34, v37, v34
	v_add_f32_e32 v34, v66, v34
	v_pk_mul_f32 v[68:69], v[48:49], v[48:49]
	v_add_f32_e32 v34, v67, v34
	v_add_f32_e32 v34, v68, v34
	v_add_f32_e32 v37, v69, v34
	v_mov_b32_e32 v68, v37
	s_nop 1
	v_permlane16_swap_b32 v37, v68
	v_lshlrev_b64 v[86:87], 11, v[98:99]
	v_lshl_add_u64 v[34:35], s[18:19], 0, v[86:87]
	v_lshl_add_u64 v[66:67], v[164:165], 1, v[34:35]
	v_cvt_pk_bf16_f32 v44, v74, v75
	s_waitcnt lgkmcnt(0)
	v_add_f32_e32 v34, v37, v68
	v_mov_b32_e32 v35, v34
	s_nop 1
	v_permlane32_swap_b32 v34, v35
	v_cvt_pk_bf16_f32 v45, v76, v77
	global_store_dwordx4 v[66:67], v[42:45], off
	v_cvt_pk_bf16_f32 v36, v38, v39
	v_cvt_pk_bf16_f32 v37, v40, v41
	v_cvt_pk_bf16_f32 v38, v46, v47
	v_cvt_pk_bf16_f32 v39, v48, v49
	global_store_dwordx4 v[66:67], v[36:39], off offset:256
	s_and_saveexec_b64 s[36:37], s[6:7]
	s_cbranch_execz .LBB0_918
	v_lshlrev_b64 v[36:37], 6, v[98:99]
	v_lshl_add_u64 v[36:37], s[20:21], 0, v[36:37]
	v_lshl_add_u64 v[36:37], s[4:5], 2, v[36:37]
	s_lshl_b32 s12, s49, 2
	v_lshl_add_u64 v[36:37], v[36:37], 0, s[12:13]
	s_waitcnt lgkmcnt(0)
	v_add_f32_e32 v34, v34, v35
	global_store_dword v[36:37], v34, off
; __device__ __forceinline__ unsigned cvt_pk_bf16(float lo, float hi) { unsigned r; asm volatile("v_cvt_pk_bf16_f32 %0, %1, %2" : "=v"(r) : "v"(lo), "v"(hi)); return r; }
; #define PLE2(kk, A, e0, BW, PW) { const f32x2 t = (f32x2){A[e0], A[e0 + 1]} * c1; f32x2 d; d.x = __builtin_amdgcn_exp2f(t.x); d.y = __builtin_amdgcn_exp2f(t.y); d = d + 1.0f; \
;                     f32x2 q2; q2.x = __builtin_amdgcn_rcpf(d.x); q2.y = __builtin_amdgcn_rcpf(d.y); const f32x2 o2 = (f32x2){bflo(BW), bfhi(BW)} + (f32x2){bflo(PW), bfhi(PW)} * q2; r[kk] = o2.x; r[kk + 1] = o2.y; }
; __device__ __forceinline__ void rstd8(const float* ss, int row0, int fq, float (&rs)[8]) {
;     f32x4 a[8];
; #pragma unroll
;     for (int k = 0; k < 8; ++k) a[k] = *(const f32x4*)(ss + (size_t)(row0 + (k >> 2) * 128 + (k & 3) * 16) * 16 + 4 * fq);
; #pragma unroll
;     for (int k = 0; k < 8; ++k) { float s = (a[k][0] + a[k][1]) + (a[k][2] + a[k][3]); s += __shfl_xor(s, 16); s += __shfl_xor(s, 32); rs[k] = __builtin_amdgcn_rsqf(s * (1.f / 1024.f) + EPS); }
;     __device__ __forceinline__ void operator()(const pg8::f32x4 (&acc)[2][2][4][2], const Unit& u, int wr, int wc, int fr, int fq) const {
;     ...
;             for (int bj = 0; bj < 2; ++bj) { const size_t o = (size_t)row * DM_ + col0 + bj * HALF; const v4u bw = cb[bj], pw = cp[bj];
;                 const float c1 = -1.4426950408889634f * rs; float r[8];
;     ...
;                 { const f32x4 a0 = acc[ai][bj][m][0], a1 = acc[ai][bj][m][1];
;                   PLE2(0, a0, 0, bw.x, pw.x) PLE2(2, a0, 2, bw.y, pw.y) PLE2(4, a1, 0, bw.z, pw.z) PLE2(6, a1, 2, bw.w, pw.w) }
;     ...
; #pragma unroll
;                 for (int e = 0; e < 8; ++e) q += r[e] * r[e];
;                 v4u w; w.x = cvt_pk_bf16(r[0], r[1]); w.y = cvt_pk_bf16(r[2], r[3]); w.z = cvt_pk_bf16(r[4], r[5]); w.w = cvt_pk_bf16(r[6], r[7]); *(v4u*)(out + o) = w; }
;             q += __shfl_xor(q, 16); q += __shfl_xor(q, 32); if (fq == 0) ssq[(size_t)row * 16 + u.pn * 4 + wc] = q; }
.LBB0_918:
	s_or_b64 exec, exec, s[36:37]
	v_add_f32_e32 v34, v195, v196
	v_or_b32_e32 v66, 48, v166
	v_fmamk_f32 v34, v34, 0x3a800000, v190
	v_ashrrev_i32_e32 v67, 31, v66
	v_rsq_f32_e32 v40, v34
	s_waitcnt lgkmcnt(0)
	v_lshlrev_b64 v[34:35], 10, v[66:67]
	v_lshl_add_u64 v[34:35], v[34:35], 0, v[164:165]
	v_lshlrev_b64 v[34:35], 1, v[34:35]
	v_lshl_add_u64 v[36:37], s[10:11], 0, v[34:35]
	v_lshl_add_u64 v[38:39], s[16:17], 0, v[34:35]
	v_or_b32_e32 v34, 0x100, v34
	global_load_dwordx4 v[46:49], v[36:37], off
	global_load_dwordx4 v[42:45], v[38:39], off
	v_lshl_add_u64 v[36:37], s[10:11], 0, v[34:35]
	v_lshl_add_u64 v[34:35], s[16:17], 0, v[34:35]
	v_mul_f32_e32 v68, 0xbfb8aa3b, v40
	global_load_dwordx4 v[38:41], v[36:37], off
	s_nop 0
	global_load_dwordx4 v[34:37], v[34:35], off
	v_pk_mul_f32 v[32:33], v[32:33], v[68:69] op_sel_hi:[1,0]
	v_pk_mul_f32 v[26:27], v[26:27], v[68:69] op_sel_hi:[1,0]
	v_exp_f32_e32 v32, v32
	v_exp_f32_e32 v33, v33
	v_exp_f32_e32 v26, v26
	v_exp_f32_e32 v27, v27
	v_pk_mul_f32 v[30:31], v[30:31], v[68:69] op_sel_hi:[1,0]
	v_pk_add_f32 v[32:33], v[32:33], 1.0 op_sel_hi:[1,0]
	v_exp_f32_e32 v30, v30
	v_exp_f32_e32 v31, v31
	v_rcp_f32_e32 v32, v32
	v_rcp_f32_e32 v33, v33
	v_pk_add_f32 v[26:27], v[26:27], 1.0 op_sel_hi:[1,0]
	v_pk_mul_f32 v[28:29], v[28:29], v[68:69] op_sel_hi:[1,0]
	v_rcp_f32_e32 v26, v26
	v_rcp_f32_e32 v27, v27
	v_exp_f32_e32 v28, v28
	v_exp_f32_e32 v29, v29
	v_pk_mul_f32 v[22:23], v[22:23], v[68:69] op_sel_hi:[1,0]
	v_pk_mul_f32 v[24:25], v[24:25], v[68:69] op_sel_hi:[1,0]
	v_exp_f32_e32 v22, v22
	v_exp_f32_e32 v23, v23
	s_waitcnt vmcnt(9)
	v_lshlrev_b32_e32 v72, 16, v62
	v_and_b32_e32 v73, 0xffff0000, v62
	s_waitcnt vmcnt(8)
	v_lshlrev_b32_e32 v74, 16, v58
	v_and_b32_e32 v75, 0xffff0000, v58
	v_lshlrev_b32_e32 v62, 16, v63
	v_and_b32_e32 v63, 0xffff0000, v63
	v_lshlrev_b32_e32 v58, 16, v59
	v_and_b32_e32 v59, 0xffff0000, v59
	v_exp_f32_e32 v24, v24
	v_exp_f32_e32 v25, v25
	v_pk_mul_f32 v[18:19], v[18:19], v[68:69] op_sel_hi:[1,0]
	v_pk_add_f32 v[30:31], v[30:31], 1.0 op_sel_hi:[1,0]
	v_pk_fma_f32 v[32:33], v[32:33], v[58:59], v[62:63]
	v_lshlrev_b32_e32 v58, 16, v64
	v_and_b32_e32 v59, 0xffff0000, v64
	v_lshlrev_b32_e32 v62, 16, v60
	v_and_b32_e32 v63, 0xffff0000, v60
	v_exp_f32_e32 v18, v18
	v_exp_f32_e32 v19, v19
	v_rcp_f32_e32 v30, v30
	v_rcp_f32_e32 v31, v31
	v_pk_fma_f32 v[58:59], v[26:27], v[62:63], v[58:59]
	v_pk_add_f32 v[26:27], v[28:29], 1.0 op_sel_hi:[1,0]
	v_pk_add_f32 v[22:23], v[22:23], 1.0 op_sel_hi:[1,0]
	v_rcp_f32_e32 v26, v26
	v_rcp_f32_e32 v27, v27
	v_rcp_f32_e32 v22, v22
	v_rcp_f32_e32 v23, v23
	v_pk_add_f32 v[24:25], v[24:25], 1.0 op_sel_hi:[1,0]
	v_pk_add_f32 v[18:19], v[18:19], 1.0 op_sel_hi:[1,0]
	v_rcp_f32_e32 v24, v24
	v_rcp_f32_e32 v25, v25
	v_pk_mul_f32 v[20:21], v[20:21], v[68:69] op_sel_hi:[1,0]
	v_pk_fma_f32 v[30:31], v[30:31], v[74:75], v[72:73]
	v_lshlrev_b32_e32 v28, 16, v65
	v_and_b32_e32 v29, 0xffff0000, v65
	v_lshlrev_b32_e32 v60, 16, v61
	v_and_b32_e32 v61, 0xffff0000, v61
	v_rcp_f32_e32 v18, v18
	v_rcp_f32_e32 v19, v19
	v_exp_f32_e32 v20, v20
	v_exp_f32_e32 v21, v21
	v_pk_fma_f32 v[60:61], v[26:27], v[60:61], v[28:29]
	v_pk_mul_f32 v[62:63], v[30:31], v[30:31]
	v_pk_mul_f32 v[64:65], v[32:33], v[32:33]
	v_cvt_pk_bf16_f32 v26, v30, v31
	v_cvt_pk_bf16_f32 v27, v32, v33
	s_waitcnt vmcnt(7)
	v_lshlrev_b32_e32 v30, 16, v54
	v_and_b32_e32 v31, 0xffff0000, v54
	s_waitcnt vmcnt(6)
	v_lshlrev_b32_e32 v32, 16, v50
	v_and_b32_e32 v33, 0xffff0000, v50
	v_pk_fma_f32 v[22:23], v[22:23], v[32:33], v[30:31]
	v_lshlrev_b32_e32 v30, 16, v55
	v_and_b32_e32 v31, 0xffff0000, v55
	v_lshlrev_b32_e32 v32, 16, v51
	v_and_b32_e32 v33, 0xffff0000, v51
	v_pk_fma_f32 v[24:25], v[24:25], v[32:33], v[30:31]
	v_lshlrev_b32_e32 v30, 16, v56
	v_and_b32_e32 v31, 0xffff0000, v56
	v_lshlrev_b32_e32 v32, 16, v52
	v_and_b32_e32 v33, 0xffff0000, v52
	v_add_f32_e32 v54, v62, v63
	v_pk_fma_f32 v[30:31], v[18:19], v[32:33], v[30:31]
	v_pk_add_f32 v[18:19], v[20:21], 1.0 op_sel_hi:[1,0]
	v_add_f32_e32 v54, v64, v54
	v_pk_mul_f32 v[72:73], v[58:59], v[58:59]
	v_rcp_f32_e32 v18, v18
	v_rcp_f32_e32 v19, v19
	v_add_f32_e32 v54, v65, v54
	v_add_f32_e32 v54, v72, v54
	v_pk_mul_f32 v[74:75], v[60:61], v[60:61]
	v_add_f32_e32 v54, v73, v54
	v_lshlrev_b32_e32 v20, 16, v57
	v_and_b32_e32 v21, 0xffff0000, v57
	v_lshlrev_b32_e32 v32, 16, v53
	v_and_b32_e32 v33, 0xffff0000, v53
	v_add_f32_e32 v54, v74, v54
	v_pk_fma_f32 v[32:33], v[18:19], v[32:33], v[20:21]
	v_pk_mul_f32 v[18:19], v[22:23], v[22:23]
	v_add_f32_e32 v54, v75, v54
	v_add_f32_e32 v18, v18, v54
	v_pk_mul_f32 v[20:21], v[24:25], v[24:25]
	v_add_f32_e32 v18, v19, v18
	v_add_f32_e32 v18, v20, v18
	v_pk_mul_f32 v[50:51], v[30:31], v[30:31]
	v_add_f32_e32 v18, v21, v18
	v_add_f32_e32 v18, v50, v18
	v_pk_mul_f32 v[52:53], v[32:33], v[32:33]
	v_add_f32_e32 v18, v51, v18
	v_add_f32_e32 v18, v52, v18
	v_add_f32_e32 v21, v53, v18
	v_mov_b32_e32 v52, v21
	s_nop 1
	v_permlane16_swap_b32 v21, v52
	v_lshlrev_b64 v[70:71], 11, v[82:83]
	v_lshl_add_u64 v[18:19], s[18:19], 0, v[70:71]
	v_lshl_add_u64 v[50:51], v[164:165], 1, v[18:19]
	v_cvt_pk_bf16_f32 v28, v58, v59
	s_waitcnt lgkmcnt(0)
	v_add_f32_e32 v18, v21, v52
	v_mov_b32_e32 v19, v18
	s_nop 1
	v_permlane32_swap_b32 v18, v19
	v_cvt_pk_bf16_f32 v29, v60, v61
	global_store_dwordx4 v[50:51], v[26:29], off
	v_cvt_pk_bf16_f32 v20, v22, v23
	v_cvt_pk_bf16_f32 v21, v24, v25
	v_cvt_pk_bf16_f32 v22, v30, v31
	v_cvt_pk_bf16_f32 v23, v32, v33
	global_store_dwordx4 v[50:51], v[20:23], off offset:256
	s_and_saveexec_b64 s[36:37], s[6:7]
	s_cbranch_execz .LBB0_920
	v_lshlrev_b64 v[20:21], 6, v[82:83]
	v_lshl_add_u64 v[20:21], s[20:21], 0, v[20:21]
	v_lshl_add_u64 v[20:21], s[4:5], 2, v[20:21]
	s_lshl_b32 s12, s49, 2
	v_lshl_add_u64 v[20:21], v[20:21], 0, s[12:13]
	s_waitcnt lgkmcnt(0)
	v_add_f32_e32 v18, v18, v19
	global_store_dword v[20:21], v18, off
; __device__ __forceinline__ unsigned cvt_pk_bf16(float lo, float hi) { unsigned r; asm volatile("v_cvt_pk_bf16_f32 %0, %1, %2" : "=v"(r) : "v"(lo), "v"(hi)); return r; }
; #define PLE2(kk, A, e0, BW, PW) { const f32x2 t = (f32x2){A[e0], A[e0 + 1]} * c1; f32x2 d; d.x = __builtin_amdgcn_exp2f(t.x); d.y = __builtin_amdgcn_exp2f(t.y); d = d + 1.0f; \
;                     f32x2 q2; q2.x = __builtin_amdgcn_rcpf(d.x); q2.y = __builtin_amdgcn_rcpf(d.y); const f32x2 o2 = (f32x2){bflo(BW), bfhi(BW)} + (f32x2){bflo(PW), bfhi(PW)} * q2; r[kk] = o2.x; r[kk + 1] = o2.y; }
;     __device__ __forceinline__ void operator()(const pg8::f32x4 (&acc)[2][2][4][2], const Unit& u, int wr, int wc, int fr, int fq) const {
;     ...
;         for (int k = 0; k < 8; ++k) { const int ai = k >> 2, m = k & 3; const int row = row0 + ai * HALF + m * 16; const float rs = rsv[k]; float q = 0.f;
;             v4u cb[2], cp[2];
; #pragma unroll
;             for (int bj = 0; bj < 2; ++bj) { cb[bj] = nb[bj]; cp[bj] = np[bj]; }
;             if (k < 7) {
; #pragma unroll
;                 for (int bj = 0; bj < 2; ++bj) { const size_t o = (size_t)(row0 + ((k + 1) >> 2) * HALF + ((k + 1) & 3) * 16) * DM_ + col0 + bj * HALF; nb[bj] = *(const v4u*)(base + o); np[bj] = *(const v4u*)(pp + o); } }
; #pragma unroll
;             for (int bj = 0; bj < 2; ++bj) { const size_t o = (size_t)row * DM_ + col0 + bj * HALF; const v4u bw = cb[bj], pw = cp[bj];
;                 const float c1 = -1.4426950408889634f * rs; float r[8];
;     ...
;                 { const f32x4 a0 = acc[ai][bj][m][0], a1 = acc[ai][bj][m][1];
;                   PLE2(0, a0, 0, bw.x, pw.x) PLE2(2, a0, 2, bw.y, pw.y) PLE2(4, a1, 0, bw.z, pw.z) PLE2(6, a1, 2, bw.w, pw.w) }
;     ...
; #pragma unroll
;                 for (int e = 0; e < 8; ++e) q += r[e] * r[e];
;                 v4u w; w.x = cvt_pk_bf16(r[0], r[1]); w.y = cvt_pk_bf16(r[2], r[3]); w.z = cvt_pk_bf16(r[4], r[5]); w.w = cvt_pk_bf16(r[6], r[7]); *(v4u*)(out + o) = w; }
;             q += __shfl_xor(q, 16); q += __shfl_xor(q, 32); if (fq == 0) ssq[(size_t)row * 16 + u.pn * 4 + wc] = q; }
.LBB0_920:
	s_or_b64 exec, exec, s[36:37]
	v_add_f32_e32 v18, v193, v194
	v_fmamk_f32 v18, v18, 0x3a800000, v190
	v_rsq_f32_e32 v20, v18
	s_waitcnt vmcnt(5)
	v_lshlrev_b32_e32 v22, 16, v46
	v_and_b32_e32 v23, 0xffff0000, v46
	s_waitcnt vmcnt(4)
	v_lshlrev_b32_e32 v24, 16, v42
	v_mul_f32_e32 v20, 0xbfb8aa3b, v20
	v_pk_mul_f32 v[14:15], v[14:15], v[20:21] op_sel_hi:[1,0]
	v_pk_mul_f32 v[16:17], v[16:17], v[20:21] op_sel_hi:[1,0]
	v_exp_f32_e32 v14, v14
	v_exp_f32_e32 v15, v15
	v_exp_f32_e32 v16, v16
	v_exp_f32_e32 v17, v17
	v_pk_mul_f32 v[10:11], v[10:11], v[20:21] op_sel_hi:[1,0]
	v_pk_add_f32 v[14:15], v[14:15], 1.0 op_sel_hi:[1,0]
	v_exp_f32_e32 v10, v10
	v_exp_f32_e32 v11, v11
	v_rcp_f32_e32 v14, v14
	v_rcp_f32_e32 v15, v15
	v_pk_add_f32 v[16:17], v[16:17], 1.0 op_sel_hi:[1,0]
	v_pk_add_f32 v[10:11], v[10:11], 1.0 op_sel_hi:[1,0]
	v_rcp_f32_e32 v16, v16
	v_rcp_f32_e32 v17, v17
	v_pk_mul_f32 v[12:13], v[12:13], v[20:21] op_sel_hi:[1,0]
	v_rcp_f32_e32 v10, v10
	v_rcp_f32_e32 v11, v11
	v_exp_f32_e32 v12, v12
	v_exp_f32_e32 v13, v13
	v_pk_mul_f32 v[6:7], v[6:7], v[20:21] op_sel_hi:[1,0]
	v_and_b32_e32 v25, 0xffff0000, v42
	v_exp_f32_e32 v6, v6
	v_exp_f32_e32 v7, v7
	v_pk_mul_f32 v[8:9], v[8:9], v[20:21] op_sel_hi:[1,0]
	v_pk_fma_f32 v[14:15], v[14:15], v[24:25], v[22:23]
	v_lshlrev_b32_e32 v22, 16, v47
	v_and_b32_e32 v23, 0xffff0000, v47
	v_lshlrev_b32_e32 v24, 16, v43
	v_and_b32_e32 v25, 0xffff0000, v43
	v_exp_f32_e32 v8, v8
	v_exp_f32_e32 v9, v9
	v_pk_mul_f32 v[2:3], v[2:3], v[20:21] op_sel_hi:[1,0]
	v_pk_fma_f32 v[16:17], v[16:17], v[24:25], v[22:23]
	v_lshlrev_b32_e32 v22, 16, v48
	v_and_b32_e32 v23, 0xffff0000, v48
	v_lshlrev_b32_e32 v24, 16, v44
	v_and_b32_e32 v25, 0xffff0000, v44
	v_exp_f32_e32 v2, v2
	v_exp_f32_e32 v3, v3
	v_pk_fma_f32 v[22:23], v[10:11], v[24:25], v[22:23]
	v_pk_add_f32 v[10:11], v[12:13], 1.0 op_sel_hi:[1,0]
	v_pk_add_f32 v[6:7], v[6:7], 1.0 op_sel_hi:[1,0]
	v_rcp_f32_e32 v10, v10
	v_rcp_f32_e32 v11, v11
	v_rcp_f32_e32 v6, v6
	v_rcp_f32_e32 v7, v7
	v_pk_add_f32 v[8:9], v[8:9], 1.0 op_sel_hi:[1,0]
	v_pk_add_f32 v[2:3], v[2:3], 1.0 op_sel_hi:[1,0]
	v_rcp_f32_e32 v8, v8
	v_rcp_f32_e32 v9, v9
	v_pk_mul_f32 v[4:5], v[4:5], v[20:21] op_sel_hi:[1,0]
	v_lshlrev_b32_e32 v12, 16, v49
	v_and_b32_e32 v13, 0xffff0000, v49
	v_lshlrev_b32_e32 v24, 16, v45
	v_and_b32_e32 v25, 0xffff0000, v45
	v_rcp_f32_e32 v2, v2
	v_rcp_f32_e32 v3, v3
	v_exp_f32_e32 v4, v4
	v_exp_f32_e32 v5, v5
	v_pk_fma_f32 v[24:25], v[10:11], v[24:25], v[12:13]
	v_pk_mul_f32 v[26:27], v[14:15], v[14:15]
	v_pk_mul_f32 v[28:29], v[16:17], v[16:17]
	v_cvt_pk_bf16_f32 v10, v14, v15
	v_cvt_pk_bf16_f32 v11, v16, v17
	s_waitcnt vmcnt(3)
	v_lshlrev_b32_e32 v14, 16, v38
	v_and_b32_e32 v15, 0xffff0000, v38
	s_waitcnt vmcnt(2)
	v_lshlrev_b32_e32 v16, 16, v34
	v_and_b32_e32 v17, 0xffff0000, v34
	v_pk_fma_f32 v[6:7], v[6:7], v[16:17], v[14:15]
	v_lshlrev_b32_e32 v14, 16, v39
	v_and_b32_e32 v15, 0xffff0000, v39
	v_lshlrev_b32_e32 v16, 16, v35
	v_and_b32_e32 v17, 0xffff0000, v35
	v_pk_mul_f32 v[32:33], v[24:25], v[24:25]
	v_cvt_pk_bf16_f32 v12, v22, v23
	v_cvt_pk_bf16_f32 v13, v24, v25
	v_pk_fma_f32 v[8:9], v[8:9], v[16:17], v[14:15]
	v_lshlrev_b32_e32 v14, 16, v40
	v_and_b32_e32 v15, 0xffff0000, v40
	v_lshlrev_b32_e32 v16, 16, v36
	v_and_b32_e32 v17, 0xffff0000, v36
	v_add_f32_e32 v24, v26, v27
	v_pk_fma_f32 v[14:15], v[2:3], v[16:17], v[14:15]
	v_pk_add_f32 v[2:3], v[4:5], 1.0 op_sel_hi:[1,0]
	v_add_f32_e32 v24, v28, v24
	v_pk_mul_f32 v[30:31], v[22:23], v[22:23]
	v_rcp_f32_e32 v2, v2
	v_rcp_f32_e32 v3, v3
	v_add_f32_e32 v24, v29, v24
	v_add_f32_e32 v24, v30, v24
	v_add_f32_e32 v24, v31, v24
	v_lshlrev_b32_e32 v4, 16, v41
	v_and_b32_e32 v5, 0xffff0000, v41
	v_lshlrev_b32_e32 v16, 16, v37
	v_and_b32_e32 v17, 0xffff0000, v37
	v_add_f32_e32 v24, v32, v24
	v_pk_fma_f32 v[16:17], v[2:3], v[16:17], v[4:5]
	v_pk_mul_f32 v[2:3], v[6:7], v[6:7]
	v_add_f32_e32 v24, v33, v24
	v_add_f32_e32 v2, v2, v24
	v_pk_mul_f32 v[4:5], v[8:9], v[8:9]
	v_add_f32_e32 v2, v3, v2
	v_add_f32_e32 v2, v4, v2
	v_pk_mul_f32 v[20:21], v[14:15], v[14:15]
	v_add_f32_e32 v2, v5, v2
	v_add_f32_e32 v2, v20, v2
	v_pk_mul_f32 v[22:23], v[16:17], v[16:17]
	v_add_f32_e32 v2, v21, v2
	v_add_f32_e32 v2, v22, v2
	v_add_f32_e32 v5, v23, v2
	v_mov_b32_e32 v20, v5
	s_nop 1
	v_permlane16_swap_b32 v5, v20
	s_waitcnt lgkmcnt(1)
	v_lshlrev_b64 v[18:19], 11, v[66:67]
	v_lshl_add_u64 v[2:3], s[18:19], 0, v[18:19]
	v_lshl_add_u64 v[18:19], v[164:165], 1, v[2:3]
	global_store_dwordx4 v[18:19], v[10:13], off
	s_waitcnt lgkmcnt(0)
	v_add_f32_e32 v2, v5, v20
	v_mov_b32_e32 v3, v2
	s_nop 1
	v_permlane32_swap_b32 v2, v3
	v_cvt_pk_bf16_f32 v4, v6, v7
	v_cvt_pk_bf16_f32 v5, v8, v9
	v_cvt_pk_bf16_f32 v6, v14, v15
	v_cvt_pk_bf16_f32 v7, v16, v17
	global_store_dwordx4 v[18:19], v[4:7], off offset:256
	s_and_saveexec_b64 s[36:37], s[6:7]
	s_cbranch_execz .LBB0_922
	v_lshlrev_b64 v[4:5], 6, v[66:67]
	v_lshl_add_u64 v[4:5], s[20:21], 0, v[4:5]
	v_lshl_add_u64 v[4:5], s[4:5], 2, v[4:5]
	s_lshl_b32 s12, s49, 2
	v_lshl_add_u64 v[4:5], v[4:5], 0, s[12:13]
	s_waitcnt lgkmcnt(0)
	v_add_f32_e32 v2, v2, v3
	global_store_dword v[4:5], v2, off

; __device__ __forceinline__ void rstd8(const float* ss, int row0, int fq, float (&rs)[8]) {
;     f32x4 a[8];
; #pragma unroll
;     for (int k = 0; k < 8; ++k) a[k] = *(const f32x4*)(ss + (size_t)(row0 + (k >> 2) * 128 + (k & 3) * 16) * 16 + 4 * fq);
; #pragma unroll
;     for (int k = 0; k < 8; ++k) { float s = (a[k][0] + a[k][1]) + (a[k][2] + a[k][3]); s += __shfl_xor(s, 16); s += __shfl_xor(s, 32); rs[k] = __builtin_amdgcn_rsqf(s * (1.f / 1024.f) + EPS); }
; }
;     __device__ __forceinline__ void operator()(const pg8::f32x4 (&acc)[2][2][4][2], const Unit& u, int wr, int wc, int fr, int fq) const {
;         const int pn = u.pn; const int row0 = u.pm * BM + wr * 64 + fr; const int sp = pn / tps, pt = pn - sp * tps; bf16* const Ob = O + (size_t)sp * sstride;
;         float rsv[8]; rstd8(ss, row0, fq, rsv);
;         if (pn < rope_tiles) {
.LBB0_992:
	s_lshl_b32 s1, s4, 8
	s_add_i32 s1, s1, s46
	v_or_b32_e32 v174, s1, v1
	v_or_b32_e32 v168, 16, v174
	v_ashrrev_i32_e32 v175, 31, v174
	v_ashrrev_i32_e32 v169, 31, v168
	v_lshlrev_b64 v[154:155], 6, v[174:175]
	v_lshlrev_b64 v[164:165], 6, v[168:169]
	v_or_b32_e32 v210, 32, v174
	v_lshl_add_u64 v[154:155], v[142:143], 0, v[154:155]
	v_lshl_add_u64 v[176:177], v[142:143], 0, v[164:165]
	v_ashrrev_i32_e32 v211, 31, v210
	v_or_b32_e32 v212, 48, v174
	global_load_dwordx4 v[164:167], v[154:155], off
	s_nop 0
	global_load_dwordx4 v[176:179], v[176:177], off
	v_lshlrev_b64 v[154:155], 6, v[210:211]
	v_ashrrev_i32_e32 v213, 31, v212
	v_lshl_add_u64 v[154:155], v[142:143], 0, v[154:155]
	v_lshlrev_b64 v[180:181], 6, v[212:213]
	v_lshl_add_u64 v[184:185], v[142:143], 0, v[180:181]
	global_load_dwordx4 v[180:183], v[154:155], off
	global_load_dwordx4 v[190:193], v[184:185], off
	v_add_u32_e32 v154, 0x80, v174
	v_ashrrev_i32_e32 v155, 31, v154
	v_lshlrev_b64 v[184:185], 6, v[154:155]
	v_lshl_add_u64 v[184:185], v[142:143], 0, v[184:185]
	global_load_dwordx4 v[194:197], v[184:185], off
	v_add_u32_e32 v186, 0xa0, v174
	v_ashrrev_i32_e32 v187, 31, v186
	v_add_u32_e32 v188, 0x90, v174
	v_lshlrev_b64 v[202:203], 6, v[186:187]
	v_ashrrev_i32_e32 v189, 31, v188
	v_lshl_add_u64 v[202:203], v[142:143], 0, v[202:203]
	global_load_dwordx4 v[202:205], v[202:203], off
	v_lshlrev_b64 v[184:185], 6, v[188:189]
	v_lshl_add_u64 v[184:185], v[142:143], 0, v[184:185]
	global_load_dwordx4 v[198:201], v[184:185], off
	v_add_u32_e32 v184, 0xb0, v174
	v_ashrrev_i32_e32 v185, 31, v184
	v_lshlrev_b64 v[206:207], 6, v[184:185]
	v_lshl_add_u64 v[206:207], v[142:143], 0, v[206:207]
	global_load_dwordx4 v[206:209], v[206:207], off
	v_and_b32_e32 v153, 64, v163
	v_xor_b32_e32 v138, 16, v163
	v_add_u32_e32 v153, 64, v153
	v_xor_b32_e32 v156, 32, v163
	v_cmp_lt_i32_e32 vcc, v138, v153
	s_ashr_i32 s1, s0, 31
	s_lshr_b32 s1, s1, 30
	v_cndmask_b32_e32 v138, v163, v138, vcc
	v_cmp_lt_i32_e32 vcc, v156, v153
	v_lshlrev_b32_e32 v138, 2, v138
	s_add_i32 s1, s0, s1
	v_cndmask_b32_e32 v153, v163, v156, vcc
	v_lshlrev_b32_e32 v153, 2, v153
	s_ashr_i32 s4, s1, 2
	s_and_b32 s1, s1, -4
	s_ashr_i32 s5, s4, 31
	s_sub_i32 s19, s0, s1
	s_lshl_b64 s[4:5], s[4:5], 26
	s_add_u32 s17, s44, s4
	s_addc_u32 s1, s45, s5
	s_mov_b64 s[4:5], -1
	s_cmp_gt_i32 s0, 7
	s_waitcnt vmcnt(0)
	v_add_f32_e32 v156, v164, v165
	v_add_f32_e32 v158, v166, v167
	v_add_f32_e32 v156, v156, v158
	v_add_f32_e32 v158, v176, v177
	v_add_f32_e32 v160, v178, v179
	v_mov_b32_e32 v172, v156
	s_nop 1
	v_permlane16_swap_b32 v156, v172
	v_add_f32_e32 v162, v180, v181
	v_add_f32_e32 v164, v182, v183
	v_add_f32_e32 v165, v190, v191
	v_add_f32_e32 v166, v192, v193
	v_add_f32_e32 v158, v158, v160
	v_add_f32_e32 v160, v162, v164
	v_add_f32_e32 v162, v165, v166
	v_mov_b32_e32 v165, v158
	s_nop 1
	v_permlane16_swap_b32 v158, v165
	v_mov_b32_e32 v166, v160
	s_nop 1
	v_permlane16_swap_b32 v160, v166
	s_waitcnt lgkmcnt(2)
	v_add_f32_e32 v156, v156, v172
	v_add_f32_e32 v167, v194, v195
	v_add_f32_e32 v170, v196, v197
	v_mov_b32_e32 v172, v156
	s_nop 1
	v_permlane32_swap_b32 v156, v172
	s_waitcnt lgkmcnt(2)
	v_add_f32_e32 v158, v158, v165
	s_waitcnt lgkmcnt(1)
	v_add_f32_e32 v160, v160, v166
	v_add_f32_e32 v164, v167, v170
	v_mov_b32_e32 v167, v162
	s_nop 1
	v_permlane16_swap_b32 v162, v167
	v_mov_b32_e32 v165, v158
	s_nop 1
	v_permlane32_swap_b32 v158, v165
	v_mov_b32_e32 v166, v160
	s_nop 1
	v_permlane32_swap_b32 v160, v166
	v_mov_b32_e32 v170, v164
	s_nop 1
	v_permlane16_swap_b32 v164, v170
	s_waitcnt lgkmcnt(4)
	v_add_f32_e32 v156, v156, v172
	s_waitcnt lgkmcnt(3)
	v_add_f32_e32 v162, v162, v167
	v_fmamk_f32 v156, v156, 0x3a800000, v171
	s_waitcnt lgkmcnt(2)
	v_add_f32_e32 v158, v158, v165
	s_waitcnt lgkmcnt(1)
	v_add_f32_e32 v160, v160, v166
	v_mov_b32_e32 v167, v162
	s_nop 1
	v_permlane32_swap_b32 v162, v167
	v_rsq_f32_e32 v182, v156
	v_fmamk_f32 v156, v158, 0x3a800000, v171
	v_fmamk_f32 v158, v160, 0x3a800000, v171
	s_waitcnt lgkmcnt(1)
	v_add_f32_e32 v164, v164, v170
	v_rsq_f32_e32 v180, v156
	v_rsq_f32_e32 v170, v158
	v_add_f32_e32 v156, v198, v199
	v_add_f32_e32 v158, v200, v201
	v_mov_b32_e32 v176, v164
	s_nop 1
	v_permlane32_swap_b32 v164, v176
	v_add_f32_e32 v156, v156, v158
	v_mov_b32_e32 v158, v156
	s_nop 1
	v_permlane16_swap_b32 v156, v158
	s_waitcnt lgkmcnt(2)
	v_add_f32_e32 v162, v162, v167
	v_fmamk_f32 v160, v162, 0x3a800000, v171
	v_rsq_f32_e32 v172, v160
	s_waitcnt lgkmcnt(1)
	v_add_f32_e32 v160, v164, v176
	v_add_f32_e32 v162, v202, v203
	v_add_f32_e32 v164, v204, v205
	v_add_f32_e32 v165, v206, v207
	v_add_f32_e32 v166, v208, v209
	s_waitcnt lgkmcnt(0)
	v_add_f32_e32 v156, v156, v158
	v_add_f32_e32 v162, v162, v164
	v_add_f32_e32 v165, v165, v166
	v_mov_b32_e32 v158, v156
	s_nop 1
	v_permlane32_swap_b32 v156, v158
	v_mov_b32_e32 v164, v162
	s_nop 1
	v_permlane16_swap_b32 v162, v164
	v_mov_b32_e32 v138, v165
	s_nop 1
	v_permlane16_swap_b32 v165, v138
	v_fmamk_f32 v160, v160, 0x3a800000, v171
	v_rsq_f32_e32 v160, v160
	s_waitcnt lgkmcnt(2)
	v_add_f32_e32 v156, v156, v158
	s_waitcnt lgkmcnt(1)
	v_add_f32_e32 v158, v162, v164
	s_waitcnt lgkmcnt(0)
	v_add_f32_e32 v138, v165, v138
	v_mov_b32_e32 v164, v158
	s_nop 1
	v_permlane32_swap_b32 v158, v164
	v_mov_b32_e32 v153, v138
	s_nop 1
	v_permlane32_swap_b32 v138, v153
	v_fmamk_f32 v156, v156, 0x3a800000, v171
	v_rsq_f32_e32 v162, v156
	v_lshlrev_b64 v[176:177], 11, v[174:175]
	s_waitcnt lgkmcnt(1)
	v_add_f32_e32 v156, v158, v164
	s_waitcnt lgkmcnt(0)
	v_add_f32_e32 v138, v138, v153
	v_fmamk_f32 v156, v156, 0x3a800000, v171
	v_fmamk_f32 v138, v138, 0x3a800000, v171
	v_rsq_f32_e32 v156, v156
	v_rsq_f32_e32 v158, v138
	v_lshlrev_b64 v[178:179], 11, v[168:169]
	v_lshlrev_b64 v[166:167], 11, v[210:211]
	v_lshlrev_b64 v[168:169], 11, v[212:213]
	v_lshlrev_b64 v[164:165], 11, v[154:155]
	s_cbranch_scc1 .LBB0_995
	s_andn2_b64 vcc, exec, s[4:5]
	s_cbranch_vccz .LBB0_996

; __device__ __forceinline__ unsigned cvt_pk_bf16(float lo, float hi) { unsigned r; asm volatile("v_cvt_pk_bf16_f32 %0, %1, %2" : "=v"(r) : "v"(lo), "v"(hi)); return r; }
; __device__ __forceinline__ float bflo(unsigned w) { return __uint_as_float(w << 16); }
; __device__ __forceinline__ float bfhi(unsigned w) { return __uint_as_float(w & 0xffff0000u); }
;     __device__ __forceinline__ void ld(Ld& L, size_t o) const {
; #pragma unroll
;         for (int bj = 0; bj < 2; ++bj) { if (BASEF32) { L.a[bj][0] = *(const f32x4*)((const float*)base + o + bj * HALF); L.a[bj][1] = *(const f32x4*)((const float*)base + o + bj * HALF + 4); }
;             else { const v4u w = *(const v4u*)((const bf16*)base + o + bj * HALF); L.a[bj][0] = __builtin_bit_cast(f32x4, w); } }
;     }
;     __device__ __forceinline__ void operator()(const pg8::f32x4 (&acc)[2][2][4][2], const Unit& u, int wr, int wc, int fr, int fq) const {
;         const int row0 = u.pm * BM + wr * 64 + fr, col0 = u.pn * BM + wc * 32 + 8 * fq;
;         Ld nx; ld(nx, (size_t)row0 * DM_ + col0);
; #pragma unroll
;         for (int k = 0; k < 8; ++k) { const int ai = k >> 2, m = k & 3; const int row = row0 + ai * HALF + m * 16; float q = 0.f; const Ld cu = nx;
;             if (k < 7) ld(nx, (size_t)(row0 + ((k + 1) >> 2) * HALF + ((k + 1) & 3) * 16) * DM_ + col0);
; #pragma unroll
;             for (int bj = 0; bj < 2; ++bj) { const size_t o = (size_t)row * DM_ + col0 + bj * HALF; f32x4 b0, b1;
;                 if (BASEF32) { b0 = cu.a[bj][0]; b1 = cu.a[bj][1]; }
;                 else { const v4u w = __builtin_bit_cast(v4u, cu.a[bj][0]); b0 = (f32x4){bflo(w.x), bfhi(w.x), bflo(w.y), bfhi(w.y)}; b1 = (f32x4){bflo(w.z), bfhi(w.z), bflo(w.w), bfhi(w.w)}; }
;                 const f32x4 r0 = b0 + acc[ai][bj][m][0], r1 = b1 + acc[ai][bj][m][1];
;                 q += (r0[0] * r0[0] + r0[1] * r0[1]) + (r0[2] * r0[2] + r0[3] * r0[3]) + (r1[0] * r1[0] + r1[1] * r1[1]) + (r1[2] * r1[2] + r1[3] * r1[3]);
;                 v4u w; w.x = cvt_pk_bf16(r0[0], r0[1]); w.y = cvt_pk_bf16(r0[2], r0[3]); w.z = cvt_pk_bf16(r1[0], r1[1]); w.w = cvt_pk_bf16(r1[2], r1[3]); *(v4u*)(out + o) = w; }
;             q += __shfl_xor(q, 16); q += __shfl_xor(q, 32); if (fq == 0) ssq[(size_t)row * 16 + u.pn * 4 + wc] = q; }
;     }
.LBB0_1470:
	v_lshl_add_u32 v156, s28, 8, v1
	v_lshl_or_b32 v154, s4, 8, v163
	v_ashrrev_i32_e32 v157, 31, v156
	v_ashrrev_i32_e32 v155, 31, v154
	v_lshlrev_b64 v[130:131], 11, v[156:157]
	v_lshl_add_u64 v[130:131], s[12:13], 0, v[130:131]
	v_lshlrev_b64 v[132:133], 1, v[154:155]
	v_lshl_add_u64 v[178:179], v[130:131], 0, v[132:133]
	global_load_dwordx4 v[170:173], v[178:179], off
	global_load_dwordx4 v[174:177], v[178:179], off offset:256
	v_or_b32_e32 v158, 16, v156
	v_ashrrev_i32_e32 v159, 31, v158
	v_lshlrev_b64 v[130:131], 11, v[158:159]
	v_lshl_add_u64 v[130:131], s[12:13], 0, v[130:131]
	v_lshl_add_u64 v[160:161], v[130:131], 0, v[132:133]
	global_load_dwordx4 v[134:137], v[160:161], off
	global_load_dwordx4 v[130:133], v[160:161], off offset:256
	v_and_b32_e32 v169, 64, v167
	v_xor_b32_e32 v168, 16, v167
	v_add_u32_e32 v169, 64, v169
	v_xor_b32_e32 v180, 32, v167
	v_cmp_lt_i32_e32 vcc, v168, v169
	s_lshl_b32 s28, s4, 2
	s_ashr_i32 s29, s28, 31
	v_cndmask_b32_e32 v168, v167, v168, vcc
	v_cmp_lt_i32_e32 vcc, v180, v169
	v_lshlrev_b32_e32 v168, 2, v168
	s_waitcnt vmcnt(0)
	v_and_b32_e32 v181, 0xffff0000, v170
	v_cndmask_b32_e32 v169, v167, v180, vcc
	v_lshlrev_b32_e32 v180, 16, v170
	v_lshlrev_b32_e32 v170, 16, v171
	v_and_b32_e32 v171, 0xffff0000, v171
	v_lshlrev_b32_e32 v184, 16, v174
	v_and_b32_e32 v185, 0xffff0000, v174
	v_lshlrev_b32_e32 v174, 16, v175
	v_and_b32_e32 v175, 0xffff0000, v175
	v_lshlrev_b32_e32 v182, 16, v172
	v_and_b32_e32 v183, 0xffff0000, v172
	v_lshlrev_b32_e32 v172, 16, v173
	v_and_b32_e32 v173, 0xffff0000, v173
	v_lshlrev_b32_e32 v186, 16, v176
	v_and_b32_e32 v187, 0xffff0000, v176
	v_lshlrev_b32_e32 v176, 16, v177
	v_and_b32_e32 v177, 0xffff0000, v177
	v_pk_add_f32 v[128:129], v[128:129], v[170:171]
	v_pk_add_f32 v[126:127], v[126:127], v[180:181]
	v_pk_add_f32 v[120:121], v[120:121], v[174:175]
	v_pk_add_f32 v[118:119], v[118:119], v[184:185]
	v_pk_add_f32 v[124:125], v[124:125], v[172:173]
	v_pk_add_f32 v[122:123], v[122:123], v[182:183]
	v_pk_add_f32 v[170:171], v[116:117], v[176:177]
	v_pk_add_f32 v[172:173], v[114:115], v[186:187]
	v_mul_f32_e32 v116, v127, v127
	v_mul_f32_e32 v117, v129, v129
	v_cvt_pk_bf16_f32 v114, v126, v127
	v_cvt_pk_bf16_f32 v115, v128, v129
	v_mul_f32_e32 v127, v119, v119
	v_mul_f32_e32 v129, v121, v121
	v_mul_f32_e32 v174, v123, v123
	v_mul_f32_e32 v176, v173, v173
	v_fmac_f32_e32 v116, v126, v126
	v_fmac_f32_e32 v117, v128, v128
	v_fmac_f32_e32 v127, v118, v118
	v_fmac_f32_e32 v129, v120, v120
	v_mul_f32_e32 v175, v125, v125
	v_mul_f32_e32 v177, v171, v171
	v_fmac_f32_e32 v174, v122, v122
	v_fmac_f32_e32 v176, v172, v172
	v_add_f32_e32 v116, v116, v117
	v_add_f32_e32 v117, v127, v129
	v_fmac_f32_e32 v175, v124, v124
	v_fmac_f32_e32 v177, v170, v170
	v_add_f32_e32 v116, v174, v116
	v_add_f32_e32 v117, v176, v117
	v_add_f32_e32 v116, v175, v116
	v_add_f32_e32 v117, v177, v117
	v_add_f32_e32 v126, v116, v117
	v_mov_b32_e32 v127, v126
	s_nop 1
	v_permlane16_swap_b32 v126, v127
	v_cvt_pk_bf16_f32 v116, v122, v123
	v_cvt_pk_bf16_f32 v117, v124, v125
	global_store_dwordx4 v[178:179], v[114:117], off
	s_waitcnt lgkmcnt(0)
	s_nop 0
	v_add_f32_e32 v114, v126, v127
	v_lshlrev_b32_e32 v126, 2, v169
	v_mov_b32_e32 v115, v114
	s_nop 1
	v_permlane32_swap_b32 v114, v115
	v_cvt_pk_bf16_f32 v116, v118, v119
	v_cvt_pk_bf16_f32 v117, v120, v121
	v_cvt_pk_bf16_f32 v118, v172, v173
	v_cvt_pk_bf16_f32 v119, v170, v171
	global_store_dwordx4 v[178:179], v[116:119], off offset:256
	s_and_saveexec_b64 s[30:31], s[6:7]
	s_cbranch_execz .LBB0_1472
	v_lshlrev_b64 v[116:117], 6, v[156:157]
	v_lshl_add_u64 v[116:117], s[14:15], 0, v[116:117]
	v_lshl_add_u64 v[116:117], s[28:29], 2, v[116:117]
	s_lshl_b32 s4, s42, 2
	v_lshl_add_u64 v[116:117], v[116:117], 0, s[4:5]
	s_waitcnt lgkmcnt(0)
	v_add_f32_e32 v114, v114, v115
	global_store_dword v[116:117], v114, off
.LBB0_1472:
	s_or_b64 exec, exec, s[30:31]
	v_or_b32_e32 v122, 32, v156
	v_ashrrev_i32_e32 v123, 31, v122
	s_waitcnt lgkmcnt(0)
	v_lshlrev_b64 v[114:115], 11, v[122:123]
	v_lshl_add_u64 v[114:115], s[12:13], 0, v[114:115]
	v_lshl_add_u64 v[124:125], v[154:155], 1, v[114:115]
	global_load_dwordx4 v[118:121], v[124:125], off
	global_load_dwordx4 v[114:117], v[124:125], off offset:256
	v_lshlrev_b32_e32 v128, 16, v134
	v_and_b32_e32 v129, 0xffff0000, v134
	v_lshlrev_b32_e32 v134, 16, v135
	v_and_b32_e32 v135, 0xffff0000, v135
	v_lshlrev_b32_e32 v170, 16, v136
	v_and_b32_e32 v171, 0xffff0000, v136
	v_lshlrev_b32_e32 v136, 16, v137
	v_and_b32_e32 v137, 0xffff0000, v137
	v_pk_add_f32 v[112:113], v[112:113], v[134:135]
	v_pk_add_f32 v[110:111], v[110:111], v[128:129]
	v_pk_add_f32 v[128:129], v[108:109], v[136:137]
	v_pk_add_f32 v[108:109], v[106:107], v[170:171]
	v_mul_f32_e32 v106, v111, v111
	v_mul_f32_e32 v107, v113, v113
	v_fmac_f32_e32 v106, v110, v110
	v_fmac_f32_e32 v107, v112, v112
	v_add_f32_e32 v106, v106, v107
	v_mul_f32_e32 v107, v109, v109
	v_fmac_f32_e32 v107, v108, v108
	v_add_f32_e32 v106, v107, v106
	v_mul_f32_e32 v107, v129, v129
	v_fmac_f32_e32 v107, v128, v128
	v_add_f32_e32 v127, v107, v106
	v_cvt_pk_bf16_f32 v106, v110, v111
	v_cvt_pk_bf16_f32 v107, v112, v113
	v_lshlrev_b32_e32 v110, 16, v130
	v_and_b32_e32 v111, 0xffff0000, v130
	v_lshlrev_b32_e32 v112, 16, v131
	v_and_b32_e32 v113, 0xffff0000, v131
	v_lshlrev_b32_e32 v130, 16, v132
	v_and_b32_e32 v131, 0xffff0000, v132
	v_pk_add_f32 v[104:105], v[104:105], v[112:113]
	v_pk_add_f32 v[102:103], v[102:103], v[110:111]
	v_pk_add_f32 v[112:113], v[98:99], v[130:131]
	v_mul_f32_e32 v98, v103, v103
	v_mul_f32_e32 v99, v105, v105
	v_fmac_f32_e32 v98, v102, v102
	v_fmac_f32_e32 v99, v104, v104
	v_lshlrev_b32_e32 v132, 16, v133
	v_and_b32_e32 v133, 0xffff0000, v133
	v_add_f32_e32 v98, v98, v99
	v_mul_f32_e32 v99, v113, v113
	v_pk_add_f32 v[110:111], v[100:101], v[132:133]
	v_fmac_f32_e32 v99, v112, v112
	v_add_f32_e32 v98, v99, v98
	v_mul_f32_e32 v99, v111, v111
	v_fmac_f32_e32 v99, v110, v110
	v_add_f32_e32 v98, v99, v98
	v_add_f32_e32 v98, v127, v98
	v_mov_b32_e32 v99, v98
	s_nop 1
	v_permlane16_swap_b32 v98, v99
	v_cvt_pk_bf16_f32 v108, v108, v109
	v_cvt_pk_bf16_f32 v109, v128, v129
	global_store_dwordx4 v[160:161], v[106:109], off
	v_cvt_pk_bf16_f32 v100, v102, v103
	s_waitcnt lgkmcnt(0)
	v_add_f32_e32 v98, v98, v99
	v_mov_b32_e32 v99, v98
	s_nop 1
	v_permlane32_swap_b32 v98, v99
	v_cvt_pk_bf16_f32 v101, v104, v105
	v_cvt_pk_bf16_f32 v102, v112, v113
	v_cvt_pk_bf16_f32 v103, v110, v111
	global_store_dwordx4 v[160:161], v[100:103], off offset:256
	s_and_saveexec_b64 s[30:31], s[6:7]
	s_cbranch_execz .LBB0_1474
	v_lshlrev_b64 v[100:101], 6, v[158:159]
	v_lshl_add_u64 v[100:101], s[14:15], 0, v[100:101]
	v_lshl_add_u64 v[100:101], s[28:29], 2, v[100:101]
	s_lshl_b32 s4, s42, 2
	v_lshl_add_u64 v[100:101], v[100:101], 0, s[4:5]
	s_waitcnt lgkmcnt(0)
	v_add_f32_e32 v98, v98, v99
	global_store_dword v[100:101], v98, off
; __device__ __forceinline__ unsigned cvt_pk_bf16(float lo, float hi) { unsigned r; asm volatile("v_cvt_pk_bf16_f32 %0, %1, %2" : "=v"(r) : "v"(lo), "v"(hi)); return r; }
; __device__ __forceinline__ float bflo(unsigned w) { return __uint_as_float(w << 16); }
; __device__ __forceinline__ float bfhi(unsigned w) { return __uint_as_float(w & 0xffff0000u); }
;     __device__ __forceinline__ void ld(Ld& L, size_t o) const {
; #pragma unroll
;         for (int bj = 0; bj < 2; ++bj) { if (BASEF32) { L.a[bj][0] = *(const f32x4*)((const float*)base + o + bj * HALF); L.a[bj][1] = *(const f32x4*)((const float*)base + o + bj * HALF + 4); }
;             else { const v4u w = *(const v4u*)((const bf16*)base + o + bj * HALF); L.a[bj][0] = __builtin_bit_cast(f32x4, w); } }
;     }
;     __device__ __forceinline__ void operator()(const pg8::f32x4 (&acc)[2][2][4][2], const Unit& u, int wr, int wc, int fr, int fq) const {
;         const int row0 = u.pm * BM + wr * 64 + fr, col0 = u.pn * BM + wc * 32 + 8 * fq;
;         Ld nx; ld(nx, (size_t)row0 * DM_ + col0);
; #pragma unroll
;         for (int k = 0; k < 8; ++k) { const int ai = k >> 2, m = k & 3; const int row = row0 + ai * HALF + m * 16; float q = 0.f; const Ld cu = nx;
;             if (k < 7) ld(nx, (size_t)(row0 + ((k + 1) >> 2) * HALF + ((k + 1) & 3) * 16) * DM_ + col0);
; #pragma unroll
;             for (int bj = 0; bj < 2; ++bj) { const size_t o = (size_t)row * DM_ + col0 + bj * HALF; f32x4 b0, b1;
;                 if (BASEF32) { b0 = cu.a[bj][0]; b1 = cu.a[bj][1]; }
;                 else { const v4u w = __builtin_bit_cast(v4u, cu.a[bj][0]); b0 = (f32x4){bflo(w.x), bfhi(w.x), bflo(w.y), bfhi(w.y)}; b1 = (f32x4){bflo(w.z), bfhi(w.z), bflo(w.w), bfhi(w.w)}; }
;                 const f32x4 r0 = b0 + acc[ai][bj][m][0], r1 = b1 + acc[ai][bj][m][1];
;                 q += (r0[0] * r0[0] + r0[1] * r0[1]) + (r0[2] * r0[2] + r0[3] * r0[3]) + (r1[0] * r1[0] + r1[1] * r1[1]) + (r1[2] * r1[2] + r1[3] * r1[3]);
;                 v4u w; w.x = cvt_pk_bf16(r0[0], r0[1]); w.y = cvt_pk_bf16(r0[2], r0[3]); w.z = cvt_pk_bf16(r1[0], r1[1]); w.w = cvt_pk_bf16(r1[2], r1[3]); *(v4u*)(out + o) = w; }
;             q += __shfl_xor(q, 16); q += __shfl_xor(q, 32); if (fq == 0) ssq[(size_t)row * 16 + u.pn * 4 + wc] = q; }
;     }
.LBB0_1474:
	s_or_b64 exec, exec, s[30:31]
	v_or_b32_e32 v106, 48, v156
	v_ashrrev_i32_e32 v107, 31, v106
	s_waitcnt lgkmcnt(0)
	v_lshlrev_b64 v[98:99], 11, v[106:107]
	v_lshl_add_u64 v[98:99], s[12:13], 0, v[98:99]
	v_lshl_add_u64 v[108:109], v[154:155], 1, v[98:99]
	global_load_dwordx4 v[102:105], v[108:109], off
	global_load_dwordx4 v[98:101], v[108:109], off offset:256
	s_waitcnt vmcnt(5)
	v_lshlrev_b32_e32 v110, 16, v118
	v_and_b32_e32 v111, 0xffff0000, v118
	v_lshlrev_b32_e32 v112, 16, v119
	v_and_b32_e32 v113, 0xffff0000, v119
	v_lshlrev_b32_e32 v118, 16, v120
	v_and_b32_e32 v119, 0xffff0000, v120
	v_lshlrev_b32_e32 v120, 16, v121
	v_and_b32_e32 v121, 0xffff0000, v121
	v_pk_add_f32 v[96:97], v[96:97], v[112:113]
	v_pk_add_f32 v[94:95], v[94:95], v[110:111]
	v_pk_add_f32 v[110:111], v[92:93], v[120:121]
	v_pk_add_f32 v[92:93], v[90:91], v[118:119]
	v_mul_f32_e32 v90, v95, v95
	v_mul_f32_e32 v91, v97, v97
	v_fmac_f32_e32 v90, v94, v94
	v_fmac_f32_e32 v91, v96, v96
	v_add_f32_e32 v90, v90, v91
	v_mul_f32_e32 v91, v93, v93
	v_fmac_f32_e32 v91, v92, v92
	v_add_f32_e32 v90, v91, v90
	v_mul_f32_e32 v91, v111, v111
	v_fmac_f32_e32 v91, v110, v110
	v_add_f32_e32 v118, v91, v90
	v_cvt_pk_bf16_f32 v90, v94, v95
	v_cvt_pk_bf16_f32 v91, v96, v97
	s_waitcnt vmcnt(4)
	v_lshlrev_b32_e32 v94, 16, v114
	v_and_b32_e32 v95, 0xffff0000, v114
	v_lshlrev_b32_e32 v96, 16, v115
	v_and_b32_e32 v97, 0xffff0000, v115
	v_lshlrev_b32_e32 v112, 16, v116
	v_and_b32_e32 v113, 0xffff0000, v116
	v_pk_add_f32 v[88:89], v[88:89], v[96:97]
	v_pk_add_f32 v[86:87], v[86:87], v[94:95]
	v_pk_add_f32 v[96:97], v[82:83], v[112:113]
	v_mul_f32_e32 v82, v87, v87
	v_mul_f32_e32 v83, v89, v89
	v_fmac_f32_e32 v82, v86, v86
	v_fmac_f32_e32 v83, v88, v88
	v_lshlrev_b32_e32 v114, 16, v117
	v_and_b32_e32 v115, 0xffff0000, v117
	v_add_f32_e32 v82, v82, v83
	v_mul_f32_e32 v83, v97, v97
	v_pk_add_f32 v[94:95], v[84:85], v[114:115]
	v_fmac_f32_e32 v83, v96, v96
	v_add_f32_e32 v82, v83, v82
	v_mul_f32_e32 v83, v95, v95
	v_fmac_f32_e32 v83, v94, v94
	v_add_f32_e32 v82, v83, v82
	v_add_f32_e32 v82, v118, v82
	v_mov_b32_e32 v83, v82
	s_nop 1
	v_permlane16_swap_b32 v82, v83
	v_cvt_pk_bf16_f32 v92, v92, v93
	v_cvt_pk_bf16_f32 v93, v110, v111
	global_store_dwordx4 v[124:125], v[90:93], off
	v_cvt_pk_bf16_f32 v84, v86, v87
	s_waitcnt lgkmcnt(0)
	v_add_f32_e32 v82, v82, v83
	v_mov_b32_e32 v83, v82
	s_nop 1
	v_permlane32_swap_b32 v82, v83
	v_cvt_pk_bf16_f32 v85, v88, v89
	v_cvt_pk_bf16_f32 v86, v96, v97
	v_cvt_pk_bf16_f32 v87, v94, v95
	global_store_dwordx4 v[124:125], v[84:87], off offset:256
	s_and_saveexec_b64 s[30:31], s[6:7]
	s_cbranch_execz .LBB0_1476
	v_lshlrev_b64 v[84:85], 6, v[122:123]
	v_lshl_add_u64 v[84:85], s[14:15], 0, v[84:85]
	v_lshl_add_u64 v[84:85], s[28:29], 2, v[84:85]
	s_lshl_b32 s4, s42, 2
	v_lshl_add_u64 v[84:85], v[84:85], 0, s[4:5]
	s_waitcnt lgkmcnt(0)
	v_add_f32_e32 v82, v82, v83
	global_store_dword v[84:85], v82, off
.LBB0_1476:
	s_or_b64 exec, exec, s[30:31]
	v_add_u32_e32 v90, 0x80, v156
	v_ashrrev_i32_e32 v91, 31, v90
	s_waitcnt lgkmcnt(0)
	v_lshlrev_b64 v[82:83], 11, v[90:91]
	v_lshl_add_u64 v[82:83], s[12:13], 0, v[82:83]
	v_lshl_add_u64 v[92:93], v[154:155], 1, v[82:83]
	global_load_dwordx4 v[86:89], v[92:93], off
	global_load_dwordx4 v[82:85], v[92:93], off offset:256
	s_waitcnt vmcnt(5)
	v_lshlrev_b32_e32 v94, 16, v102
	v_and_b32_e32 v95, 0xffff0000, v102
	v_lshlrev_b32_e32 v96, 16, v103
	v_and_b32_e32 v97, 0xffff0000, v103
	v_lshlrev_b32_e32 v102, 16, v104
	v_and_b32_e32 v103, 0xffff0000, v104
	v_lshlrev_b32_e32 v104, 16, v105
	v_and_b32_e32 v105, 0xffff0000, v105
	v_pk_add_f32 v[80:81], v[80:81], v[96:97]
	v_pk_add_f32 v[78:79], v[78:79], v[94:95]
	v_pk_add_f32 v[94:95], v[76:77], v[104:105]
	v_pk_add_f32 v[76:77], v[74:75], v[102:103]
	v_mul_f32_e32 v74, v79, v79
	v_mul_f32_e32 v75, v81, v81
	v_fmac_f32_e32 v74, v78, v78
	v_fmac_f32_e32 v75, v80, v80
	v_add_f32_e32 v74, v74, v75
	v_mul_f32_e32 v75, v77, v77
	v_fmac_f32_e32 v75, v76, v76
	v_add_f32_e32 v74, v75, v74
	v_mul_f32_e32 v75, v95, v95
	v_fmac_f32_e32 v75, v94, v94
	v_add_f32_e32 v102, v75, v74
	v_cvt_pk_bf16_f32 v74, v78, v79
	v_cvt_pk_bf16_f32 v75, v80, v81
	s_waitcnt vmcnt(4)
	v_lshlrev_b32_e32 v78, 16, v98
	v_and_b32_e32 v79, 0xffff0000, v98
	v_lshlrev_b32_e32 v80, 16, v99
	v_and_b32_e32 v81, 0xffff0000, v99
	v_lshlrev_b32_e32 v96, 16, v100
	v_and_b32_e32 v97, 0xffff0000, v100
	v_pk_add_f32 v[72:73], v[72:73], v[80:81]
	v_pk_add_f32 v[70:71], v[70:71], v[78:79]
	v_pk_add_f32 v[80:81], v[66:67], v[96:97]
	v_mul_f32_e32 v66, v71, v71
	v_mul_f32_e32 v67, v73, v73
	v_fmac_f32_e32 v66, v70, v70
	v_fmac_f32_e32 v67, v72, v72
	v_lshlrev_b32_e32 v98, 16, v101
	v_and_b32_e32 v99, 0xffff0000, v101
	v_add_f32_e32 v66, v66, v67
	v_mul_f32_e32 v67, v81, v81
	v_pk_add_f32 v[78:79], v[68:69], v[98:99]
	v_fmac_f32_e32 v67, v80, v80
	v_add_f32_e32 v66, v67, v66
	v_mul_f32_e32 v67, v79, v79
	v_fmac_f32_e32 v67, v78, v78
	v_add_f32_e32 v66, v67, v66
	v_add_f32_e32 v66, v102, v66
	v_mov_b32_e32 v67, v66
	s_nop 1
	v_permlane16_swap_b32 v66, v67
	v_cvt_pk_bf16_f32 v76, v76, v77
	v_cvt_pk_bf16_f32 v77, v94, v95
	global_store_dwordx4 v[108:109], v[74:77], off
	v_cvt_pk_bf16_f32 v68, v70, v71
	s_waitcnt lgkmcnt(0)
	v_add_f32_e32 v66, v66, v67
	v_mov_b32_e32 v67, v66
	s_nop 1
	v_permlane32_swap_b32 v66, v67
	v_cvt_pk_bf16_f32 v69, v72, v73
	v_cvt_pk_bf16_f32 v70, v80, v81
	v_cvt_pk_bf16_f32 v71, v78, v79
	global_store_dwordx4 v[108:109], v[68:71], off offset:256
	s_and_saveexec_b64 s[30:31], s[6:7]
	s_cbranch_execz .LBB0_1478
	v_lshlrev_b64 v[68:69], 6, v[106:107]
	v_lshl_add_u64 v[68:69], s[14:15], 0, v[68:69]
	v_lshl_add_u64 v[68:69], s[28:29], 2, v[68:69]
	s_lshl_b32 s4, s42, 2
	v_lshl_add_u64 v[68:69], v[68:69], 0, s[4:5]
	s_waitcnt lgkmcnt(0)
	v_add_f32_e32 v66, v66, v67
	global_store_dword v[68:69], v66, off
; __device__ __forceinline__ unsigned cvt_pk_bf16(float lo, float hi) { unsigned r; asm volatile("v_cvt_pk_bf16_f32 %0, %1, %2" : "=v"(r) : "v"(lo), "v"(hi)); return r; }
; __device__ __forceinline__ float bflo(unsigned w) { return __uint_as_float(w << 16); }
; __device__ __forceinline__ float bfhi(unsigned w) { return __uint_as_float(w & 0xffff0000u); }
;     __device__ __forceinline__ void ld(Ld& L, size_t o) const {
; #pragma unroll
;         for (int bj = 0; bj < 2; ++bj) { if (BASEF32) { L.a[bj][0] = *(const f32x4*)((const float*)base + o + bj * HALF); L.a[bj][1] = *(const f32x4*)((const float*)base + o + bj * HALF + 4); }
;             else { const v4u w = *(const v4u*)((const bf16*)base + o + bj * HALF); L.a[bj][0] = __builtin_bit_cast(f32x4, w); } }
;     }
;     __device__ __forceinline__ void operator()(const pg8::f32x4 (&acc)[2][2][4][2], const Unit& u, int wr, int wc, int fr, int fq) const {
;         const int row0 = u.pm * BM + wr * 64 + fr, col0 = u.pn * BM + wc * 32 + 8 * fq;
;         Ld nx; ld(nx, (size_t)row0 * DM_ + col0);
; #pragma unroll
;         for (int k = 0; k < 8; ++k) { const int ai = k >> 2, m = k & 3; const int row = row0 + ai * HALF + m * 16; float q = 0.f; const Ld cu = nx;
;             if (k < 7) ld(nx, (size_t)(row0 + ((k + 1) >> 2) * HALF + ((k + 1) & 3) * 16) * DM_ + col0);
; #pragma unroll
;             for (int bj = 0; bj < 2; ++bj) { const size_t o = (size_t)row * DM_ + col0 + bj * HALF; f32x4 b0, b1;
;                 if (BASEF32) { b0 = cu.a[bj][0]; b1 = cu.a[bj][1]; }
;                 else { const v4u w = __builtin_bit_cast(v4u, cu.a[bj][0]); b0 = (f32x4){bflo(w.x), bfhi(w.x), bflo(w.y), bfhi(w.y)}; b1 = (f32x4){bflo(w.z), bfhi(w.z), bflo(w.w), bfhi(w.w)}; }
;                 const f32x4 r0 = b0 + acc[ai][bj][m][0], r1 = b1 + acc[ai][bj][m][1];
;                 q += (r0[0] * r0[0] + r0[1] * r0[1]) + (r0[2] * r0[2] + r0[3] * r0[3]) + (r1[0] * r1[0] + r1[1] * r1[1]) + (r1[2] * r1[2] + r1[3] * r1[3]);
;                 v4u w; w.x = cvt_pk_bf16(r0[0], r0[1]); w.y = cvt_pk_bf16(r0[2], r0[3]); w.z = cvt_pk_bf16(r1[0], r1[1]); w.w = cvt_pk_bf16(r1[2], r1[3]); *(v4u*)(out + o) = w; }
;             q += __shfl_xor(q, 16); q += __shfl_xor(q, 32); if (fq == 0) ssq[(size_t)row * 16 + u.pn * 4 + wc] = q; }
;     }
.LBB0_1478:
	s_or_b64 exec, exec, s[30:31]
	v_or_b32_e32 v74, 16, v90
	v_ashrrev_i32_e32 v75, 31, v74
	s_waitcnt lgkmcnt(0)
	v_lshlrev_b64 v[66:67], 11, v[74:75]
	v_lshl_add_u64 v[66:67], s[12:13], 0, v[66:67]
	v_lshl_add_u64 v[76:77], v[154:155], 1, v[66:67]
	global_load_dwordx4 v[70:73], v[76:77], off
	global_load_dwordx4 v[66:69], v[76:77], off offset:256
	s_waitcnt vmcnt(5)
	v_lshlrev_b32_e32 v78, 16, v86
	v_and_b32_e32 v79, 0xffff0000, v86
	v_lshlrev_b32_e32 v80, 16, v87
	v_and_b32_e32 v81, 0xffff0000, v87
	v_lshlrev_b32_e32 v86, 16, v88
	v_and_b32_e32 v87, 0xffff0000, v88
	v_lshlrev_b32_e32 v88, 16, v89
	v_and_b32_e32 v89, 0xffff0000, v89
	v_pk_add_f32 v[64:65], v[64:65], v[80:81]
	v_pk_add_f32 v[62:63], v[62:63], v[78:79]
	v_pk_add_f32 v[78:79], v[60:61], v[88:89]
	v_pk_add_f32 v[60:61], v[58:59], v[86:87]
	v_mul_f32_e32 v58, v63, v63
	v_mul_f32_e32 v59, v65, v65
	v_fmac_f32_e32 v58, v62, v62
	v_fmac_f32_e32 v59, v64, v64
	v_add_f32_e32 v58, v58, v59
	v_mul_f32_e32 v59, v61, v61
	v_fmac_f32_e32 v59, v60, v60
	v_add_f32_e32 v58, v59, v58
	v_mul_f32_e32 v59, v79, v79
	v_fmac_f32_e32 v59, v78, v78
	v_add_f32_e32 v86, v59, v58
	v_cvt_pk_bf16_f32 v58, v62, v63
	v_cvt_pk_bf16_f32 v59, v64, v65
	s_waitcnt vmcnt(4)
	v_lshlrev_b32_e32 v62, 16, v82
	v_and_b32_e32 v63, 0xffff0000, v82
	v_lshlrev_b32_e32 v64, 16, v83
	v_and_b32_e32 v65, 0xffff0000, v83
	v_lshlrev_b32_e32 v80, 16, v84
	v_and_b32_e32 v81, 0xffff0000, v84
	v_pk_add_f32 v[56:57], v[56:57], v[64:65]
	v_pk_add_f32 v[54:55], v[54:55], v[62:63]
	v_pk_add_f32 v[64:65], v[50:51], v[80:81]
	v_mul_f32_e32 v50, v55, v55
	v_mul_f32_e32 v51, v57, v57
	v_fmac_f32_e32 v50, v54, v54
	v_fmac_f32_e32 v51, v56, v56
	v_lshlrev_b32_e32 v82, 16, v85
	v_and_b32_e32 v83, 0xffff0000, v85
	v_add_f32_e32 v50, v50, v51
	v_mul_f32_e32 v51, v65, v65
	v_pk_add_f32 v[62:63], v[52:53], v[82:83]
	v_fmac_f32_e32 v51, v64, v64
	v_add_f32_e32 v50, v51, v50
	v_mul_f32_e32 v51, v63, v63
	v_fmac_f32_e32 v51, v62, v62
	v_add_f32_e32 v50, v51, v50
	v_add_f32_e32 v50, v86, v50
	v_mov_b32_e32 v51, v50
	s_nop 1
	v_permlane16_swap_b32 v50, v51
	v_cvt_pk_bf16_f32 v60, v60, v61
	v_cvt_pk_bf16_f32 v61, v78, v79
	global_store_dwordx4 v[92:93], v[58:61], off
	v_cvt_pk_bf16_f32 v52, v54, v55
	s_waitcnt lgkmcnt(0)
	v_add_f32_e32 v50, v50, v51
	v_mov_b32_e32 v51, v50
	s_nop 1
	v_permlane32_swap_b32 v50, v51
	v_cvt_pk_bf16_f32 v53, v56, v57
	v_cvt_pk_bf16_f32 v54, v64, v65
	v_cvt_pk_bf16_f32 v55, v62, v63
	global_store_dwordx4 v[92:93], v[52:55], off offset:256
	s_and_saveexec_b64 s[30:31], s[6:7]
	s_cbranch_execz .LBB0_1480
	v_lshlrev_b64 v[52:53], 6, v[90:91]
	v_lshl_add_u64 v[52:53], s[14:15], 0, v[52:53]
	v_lshl_add_u64 v[52:53], s[28:29], 2, v[52:53]
	s_lshl_b32 s4, s42, 2
	v_lshl_add_u64 v[52:53], v[52:53], 0, s[4:5]
	s_waitcnt lgkmcnt(0)
	v_add_f32_e32 v50, v50, v51
	global_store_dword v[52:53], v50, off
.LBB0_1480:
	s_or_b64 exec, exec, s[30:31]
	v_or_b32_e32 v58, 32, v90
	v_ashrrev_i32_e32 v59, 31, v58
	s_waitcnt lgkmcnt(0)
	v_lshlrev_b64 v[50:51], 11, v[58:59]
	v_lshl_add_u64 v[50:51], s[12:13], 0, v[50:51]
	v_lshl_add_u64 v[60:61], v[154:155], 1, v[50:51]
	global_load_dwordx4 v[54:57], v[60:61], off
	global_load_dwordx4 v[50:53], v[60:61], off offset:256
	s_waitcnt vmcnt(5)
	v_lshlrev_b32_e32 v62, 16, v70
	v_and_b32_e32 v63, 0xffff0000, v70
	v_lshlrev_b32_e32 v64, 16, v71
	v_and_b32_e32 v65, 0xffff0000, v71
	v_lshlrev_b32_e32 v70, 16, v72
	v_and_b32_e32 v71, 0xffff0000, v72
	v_lshlrev_b32_e32 v72, 16, v73
	v_and_b32_e32 v73, 0xffff0000, v73
	v_pk_add_f32 v[48:49], v[48:49], v[64:65]
	v_pk_add_f32 v[46:47], v[46:47], v[62:63]
	v_pk_add_f32 v[62:63], v[44:45], v[72:73]
	v_pk_add_f32 v[44:45], v[42:43], v[70:71]
	v_mul_f32_e32 v42, v47, v47
	v_mul_f32_e32 v43, v49, v49
	v_fmac_f32_e32 v42, v46, v46
	v_fmac_f32_e32 v43, v48, v48
	v_add_f32_e32 v42, v42, v43
	v_mul_f32_e32 v43, v45, v45
	v_fmac_f32_e32 v43, v44, v44
	v_add_f32_e32 v42, v43, v42
	v_mul_f32_e32 v43, v63, v63
	v_fmac_f32_e32 v43, v62, v62
	v_add_f32_e32 v70, v43, v42
	v_cvt_pk_bf16_f32 v42, v46, v47
	v_cvt_pk_bf16_f32 v43, v48, v49
	s_waitcnt vmcnt(4)
	v_lshlrev_b32_e32 v46, 16, v66
	v_and_b32_e32 v47, 0xffff0000, v66
	v_lshlrev_b32_e32 v48, 16, v67
	v_and_b32_e32 v49, 0xffff0000, v67
	v_lshlrev_b32_e32 v64, 16, v68
	v_and_b32_e32 v65, 0xffff0000, v68
	v_pk_add_f32 v[40:41], v[40:41], v[48:49]
	v_pk_add_f32 v[38:39], v[38:39], v[46:47]
	v_pk_add_f32 v[48:49], v[34:35], v[64:65]
	v_mul_f32_e32 v34, v39, v39
	v_mul_f32_e32 v35, v41, v41
	v_fmac_f32_e32 v34, v38, v38
	v_fmac_f32_e32 v35, v40, v40
	v_lshlrev_b32_e32 v66, 16, v69
	v_and_b32_e32 v67, 0xffff0000, v69
	v_add_f32_e32 v34, v34, v35
	v_mul_f32_e32 v35, v49, v49
	v_pk_add_f32 v[46:47], v[36:37], v[66:67]
	v_fmac_f32_e32 v35, v48, v48
	v_add_f32_e32 v34, v35, v34
	v_mul_f32_e32 v35, v47, v47
	v_fmac_f32_e32 v35, v46, v46
	v_add_f32_e32 v34, v35, v34
	v_add_f32_e32 v34, v70, v34
	v_mov_b32_e32 v35, v34
	s_nop 1
	v_permlane16_swap_b32 v34, v35
	v_cvt_pk_bf16_f32 v44, v44, v45
	v_cvt_pk_bf16_f32 v45, v62, v63
	global_store_dwordx4 v[76:77], v[42:45], off
	v_cvt_pk_bf16_f32 v36, v38, v39
	s_waitcnt lgkmcnt(0)
	v_add_f32_e32 v34, v34, v35
	v_mov_b32_e32 v35, v34
	s_nop 1
	v_permlane32_swap_b32 v34, v35
	v_cvt_pk_bf16_f32 v37, v40, v41
	v_cvt_pk_bf16_f32 v38, v48, v49
	v_cvt_pk_bf16_f32 v39, v46, v47
	global_store_dwordx4 v[76:77], v[36:39], off offset:256
	s_and_saveexec_b64 s[30:31], s[6:7]
	s_cbranch_execz .LBB0_1482
	v_lshlrev_b64 v[36:37], 6, v[74:75]
	v_lshl_add_u64 v[36:37], s[14:15], 0, v[36:37]
	v_lshl_add_u64 v[36:37], s[28:29], 2, v[36:37]
	s_lshl_b32 s4, s42, 2
	v_lshl_add_u64 v[36:37], v[36:37], 0, s[4:5]
	s_waitcnt lgkmcnt(0)
	v_add_f32_e32 v34, v34, v35
	global_store_dword v[36:37], v34, off
; __device__ __forceinline__ unsigned cvt_pk_bf16(float lo, float hi) { unsigned r; asm volatile("v_cvt_pk_bf16_f32 %0, %1, %2" : "=v"(r) : "v"(lo), "v"(hi)); return r; }
; __device__ __forceinline__ float bflo(unsigned w) { return __uint_as_float(w << 16); }
; __device__ __forceinline__ float bfhi(unsigned w) { return __uint_as_float(w & 0xffff0000u); }
;     __device__ __forceinline__ void ld(Ld& L, size_t o) const {
; #pragma unroll
;         for (int bj = 0; bj < 2; ++bj) { if (BASEF32) { L.a[bj][0] = *(const f32x4*)((const float*)base + o + bj * HALF); L.a[bj][1] = *(const f32x4*)((const float*)base + o + bj * HALF + 4); }
;             else { const v4u w = *(const v4u*)((const bf16*)base + o + bj * HALF); L.a[bj][0] = __builtin_bit_cast(f32x4, w); } }
;     }
;     __device__ __forceinline__ void operator()(const pg8::f32x4 (&acc)[2][2][4][2], const Unit& u, int wr, int wc, int fr, int fq) const {
;         const int row0 = u.pm * BM + wr * 64 + fr, col0 = u.pn * BM + wc * 32 + 8 * fq;
;         Ld nx; ld(nx, (size_t)row0 * DM_ + col0);
; #pragma unroll
;         for (int k = 0; k < 8; ++k) { const int ai = k >> 2, m = k & 3; const int row = row0 + ai * HALF + m * 16; float q = 0.f; const Ld cu = nx;
;             if (k < 7) ld(nx, (size_t)(row0 + ((k + 1) >> 2) * HALF + ((k + 1) & 3) * 16) * DM_ + col0);
; #pragma unroll
;             for (int bj = 0; bj < 2; ++bj) { const size_t o = (size_t)row * DM_ + col0 + bj * HALF; f32x4 b0, b1;
;                 if (BASEF32) { b0 = cu.a[bj][0]; b1 = cu.a[bj][1]; }
;                 else { const v4u w = __builtin_bit_cast(v4u, cu.a[bj][0]); b0 = (f32x4){bflo(w.x), bfhi(w.x), bflo(w.y), bfhi(w.y)}; b1 = (f32x4){bflo(w.z), bfhi(w.z), bflo(w.w), bfhi(w.w)}; }
;                 const f32x4 r0 = b0 + acc[ai][bj][m][0], r1 = b1 + acc[ai][bj][m][1];
;                 q += (r0[0] * r0[0] + r0[1] * r0[1]) + (r0[2] * r0[2] + r0[3] * r0[3]) + (r1[0] * r1[0] + r1[1] * r1[1]) + (r1[2] * r1[2] + r1[3] * r1[3]);
;                 v4u w; w.x = cvt_pk_bf16(r0[0], r0[1]); w.y = cvt_pk_bf16(r0[2], r0[3]); w.z = cvt_pk_bf16(r1[0], r1[1]); w.w = cvt_pk_bf16(r1[2], r1[3]); *(v4u*)(out + o) = w; }
;             q += __shfl_xor(q, 16); q += __shfl_xor(q, 32); if (fq == 0) ssq[(size_t)row * 16 + u.pn * 4 + wc] = q; }
;     }
.LBB0_1482:
	s_or_b64 exec, exec, s[30:31]
	v_or_b32_e32 v42, 48, v90
	v_ashrrev_i32_e32 v43, 31, v42
	s_waitcnt lgkmcnt(0)
	v_lshlrev_b64 v[34:35], 11, v[42:43]
	v_lshl_add_u64 v[34:35], s[12:13], 0, v[34:35]
	v_lshl_add_u64 v[44:45], v[154:155], 1, v[34:35]
	global_load_dwordx4 v[38:41], v[44:45], off
	global_load_dwordx4 v[34:37], v[44:45], off offset:256
	s_waitcnt vmcnt(5)
	v_lshlrev_b32_e32 v46, 16, v54
	v_and_b32_e32 v47, 0xffff0000, v54
	v_lshlrev_b32_e32 v48, 16, v55
	v_and_b32_e32 v49, 0xffff0000, v55
	v_lshlrev_b32_e32 v54, 16, v56
	v_and_b32_e32 v55, 0xffff0000, v56
	v_lshlrev_b32_e32 v56, 16, v57
	v_and_b32_e32 v57, 0xffff0000, v57
	v_pk_add_f32 v[32:33], v[32:33], v[48:49]
	v_pk_add_f32 v[30:31], v[30:31], v[46:47]
	v_pk_add_f32 v[46:47], v[28:29], v[56:57]
	v_pk_add_f32 v[28:29], v[26:27], v[54:55]
	v_mul_f32_e32 v26, v31, v31
	v_mul_f32_e32 v27, v33, v33
	v_fmac_f32_e32 v26, v30, v30
	v_fmac_f32_e32 v27, v32, v32
	v_add_f32_e32 v26, v26, v27
	v_mul_f32_e32 v27, v29, v29
	v_fmac_f32_e32 v27, v28, v28
	v_add_f32_e32 v26, v27, v26
	v_mul_f32_e32 v27, v47, v47
	v_fmac_f32_e32 v27, v46, v46
	v_add_f32_e32 v54, v27, v26
	v_cvt_pk_bf16_f32 v26, v30, v31
	v_cvt_pk_bf16_f32 v27, v32, v33
	s_waitcnt vmcnt(4)
	v_lshlrev_b32_e32 v30, 16, v50
	v_and_b32_e32 v31, 0xffff0000, v50
	v_lshlrev_b32_e32 v32, 16, v51
	v_and_b32_e32 v33, 0xffff0000, v51
	v_lshlrev_b32_e32 v48, 16, v52
	v_and_b32_e32 v49, 0xffff0000, v52
	v_pk_add_f32 v[24:25], v[24:25], v[32:33]
	v_pk_add_f32 v[22:23], v[22:23], v[30:31]
	v_pk_add_f32 v[32:33], v[18:19], v[48:49]
	v_mul_f32_e32 v18, v23, v23
	v_mul_f32_e32 v19, v25, v25
	v_fmac_f32_e32 v18, v22, v22
	v_fmac_f32_e32 v19, v24, v24
	v_lshlrev_b32_e32 v50, 16, v53
	v_and_b32_e32 v51, 0xffff0000, v53
	v_add_f32_e32 v18, v18, v19
	v_mul_f32_e32 v19, v33, v33
	v_pk_add_f32 v[30:31], v[20:21], v[50:51]
	v_fmac_f32_e32 v19, v32, v32
	v_add_f32_e32 v18, v19, v18
	v_mul_f32_e32 v19, v31, v31
	v_fmac_f32_e32 v19, v30, v30
	v_add_f32_e32 v18, v19, v18
	v_add_f32_e32 v18, v54, v18
	v_mov_b32_e32 v19, v18
	s_nop 1
	v_permlane16_swap_b32 v18, v19
	v_cvt_pk_bf16_f32 v28, v28, v29
	v_cvt_pk_bf16_f32 v29, v46, v47
	global_store_dwordx4 v[60:61], v[26:29], off
	v_cvt_pk_bf16_f32 v20, v22, v23
	s_waitcnt lgkmcnt(0)
	v_add_f32_e32 v18, v18, v19
	v_mov_b32_e32 v19, v18
	s_nop 1
	v_permlane32_swap_b32 v18, v19
	v_cvt_pk_bf16_f32 v21, v24, v25
	v_cvt_pk_bf16_f32 v22, v32, v33
	v_cvt_pk_bf16_f32 v23, v30, v31
	global_store_dwordx4 v[60:61], v[20:23], off offset:256
	s_and_saveexec_b64 s[30:31], s[6:7]
	s_cbranch_execz .LBB0_1484
	v_lshlrev_b64 v[20:21], 6, v[58:59]
	v_lshl_add_u64 v[20:21], s[14:15], 0, v[20:21]
	v_lshl_add_u64 v[20:21], s[28:29], 2, v[20:21]
	s_lshl_b32 s4, s42, 2
	v_lshl_add_u64 v[20:21], v[20:21], 0, s[4:5]
	s_waitcnt lgkmcnt(0)
	v_add_f32_e32 v18, v18, v19
	global_store_dword v[20:21], v18, off
.LBB0_1484:
	s_or_b64 exec, exec, s[30:31]
	s_waitcnt vmcnt(3)
	v_lshlrev_b32_e32 v18, 16, v38
	s_waitcnt lgkmcnt(0)
	v_and_b32_e32 v19, 0xffff0000, v38
	v_lshlrev_b32_e32 v20, 16, v39
	v_and_b32_e32 v21, 0xffff0000, v39
	v_lshlrev_b32_e32 v22, 16, v40
	v_and_b32_e32 v23, 0xffff0000, v40
	v_lshlrev_b32_e32 v24, 16, v41
	v_and_b32_e32 v25, 0xffff0000, v41
	v_pk_add_f32 v[16:17], v[16:17], v[20:21]
	v_pk_add_f32 v[14:15], v[14:15], v[18:19]
	v_pk_add_f32 v[18:19], v[12:13], v[24:25]
	v_pk_add_f32 v[12:13], v[10:11], v[22:23]
	v_mul_f32_e32 v10, v15, v15
	v_mul_f32_e32 v11, v17, v17
	v_fmac_f32_e32 v10, v14, v14
	v_fmac_f32_e32 v11, v16, v16
	v_add_f32_e32 v10, v10, v11
	v_mul_f32_e32 v11, v13, v13
	v_fmac_f32_e32 v11, v12, v12
	v_add_f32_e32 v10, v11, v10
	v_mul_f32_e32 v11, v19, v19
	v_fmac_f32_e32 v11, v18, v18
	v_add_f32_e32 v24, v11, v10
	v_cvt_pk_bf16_f32 v10, v14, v15
	v_cvt_pk_bf16_f32 v11, v16, v17
	s_waitcnt vmcnt(2)
	v_lshlrev_b32_e32 v14, 16, v34
	v_and_b32_e32 v15, 0xffff0000, v34
	v_lshlrev_b32_e32 v16, 16, v35
	v_and_b32_e32 v17, 0xffff0000, v35
	v_lshlrev_b32_e32 v20, 16, v36
	v_and_b32_e32 v21, 0xffff0000, v36
	v_pk_add_f32 v[8:9], v[8:9], v[16:17]
	v_pk_add_f32 v[6:7], v[6:7], v[14:15]
	v_pk_add_f32 v[16:17], v[2:3], v[20:21]
	v_mul_f32_e32 v2, v7, v7
	v_mul_f32_e32 v3, v9, v9
	v_fmac_f32_e32 v2, v6, v6
	v_fmac_f32_e32 v3, v8, v8
	v_lshlrev_b32_e32 v22, 16, v37
	v_and_b32_e32 v23, 0xffff0000, v37
	v_add_f32_e32 v2, v2, v3
	v_mul_f32_e32 v3, v17, v17
	v_pk_add_f32 v[14:15], v[4:5], v[22:23]
	v_fmac_f32_e32 v3, v16, v16
	v_add_f32_e32 v2, v3, v2
	v_mul_f32_e32 v3, v15, v15
	v_fmac_f32_e32 v3, v14, v14
	v_add_f32_e32 v2, v3, v2
	v_add_f32_e32 v2, v24, v2
	v_mov_b32_e32 v3, v2
	s_nop 1
	v_permlane16_swap_b32 v2, v3
	v_cvt_pk_bf16_f32 v12, v12, v13
	v_cvt_pk_bf16_f32 v13, v18, v19
	global_store_dwordx4 v[44:45], v[10:13], off
	v_cvt_pk_bf16_f32 v4, v6, v7
	s_waitcnt lgkmcnt(0)
	v_add_f32_e32 v2, v2, v3
	v_mov_b32_e32 v3, v2
	s_nop 1
	v_permlane32_swap_b32 v2, v3
	v_cvt_pk_bf16_f32 v5, v8, v9
	v_cvt_pk_bf16_f32 v6, v16, v17
	v_cvt_pk_bf16_f32 v7, v14, v15
	global_store_dwordx4 v[44:45], v[4:7], off offset:256
	s_and_saveexec_b64 s[30:31], s[6:7]
	s_cbranch_execz .LBB0_1486
	v_lshlrev_b64 v[4:5], 6, v[42:43]
	v_lshl_add_u64 v[4:5], s[14:15], 0, v[4:5]
	v_lshl_add_u64 v[4:5], s[28:29], 2, v[4:5]
	s_lshl_b32 s4, s42, 2
	v_lshl_add_u64 v[4:5], v[4:5], 0, s[4:5]
	s_waitcnt lgkmcnt(0)
	v_add_f32_e32 v2, v2, v3
	global_store_dword v[4:5], v2, off

; __device__ __forceinline__ void rstd8(const float* ss, int row0, int fq, float (&rs)[8]) {
;     f32x4 a[8];
; #pragma unroll
;     for (int k = 0; k < 8; ++k) a[k] = *(const f32x4*)(ss + (size_t)(row0 + (k >> 2) * 128 + (k & 3) * 16) * 16 + 4 * fq);
; #pragma unroll
;     for (int k = 0; k < 8; ++k) { float s = (a[k][0] + a[k][1]) + (a[k][2] + a[k][3]); s += __shfl_xor(s, 16); s += __shfl_xor(s, 32); rs[k] = __builtin_amdgcn_rsqf(s * (1.f / 1024.f) + EPS); }
; }
;     __device__ __forceinline__ void operator()(const pg8::f32x4 (&acc)[2][2][4][2], const Unit& u, int wr, int wc, int fr, int fq) const {
;         const int row0 = u.pm * BM + wr * 64 + fr, col0 = u.pn * BM + wc * 32 + 8 * fq;
;         float rsv[8]; rstd8(ss, row0, fq, rsv);
;         v4u nb[2], np[2];
; #pragma unroll
;         for (int bj = 0; bj < 2; ++bj) { const size_t o = (size_t)row0 * DM_ + col0 + bj * HALF; nb[bj] = *(const v4u*)(base + o); np[bj] = *(const v4u*)(pp + o); }
.LBB0_1768:
	v_lshl_add_u32 v226, s12, 8, v1
	v_or_b32_e32 v180, 16, v226
	v_ashrrev_i32_e32 v227, 31, v226
	v_ashrrev_i32_e32 v181, 31, v180
	v_or_b32_e32 v176, 32, v226
	v_or_b32_e32 v172, 48, v226
	v_add_u32_e32 v166, 0x80, v226
	v_lshlrev_b64 v[182:183], 6, v[226:227]
	v_lshlrev_b64 v[178:179], 6, v[180:181]
	v_ashrrev_i32_e32 v177, 31, v176
	v_ashrrev_i32_e32 v173, 31, v172
	v_ashrrev_i32_e32 v167, 31, v166
	v_lshl_add_u64 v[164:165], v[154:155], 0, v[182:183]
	v_lshl_add_u64 v[134:135], v[154:155], 0, v[178:179]
	v_lshlrev_b64 v[174:175], 6, v[176:177]
	v_lshlrev_b64 v[170:171], 6, v[172:173]
	v_lshlrev_b64 v[168:169], 6, v[166:167]
	global_load_dwordx4 v[130:133], v[164:165], off
	s_nop 0
	global_load_dwordx4 v[134:137], v[134:135], off
	v_lshl_add_u64 v[138:139], v[154:155], 0, v[174:175]
	v_lshl_add_u64 v[142:143], v[154:155], 0, v[170:171]
	v_lshl_add_u64 v[192:193], v[154:155], 0, v[168:169]
	global_load_dwordx4 v[138:141], v[138:139], off
	s_nop 0
	global_load_dwordx4 v[142:145], v[142:143], off
	v_add_co_u32_e32 v164, vcc, s48, v164
	global_load_dwordx4 v[194:197], v[192:193], off
	s_nop 0
	v_addc_co_u32_e32 v165, vcc, 0, v165, vcc
	global_load_dwordx4 v[198:201], v[164:165], off offset:1024
	global_load_dwordx4 v[202:205], v[164:165], off offset:2048
	global_load_dwordx4 v[206:209], v[164:165], off offset:3072
	v_and_b32_e32 v165, 64, v189
	v_xor_b32_e32 v191, 16, v189
	v_add_u32_e32 v193, 64, v165
	v_xor_b32_e32 v192, 32, v189
	v_cmp_lt_i32_e32 vcc, v191, v193
	v_lshl_or_b32 v164, s4, 8, v185
	v_ashrrev_i32_e32 v165, 31, v164
	v_cndmask_b32_e32 v191, v189, v191, vcc
	v_cmp_lt_i32_e32 vcc, v192, v193
	v_lshlrev_b64 v[210:211], 10, v[226:227]
	v_lshl_add_u64 v[210:211], v[210:211], 0, v[164:165]
	v_cndmask_b32_e32 v193, v189, v192, vcc
	v_lshlrev_b32_e32 v192, 2, v191
	v_lshlrev_b32_e32 v191, 2, v193
	v_lshlrev_b64 v[222:223], 1, v[210:211]
	v_lshl_add_u64 v[210:211], s[10:11], 0, v[222:223]
	v_lshl_add_u64 v[214:215], s[16:17], 0, v[222:223]
	global_load_dwordx4 v[210:213], v[210:211], off
	s_nop 0
	global_load_dwordx4 v[214:217], v[214:215], off
	v_or_b32_e32 v222, 0x100, v222
	v_lshlrev_b64 v[226:227], 11, v[226:227]
	s_lshl_b32 s4, s4, 2
	s_ashr_i32 s5, s4, 31
	s_waitcnt vmcnt(0)
	v_mov_b32_e32 v218, v131
	v_mov_b32_e32 v219, v132
	v_mov_b32_e32 v131, v133
	v_pk_add_f32 v[130:131], v[218:219], v[130:131]
	v_add_f32_e32 v132, v134, v135
	v_add_f32_e32 v133, v136, v137
	v_add_f32_e32 v134, v138, v139
	v_add_f32_e32 v135, v140, v141
	v_add_f32_e32 v138, v194, v195
	v_add_f32_e32 v139, v196, v197
	v_add_f32_e32 v130, v130, v131
	v_add_f32_e32 v131, v132, v133
	v_add_f32_e32 v132, v134, v135
	v_add_f32_e32 v134, v138, v139
	v_mov_b32_e32 v138, v130
	s_nop 1
	v_permlane16_swap_b32 v130, v138
	v_mov_b32_e32 v139, v131
	s_nop 1
	v_permlane16_swap_b32 v131, v139
	v_add_f32_e32 v136, v142, v143
	v_add_f32_e32 v137, v144, v145
	v_add_f32_e32 v142, v202, v203
	s_waitcnt lgkmcnt(1)
	v_add_f32_e32 v130, v130, v138
	v_add_f32_e32 v143, v204, v205
	s_waitcnt lgkmcnt(0)
	v_add_f32_e32 v205, v131, v139
	v_mov_b32_e32 v131, v130
	s_nop 1
	v_permlane32_swap_b32 v130, v131
	v_add_f32_e32 v144, v206, v207
	v_add_f32_e32 v145, v208, v209
	v_add_f32_e32 v133, v136, v137
	v_add_f32_e32 v136, v142, v143
	v_add_f32_e32 v137, v144, v145
	v_mov_b32_e32 v144, v136
	s_nop 1
	v_permlane16_swap_b32 v136, v144
	s_waitcnt lgkmcnt(1)
	v_add_f32_e32 v130, v130, v131
	v_fmamk_f32 v130, v130, 0x3a800000, v190
	v_add_f32_e32 v140, v198, v199
	v_add_f32_e32 v141, v200, v201
	s_waitcnt lgkmcnt(0)
	v_add_f32_e32 v195, v136, v144
	v_rsq_f32_e32 v136, v130
	v_lshl_add_u64 v[130:131], s[10:11], 0, v[222:223]
	global_load_dwordx4 v[218:221], v[130:131], off
	v_lshl_add_u64 v[130:131], s[16:17], 0, v[222:223]
	global_load_dwordx4 v[222:225], v[130:131], off
	v_add_f32_e32 v135, v140, v141
	v_mov_b32_e32 v140, v132
	s_nop 1
	v_permlane16_swap_b32 v132, v140
	v_mov_b32_e32 v141, v133
	s_nop 1
	v_permlane16_swap_b32 v133, v141
	v_mov_b32_e32 v142, v134
	s_nop 1
	v_permlane16_swap_b32 v134, v142
	v_mov_b32_e32 v143, v135
	s_nop 1
	v_permlane16_swap_b32 v135, v143
	v_mov_b32_e32 v145, v137
	s_nop 1
	v_permlane16_swap_b32 v137, v145
	v_lshlrev_b64 v[130:131], 10, v[180:181]
	v_lshl_add_u64 v[130:131], v[130:131], 0, v[164:165]
	v_lshlrev_b64 v[130:131], 1, v[130:131]
	s_waitcnt lgkmcnt(4)
	v_add_f32_e32 v203, v132, v140
	s_waitcnt lgkmcnt(3)
	v_add_f32_e32 v201, v133, v141
	s_waitcnt lgkmcnt(2)
	v_add_f32_e32 v199, v134, v142
	s_waitcnt lgkmcnt(1)
	v_add_f32_e32 v197, v135, v143
	v_lshl_add_u64 v[132:133], s[10:11], 0, v[130:131]
	v_lshl_add_u64 v[134:135], s[16:17], 0, v[130:131]
	v_or_b32_e32 v130, 0x100, v130
	s_waitcnt lgkmcnt(0)
; __device__ __forceinline__ unsigned cvt_pk_bf16(float lo, float hi) { unsigned r; asm volatile("v_cvt_pk_bf16_f32 %0, %1, %2" : "=v"(r) : "v"(lo), "v"(hi)); return r; }
; __device__ __forceinline__ void rstd8(const float* ss, int row0, int fq, float (&rs)[8]) {
;     f32x4 a[8];
; #pragma unroll
;     for (int k = 0; k < 8; ++k) a[k] = *(const f32x4*)(ss + (size_t)(row0 + (k >> 2) * 128 + (k & 3) * 16) * 16 + 4 * fq);
; #pragma unroll
;     for (int k = 0; k < 8; ++k) { float s = (a[k][0] + a[k][1]) + (a[k][2] + a[k][3]); s += __shfl_xor(s, 16); s += __shfl_xor(s, 32); rs[k] = __builtin_amdgcn_rsqf(s * (1.f / 1024.f) + EPS); }
; }
;     __device__ __forceinline__ void operator()(const pg8::f32x4 (&acc)[2][2][4][2], const Unit& u, int wr, int wc, int fr, int fq) const {
;     ...
;         for (int k = 0; k < 8; ++k) { const int ai = k >> 2, m = k & 3; const int row = row0 + ai * HALF + m * 16; const float rs = rsv[k]; float q = 0.f;
;             v4u cb[2], cp[2];
; #pragma unroll
;             for (int bj = 0; bj < 2; ++bj) { cb[bj] = nb[bj]; cp[bj] = np[bj]; }
;             if (k < 7) {
; #pragma unroll
;                 for (int bj = 0; bj < 2; ++bj) { const size_t o = (size_t)(row0 + ((k + 1) >> 2) * HALF + ((k + 1) & 3) * 16) * DM_ + col0 + bj * HALF; nb[bj] = *(const v4u*)(base + o); np[bj] = *(const v4u*)(pp + o); } }
; #pragma unroll
;             for (int bj = 0; bj < 2; ++bj) { const size_t o = (size_t)row * DM_ + col0 + bj * HALF; const v4u bw = cb[bj], pw = cp[bj];
;                 const float c1 = -1.4426950408889634f * rs; float r[8];
;     ...
;                 { const f32x4 a0 = acc[ai][bj][m][0], a1 = acc[ai][bj][m][1];
;                   PLE2(0, a0, 0, bw.x, pw.x) PLE2(2, a0, 2, bw.y, pw.y) PLE2(4, a1, 0, bw.z, pw.z) PLE2(6, a1, 2, bw.w, pw.w) }
;     ...
; #pragma unroll
;                 for (int e = 0; e < 8; ++e) q += r[e] * r[e];
;                 v4u w; w.x = cvt_pk_bf16(r[0], r[1]); w.y = cvt_pk_bf16(r[2], r[3]); w.z = cvt_pk_bf16(r[4], r[5]); w.w = cvt_pk_bf16(r[6], r[7]); *(v4u*)(out + o) = w; }
;             q += __shfl_xor(q, 16); q += __shfl_xor(q, 32); if (fq == 0) ssq[(size_t)row * 16 + u.pn * 4 + wc] = q; }
	v_add_f32_e32 v193, v137, v145
	global_load_dwordx4 v[142:145], v[132:133], off
	global_load_dwordx4 v[138:141], v[134:135], off
	v_lshl_add_u64 v[132:133], s[10:11], 0, v[130:131]
	v_lshl_add_u64 v[130:131], s[16:17], 0, v[130:131]
	v_mul_f32_e32 v208, 0xbfb8aa3b, v136
	global_load_dwordx4 v[134:137], v[132:133], off
	s_nop 0
	global_load_dwordx4 v[130:133], v[130:131], off
	v_pk_mul_f32 v[128:129], v[128:129], v[208:209] op_sel_hi:[1,0]
	v_pk_mul_f32 v[122:123], v[122:123], v[208:209] op_sel_hi:[1,0]
	v_exp_f32_e32 v128, v128
	v_exp_f32_e32 v129, v129
	v_exp_f32_e32 v122, v122
	v_exp_f32_e32 v123, v123
	v_pk_mul_f32 v[126:127], v[126:127], v[208:209] op_sel_hi:[1,0]
	v_pk_add_f32 v[128:129], v[128:129], 1.0 op_sel_hi:[1,0]
	v_exp_f32_e32 v126, v126
	v_exp_f32_e32 v127, v127
	v_rcp_f32_e32 v128, v128
	v_rcp_f32_e32 v129, v129
	v_pk_add_f32 v[122:123], v[122:123], 1.0 op_sel_hi:[1,0]
	v_pk_mul_f32 v[124:125], v[124:125], v[208:209] op_sel_hi:[1,0]
	v_rcp_f32_e32 v122, v122
	v_rcp_f32_e32 v123, v123
	v_exp_f32_e32 v124, v124
	v_exp_f32_e32 v125, v125
	v_pk_mul_f32 v[118:119], v[118:119], v[208:209] op_sel_hi:[1,0]
	v_pk_mul_f32 v[120:121], v[120:121], v[208:209] op_sel_hi:[1,0]
	v_exp_f32_e32 v118, v118
	v_exp_f32_e32 v119, v119
	v_lshlrev_b32_e32 v228, 16, v210
	v_and_b32_e32 v229, 0xffff0000, v210
	v_lshlrev_b32_e32 v230, 16, v214
	v_and_b32_e32 v231, 0xffff0000, v214
	v_lshlrev_b32_e32 v210, 16, v211
	v_and_b32_e32 v211, 0xffff0000, v211
	v_lshlrev_b32_e32 v214, 16, v215
	v_and_b32_e32 v215, 0xffff0000, v215
	v_exp_f32_e32 v120, v120
	v_exp_f32_e32 v121, v121
	v_pk_mul_f32 v[114:115], v[114:115], v[208:209] op_sel_hi:[1,0]
	v_pk_add_f32 v[126:127], v[126:127], 1.0 op_sel_hi:[1,0]
	v_pk_fma_f32 v[128:129], v[128:129], v[214:215], v[210:211]
	v_lshlrev_b32_e32 v210, 16, v212
	v_and_b32_e32 v211, 0xffff0000, v212
	v_lshlrev_b32_e32 v214, 16, v216
	v_and_b32_e32 v215, 0xffff0000, v216
	v_exp_f32_e32 v114, v114
	v_exp_f32_e32 v115, v115
	v_rcp_f32_e32 v126, v126
	v_rcp_f32_e32 v127, v127
	v_pk_fma_f32 v[210:211], v[122:123], v[214:215], v[210:211]
	v_pk_add_f32 v[122:123], v[124:125], 1.0 op_sel_hi:[1,0]
	v_pk_add_f32 v[118:119], v[118:119], 1.0 op_sel_hi:[1,0]
	v_rcp_f32_e32 v122, v122
	v_rcp_f32_e32 v123, v123
	v_rcp_f32_e32 v118, v118
	v_rcp_f32_e32 v119, v119
	v_pk_add_f32 v[120:121], v[120:121], 1.0 op_sel_hi:[1,0]
	v_pk_add_f32 v[114:115], v[114:115], 1.0 op_sel_hi:[1,0]
	v_rcp_f32_e32 v120, v120
	v_rcp_f32_e32 v121, v121
	v_pk_mul_f32 v[116:117], v[116:117], v[208:209] op_sel_hi:[1,0]
	v_pk_fma_f32 v[126:127], v[126:127], v[230:231], v[228:229]
	v_lshlrev_b32_e32 v124, 16, v213
	v_and_b32_e32 v125, 0xffff0000, v213
	v_lshlrev_b32_e32 v212, 16, v217
	v_and_b32_e32 v213, 0xffff0000, v217
	v_rcp_f32_e32 v114, v114
	v_rcp_f32_e32 v115, v115
	v_exp_f32_e32 v116, v116
	v_exp_f32_e32 v117, v117
	v_pk_fma_f32 v[212:213], v[122:123], v[212:213], v[124:125]
	v_pk_mul_f32 v[214:215], v[126:127], v[126:127]
	v_pk_mul_f32 v[216:217], v[128:129], v[128:129]
	v_cvt_pk_bf16_f32 v122, v126, v127
	v_cvt_pk_bf16_f32 v123, v128, v129
	s_waitcnt vmcnt(5)
	v_lshlrev_b32_e32 v126, 16, v218
	v_and_b32_e32 v127, 0xffff0000, v218
	s_waitcnt vmcnt(4)
	v_lshlrev_b32_e32 v128, 16, v222
	v_and_b32_e32 v129, 0xffff0000, v222
	v_pk_fma_f32 v[118:119], v[118:119], v[128:129], v[126:127]
	v_lshlrev_b32_e32 v126, 16, v219
	v_and_b32_e32 v127, 0xffff0000, v219
	v_lshlrev_b32_e32 v128, 16, v223
	v_and_b32_e32 v129, 0xffff0000, v223
	v_pk_fma_f32 v[120:121], v[120:121], v[128:129], v[126:127]
	v_lshlrev_b32_e32 v126, 16, v220
	v_and_b32_e32 v127, 0xffff0000, v220
	v_lshlrev_b32_e32 v128, 16, v224
	v_and_b32_e32 v129, 0xffff0000, v224
	v_add_f32_e32 v207, v214, v215
	v_pk_fma_f32 v[126:127], v[114:115], v[128:129], v[126:127]
	v_pk_add_f32 v[114:115], v[116:117], 1.0 op_sel_hi:[1,0]
	v_add_f32_e32 v207, v216, v207
	v_pk_mul_f32 v[228:229], v[210:211], v[210:211]
	v_rcp_f32_e32 v114, v114
	v_rcp_f32_e32 v115, v115
	v_add_f32_e32 v207, v217, v207
	v_add_f32_e32 v207, v228, v207
	v_pk_mul_f32 v[230:231], v[212:213], v[212:213]
	v_add_f32_e32 v207, v229, v207
	v_lshlrev_b32_e32 v116, 16, v221
	v_and_b32_e32 v117, 0xffff0000, v221
	v_lshlrev_b32_e32 v128, 16, v225
	v_and_b32_e32 v129, 0xffff0000, v225
	v_add_f32_e32 v207, v230, v207
	v_pk_fma_f32 v[128:129], v[114:115], v[128:129], v[116:117]
	v_pk_mul_f32 v[114:115], v[118:119], v[118:119]
	v_add_f32_e32 v207, v231, v207
	v_add_f32_e32 v114, v114, v207
	v_pk_mul_f32 v[116:117], v[120:121], v[120:121]
	v_add_f32_e32 v114, v115, v114
	v_add_f32_e32 v114, v116, v114
	v_pk_mul_f32 v[208:209], v[126:127], v[126:127]
	v_add_f32_e32 v114, v117, v114
	v_add_f32_e32 v114, v208, v114
	v_cvt_pk_bf16_f32 v124, v210, v211
	v_pk_mul_f32 v[210:211], v[128:129], v[128:129]
	v_add_f32_e32 v114, v209, v114
	v_add_f32_e32 v114, v210, v114
	v_add_f32_e32 v117, v211, v114
	v_mov_b32_e32 v207, v117
	s_nop 1
	v_permlane16_swap_b32 v117, v207
	v_lshl_add_u64 v[114:115], s[20:21], 0, v[226:227]
	v_lshl_add_u64 v[208:209], v[164:165], 1, v[114:115]
	v_mov_b32_e32 v206, v205
	s_nop 1
	v_permlane32_swap_b32 v205, v206
	v_mov_b32_e32 v204, v203
	s_nop 1
	v_permlane32_swap_b32 v203, v204
	s_waitcnt lgkmcnt(2)
	v_add_f32_e32 v114, v117, v207
	v_mov_b32_e32 v202, v201
	s_nop 1
	v_permlane32_swap_b32 v201, v202
	v_mov_b32_e32 v200, v199
	s_nop 1
	v_permlane32_swap_b32 v199, v200
	v_mov_b32_e32 v198, v197
	s_nop 1
	v_permlane32_swap_b32 v197, v198
	v_mov_b32_e32 v196, v195
	s_nop 1
	v_permlane32_swap_b32 v195, v196
	v_mov_b32_e32 v194, v193
	s_nop 1
	v_permlane32_swap_b32 v193, v194
	v_mov_b32_e32 v115, v114
	s_nop 1
	v_permlane32_swap_b32 v114, v115
	v_cvt_pk_bf16_f32 v125, v212, v213
	global_store_dwordx4 v[208:209], v[122:125], off
	v_cvt_pk_bf16_f32 v116, v118, v119
	v_cvt_pk_bf16_f32 v117, v120, v121
	v_cvt_pk_bf16_f32 v118, v126, v127
	v_cvt_pk_bf16_f32 v119, v128, v129
	global_store_dwordx4 v[208:209], v[116:119], off offset:256
	s_and_saveexec_b64 s[36:37], s[6:7]
	s_cbranch_execz .LBB0_1770
	v_lshl_add_u64 v[116:117], s[18:19], 0, v[182:183]
	v_lshl_add_u64 v[116:117], s[4:5], 2, v[116:117]
	s_lshl_b32 s12, s49, 2
	v_lshl_add_u64 v[116:117], v[116:117], 0, s[12:13]
	s_waitcnt lgkmcnt(0)
	v_add_f32_e32 v114, v114, v115
	global_store_dword v[116:117], v114, off
; __device__ __forceinline__ unsigned cvt_pk_bf16(float lo, float hi) { unsigned r; asm volatile("v_cvt_pk_bf16_f32 %0, %1, %2" : "=v"(r) : "v"(lo), "v"(hi)); return r; }
; #define PLE2(kk, A, e0, BW, PW) { const f32x2 t = (f32x2){A[e0], A[e0 + 1]} * c1; f32x2 d; d.x = __builtin_amdgcn_exp2f(t.x); d.y = __builtin_amdgcn_exp2f(t.y); d = d + 1.0f; \
;                     f32x2 q2; q2.x = __builtin_amdgcn_rcpf(d.x); q2.y = __builtin_amdgcn_rcpf(d.y); const f32x2 o2 = (f32x2){bflo(BW), bfhi(BW)} + (f32x2){bflo(PW), bfhi(PW)} * q2; r[kk] = o2.x; r[kk + 1] = o2.y; }
;     __device__ __forceinline__ void operator()(const pg8::f32x4 (&acc)[2][2][4][2], const Unit& u, int wr, int wc, int fr, int fq) const {
;     ...
;         for (int k = 0; k < 8; ++k) { const int ai = k >> 2, m = k & 3; const int row = row0 + ai * HALF + m * 16; const float rs = rsv[k]; float q = 0.f;
;             v4u cb[2], cp[2];
; #pragma unroll
;             for (int bj = 0; bj < 2; ++bj) { cb[bj] = nb[bj]; cp[bj] = np[bj]; }
;             if (k < 7) {
; #pragma unroll
;                 for (int bj = 0; bj < 2; ++bj) { const size_t o = (size_t)(row0 + ((k + 1) >> 2) * HALF + ((k + 1) & 3) * 16) * DM_ + col0 + bj * HALF; nb[bj] = *(const v4u*)(base + o); np[bj] = *(const v4u*)(pp + o); } }
; #pragma unroll
;             for (int bj = 0; bj < 2; ++bj) { const size_t o = (size_t)row * DM_ + col0 + bj * HALF; const v4u bw = cb[bj], pw = cp[bj];
;                 const float c1 = -1.4426950408889634f * rs; float r[8];
;     ...
;                 { const f32x4 a0 = acc[ai][bj][m][0], a1 = acc[ai][bj][m][1];
;                   PLE2(0, a0, 0, bw.x, pw.x) PLE2(2, a0, 2, bw.y, pw.y) PLE2(4, a1, 0, bw.z, pw.z) PLE2(6, a1, 2, bw.w, pw.w) }
;     ...
; #pragma unroll
;                 for (int e = 0; e < 8; ++e) q += r[e] * r[e];
;                 v4u w; w.x = cvt_pk_bf16(r[0], r[1]); w.y = cvt_pk_bf16(r[2], r[3]); w.z = cvt_pk_bf16(r[4], r[5]); w.w = cvt_pk_bf16(r[6], r[7]); *(v4u*)(out + o) = w; }
;             q += __shfl_xor(q, 16); q += __shfl_xor(q, 32); if (fq == 0) ssq[(size_t)row * 16 + u.pn * 4 + wc] = q; }
.LBB0_1770:
	s_or_b64 exec, exec, s[36:37]
	s_waitcnt lgkmcnt(7)
	v_add_f32_e32 v114, v205, v206
	v_fmamk_f32 v114, v114, 0x3a800000, v190
	v_rsq_f32_e32 v120, v114
	s_waitcnt lgkmcnt(0)
	v_lshlrev_b64 v[114:115], 10, v[176:177]
	v_lshl_add_u64 v[114:115], v[114:115], 0, v[164:165]
	v_lshlrev_b64 v[114:115], 1, v[114:115]
	v_lshl_add_u64 v[116:117], s[10:11], 0, v[114:115]
	v_lshl_add_u64 v[118:119], s[16:17], 0, v[114:115]
	v_or_b32_e32 v114, 0x100, v114
	global_load_dwordx4 v[126:129], v[116:117], off
	global_load_dwordx4 v[122:125], v[118:119], off
	v_lshl_add_u64 v[116:117], s[10:11], 0, v[114:115]
	v_lshl_add_u64 v[114:115], s[16:17], 0, v[114:115]
	v_mul_f32_e32 v182, 0xbfb8aa3b, v120
	global_load_dwordx4 v[118:121], v[116:117], off
	s_nop 0
	global_load_dwordx4 v[114:117], v[114:115], off
	v_pk_mul_f32 v[112:113], v[112:113], v[182:183] op_sel_hi:[1,0]
	v_pk_mul_f32 v[106:107], v[106:107], v[182:183] op_sel_hi:[1,0]
	v_exp_f32_e32 v112, v112
	v_exp_f32_e32 v113, v113
	v_exp_f32_e32 v106, v106
	v_exp_f32_e32 v107, v107
	v_pk_mul_f32 v[110:111], v[110:111], v[182:183] op_sel_hi:[1,0]
	v_pk_add_f32 v[112:113], v[112:113], 1.0 op_sel_hi:[1,0]
	v_exp_f32_e32 v110, v110
	v_exp_f32_e32 v111, v111
	v_rcp_f32_e32 v112, v112
	v_rcp_f32_e32 v113, v113
	v_pk_add_f32 v[106:107], v[106:107], 1.0 op_sel_hi:[1,0]
	v_pk_mul_f32 v[108:109], v[108:109], v[182:183] op_sel_hi:[1,0]
	v_rcp_f32_e32 v106, v106
	v_rcp_f32_e32 v107, v107
	v_exp_f32_e32 v108, v108
	v_exp_f32_e32 v109, v109
	v_pk_mul_f32 v[102:103], v[102:103], v[182:183] op_sel_hi:[1,0]
	v_pk_mul_f32 v[104:105], v[104:105], v[182:183] op_sel_hi:[1,0]
	v_exp_f32_e32 v102, v102
	v_exp_f32_e32 v103, v103
	s_waitcnt vmcnt(9)
	v_lshlrev_b32_e32 v206, 16, v142
	v_and_b32_e32 v207, 0xffff0000, v142
	s_waitcnt vmcnt(8)
	v_lshlrev_b32_e32 v208, 16, v138
	v_and_b32_e32 v209, 0xffff0000, v138
	v_lshlrev_b32_e32 v142, 16, v143
	v_and_b32_e32 v143, 0xffff0000, v143
	v_lshlrev_b32_e32 v138, 16, v139
	v_and_b32_e32 v139, 0xffff0000, v139
	v_exp_f32_e32 v104, v104
	v_exp_f32_e32 v105, v105
	v_pk_mul_f32 v[98:99], v[98:99], v[182:183] op_sel_hi:[1,0]
	v_pk_add_f32 v[110:111], v[110:111], 1.0 op_sel_hi:[1,0]
	v_pk_fma_f32 v[112:113], v[112:113], v[138:139], v[142:143]
	v_lshlrev_b32_e32 v138, 16, v144
	v_and_b32_e32 v139, 0xffff0000, v144
	v_lshlrev_b32_e32 v142, 16, v140
	v_and_b32_e32 v143, 0xffff0000, v140
	v_exp_f32_e32 v98, v98
	v_exp_f32_e32 v99, v99
	v_rcp_f32_e32 v110, v110
	v_rcp_f32_e32 v111, v111
	v_pk_fma_f32 v[138:139], v[106:107], v[142:143], v[138:139]
	v_pk_add_f32 v[106:107], v[108:109], 1.0 op_sel_hi:[1,0]
	v_pk_add_f32 v[102:103], v[102:103], 1.0 op_sel_hi:[1,0]
	v_rcp_f32_e32 v106, v106
	v_rcp_f32_e32 v107, v107
	v_rcp_f32_e32 v102, v102
	v_rcp_f32_e32 v103, v103
	v_pk_add_f32 v[104:105], v[104:105], 1.0 op_sel_hi:[1,0]
	v_pk_add_f32 v[98:99], v[98:99], 1.0 op_sel_hi:[1,0]
	v_rcp_f32_e32 v104, v104
	v_rcp_f32_e32 v105, v105
	v_pk_mul_f32 v[100:101], v[100:101], v[182:183] op_sel_hi:[1,0]
	v_pk_fma_f32 v[110:111], v[110:111], v[208:209], v[206:207]
	v_lshlrev_b32_e32 v108, 16, v145
	v_and_b32_e32 v109, 0xffff0000, v145
	v_lshlrev_b32_e32 v140, 16, v141
	v_and_b32_e32 v141, 0xffff0000, v141
	v_rcp_f32_e32 v98, v98
	v_rcp_f32_e32 v99, v99
	v_exp_f32_e32 v100, v100
	v_exp_f32_e32 v101, v101
	v_pk_fma_f32 v[140:141], v[106:107], v[140:141], v[108:109]
	v_pk_mul_f32 v[142:143], v[110:111], v[110:111]
	v_pk_mul_f32 v[144:145], v[112:113], v[112:113]
	v_cvt_pk_bf16_f32 v106, v110, v111
	v_cvt_pk_bf16_f32 v107, v112, v113
	s_waitcnt vmcnt(7)
	v_lshlrev_b32_e32 v110, 16, v134
	v_and_b32_e32 v111, 0xffff0000, v134
	s_waitcnt vmcnt(6)
	v_lshlrev_b32_e32 v112, 16, v130
	v_and_b32_e32 v113, 0xffff0000, v130
	v_pk_fma_f32 v[102:103], v[102:103], v[112:113], v[110:111]
	v_lshlrev_b32_e32 v110, 16, v135
	v_and_b32_e32 v111, 0xffff0000, v135
	v_lshlrev_b32_e32 v112, 16, v131
	v_and_b32_e32 v113, 0xffff0000, v131
	v_pk_fma_f32 v[104:105], v[104:105], v[112:113], v[110:111]
	v_lshlrev_b32_e32 v110, 16, v136
	v_and_b32_e32 v111, 0xffff0000, v136
	v_lshlrev_b32_e32 v112, 16, v132
	v_and_b32_e32 v113, 0xffff0000, v132
	v_add_f32_e32 v134, v142, v143
	v_pk_fma_f32 v[110:111], v[98:99], v[112:113], v[110:111]
	v_pk_add_f32 v[98:99], v[100:101], 1.0 op_sel_hi:[1,0]
	v_add_f32_e32 v134, v144, v134
	v_pk_mul_f32 v[206:207], v[138:139], v[138:139]
	v_rcp_f32_e32 v98, v98
	v_rcp_f32_e32 v99, v99
	v_add_f32_e32 v134, v145, v134
	v_add_f32_e32 v134, v206, v134
	v_pk_mul_f32 v[208:209], v[140:141], v[140:141]
	v_add_f32_e32 v134, v207, v134
	v_lshlrev_b32_e32 v100, 16, v137
	v_and_b32_e32 v101, 0xffff0000, v137
	v_lshlrev_b32_e32 v112, 16, v133
	v_and_b32_e32 v113, 0xffff0000, v133
	v_add_f32_e32 v134, v208, v134
	v_pk_fma_f32 v[112:113], v[98:99], v[112:113], v[100:101]
	v_pk_mul_f32 v[98:99], v[102:103], v[102:103]
	v_add_f32_e32 v134, v209, v134
	v_add_f32_e32 v98, v98, v134
	v_pk_mul_f32 v[100:101], v[104:105], v[104:105]
	v_add_f32_e32 v98, v99, v98
	v_add_f32_e32 v98, v100, v98
	v_pk_mul_f32 v[130:131], v[110:111], v[110:111]
	v_add_f32_e32 v98, v101, v98
	v_add_f32_e32 v98, v130, v98
	v_pk_mul_f32 v[132:133], v[112:113], v[112:113]
	v_add_f32_e32 v98, v131, v98
	v_add_f32_e32 v98, v132, v98
	v_add_f32_e32 v101, v133, v98
	v_mov_b32_e32 v132, v101
	s_nop 1
	v_permlane16_swap_b32 v101, v132
	v_lshlrev_b64 v[180:181], 11, v[180:181]
	v_lshl_add_u64 v[98:99], s[20:21], 0, v[180:181]
	v_lshl_add_u64 v[130:131], v[164:165], 1, v[98:99]
	v_cvt_pk_bf16_f32 v108, v138, v139
	s_waitcnt lgkmcnt(0)
	v_add_f32_e32 v98, v101, v132
	v_mov_b32_e32 v99, v98
	s_nop 1
	v_permlane32_swap_b32 v98, v99
	v_cvt_pk_bf16_f32 v109, v140, v141
	global_store_dwordx4 v[130:131], v[106:109], off
	v_cvt_pk_bf16_f32 v100, v102, v103
	v_cvt_pk_bf16_f32 v101, v104, v105
	v_cvt_pk_bf16_f32 v102, v110, v111
	v_cvt_pk_bf16_f32 v103, v112, v113
	global_store_dwordx4 v[130:131], v[100:103], off offset:256
	s_and_saveexec_b64 s[36:37], s[6:7]
	s_cbranch_execz .LBB0_1772
	v_lshl_add_u64 v[100:101], s[18:19], 0, v[178:179]
	v_lshl_add_u64 v[100:101], s[4:5], 2, v[100:101]
	s_lshl_b32 s12, s49, 2
	v_lshl_add_u64 v[100:101], v[100:101], 0, s[12:13]
	s_waitcnt lgkmcnt(0)
	v_add_f32_e32 v98, v98, v99
	global_store_dword v[100:101], v98, off
; __device__ __forceinline__ unsigned cvt_pk_bf16(float lo, float hi) { unsigned r; asm volatile("v_cvt_pk_bf16_f32 %0, %1, %2" : "=v"(r) : "v"(lo), "v"(hi)); return r; }
; #define PLE2(kk, A, e0, BW, PW) { const f32x2 t = (f32x2){A[e0], A[e0 + 1]} * c1; f32x2 d; d.x = __builtin_amdgcn_exp2f(t.x); d.y = __builtin_amdgcn_exp2f(t.y); d = d + 1.0f; \
;                     f32x2 q2; q2.x = __builtin_amdgcn_rcpf(d.x); q2.y = __builtin_amdgcn_rcpf(d.y); const f32x2 o2 = (f32x2){bflo(BW), bfhi(BW)} + (f32x2){bflo(PW), bfhi(PW)} * q2; r[kk] = o2.x; r[kk + 1] = o2.y; }
;     __device__ __forceinline__ void operator()(const pg8::f32x4 (&acc)[2][2][4][2], const Unit& u, int wr, int wc, int fr, int fq) const {
;     ...
;         for (int k = 0; k < 8; ++k) { const int ai = k >> 2, m = k & 3; const int row = row0 + ai * HALF + m * 16; const float rs = rsv[k]; float q = 0.f;
;             v4u cb[2], cp[2];
; #pragma unroll
;             for (int bj = 0; bj < 2; ++bj) { cb[bj] = nb[bj]; cp[bj] = np[bj]; }
;             if (k < 7) {
; #pragma unroll
;                 for (int bj = 0; bj < 2; ++bj) { const size_t o = (size_t)(row0 + ((k + 1) >> 2) * HALF + ((k + 1) & 3) * 16) * DM_ + col0 + bj * HALF; nb[bj] = *(const v4u*)(base + o); np[bj] = *(const v4u*)(pp + o); } }
; #pragma unroll
;             for (int bj = 0; bj < 2; ++bj) { const size_t o = (size_t)row * DM_ + col0 + bj * HALF; const v4u bw = cb[bj], pw = cp[bj];
;                 const float c1 = -1.4426950408889634f * rs; float r[8];
;     ...
;                 { const f32x4 a0 = acc[ai][bj][m][0], a1 = acc[ai][bj][m][1];
;                   PLE2(0, a0, 0, bw.x, pw.x) PLE2(2, a0, 2, bw.y, pw.y) PLE2(4, a1, 0, bw.z, pw.z) PLE2(6, a1, 2, bw.w, pw.w) }
;     ...
; #pragma unroll
;                 for (int e = 0; e < 8; ++e) q += r[e] * r[e];
;                 v4u w; w.x = cvt_pk_bf16(r[0], r[1]); w.y = cvt_pk_bf16(r[2], r[3]); w.z = cvt_pk_bf16(r[4], r[5]); w.w = cvt_pk_bf16(r[6], r[7]); *(v4u*)(out + o) = w; }
;             q += __shfl_xor(q, 16); q += __shfl_xor(q, 32); if (fq == 0) ssq[(size_t)row * 16 + u.pn * 4 + wc] = q; }
.LBB0_1772:
	s_or_b64 exec, exec, s[36:37]
	v_add_f32_e32 v98, v203, v204
	v_fmamk_f32 v98, v98, 0x3a800000, v190
	v_rsq_f32_e32 v104, v98
	s_waitcnt lgkmcnt(0)
	v_lshlrev_b64 v[98:99], 10, v[172:173]
	v_lshl_add_u64 v[98:99], v[98:99], 0, v[164:165]
	v_lshlrev_b64 v[98:99], 1, v[98:99]
	v_lshl_add_u64 v[100:101], s[10:11], 0, v[98:99]
	v_lshl_add_u64 v[102:103], s[16:17], 0, v[98:99]
	v_or_b32_e32 v98, 0x100, v98
	global_load_dwordx4 v[110:113], v[100:101], off
	global_load_dwordx4 v[106:109], v[102:103], off
	v_lshl_add_u64 v[100:101], s[10:11], 0, v[98:99]
	v_lshl_add_u64 v[98:99], s[16:17], 0, v[98:99]
	v_mul_f32_e32 v130, 0xbfb8aa3b, v104
	global_load_dwordx4 v[102:105], v[100:101], off
	s_nop 0
	global_load_dwordx4 v[98:101], v[98:99], off
	v_pk_mul_f32 v[96:97], v[96:97], v[130:131] op_sel_hi:[1,0]
	v_pk_mul_f32 v[90:91], v[90:91], v[130:131] op_sel_hi:[1,0]
	v_exp_f32_e32 v96, v96
	v_exp_f32_e32 v97, v97
	v_exp_f32_e32 v90, v90
	v_exp_f32_e32 v91, v91
	v_pk_mul_f32 v[94:95], v[94:95], v[130:131] op_sel_hi:[1,0]
	v_pk_add_f32 v[96:97], v[96:97], 1.0 op_sel_hi:[1,0]
	v_exp_f32_e32 v94, v94
	v_exp_f32_e32 v95, v95
	v_rcp_f32_e32 v96, v96
	v_rcp_f32_e32 v97, v97
	v_pk_add_f32 v[90:91], v[90:91], 1.0 op_sel_hi:[1,0]
	v_pk_mul_f32 v[92:93], v[92:93], v[130:131] op_sel_hi:[1,0]
	v_rcp_f32_e32 v90, v90
	v_rcp_f32_e32 v91, v91
	v_exp_f32_e32 v92, v92
	v_exp_f32_e32 v93, v93
	v_pk_mul_f32 v[86:87], v[86:87], v[130:131] op_sel_hi:[1,0]
	v_pk_mul_f32 v[88:89], v[88:89], v[130:131] op_sel_hi:[1,0]
	v_exp_f32_e32 v86, v86
	v_exp_f32_e32 v87, v87
	s_waitcnt vmcnt(9)
	v_lshlrev_b32_e32 v134, 16, v126
	v_and_b32_e32 v135, 0xffff0000, v126
	s_waitcnt vmcnt(8)
	v_lshlrev_b32_e32 v136, 16, v122
	v_and_b32_e32 v137, 0xffff0000, v122
	v_lshlrev_b32_e32 v126, 16, v127
	v_and_b32_e32 v127, 0xffff0000, v127
	v_lshlrev_b32_e32 v122, 16, v123
	v_and_b32_e32 v123, 0xffff0000, v123
	v_exp_f32_e32 v88, v88
	v_exp_f32_e32 v89, v89
	v_pk_mul_f32 v[82:83], v[82:83], v[130:131] op_sel_hi:[1,0]
	v_pk_add_f32 v[94:95], v[94:95], 1.0 op_sel_hi:[1,0]
	v_pk_fma_f32 v[96:97], v[96:97], v[122:123], v[126:127]
	v_lshlrev_b32_e32 v122, 16, v128
	v_and_b32_e32 v123, 0xffff0000, v128
	v_lshlrev_b32_e32 v126, 16, v124
	v_and_b32_e32 v127, 0xffff0000, v124
	v_exp_f32_e32 v82, v82
	v_exp_f32_e32 v83, v83
	v_rcp_f32_e32 v94, v94
	v_rcp_f32_e32 v95, v95
	v_pk_fma_f32 v[122:123], v[90:91], v[126:127], v[122:123]
	v_pk_add_f32 v[90:91], v[92:93], 1.0 op_sel_hi:[1,0]
	v_pk_add_f32 v[86:87], v[86:87], 1.0 op_sel_hi:[1,0]
	v_rcp_f32_e32 v90, v90
	v_rcp_f32_e32 v91, v91
	v_rcp_f32_e32 v86, v86
	v_rcp_f32_e32 v87, v87
	v_pk_add_f32 v[88:89], v[88:89], 1.0 op_sel_hi:[1,0]
	v_pk_add_f32 v[82:83], v[82:83], 1.0 op_sel_hi:[1,0]
	v_rcp_f32_e32 v88, v88
	v_rcp_f32_e32 v89, v89
	v_pk_mul_f32 v[84:85], v[84:85], v[130:131] op_sel_hi:[1,0]
	v_pk_fma_f32 v[94:95], v[94:95], v[136:137], v[134:135]
	v_lshlrev_b32_e32 v92, 16, v129
	v_and_b32_e32 v93, 0xffff0000, v129
	v_lshlrev_b32_e32 v124, 16, v125
	v_and_b32_e32 v125, 0xffff0000, v125
	v_rcp_f32_e32 v82, v82
	v_rcp_f32_e32 v83, v83
	v_exp_f32_e32 v84, v84
	v_exp_f32_e32 v85, v85
	v_pk_fma_f32 v[124:125], v[90:91], v[124:125], v[92:93]
	v_pk_mul_f32 v[126:127], v[94:95], v[94:95]
	v_pk_mul_f32 v[128:129], v[96:97], v[96:97]
	v_cvt_pk_bf16_f32 v90, v94, v95
	v_cvt_pk_bf16_f32 v91, v96, v97
	s_waitcnt vmcnt(7)
	v_lshlrev_b32_e32 v94, 16, v118
	v_and_b32_e32 v95, 0xffff0000, v118
	s_waitcnt vmcnt(6)
	v_lshlrev_b32_e32 v96, 16, v114
	v_and_b32_e32 v97, 0xffff0000, v114
	v_pk_fma_f32 v[86:87], v[86:87], v[96:97], v[94:95]
	v_lshlrev_b32_e32 v94, 16, v119
	v_and_b32_e32 v95, 0xffff0000, v119
	v_lshlrev_b32_e32 v96, 16, v115
	v_and_b32_e32 v97, 0xffff0000, v115
	v_pk_fma_f32 v[88:89], v[88:89], v[96:97], v[94:95]
	v_lshlrev_b32_e32 v94, 16, v120
	v_and_b32_e32 v95, 0xffff0000, v120
	v_lshlrev_b32_e32 v96, 16, v116
	v_and_b32_e32 v97, 0xffff0000, v116
	v_add_f32_e32 v118, v126, v127
	v_pk_fma_f32 v[94:95], v[82:83], v[96:97], v[94:95]
	v_pk_add_f32 v[82:83], v[84:85], 1.0 op_sel_hi:[1,0]
	v_add_f32_e32 v118, v128, v118
	v_pk_mul_f32 v[134:135], v[122:123], v[122:123]
	v_rcp_f32_e32 v82, v82
	v_rcp_f32_e32 v83, v83
	v_add_f32_e32 v118, v129, v118
	v_add_f32_e32 v118, v134, v118
	v_pk_mul_f32 v[136:137], v[124:125], v[124:125]
	v_add_f32_e32 v118, v135, v118
	v_lshlrev_b32_e32 v84, 16, v121
	v_and_b32_e32 v85, 0xffff0000, v121
	v_lshlrev_b32_e32 v96, 16, v117
	v_and_b32_e32 v97, 0xffff0000, v117
	v_add_f32_e32 v118, v136, v118
	v_pk_fma_f32 v[96:97], v[82:83], v[96:97], v[84:85]
	v_pk_mul_f32 v[82:83], v[86:87], v[86:87]
	v_add_f32_e32 v118, v137, v118
	v_add_f32_e32 v82, v82, v118
	v_pk_mul_f32 v[84:85], v[88:89], v[88:89]
	v_add_f32_e32 v82, v83, v82
	v_add_f32_e32 v82, v84, v82
	v_pk_mul_f32 v[114:115], v[94:95], v[94:95]
	v_add_f32_e32 v82, v85, v82
	v_add_f32_e32 v82, v114, v82
	v_pk_mul_f32 v[116:117], v[96:97], v[96:97]
	v_add_f32_e32 v82, v115, v82
	v_add_f32_e32 v82, v116, v82
	v_add_f32_e32 v85, v117, v82
	v_mov_b32_e32 v116, v85
	s_nop 1
	v_permlane16_swap_b32 v85, v116
	v_lshlrev_b64 v[132:133], 11, v[176:177]
	v_lshl_add_u64 v[82:83], s[20:21], 0, v[132:133]
	v_lshl_add_u64 v[114:115], v[164:165], 1, v[82:83]
	v_cvt_pk_bf16_f32 v92, v122, v123
	s_waitcnt lgkmcnt(0)
	v_add_f32_e32 v82, v85, v116
	v_mov_b32_e32 v83, v82
	s_nop 1
	v_permlane32_swap_b32 v82, v83
	v_cvt_pk_bf16_f32 v93, v124, v125
	global_store_dwordx4 v[114:115], v[90:93], off
	v_cvt_pk_bf16_f32 v84, v86, v87
	v_cvt_pk_bf16_f32 v85, v88, v89
	v_cvt_pk_bf16_f32 v86, v94, v95
	v_cvt_pk_bf16_f32 v87, v96, v97
	global_store_dwordx4 v[114:115], v[84:87], off offset:256
	s_and_saveexec_b64 s[36:37], s[6:7]
	s_cbranch_execz .LBB0_1774
	v_lshl_add_u64 v[84:85], s[18:19], 0, v[174:175]
	v_lshl_add_u64 v[84:85], s[4:5], 2, v[84:85]
	s_lshl_b32 s12, s49, 2
	v_lshl_add_u64 v[84:85], v[84:85], 0, s[12:13]
	s_waitcnt lgkmcnt(0)
	v_add_f32_e32 v82, v82, v83
	global_store_dword v[84:85], v82, off
; __device__ __forceinline__ unsigned cvt_pk_bf16(float lo, float hi) { unsigned r; asm volatile("v_cvt_pk_bf16_f32 %0, %1, %2" : "=v"(r) : "v"(lo), "v"(hi)); return r; }
; #define PLE2(kk, A, e0, BW, PW) { const f32x2 t = (f32x2){A[e0], A[e0 + 1]} * c1; f32x2 d; d.x = __builtin_amdgcn_exp2f(t.x); d.y = __builtin_amdgcn_exp2f(t.y); d = d + 1.0f; \
;                     f32x2 q2; q2.x = __builtin_amdgcn_rcpf(d.x); q2.y = __builtin_amdgcn_rcpf(d.y); const f32x2 o2 = (f32x2){bflo(BW), bfhi(BW)} + (f32x2){bflo(PW), bfhi(PW)} * q2; r[kk] = o2.x; r[kk + 1] = o2.y; }
;     __device__ __forceinline__ void operator()(const pg8::f32x4 (&acc)[2][2][4][2], const Unit& u, int wr, int wc, int fr, int fq) const {
;     ...
;         for (int k = 0; k < 8; ++k) { const int ai = k >> 2, m = k & 3; const int row = row0 + ai * HALF + m * 16; const float rs = rsv[k]; float q = 0.f;
;             v4u cb[2], cp[2];
; #pragma unroll
;             for (int bj = 0; bj < 2; ++bj) { cb[bj] = nb[bj]; cp[bj] = np[bj]; }
;             if (k < 7) {
; #pragma unroll
;                 for (int bj = 0; bj < 2; ++bj) { const size_t o = (size_t)(row0 + ((k + 1) >> 2) * HALF + ((k + 1) & 3) * 16) * DM_ + col0 + bj * HALF; nb[bj] = *(const v4u*)(base + o); np[bj] = *(const v4u*)(pp + o); } }
; #pragma unroll
;             for (int bj = 0; bj < 2; ++bj) { const size_t o = (size_t)row * DM_ + col0 + bj * HALF; const v4u bw = cb[bj], pw = cp[bj];
;                 const float c1 = -1.4426950408889634f * rs; float r[8];
;     ...
;                 { const f32x4 a0 = acc[ai][bj][m][0], a1 = acc[ai][bj][m][1];
;                   PLE2(0, a0, 0, bw.x, pw.x) PLE2(2, a0, 2, bw.y, pw.y) PLE2(4, a1, 0, bw.z, pw.z) PLE2(6, a1, 2, bw.w, pw.w) }
;     ...
; #pragma unroll
;                 for (int e = 0; e < 8; ++e) q += r[e] * r[e];
;                 v4u w; w.x = cvt_pk_bf16(r[0], r[1]); w.y = cvt_pk_bf16(r[2], r[3]); w.z = cvt_pk_bf16(r[4], r[5]); w.w = cvt_pk_bf16(r[6], r[7]); *(v4u*)(out + o) = w; }
;             q += __shfl_xor(q, 16); q += __shfl_xor(q, 32); if (fq == 0) ssq[(size_t)row * 16 + u.pn * 4 + wc] = q; }
.LBB0_1774:
	s_or_b64 exec, exec, s[36:37]
	v_add_f32_e32 v82, v201, v202
	v_fmamk_f32 v82, v82, 0x3a800000, v190
	v_rsq_f32_e32 v88, v82
	s_waitcnt lgkmcnt(0)
	v_lshlrev_b64 v[82:83], 10, v[166:167]
	v_lshl_add_u64 v[82:83], v[82:83], 0, v[164:165]
	v_lshlrev_b64 v[82:83], 1, v[82:83]
	v_lshl_add_u64 v[84:85], s[10:11], 0, v[82:83]
	v_lshl_add_u64 v[86:87], s[16:17], 0, v[82:83]
	v_or_b32_e32 v82, 0x100, v82
	global_load_dwordx4 v[94:97], v[84:85], off
	global_load_dwordx4 v[90:93], v[86:87], off
	v_lshl_add_u64 v[84:85], s[10:11], 0, v[82:83]
	v_lshl_add_u64 v[82:83], s[16:17], 0, v[82:83]
	v_mul_f32_e32 v114, 0xbfb8aa3b, v88
	global_load_dwordx4 v[86:89], v[84:85], off
	s_nop 0
	global_load_dwordx4 v[82:85], v[82:83], off
	v_pk_mul_f32 v[80:81], v[80:81], v[114:115] op_sel_hi:[1,0]
	v_pk_mul_f32 v[74:75], v[74:75], v[114:115] op_sel_hi:[1,0]
	v_exp_f32_e32 v80, v80
	v_exp_f32_e32 v81, v81
	v_exp_f32_e32 v74, v74
	v_exp_f32_e32 v75, v75
	v_pk_mul_f32 v[78:79], v[78:79], v[114:115] op_sel_hi:[1,0]
	v_pk_add_f32 v[80:81], v[80:81], 1.0 op_sel_hi:[1,0]
	v_exp_f32_e32 v78, v78
	v_exp_f32_e32 v79, v79
	v_rcp_f32_e32 v80, v80
	v_rcp_f32_e32 v81, v81
	v_pk_add_f32 v[74:75], v[74:75], 1.0 op_sel_hi:[1,0]
	v_pk_mul_f32 v[76:77], v[76:77], v[114:115] op_sel_hi:[1,0]
	v_rcp_f32_e32 v74, v74
	v_rcp_f32_e32 v75, v75
	v_exp_f32_e32 v76, v76
	v_exp_f32_e32 v77, v77
	v_pk_mul_f32 v[70:71], v[70:71], v[114:115] op_sel_hi:[1,0]
	v_pk_mul_f32 v[72:73], v[72:73], v[114:115] op_sel_hi:[1,0]
	v_exp_f32_e32 v70, v70
	v_exp_f32_e32 v71, v71
	s_waitcnt vmcnt(9)
	v_lshlrev_b32_e32 v118, 16, v110
	v_and_b32_e32 v119, 0xffff0000, v110
	s_waitcnt vmcnt(8)
	v_lshlrev_b32_e32 v120, 16, v106
	v_and_b32_e32 v121, 0xffff0000, v106
	v_lshlrev_b32_e32 v110, 16, v111
	v_and_b32_e32 v111, 0xffff0000, v111
	v_lshlrev_b32_e32 v106, 16, v107
	v_and_b32_e32 v107, 0xffff0000, v107
	v_exp_f32_e32 v72, v72
	v_exp_f32_e32 v73, v73
	v_pk_mul_f32 v[66:67], v[66:67], v[114:115] op_sel_hi:[1,0]
	v_pk_add_f32 v[78:79], v[78:79], 1.0 op_sel_hi:[1,0]
	v_pk_fma_f32 v[80:81], v[80:81], v[106:107], v[110:111]
	v_lshlrev_b32_e32 v106, 16, v112
	v_and_b32_e32 v107, 0xffff0000, v112
	v_lshlrev_b32_e32 v110, 16, v108
	v_and_b32_e32 v111, 0xffff0000, v108
	v_exp_f32_e32 v66, v66
	v_exp_f32_e32 v67, v67
	v_rcp_f32_e32 v78, v78
	v_rcp_f32_e32 v79, v79
	v_pk_fma_f32 v[106:107], v[74:75], v[110:111], v[106:107]
	v_pk_add_f32 v[74:75], v[76:77], 1.0 op_sel_hi:[1,0]
	v_pk_add_f32 v[70:71], v[70:71], 1.0 op_sel_hi:[1,0]
	v_rcp_f32_e32 v74, v74
	v_rcp_f32_e32 v75, v75
	v_rcp_f32_e32 v70, v70
	v_rcp_f32_e32 v71, v71
	v_pk_add_f32 v[72:73], v[72:73], 1.0 op_sel_hi:[1,0]
	v_pk_add_f32 v[66:67], v[66:67], 1.0 op_sel_hi:[1,0]
	v_rcp_f32_e32 v72, v72
	v_rcp_f32_e32 v73, v73
	v_pk_mul_f32 v[68:69], v[68:69], v[114:115] op_sel_hi:[1,0]
	v_pk_fma_f32 v[78:79], v[78:79], v[120:121], v[118:119]
	v_lshlrev_b32_e32 v76, 16, v113
	v_and_b32_e32 v77, 0xffff0000, v113
	v_lshlrev_b32_e32 v108, 16, v109
	v_and_b32_e32 v109, 0xffff0000, v109
	v_rcp_f32_e32 v66, v66
	v_rcp_f32_e32 v67, v67
	v_exp_f32_e32 v68, v68
	v_exp_f32_e32 v69, v69
	v_pk_fma_f32 v[108:109], v[74:75], v[108:109], v[76:77]
	v_pk_mul_f32 v[110:111], v[78:79], v[78:79]
	v_pk_mul_f32 v[112:113], v[80:81], v[80:81]
	v_cvt_pk_bf16_f32 v74, v78, v79
	v_cvt_pk_bf16_f32 v75, v80, v81
	s_waitcnt vmcnt(7)
	v_lshlrev_b32_e32 v78, 16, v102
	v_and_b32_e32 v79, 0xffff0000, v102
	s_waitcnt vmcnt(6)
	v_lshlrev_b32_e32 v80, 16, v98
	v_and_b32_e32 v81, 0xffff0000, v98
	v_pk_fma_f32 v[70:71], v[70:71], v[80:81], v[78:79]
	v_lshlrev_b32_e32 v78, 16, v103
	v_and_b32_e32 v79, 0xffff0000, v103
	v_lshlrev_b32_e32 v80, 16, v99
	v_and_b32_e32 v81, 0xffff0000, v99
	v_pk_fma_f32 v[72:73], v[72:73], v[80:81], v[78:79]
	v_lshlrev_b32_e32 v78, 16, v104
	v_and_b32_e32 v79, 0xffff0000, v104
	v_lshlrev_b32_e32 v80, 16, v100
	v_and_b32_e32 v81, 0xffff0000, v100
	v_add_f32_e32 v102, v110, v111
	v_pk_fma_f32 v[78:79], v[66:67], v[80:81], v[78:79]
	v_pk_add_f32 v[66:67], v[68:69], 1.0 op_sel_hi:[1,0]
	v_add_f32_e32 v102, v112, v102
	v_pk_mul_f32 v[118:119], v[106:107], v[106:107]
	v_rcp_f32_e32 v66, v66
	v_rcp_f32_e32 v67, v67
	v_add_f32_e32 v102, v113, v102
	v_add_f32_e32 v102, v118, v102
	v_pk_mul_f32 v[120:121], v[108:109], v[108:109]
	v_add_f32_e32 v102, v119, v102
	v_lshlrev_b32_e32 v68, 16, v105
	v_and_b32_e32 v69, 0xffff0000, v105
	v_lshlrev_b32_e32 v80, 16, v101
	v_and_b32_e32 v81, 0xffff0000, v101
	v_add_f32_e32 v102, v120, v102
	v_pk_fma_f32 v[80:81], v[66:67], v[80:81], v[68:69]
	v_pk_mul_f32 v[66:67], v[70:71], v[70:71]
	v_add_f32_e32 v102, v121, v102
	v_add_f32_e32 v66, v66, v102
	v_pk_mul_f32 v[68:69], v[72:73], v[72:73]
	v_add_f32_e32 v66, v67, v66
	v_add_f32_e32 v66, v68, v66
	v_pk_mul_f32 v[98:99], v[78:79], v[78:79]
	v_add_f32_e32 v66, v69, v66
	v_add_f32_e32 v66, v98, v66
	v_pk_mul_f32 v[100:101], v[80:81], v[80:81]
	v_add_f32_e32 v66, v99, v66
	v_add_f32_e32 v66, v100, v66
	v_add_f32_e32 v69, v101, v66
	v_mov_b32_e32 v100, v69
	s_nop 1
	v_permlane16_swap_b32 v69, v100
	v_lshlrev_b64 v[116:117], 11, v[172:173]
	v_lshl_add_u64 v[66:67], s[20:21], 0, v[116:117]
	v_lshl_add_u64 v[98:99], v[164:165], 1, v[66:67]
	v_cvt_pk_bf16_f32 v76, v106, v107
	s_waitcnt lgkmcnt(0)
	v_add_f32_e32 v66, v69, v100
	v_mov_b32_e32 v67, v66
	s_nop 1
	v_permlane32_swap_b32 v66, v67
	v_cvt_pk_bf16_f32 v77, v108, v109
	global_store_dwordx4 v[98:99], v[74:77], off
	v_cvt_pk_bf16_f32 v68, v70, v71
	v_cvt_pk_bf16_f32 v69, v72, v73
	v_cvt_pk_bf16_f32 v70, v78, v79
	v_cvt_pk_bf16_f32 v71, v80, v81
	global_store_dwordx4 v[98:99], v[68:71], off offset:256
	s_and_saveexec_b64 s[36:37], s[6:7]
	s_cbranch_execz .LBB0_1776
	v_lshl_add_u64 v[68:69], s[18:19], 0, v[170:171]
	v_lshl_add_u64 v[68:69], s[4:5], 2, v[68:69]
	s_lshl_b32 s12, s49, 2
	v_lshl_add_u64 v[68:69], v[68:69], 0, s[12:13]
	s_waitcnt lgkmcnt(0)
	v_add_f32_e32 v66, v66, v67
	global_store_dword v[68:69], v66, off
; __device__ __forceinline__ unsigned cvt_pk_bf16(float lo, float hi) { unsigned r; asm volatile("v_cvt_pk_bf16_f32 %0, %1, %2" : "=v"(r) : "v"(lo), "v"(hi)); return r; }
; #define PLE2(kk, A, e0, BW, PW) { const f32x2 t = (f32x2){A[e0], A[e0 + 1]} * c1; f32x2 d; d.x = __builtin_amdgcn_exp2f(t.x); d.y = __builtin_amdgcn_exp2f(t.y); d = d + 1.0f; \
;                     f32x2 q2; q2.x = __builtin_amdgcn_rcpf(d.x); q2.y = __builtin_amdgcn_rcpf(d.y); const f32x2 o2 = (f32x2){bflo(BW), bfhi(BW)} + (f32x2){bflo(PW), bfhi(PW)} * q2; r[kk] = o2.x; r[kk + 1] = o2.y; }
;     __device__ __forceinline__ void operator()(const pg8::f32x4 (&acc)[2][2][4][2], const Unit& u, int wr, int wc, int fr, int fq) const {
;     ...
;         for (int k = 0; k < 8; ++k) { const int ai = k >> 2, m = k & 3; const int row = row0 + ai * HALF + m * 16; const float rs = rsv[k]; float q = 0.f;
;             v4u cb[2], cp[2];
; #pragma unroll
;             for (int bj = 0; bj < 2; ++bj) { cb[bj] = nb[bj]; cp[bj] = np[bj]; }
;             if (k < 7) {
; #pragma unroll
;                 for (int bj = 0; bj < 2; ++bj) { const size_t o = (size_t)(row0 + ((k + 1) >> 2) * HALF + ((k + 1) & 3) * 16) * DM_ + col0 + bj * HALF; nb[bj] = *(const v4u*)(base + o); np[bj] = *(const v4u*)(pp + o); } }
; #pragma unroll
;             for (int bj = 0; bj < 2; ++bj) { const size_t o = (size_t)row * DM_ + col0 + bj * HALF; const v4u bw = cb[bj], pw = cp[bj];
;                 const float c1 = -1.4426950408889634f * rs; float r[8];
;     ...
;                 { const f32x4 a0 = acc[ai][bj][m][0], a1 = acc[ai][bj][m][1];
;                   PLE2(0, a0, 0, bw.x, pw.x) PLE2(2, a0, 2, bw.y, pw.y) PLE2(4, a1, 0, bw.z, pw.z) PLE2(6, a1, 2, bw.w, pw.w) }
;     ...
; #pragma unroll
;                 for (int e = 0; e < 8; ++e) q += r[e] * r[e];
;                 v4u w; w.x = cvt_pk_bf16(r[0], r[1]); w.y = cvt_pk_bf16(r[2], r[3]); w.z = cvt_pk_bf16(r[4], r[5]); w.w = cvt_pk_bf16(r[6], r[7]); *(v4u*)(out + o) = w; }
;             q += __shfl_xor(q, 16); q += __shfl_xor(q, 32); if (fq == 0) ssq[(size_t)row * 16 + u.pn * 4 + wc] = q; }
.LBB0_1776:
	s_or_b64 exec, exec, s[36:37]
	v_add_f32_e32 v66, v199, v200
	v_or_b32_e32 v98, 16, v166
	v_fmamk_f32 v66, v66, 0x3a800000, v190
	v_ashrrev_i32_e32 v99, 31, v98
	v_rsq_f32_e32 v72, v66
	s_waitcnt lgkmcnt(0)
	v_lshlrev_b64 v[66:67], 10, v[98:99]
	v_lshl_add_u64 v[66:67], v[66:67], 0, v[164:165]
	v_lshlrev_b64 v[66:67], 1, v[66:67]
	v_lshl_add_u64 v[68:69], s[10:11], 0, v[66:67]
	v_lshl_add_u64 v[70:71], s[16:17], 0, v[66:67]
	v_or_b32_e32 v66, 0x100, v66
	global_load_dwordx4 v[78:81], v[68:69], off
	global_load_dwordx4 v[74:77], v[70:71], off
	v_lshl_add_u64 v[68:69], s[10:11], 0, v[66:67]
	v_lshl_add_u64 v[66:67], s[16:17], 0, v[66:67]
	v_mul_f32_e32 v100, 0xbfb8aa3b, v72
	global_load_dwordx4 v[70:73], v[68:69], off
	s_nop 0
	global_load_dwordx4 v[66:69], v[66:67], off
	v_pk_mul_f32 v[64:65], v[64:65], v[100:101] op_sel_hi:[1,0]
	v_pk_mul_f32 v[58:59], v[58:59], v[100:101] op_sel_hi:[1,0]
	v_exp_f32_e32 v64, v64
	v_exp_f32_e32 v65, v65
	v_exp_f32_e32 v58, v58
	v_exp_f32_e32 v59, v59
	v_pk_mul_f32 v[62:63], v[62:63], v[100:101] op_sel_hi:[1,0]
	v_pk_add_f32 v[64:65], v[64:65], 1.0 op_sel_hi:[1,0]
	v_exp_f32_e32 v62, v62
	v_exp_f32_e32 v63, v63
	v_rcp_f32_e32 v64, v64
	v_rcp_f32_e32 v65, v65
	v_pk_add_f32 v[58:59], v[58:59], 1.0 op_sel_hi:[1,0]
	v_pk_mul_f32 v[60:61], v[60:61], v[100:101] op_sel_hi:[1,0]
	v_rcp_f32_e32 v58, v58
	v_rcp_f32_e32 v59, v59
	v_exp_f32_e32 v60, v60
	v_exp_f32_e32 v61, v61
	v_pk_mul_f32 v[54:55], v[54:55], v[100:101] op_sel_hi:[1,0]
	v_pk_mul_f32 v[56:57], v[56:57], v[100:101] op_sel_hi:[1,0]
	v_exp_f32_e32 v54, v54
	v_exp_f32_e32 v55, v55
	s_waitcnt vmcnt(9)
	v_lshlrev_b32_e32 v104, 16, v94
	v_and_b32_e32 v105, 0xffff0000, v94
	s_waitcnt vmcnt(8)
	v_lshlrev_b32_e32 v106, 16, v90
	v_and_b32_e32 v107, 0xffff0000, v90
	v_lshlrev_b32_e32 v94, 16, v95
	v_and_b32_e32 v95, 0xffff0000, v95
	v_lshlrev_b32_e32 v90, 16, v91
	v_and_b32_e32 v91, 0xffff0000, v91
	v_exp_f32_e32 v56, v56
	v_exp_f32_e32 v57, v57
	v_pk_mul_f32 v[50:51], v[50:51], v[100:101] op_sel_hi:[1,0]
	v_pk_add_f32 v[62:63], v[62:63], 1.0 op_sel_hi:[1,0]
	v_pk_fma_f32 v[64:65], v[64:65], v[90:91], v[94:95]
	v_lshlrev_b32_e32 v90, 16, v96
	v_and_b32_e32 v91, 0xffff0000, v96
	v_lshlrev_b32_e32 v94, 16, v92
	v_and_b32_e32 v95, 0xffff0000, v92
	v_exp_f32_e32 v50, v50
	v_exp_f32_e32 v51, v51
	v_rcp_f32_e32 v62, v62
	v_rcp_f32_e32 v63, v63
	v_pk_fma_f32 v[90:91], v[58:59], v[94:95], v[90:91]
	v_pk_add_f32 v[58:59], v[60:61], 1.0 op_sel_hi:[1,0]
	v_pk_add_f32 v[54:55], v[54:55], 1.0 op_sel_hi:[1,0]
	v_rcp_f32_e32 v58, v58
	v_rcp_f32_e32 v59, v59
	v_rcp_f32_e32 v54, v54
	v_rcp_f32_e32 v55, v55
	v_pk_add_f32 v[56:57], v[56:57], 1.0 op_sel_hi:[1,0]
	v_pk_add_f32 v[50:51], v[50:51], 1.0 op_sel_hi:[1,0]
	v_rcp_f32_e32 v56, v56
	v_rcp_f32_e32 v57, v57
	v_pk_mul_f32 v[52:53], v[52:53], v[100:101] op_sel_hi:[1,0]
	v_pk_fma_f32 v[62:63], v[62:63], v[106:107], v[104:105]
	v_lshlrev_b32_e32 v60, 16, v97
	v_and_b32_e32 v61, 0xffff0000, v97
	v_lshlrev_b32_e32 v92, 16, v93
	v_and_b32_e32 v93, 0xffff0000, v93
	v_rcp_f32_e32 v50, v50
	v_rcp_f32_e32 v51, v51
	v_exp_f32_e32 v52, v52
	v_exp_f32_e32 v53, v53
	v_pk_fma_f32 v[92:93], v[58:59], v[92:93], v[60:61]
	v_pk_mul_f32 v[94:95], v[62:63], v[62:63]
	v_pk_mul_f32 v[96:97], v[64:65], v[64:65]
	v_cvt_pk_bf16_f32 v58, v62, v63
	v_cvt_pk_bf16_f32 v59, v64, v65
	s_waitcnt vmcnt(7)
	v_lshlrev_b32_e32 v62, 16, v86
	v_and_b32_e32 v63, 0xffff0000, v86
	s_waitcnt vmcnt(6)
	v_lshlrev_b32_e32 v64, 16, v82
	v_and_b32_e32 v65, 0xffff0000, v82
	v_pk_fma_f32 v[54:55], v[54:55], v[64:65], v[62:63]
	v_lshlrev_b32_e32 v62, 16, v87
	v_and_b32_e32 v63, 0xffff0000, v87
	v_lshlrev_b32_e32 v64, 16, v83
	v_and_b32_e32 v65, 0xffff0000, v83
	v_pk_fma_f32 v[56:57], v[56:57], v[64:65], v[62:63]
	v_lshlrev_b32_e32 v62, 16, v88
	v_and_b32_e32 v63, 0xffff0000, v88
	v_lshlrev_b32_e32 v64, 16, v84
	v_and_b32_e32 v65, 0xffff0000, v84
	v_add_f32_e32 v86, v94, v95
	v_pk_fma_f32 v[62:63], v[50:51], v[64:65], v[62:63]
	v_pk_add_f32 v[50:51], v[52:53], 1.0 op_sel_hi:[1,0]
	v_add_f32_e32 v86, v96, v86
	v_pk_mul_f32 v[104:105], v[90:91], v[90:91]
	v_rcp_f32_e32 v50, v50
	v_rcp_f32_e32 v51, v51
	v_add_f32_e32 v86, v97, v86
	v_add_f32_e32 v86, v104, v86
	v_pk_mul_f32 v[106:107], v[92:93], v[92:93]
	v_add_f32_e32 v86, v105, v86
	v_lshlrev_b32_e32 v52, 16, v89
	v_and_b32_e32 v53, 0xffff0000, v89
	v_lshlrev_b32_e32 v64, 16, v85
	v_and_b32_e32 v65, 0xffff0000, v85
	v_add_f32_e32 v86, v106, v86
	v_pk_fma_f32 v[64:65], v[50:51], v[64:65], v[52:53]
	v_pk_mul_f32 v[50:51], v[54:55], v[54:55]
	v_add_f32_e32 v86, v107, v86
	v_add_f32_e32 v50, v50, v86
	v_pk_mul_f32 v[52:53], v[56:57], v[56:57]
	v_add_f32_e32 v50, v51, v50
	v_add_f32_e32 v50, v52, v50
	v_pk_mul_f32 v[82:83], v[62:63], v[62:63]
	v_add_f32_e32 v50, v53, v50
	v_add_f32_e32 v50, v82, v50
	v_pk_mul_f32 v[84:85], v[64:65], v[64:65]
	v_add_f32_e32 v50, v83, v50
	v_add_f32_e32 v50, v84, v50
	v_add_f32_e32 v53, v85, v50
	v_mov_b32_e32 v84, v53
	s_nop 1
	v_permlane16_swap_b32 v53, v84
	v_lshlrev_b64 v[102:103], 11, v[166:167]
	v_lshl_add_u64 v[50:51], s[20:21], 0, v[102:103]
	v_lshl_add_u64 v[82:83], v[164:165], 1, v[50:51]
	v_cvt_pk_bf16_f32 v60, v90, v91
	s_waitcnt lgkmcnt(0)
	v_add_f32_e32 v50, v53, v84
	v_mov_b32_e32 v51, v50
	s_nop 1
	v_permlane32_swap_b32 v50, v51
	v_cvt_pk_bf16_f32 v61, v92, v93
	global_store_dwordx4 v[82:83], v[58:61], off
	v_cvt_pk_bf16_f32 v52, v54, v55
	v_cvt_pk_bf16_f32 v53, v56, v57
	v_cvt_pk_bf16_f32 v54, v62, v63
	v_cvt_pk_bf16_f32 v55, v64, v65
	global_store_dwordx4 v[82:83], v[52:55], off offset:256
	s_and_saveexec_b64 s[36:37], s[6:7]
	s_cbranch_execz .LBB0_1778
	v_lshl_add_u64 v[52:53], s[18:19], 0, v[168:169]
	v_lshl_add_u64 v[52:53], s[4:5], 2, v[52:53]
	s_lshl_b32 s12, s49, 2
	v_lshl_add_u64 v[52:53], v[52:53], 0, s[12:13]
	s_waitcnt lgkmcnt(0)
	v_add_f32_e32 v50, v50, v51
	global_store_dword v[52:53], v50, off
; __device__ __forceinline__ unsigned cvt_pk_bf16(float lo, float hi) { unsigned r; asm volatile("v_cvt_pk_bf16_f32 %0, %1, %2" : "=v"(r) : "v"(lo), "v"(hi)); return r; }
; #define PLE2(kk, A, e0, BW, PW) { const f32x2 t = (f32x2){A[e0], A[e0 + 1]} * c1; f32x2 d; d.x = __builtin_amdgcn_exp2f(t.x); d.y = __builtin_amdgcn_exp2f(t.y); d = d + 1.0f; \
;                     f32x2 q2; q2.x = __builtin_amdgcn_rcpf(d.x); q2.y = __builtin_amdgcn_rcpf(d.y); const f32x2 o2 = (f32x2){bflo(BW), bfhi(BW)} + (f32x2){bflo(PW), bfhi(PW)} * q2; r[kk] = o2.x; r[kk + 1] = o2.y; }
;     __device__ __forceinline__ void operator()(const pg8::f32x4 (&acc)[2][2][4][2], const Unit& u, int wr, int wc, int fr, int fq) const {
;     ...
;         for (int k = 0; k < 8; ++k) { const int ai = k >> 2, m = k & 3; const int row = row0 + ai * HALF + m * 16; const float rs = rsv[k]; float q = 0.f;
;             v4u cb[2], cp[2];
; #pragma unroll
;             for (int bj = 0; bj < 2; ++bj) { cb[bj] = nb[bj]; cp[bj] = np[bj]; }
;             if (k < 7) {
; #pragma unroll
;                 for (int bj = 0; bj < 2; ++bj) { const size_t o = (size_t)(row0 + ((k + 1) >> 2) * HALF + ((k + 1) & 3) * 16) * DM_ + col0 + bj * HALF; nb[bj] = *(const v4u*)(base + o); np[bj] = *(const v4u*)(pp + o); } }
; #pragma unroll
;             for (int bj = 0; bj < 2; ++bj) { const size_t o = (size_t)row * DM_ + col0 + bj * HALF; const v4u bw = cb[bj], pw = cp[bj];
;                 const float c1 = -1.4426950408889634f * rs; float r[8];
;     ...
;                 { const f32x4 a0 = acc[ai][bj][m][0], a1 = acc[ai][bj][m][1];
;                   PLE2(0, a0, 0, bw.x, pw.x) PLE2(2, a0, 2, bw.y, pw.y) PLE2(4, a1, 0, bw.z, pw.z) PLE2(6, a1, 2, bw.w, pw.w) }
;     ...
; #pragma unroll
;                 for (int e = 0; e < 8; ++e) q += r[e] * r[e];
;                 v4u w; w.x = cvt_pk_bf16(r[0], r[1]); w.y = cvt_pk_bf16(r[2], r[3]); w.z = cvt_pk_bf16(r[4], r[5]); w.w = cvt_pk_bf16(r[6], r[7]); *(v4u*)(out + o) = w; }
;             q += __shfl_xor(q, 16); q += __shfl_xor(q, 32); if (fq == 0) ssq[(size_t)row * 16 + u.pn * 4 + wc] = q; }
.LBB0_1778:
	s_or_b64 exec, exec, s[36:37]
	v_add_f32_e32 v50, v197, v198
	v_or_b32_e32 v82, 32, v166
	v_fmamk_f32 v50, v50, 0x3a800000, v190
	v_ashrrev_i32_e32 v83, 31, v82
	v_rsq_f32_e32 v56, v50
	s_waitcnt lgkmcnt(0)
	v_lshlrev_b64 v[50:51], 10, v[82:83]
	v_lshl_add_u64 v[50:51], v[50:51], 0, v[164:165]
	v_lshlrev_b64 v[50:51], 1, v[50:51]
	v_lshl_add_u64 v[52:53], s[10:11], 0, v[50:51]
	v_lshl_add_u64 v[54:55], s[16:17], 0, v[50:51]
	v_or_b32_e32 v50, 0x100, v50
	global_load_dwordx4 v[62:65], v[52:53], off
	global_load_dwordx4 v[58:61], v[54:55], off
	v_lshl_add_u64 v[52:53], s[10:11], 0, v[50:51]
	v_lshl_add_u64 v[50:51], s[16:17], 0, v[50:51]
	v_mul_f32_e32 v84, 0xbfb8aa3b, v56
	global_load_dwordx4 v[54:57], v[52:53], off
	s_nop 0
	global_load_dwordx4 v[50:53], v[50:51], off
	v_pk_mul_f32 v[48:49], v[48:49], v[84:85] op_sel_hi:[1,0]
	v_pk_mul_f32 v[42:43], v[42:43], v[84:85] op_sel_hi:[1,0]
	v_exp_f32_e32 v48, v48
	v_exp_f32_e32 v49, v49
	v_exp_f32_e32 v42, v42
	v_exp_f32_e32 v43, v43
	v_pk_mul_f32 v[46:47], v[46:47], v[84:85] op_sel_hi:[1,0]
	v_pk_add_f32 v[48:49], v[48:49], 1.0 op_sel_hi:[1,0]
	v_exp_f32_e32 v46, v46
	v_exp_f32_e32 v47, v47
	v_rcp_f32_e32 v48, v48
	v_rcp_f32_e32 v49, v49
	v_pk_add_f32 v[42:43], v[42:43], 1.0 op_sel_hi:[1,0]
	v_pk_mul_f32 v[44:45], v[44:45], v[84:85] op_sel_hi:[1,0]
	v_rcp_f32_e32 v42, v42
	v_rcp_f32_e32 v43, v43
	v_exp_f32_e32 v44, v44
	v_exp_f32_e32 v45, v45
	v_pk_mul_f32 v[38:39], v[38:39], v[84:85] op_sel_hi:[1,0]
	v_pk_mul_f32 v[40:41], v[40:41], v[84:85] op_sel_hi:[1,0]
	v_exp_f32_e32 v38, v38
	v_exp_f32_e32 v39, v39
	s_waitcnt vmcnt(9)
	v_lshlrev_b32_e32 v88, 16, v78
	v_and_b32_e32 v89, 0xffff0000, v78
	s_waitcnt vmcnt(8)
	v_lshlrev_b32_e32 v90, 16, v74
	v_and_b32_e32 v91, 0xffff0000, v74
	v_lshlrev_b32_e32 v78, 16, v79
	v_and_b32_e32 v79, 0xffff0000, v79
	v_lshlrev_b32_e32 v74, 16, v75
	v_and_b32_e32 v75, 0xffff0000, v75
	v_exp_f32_e32 v40, v40
	v_exp_f32_e32 v41, v41
	v_pk_mul_f32 v[34:35], v[34:35], v[84:85] op_sel_hi:[1,0]
	v_pk_add_f32 v[46:47], v[46:47], 1.0 op_sel_hi:[1,0]
	v_pk_fma_f32 v[48:49], v[48:49], v[74:75], v[78:79]
	v_lshlrev_b32_e32 v74, 16, v80
	v_and_b32_e32 v75, 0xffff0000, v80
	v_lshlrev_b32_e32 v78, 16, v76
	v_and_b32_e32 v79, 0xffff0000, v76
	v_exp_f32_e32 v34, v34
	v_exp_f32_e32 v35, v35
	v_rcp_f32_e32 v46, v46
	v_rcp_f32_e32 v47, v47
	v_pk_fma_f32 v[74:75], v[42:43], v[78:79], v[74:75]
	v_pk_add_f32 v[42:43], v[44:45], 1.0 op_sel_hi:[1,0]
	v_pk_add_f32 v[38:39], v[38:39], 1.0 op_sel_hi:[1,0]
	v_rcp_f32_e32 v42, v42
	v_rcp_f32_e32 v43, v43
	v_rcp_f32_e32 v38, v38
	v_rcp_f32_e32 v39, v39
	v_pk_add_f32 v[40:41], v[40:41], 1.0 op_sel_hi:[1,0]
	v_pk_add_f32 v[34:35], v[34:35], 1.0 op_sel_hi:[1,0]
	v_rcp_f32_e32 v40, v40
	v_rcp_f32_e32 v41, v41
	v_pk_mul_f32 v[36:37], v[36:37], v[84:85] op_sel_hi:[1,0]
	v_pk_fma_f32 v[46:47], v[46:47], v[90:91], v[88:89]
	v_lshlrev_b32_e32 v44, 16, v81
	v_and_b32_e32 v45, 0xffff0000, v81
	v_lshlrev_b32_e32 v76, 16, v77
	v_and_b32_e32 v77, 0xffff0000, v77
	v_rcp_f32_e32 v34, v34
	v_rcp_f32_e32 v35, v35
	v_exp_f32_e32 v36, v36
	v_exp_f32_e32 v37, v37
	v_pk_fma_f32 v[76:77], v[42:43], v[76:77], v[44:45]
	v_pk_mul_f32 v[78:79], v[46:47], v[46:47]
	v_pk_mul_f32 v[80:81], v[48:49], v[48:49]
	v_cvt_pk_bf16_f32 v42, v46, v47
	v_cvt_pk_bf16_f32 v43, v48, v49
	s_waitcnt vmcnt(7)
	v_lshlrev_b32_e32 v46, 16, v70
	v_and_b32_e32 v47, 0xffff0000, v70
	s_waitcnt vmcnt(6)
	v_lshlrev_b32_e32 v48, 16, v66
	v_and_b32_e32 v49, 0xffff0000, v66
	v_pk_fma_f32 v[38:39], v[38:39], v[48:49], v[46:47]
	v_lshlrev_b32_e32 v46, 16, v71
	v_and_b32_e32 v47, 0xffff0000, v71
	v_lshlrev_b32_e32 v48, 16, v67
	v_and_b32_e32 v49, 0xffff0000, v67
	v_pk_fma_f32 v[40:41], v[40:41], v[48:49], v[46:47]
	v_lshlrev_b32_e32 v46, 16, v72
	v_and_b32_e32 v47, 0xffff0000, v72
	v_lshlrev_b32_e32 v48, 16, v68
	v_and_b32_e32 v49, 0xffff0000, v68
	v_add_f32_e32 v70, v78, v79
	v_pk_fma_f32 v[46:47], v[34:35], v[48:49], v[46:47]
	v_pk_add_f32 v[34:35], v[36:37], 1.0 op_sel_hi:[1,0]
	v_add_f32_e32 v70, v80, v70
	v_pk_mul_f32 v[88:89], v[74:75], v[74:75]
	v_rcp_f32_e32 v34, v34
	v_rcp_f32_e32 v35, v35
	v_add_f32_e32 v70, v81, v70
	v_add_f32_e32 v70, v88, v70
	v_pk_mul_f32 v[90:91], v[76:77], v[76:77]
	v_add_f32_e32 v70, v89, v70
	v_lshlrev_b32_e32 v36, 16, v73
	v_and_b32_e32 v37, 0xffff0000, v73
	v_lshlrev_b32_e32 v48, 16, v69
	v_and_b32_e32 v49, 0xffff0000, v69
	v_add_f32_e32 v70, v90, v70
	v_pk_fma_f32 v[48:49], v[34:35], v[48:49], v[36:37]
	v_pk_mul_f32 v[34:35], v[38:39], v[38:39]
	v_add_f32_e32 v70, v91, v70
	v_add_f32_e32 v34, v34, v70
	v_pk_mul_f32 v[36:37], v[40:41], v[40:41]
	v_add_f32_e32 v34, v35, v34
	v_add_f32_e32 v34, v36, v34
	v_pk_mul_f32 v[66:67], v[46:47], v[46:47]
	v_add_f32_e32 v34, v37, v34
	v_add_f32_e32 v34, v66, v34
	v_pk_mul_f32 v[68:69], v[48:49], v[48:49]
	v_add_f32_e32 v34, v67, v34
	v_add_f32_e32 v34, v68, v34
	v_add_f32_e32 v37, v69, v34
	v_mov_b32_e32 v68, v37
	s_nop 1
	v_permlane16_swap_b32 v37, v68
	v_lshlrev_b64 v[86:87], 11, v[98:99]
	v_lshl_add_u64 v[34:35], s[20:21], 0, v[86:87]
	v_lshl_add_u64 v[66:67], v[164:165], 1, v[34:35]
	v_cvt_pk_bf16_f32 v44, v74, v75
	s_waitcnt lgkmcnt(0)
	v_add_f32_e32 v34, v37, v68
	v_mov_b32_e32 v35, v34
	s_nop 1
	v_permlane32_swap_b32 v34, v35
	v_cvt_pk_bf16_f32 v45, v76, v77
	global_store_dwordx4 v[66:67], v[42:45], off
	v_cvt_pk_bf16_f32 v36, v38, v39
	v_cvt_pk_bf16_f32 v37, v40, v41
	v_cvt_pk_bf16_f32 v38, v46, v47
	v_cvt_pk_bf16_f32 v39, v48, v49
	global_store_dwordx4 v[66:67], v[36:39], off offset:256
	s_and_saveexec_b64 s[36:37], s[6:7]
	s_cbranch_execz .LBB0_1780
	v_lshlrev_b64 v[36:37], 6, v[98:99]
	v_lshl_add_u64 v[36:37], s[18:19], 0, v[36:37]
	v_lshl_add_u64 v[36:37], s[4:5], 2, v[36:37]
	s_lshl_b32 s12, s49, 2
	v_lshl_add_u64 v[36:37], v[36:37], 0, s[12:13]
	s_waitcnt lgkmcnt(0)
	v_add_f32_e32 v34, v34, v35
	global_store_dword v[36:37], v34, off
; __device__ __forceinline__ unsigned cvt_pk_bf16(float lo, float hi) { unsigned r; asm volatile("v_cvt_pk_bf16_f32 %0, %1, %2" : "=v"(r) : "v"(lo), "v"(hi)); return r; }
; #define PLE2(kk, A, e0, BW, PW) { const f32x2 t = (f32x2){A[e0], A[e0 + 1]} * c1; f32x2 d; d.x = __builtin_amdgcn_exp2f(t.x); d.y = __builtin_amdgcn_exp2f(t.y); d = d + 1.0f; \
;                     f32x2 q2; q2.x = __builtin_amdgcn_rcpf(d.x); q2.y = __builtin_amdgcn_rcpf(d.y); const f32x2 o2 = (f32x2){bflo(BW), bfhi(BW)} + (f32x2){bflo(PW), bfhi(PW)} * q2; r[kk] = o2.x; r[kk + 1] = o2.y; }
;     __device__ __forceinline__ void operator()(const pg8::f32x4 (&acc)[2][2][4][2], const Unit& u, int wr, int wc, int fr, int fq) const {
;     ...
;         for (int k = 0; k < 8; ++k) { const int ai = k >> 2, m = k & 3; const int row = row0 + ai * HALF + m * 16; const float rs = rsv[k]; float q = 0.f;
;             v4u cb[2], cp[2];
; #pragma unroll
;             for (int bj = 0; bj < 2; ++bj) { cb[bj] = nb[bj]; cp[bj] = np[bj]; }
;             if (k < 7) {
; #pragma unroll
;                 for (int bj = 0; bj < 2; ++bj) { const size_t o = (size_t)(row0 + ((k + 1) >> 2) * HALF + ((k + 1) & 3) * 16) * DM_ + col0 + bj * HALF; nb[bj] = *(const v4u*)(base + o); np[bj] = *(const v4u*)(pp + o); } }
; #pragma unroll
;             for (int bj = 0; bj < 2; ++bj) { const size_t o = (size_t)row * DM_ + col0 + bj * HALF; const v4u bw = cb[bj], pw = cp[bj];
;                 const float c1 = -1.4426950408889634f * rs; float r[8];
;     ...
;                 { const f32x4 a0 = acc[ai][bj][m][0], a1 = acc[ai][bj][m][1];
;                   PLE2(0, a0, 0, bw.x, pw.x) PLE2(2, a0, 2, bw.y, pw.y) PLE2(4, a1, 0, bw.z, pw.z) PLE2(6, a1, 2, bw.w, pw.w) }
;     ...
; #pragma unroll
;                 for (int e = 0; e < 8; ++e) q += r[e] * r[e];
;                 v4u w; w.x = cvt_pk_bf16(r[0], r[1]); w.y = cvt_pk_bf16(r[2], r[3]); w.z = cvt_pk_bf16(r[4], r[5]); w.w = cvt_pk_bf16(r[6], r[7]); *(v4u*)(out + o) = w; }
;             q += __shfl_xor(q, 16); q += __shfl_xor(q, 32); if (fq == 0) ssq[(size_t)row * 16 + u.pn * 4 + wc] = q; }
.LBB0_1780:
	s_or_b64 exec, exec, s[36:37]
	v_add_f32_e32 v34, v195, v196
	v_or_b32_e32 v66, 48, v166
	v_fmamk_f32 v34, v34, 0x3a800000, v190
	v_ashrrev_i32_e32 v67, 31, v66
	v_rsq_f32_e32 v40, v34
	s_waitcnt lgkmcnt(0)
	v_lshlrev_b64 v[34:35], 10, v[66:67]
	v_lshl_add_u64 v[34:35], v[34:35], 0, v[164:165]
	v_lshlrev_b64 v[34:35], 1, v[34:35]
	v_lshl_add_u64 v[36:37], s[10:11], 0, v[34:35]
	v_lshl_add_u64 v[38:39], s[16:17], 0, v[34:35]
	v_or_b32_e32 v34, 0x100, v34
	global_load_dwordx4 v[46:49], v[36:37], off
	global_load_dwordx4 v[42:45], v[38:39], off
	v_lshl_add_u64 v[36:37], s[10:11], 0, v[34:35]
	v_lshl_add_u64 v[34:35], s[16:17], 0, v[34:35]
	v_mul_f32_e32 v68, 0xbfb8aa3b, v40
	global_load_dwordx4 v[38:41], v[36:37], off
	s_nop 0
	global_load_dwordx4 v[34:37], v[34:35], off
	v_pk_mul_f32 v[32:33], v[32:33], v[68:69] op_sel_hi:[1,0]
	v_pk_mul_f32 v[26:27], v[26:27], v[68:69] op_sel_hi:[1,0]
	v_exp_f32_e32 v32, v32
	v_exp_f32_e32 v33, v33
	v_exp_f32_e32 v26, v26
	v_exp_f32_e32 v27, v27
	v_pk_mul_f32 v[30:31], v[30:31], v[68:69] op_sel_hi:[1,0]
	v_pk_add_f32 v[32:33], v[32:33], 1.0 op_sel_hi:[1,0]
	v_exp_f32_e32 v30, v30
	v_exp_f32_e32 v31, v31
	v_rcp_f32_e32 v32, v32
	v_rcp_f32_e32 v33, v33
	v_pk_add_f32 v[26:27], v[26:27], 1.0 op_sel_hi:[1,0]
	v_pk_mul_f32 v[28:29], v[28:29], v[68:69] op_sel_hi:[1,0]
	v_rcp_f32_e32 v26, v26
	v_rcp_f32_e32 v27, v27
	v_exp_f32_e32 v28, v28
	v_exp_f32_e32 v29, v29
	v_pk_mul_f32 v[22:23], v[22:23], v[68:69] op_sel_hi:[1,0]
	v_pk_mul_f32 v[24:25], v[24:25], v[68:69] op_sel_hi:[1,0]
	v_exp_f32_e32 v22, v22
	v_exp_f32_e32 v23, v23
	s_waitcnt vmcnt(9)
	v_lshlrev_b32_e32 v72, 16, v62
	v_and_b32_e32 v73, 0xffff0000, v62
	s_waitcnt vmcnt(8)
	v_lshlrev_b32_e32 v74, 16, v58
	v_and_b32_e32 v75, 0xffff0000, v58
	v_lshlrev_b32_e32 v62, 16, v63
	v_and_b32_e32 v63, 0xffff0000, v63
	v_lshlrev_b32_e32 v58, 16, v59
	v_and_b32_e32 v59, 0xffff0000, v59
	v_exp_f32_e32 v24, v24
	v_exp_f32_e32 v25, v25
	v_pk_mul_f32 v[18:19], v[18:19], v[68:69] op_sel_hi:[1,0]
	v_pk_add_f32 v[30:31], v[30:31], 1.0 op_sel_hi:[1,0]
	v_pk_fma_f32 v[32:33], v[32:33], v[58:59], v[62:63]
	v_lshlrev_b32_e32 v58, 16, v64
	v_and_b32_e32 v59, 0xffff0000, v64
	v_lshlrev_b32_e32 v62, 16, v60
	v_and_b32_e32 v63, 0xffff0000, v60
	v_exp_f32_e32 v18, v18
	v_exp_f32_e32 v19, v19
	v_rcp_f32_e32 v30, v30
	v_rcp_f32_e32 v31, v31
	v_pk_fma_f32 v[58:59], v[26:27], v[62:63], v[58:59]
	v_pk_add_f32 v[26:27], v[28:29], 1.0 op_sel_hi:[1,0]
	v_pk_add_f32 v[22:23], v[22:23], 1.0 op_sel_hi:[1,0]
	v_rcp_f32_e32 v26, v26
	v_rcp_f32_e32 v27, v27
	v_rcp_f32_e32 v22, v22
	v_rcp_f32_e32 v23, v23
	v_pk_add_f32 v[24:25], v[24:25], 1.0 op_sel_hi:[1,0]
	v_pk_add_f32 v[18:19], v[18:19], 1.0 op_sel_hi:[1,0]
	v_rcp_f32_e32 v24, v24
	v_rcp_f32_e32 v25, v25
	v_pk_mul_f32 v[20:21], v[20:21], v[68:69] op_sel_hi:[1,0]
	v_pk_fma_f32 v[30:31], v[30:31], v[74:75], v[72:73]
	v_lshlrev_b32_e32 v28, 16, v65
	v_and_b32_e32 v29, 0xffff0000, v65
	v_lshlrev_b32_e32 v60, 16, v61
	v_and_b32_e32 v61, 0xffff0000, v61
	v_rcp_f32_e32 v18, v18
	v_rcp_f32_e32 v19, v19
	v_exp_f32_e32 v20, v20
	v_exp_f32_e32 v21, v21
	v_pk_fma_f32 v[60:61], v[26:27], v[60:61], v[28:29]
	v_pk_mul_f32 v[62:63], v[30:31], v[30:31]
	v_pk_mul_f32 v[64:65], v[32:33], v[32:33]
	v_cvt_pk_bf16_f32 v26, v30, v31
	v_cvt_pk_bf16_f32 v27, v32, v33
	s_waitcnt vmcnt(7)
	v_lshlrev_b32_e32 v30, 16, v54
	v_and_b32_e32 v31, 0xffff0000, v54
	s_waitcnt vmcnt(6)
	v_lshlrev_b32_e32 v32, 16, v50
	v_and_b32_e32 v33, 0xffff0000, v50
	v_pk_fma_f32 v[22:23], v[22:23], v[32:33], v[30:31]
	v_lshlrev_b32_e32 v30, 16, v55
	v_and_b32_e32 v31, 0xffff0000, v55
	v_lshlrev_b32_e32 v32, 16, v51
	v_and_b32_e32 v33, 0xffff0000, v51
	v_pk_fma_f32 v[24:25], v[24:25], v[32:33], v[30:31]
	v_lshlrev_b32_e32 v30, 16, v56
	v_and_b32_e32 v31, 0xffff0000, v56
	v_lshlrev_b32_e32 v32, 16, v52
	v_and_b32_e32 v33, 0xffff0000, v52
	v_add_f32_e32 v54, v62, v63
	v_pk_fma_f32 v[30:31], v[18:19], v[32:33], v[30:31]
	v_pk_add_f32 v[18:19], v[20:21], 1.0 op_sel_hi:[1,0]
	v_add_f32_e32 v54, v64, v54
	v_pk_mul_f32 v[72:73], v[58:59], v[58:59]
	v_rcp_f32_e32 v18, v18
	v_rcp_f32_e32 v19, v19
	v_add_f32_e32 v54, v65, v54
	v_add_f32_e32 v54, v72, v54
	v_pk_mul_f32 v[74:75], v[60:61], v[60:61]
	v_add_f32_e32 v54, v73, v54
	v_lshlrev_b32_e32 v20, 16, v57
	v_and_b32_e32 v21, 0xffff0000, v57
	v_lshlrev_b32_e32 v32, 16, v53
	v_and_b32_e32 v33, 0xffff0000, v53
	v_add_f32_e32 v54, v74, v54
	v_pk_fma_f32 v[32:33], v[18:19], v[32:33], v[20:21]
	v_pk_mul_f32 v[18:19], v[22:23], v[22:23]
	v_add_f32_e32 v54, v75, v54
	v_add_f32_e32 v18, v18, v54
	v_pk_mul_f32 v[20:21], v[24:25], v[24:25]
	v_add_f32_e32 v18, v19, v18
	v_add_f32_e32 v18, v20, v18
	v_pk_mul_f32 v[50:51], v[30:31], v[30:31]
	v_add_f32_e32 v18, v21, v18
	v_add_f32_e32 v18, v50, v18
	v_pk_mul_f32 v[52:53], v[32:33], v[32:33]
	v_add_f32_e32 v18, v51, v18
	v_add_f32_e32 v18, v52, v18
	v_add_f32_e32 v21, v53, v18
	v_mov_b32_e32 v52, v21
	s_nop 1
	v_permlane16_swap_b32 v21, v52
	v_lshlrev_b64 v[70:71], 11, v[82:83]
	v_lshl_add_u64 v[18:19], s[20:21], 0, v[70:71]
	v_lshl_add_u64 v[50:51], v[164:165], 1, v[18:19]
	v_cvt_pk_bf16_f32 v28, v58, v59
	s_waitcnt lgkmcnt(0)
	v_add_f32_e32 v18, v21, v52
	v_mov_b32_e32 v19, v18
	s_nop 1
	v_permlane32_swap_b32 v18, v19
	v_cvt_pk_bf16_f32 v29, v60, v61
	global_store_dwordx4 v[50:51], v[26:29], off
	v_cvt_pk_bf16_f32 v20, v22, v23
	v_cvt_pk_bf16_f32 v21, v24, v25
	v_cvt_pk_bf16_f32 v22, v30, v31
	v_cvt_pk_bf16_f32 v23, v32, v33
	global_store_dwordx4 v[50:51], v[20:23], off offset:256
	s_and_saveexec_b64 s[36:37], s[6:7]
	s_cbranch_execz .LBB0_1782
	v_lshlrev_b64 v[20:21], 6, v[82:83]
	v_lshl_add_u64 v[20:21], s[18:19], 0, v[20:21]
	v_lshl_add_u64 v[20:21], s[4:5], 2, v[20:21]
	s_lshl_b32 s12, s49, 2
	v_lshl_add_u64 v[20:21], v[20:21], 0, s[12:13]
	s_waitcnt lgkmcnt(0)
	v_add_f32_e32 v18, v18, v19
	global_store_dword v[20:21], v18, off
; __device__ __forceinline__ unsigned cvt_pk_bf16(float lo, float hi) { unsigned r; asm volatile("v_cvt_pk_bf16_f32 %0, %1, %2" : "=v"(r) : "v"(lo), "v"(hi)); return r; }
; #define PLE2(kk, A, e0, BW, PW) { const f32x2 t = (f32x2){A[e0], A[e0 + 1]} * c1; f32x2 d; d.x = __builtin_amdgcn_exp2f(t.x); d.y = __builtin_amdgcn_exp2f(t.y); d = d + 1.0f; \
;                     f32x2 q2; q2.x = __builtin_amdgcn_rcpf(d.x); q2.y = __builtin_amdgcn_rcpf(d.y); const f32x2 o2 = (f32x2){bflo(BW), bfhi(BW)} + (f32x2){bflo(PW), bfhi(PW)} * q2; r[kk] = o2.x; r[kk + 1] = o2.y; }
;     __device__ __forceinline__ void operator()(const pg8::f32x4 (&acc)[2][2][4][2], const Unit& u, int wr, int wc, int fr, int fq) const {
;     ...
;         for (int k = 0; k < 8; ++k) { const int ai = k >> 2, m = k & 3; const int row = row0 + ai * HALF + m * 16; const float rs = rsv[k]; float q = 0.f;
;             v4u cb[2], cp[2];
; #pragma unroll
;             for (int bj = 0; bj < 2; ++bj) { cb[bj] = nb[bj]; cp[bj] = np[bj]; }
;             if (k < 7) {
; #pragma unroll
;                 for (int bj = 0; bj < 2; ++bj) { const size_t o = (size_t)(row0 + ((k + 1) >> 2) * HALF + ((k + 1) & 3) * 16) * DM_ + col0 + bj * HALF; nb[bj] = *(const v4u*)(base + o); np[bj] = *(const v4u*)(pp + o); } }
; #pragma unroll
;             for (int bj = 0; bj < 2; ++bj) { const size_t o = (size_t)row * DM_ + col0 + bj * HALF; const v4u bw = cb[bj], pw = cp[bj];
;                 const float c1 = -1.4426950408889634f * rs; float r[8];
;     ...
;                 { const f32x4 a0 = acc[ai][bj][m][0], a1 = acc[ai][bj][m][1];
;                   PLE2(0, a0, 0, bw.x, pw.x) PLE2(2, a0, 2, bw.y, pw.y) PLE2(4, a1, 0, bw.z, pw.z) PLE2(6, a1, 2, bw.w, pw.w) }
;     ...
; #pragma unroll
;                 for (int e = 0; e < 8; ++e) q += r[e] * r[e];
;                 v4u w; w.x = cvt_pk_bf16(r[0], r[1]); w.y = cvt_pk_bf16(r[2], r[3]); w.z = cvt_pk_bf16(r[4], r[5]); w.w = cvt_pk_bf16(r[6], r[7]); *(v4u*)(out + o) = w; }
;             q += __shfl_xor(q, 16); q += __shfl_xor(q, 32); if (fq == 0) ssq[(size_t)row * 16 + u.pn * 4 + wc] = q; }
.LBB0_1782:
	s_or_b64 exec, exec, s[36:37]
	v_add_f32_e32 v18, v193, v194
	v_fmamk_f32 v18, v18, 0x3a800000, v190
	v_rsq_f32_e32 v20, v18
	s_waitcnt vmcnt(5)
	v_lshlrev_b32_e32 v22, 16, v46
	v_and_b32_e32 v23, 0xffff0000, v46
	s_waitcnt vmcnt(4)
	v_lshlrev_b32_e32 v24, 16, v42
	v_mul_f32_e32 v20, 0xbfb8aa3b, v20
	v_pk_mul_f32 v[14:15], v[14:15], v[20:21] op_sel_hi:[1,0]
	v_pk_mul_f32 v[16:17], v[16:17], v[20:21] op_sel_hi:[1,0]
	v_exp_f32_e32 v14, v14
	v_exp_f32_e32 v15, v15
	v_exp_f32_e32 v16, v16
	v_exp_f32_e32 v17, v17
	v_pk_mul_f32 v[10:11], v[10:11], v[20:21] op_sel_hi:[1,0]
	v_pk_add_f32 v[14:15], v[14:15], 1.0 op_sel_hi:[1,0]
	v_exp_f32_e32 v10, v10
	v_exp_f32_e32 v11, v11
	v_rcp_f32_e32 v14, v14
	v_rcp_f32_e32 v15, v15
	v_pk_add_f32 v[16:17], v[16:17], 1.0 op_sel_hi:[1,0]
	v_pk_add_f32 v[10:11], v[10:11], 1.0 op_sel_hi:[1,0]
	v_rcp_f32_e32 v16, v16
	v_rcp_f32_e32 v17, v17
	v_pk_mul_f32 v[12:13], v[12:13], v[20:21] op_sel_hi:[1,0]
	v_rcp_f32_e32 v10, v10
	v_rcp_f32_e32 v11, v11
	v_exp_f32_e32 v12, v12
	v_exp_f32_e32 v13, v13
	v_pk_mul_f32 v[6:7], v[6:7], v[20:21] op_sel_hi:[1,0]
	v_and_b32_e32 v25, 0xffff0000, v42
	v_exp_f32_e32 v6, v6
	v_exp_f32_e32 v7, v7
	v_pk_mul_f32 v[8:9], v[8:9], v[20:21] op_sel_hi:[1,0]
	v_pk_fma_f32 v[14:15], v[14:15], v[24:25], v[22:23]
	v_lshlrev_b32_e32 v22, 16, v47
	v_and_b32_e32 v23, 0xffff0000, v47
	v_lshlrev_b32_e32 v24, 16, v43
	v_and_b32_e32 v25, 0xffff0000, v43
	v_exp_f32_e32 v8, v8
	v_exp_f32_e32 v9, v9
	v_pk_mul_f32 v[2:3], v[2:3], v[20:21] op_sel_hi:[1,0]
	v_pk_fma_f32 v[16:17], v[16:17], v[24:25], v[22:23]
	v_lshlrev_b32_e32 v22, 16, v48
	v_and_b32_e32 v23, 0xffff0000, v48
	v_lshlrev_b32_e32 v24, 16, v44
	v_and_b32_e32 v25, 0xffff0000, v44
	v_exp_f32_e32 v2, v2
	v_exp_f32_e32 v3, v3
	v_pk_fma_f32 v[22:23], v[10:11], v[24:25], v[22:23]
	v_pk_add_f32 v[10:11], v[12:13], 1.0 op_sel_hi:[1,0]
	v_pk_add_f32 v[6:7], v[6:7], 1.0 op_sel_hi:[1,0]
	v_rcp_f32_e32 v10, v10
	v_rcp_f32_e32 v11, v11
	v_rcp_f32_e32 v6, v6
	v_rcp_f32_e32 v7, v7
	v_pk_add_f32 v[8:9], v[8:9], 1.0 op_sel_hi:[1,0]
	v_pk_add_f32 v[2:3], v[2:3], 1.0 op_sel_hi:[1,0]
	v_rcp_f32_e32 v8, v8
	v_rcp_f32_e32 v9, v9
	v_pk_mul_f32 v[4:5], v[4:5], v[20:21] op_sel_hi:[1,0]
	v_lshlrev_b32_e32 v12, 16, v49
	v_and_b32_e32 v13, 0xffff0000, v49
	v_lshlrev_b32_e32 v24, 16, v45
	v_and_b32_e32 v25, 0xffff0000, v45
	v_rcp_f32_e32 v2, v2
	v_rcp_f32_e32 v3, v3
	v_exp_f32_e32 v4, v4
	v_exp_f32_e32 v5, v5
	v_pk_fma_f32 v[24:25], v[10:11], v[24:25], v[12:13]
	v_pk_mul_f32 v[26:27], v[14:15], v[14:15]
	v_pk_mul_f32 v[28:29], v[16:17], v[16:17]
	v_cvt_pk_bf16_f32 v10, v14, v15
	v_cvt_pk_bf16_f32 v11, v16, v17
	s_waitcnt vmcnt(3)
	v_lshlrev_b32_e32 v14, 16, v38
	v_and_b32_e32 v15, 0xffff0000, v38
	s_waitcnt vmcnt(2)
	v_lshlrev_b32_e32 v16, 16, v34
	v_and_b32_e32 v17, 0xffff0000, v34
	v_pk_fma_f32 v[6:7], v[6:7], v[16:17], v[14:15]
	v_lshlrev_b32_e32 v14, 16, v39
	v_and_b32_e32 v15, 0xffff0000, v39
	v_lshlrev_b32_e32 v16, 16, v35
	v_and_b32_e32 v17, 0xffff0000, v35
	v_pk_mul_f32 v[32:33], v[24:25], v[24:25]
	v_cvt_pk_bf16_f32 v12, v22, v23
	v_cvt_pk_bf16_f32 v13, v24, v25
	v_pk_fma_f32 v[8:9], v[8:9], v[16:17], v[14:15]
	v_lshlrev_b32_e32 v14, 16, v40
	v_and_b32_e32 v15, 0xffff0000, v40
	v_lshlrev_b32_e32 v16, 16, v36
	v_and_b32_e32 v17, 0xffff0000, v36
	v_add_f32_e32 v24, v26, v27
	v_pk_fma_f32 v[14:15], v[2:3], v[16:17], v[14:15]
	v_pk_add_f32 v[2:3], v[4:5], 1.0 op_sel_hi:[1,0]
	v_add_f32_e32 v24, v28, v24
	v_pk_mul_f32 v[30:31], v[22:23], v[22:23]
	v_rcp_f32_e32 v2, v2
	v_rcp_f32_e32 v3, v3
	v_add_f32_e32 v24, v29, v24
	v_add_f32_e32 v24, v30, v24
	v_add_f32_e32 v24, v31, v24
	v_lshlrev_b32_e32 v4, 16, v41
	v_and_b32_e32 v5, 0xffff0000, v41
	v_lshlrev_b32_e32 v16, 16, v37
	v_and_b32_e32 v17, 0xffff0000, v37
	v_add_f32_e32 v24, v32, v24
	v_pk_fma_f32 v[16:17], v[2:3], v[16:17], v[4:5]
	v_pk_mul_f32 v[2:3], v[6:7], v[6:7]
	v_add_f32_e32 v24, v33, v24
	v_add_f32_e32 v2, v2, v24
	v_pk_mul_f32 v[4:5], v[8:9], v[8:9]
	v_add_f32_e32 v2, v3, v2
	v_add_f32_e32 v2, v4, v2
	v_pk_mul_f32 v[20:21], v[14:15], v[14:15]
	v_add_f32_e32 v2, v5, v2
	v_add_f32_e32 v2, v20, v2
	v_pk_mul_f32 v[22:23], v[16:17], v[16:17]
	v_add_f32_e32 v2, v21, v2
	v_add_f32_e32 v2, v22, v2
	v_add_f32_e32 v5, v23, v2
	v_mov_b32_e32 v20, v5
	s_nop 1
	v_permlane16_swap_b32 v5, v20
	s_waitcnt lgkmcnt(1)
	v_lshlrev_b64 v[18:19], 11, v[66:67]
	v_lshl_add_u64 v[2:3], s[20:21], 0, v[18:19]
	v_lshl_add_u64 v[18:19], v[164:165], 1, v[2:3]
	global_store_dwordx4 v[18:19], v[10:13], off
	s_waitcnt lgkmcnt(0)
	v_add_f32_e32 v2, v5, v20
	v_mov_b32_e32 v3, v2
	s_nop 1
	v_permlane32_swap_b32 v2, v3
	v_cvt_pk_bf16_f32 v4, v6, v7
	v_cvt_pk_bf16_f32 v5, v8, v9
	v_cvt_pk_bf16_f32 v6, v14, v15
	v_cvt_pk_bf16_f32 v7, v16, v17
	global_store_dwordx4 v[18:19], v[4:7], off offset:256
	s_and_saveexec_b64 s[36:37], s[6:7]
	s_cbranch_execz .LBB0_1784
	v_lshlrev_b64 v[4:5], 6, v[66:67]
	v_lshl_add_u64 v[4:5], s[18:19], 0, v[4:5]
	v_lshl_add_u64 v[4:5], s[4:5], 2, v[4:5]
	s_lshl_b32 s12, s49, 2
	v_lshl_add_u64 v[4:5], v[4:5], 0, s[12:13]
	s_waitcnt lgkmcnt(0)
	v_add_f32_e32 v2, v2, v3
	global_store_dword v[4:5], v2, off
